# write-through (sc1) stores in all phases except the In/DFT/GU GEMM epilogues, to shorten grid-barrier L2 flushes; on top of the combined version
# baseline (speedup 1.0000x reference)
; #define LAS __attribute__((address_space(3)))
; __device__ __forceinline__ void transpose_item(const float* W, int ldw, int k0, int n0, bf16_t* WT, int ldt, int drow0, int dk0, LAS float* scr, int lane) {
;     float tv[32];
; #pragma unroll
;     for (int i = 0; i < 32; ++i) { const int kk = 2 * i + (lane >> 5); tv[i] = W[(size_t)(k0 + kk) * ldw + n0 + (lane & 31)]; }
; __device__ __forceinline__ void prep_weights(const Params& P, LAS unsigned char* lds, int lay, int bid, int G, int sel) {
;     ...
;           if (r < 2 * I_GU) { if (!((sel >> (r / I_GU)) & 1)) continue; const int mat = lay * 2 + r / I_GU, ii = r % I_GU, kb = ii / 176, nb = ii % 176, n0 = nb * 32;
;               const int drow = n0 < DFF ? (n0 >> 7) * 256 + (n0 & 127) : ((n0 - DFF) >> 7) * 256 + 128 + ((n0 - DFF) & 127);
;               transpose_item(P.w_gu + (size_t)mat * 1024 * 5632, 5632, kb * 64, n0, (bf16_t*)(ws + OFF_WGU + mat * SZ_WGU1), 1024, drow, kb * 64, scr, lane); continue; }
.LBB0_24:
	s_or_b64 exec, exec, s[16:17]
	v_mov_b64_e32 v[32:33], s[78:79]
	v_lshlrev_b32_sdwa v38, v29, sext(v9) dst_sel:DWORD dst_unused:UNUSED_PAD src0_sel:DWORD src1_sel:WORD_0
	v_mad_i64_i32 v[32:33], s[16:17], v7, s13, v[32:33]
	v_or_b32_e32 v31, v38, v12
	v_ashrrev_i32_e32 v9, 31, v8
	v_lshl_add_u64 v[8:9], v[8:9], 2, v[32:33]
	v_mul_i32_i24_e32 v32, 0x1600, v31
	v_lshl_add_u64 v[8:9], v[8:9], 0, v[0:1]
	v_ashrrev_i32_e32 v33, 31, v32
	v_lshl_add_u64 v[8:9], v[32:33], 2, v[8:9]
	v_add_co_u32_e32 v32, vcc, s15, v8
	s_mov_b32 s16, 0x16000
	s_nop 0
	v_addc_co_u32_e32 v33, vcc, 0, v9, vcc
	v_add_co_u32_e32 v34, vcc, s16, v8
	s_mov_b32 s16, 0x2c000
	s_nop 0
	v_addc_co_u32_e32 v35, vcc, 0, v9, vcc
	v_add_co_u32_e32 v40, vcc, s18, v8
	s_nop 1
	v_addc_co_u32_e32 v41, vcc, 0, v9, vcc
	v_add_co_u32_e32 v42, vcc, s16, v8
	s_nop 1
	v_addc_co_u32_e32 v43, vcc, 0, v9, vcc
	v_add_co_u32_e32 v44, vcc, s19, v8
	s_nop 1
	v_addc_co_u32_e32 v45, vcc, 0, v9, vcc
	v_add_co_u32_e32 v46, vcc, s20, v8
	s_nop 1
	v_addc_co_u32_e32 v47, vcc, 0, v9, vcc
	v_add_co_u32_e32 v48, vcc, s21, v8
	s_nop 1
	v_addc_co_u32_e32 v49, vcc, 0, v9, vcc
	global_load_dword v31, v[8:9], off
	global_load_dword v37, v[32:33], off
	global_load_dword v39, v[34:35], off
	global_load_dword v52, v[40:41], off
	global_load_dword v53, v[42:43], off
	global_load_dword v54, v[44:45], off
	global_load_dword v55, v[46:47], off
	global_load_dword v56, v[48:49], off
	v_add_co_u32_e32 v32, vcc, s22, v8
	s_nop 1
	v_addc_co_u32_e32 v33, vcc, 0, v9, vcc
	v_add_co_u32_e32 v34, vcc, s23, v8
	s_nop 1
	v_addc_co_u32_e32 v35, vcc, 0, v9, vcc
	v_add_co_u32_e32 v40, vcc, s24, v8
	s_nop 1
	v_addc_co_u32_e32 v41, vcc, 0, v9, vcc
	v_add_co_u32_e32 v42, vcc, s25, v8
	s_nop 1
	v_addc_co_u32_e32 v43, vcc, 0, v9, vcc
	v_add_co_u32_e32 v44, vcc, s26, v8
	s_nop 1
	v_addc_co_u32_e32 v45, vcc, 0, v9, vcc
	v_add_co_u32_e32 v46, vcc, s27, v8
	s_nop 1
	v_addc_co_u32_e32 v47, vcc, 0, v9, vcc
	v_add_co_u32_e32 v48, vcc, s28, v8
	s_nop 1
	v_addc_co_u32_e32 v49, vcc, 0, v9, vcc
	v_add_co_u32_e32 v50, vcc, s29, v8
	s_nop 1
	v_addc_co_u32_e32 v51, vcc, 0, v9, vcc
	global_load_dword v57, v[32:33], off
	global_load_dword v58, v[34:35], off
	global_load_dword v59, v[40:41], off
	global_load_dword v60, v[42:43], off
	global_load_dword v61, v[44:45], off
	global_load_dword v62, v[46:47], off
	global_load_dword v63, v[48:49], off
	global_load_dword v64, v[50:51], off
	v_add_co_u32_e32 v32, vcc, s30, v8
	s_nop 1
	v_addc_co_u32_e32 v33, vcc, 0, v9, vcc
	v_add_co_u32_e32 v34, vcc, s31, v8
	s_nop 1
	v_addc_co_u32_e32 v35, vcc, 0, v9, vcc
	v_add_co_u32_e32 v40, vcc, s34, v8
	s_nop 1
	v_addc_co_u32_e32 v41, vcc, 0, v9, vcc
	v_add_co_u32_e32 v42, vcc, s35, v8
	s_nop 1
	v_addc_co_u32_e32 v43, vcc, 0, v9, vcc
	v_add_co_u32_e32 v44, vcc, s36, v8
	s_nop 1
	v_addc_co_u32_e32 v45, vcc, 0, v9, vcc
	v_add_co_u32_e32 v46, vcc, s37, v8
	s_nop 1
	v_addc_co_u32_e32 v47, vcc, 0, v9, vcc
	v_add_co_u32_e32 v48, vcc, s38, v8
	s_nop 1
	v_addc_co_u32_e32 v49, vcc, 0, v9, vcc
	v_add_co_u32_e32 v50, vcc, s39, v8
	s_nop 1
	v_addc_co_u32_e32 v51, vcc, 0, v9, vcc
	global_load_dword v65, v[32:33], off
	global_load_dword v66, v[34:35], off
	global_load_dword v67, v[40:41], off
	global_load_dword v68, v[42:43], off
	global_load_dword v69, v[44:45], off
	global_load_dword v70, v[46:47], off
	global_load_dword v71, v[48:49], off
	s_nop 0
	global_load_dword v50, v[50:51], off
	v_add_co_u32_e32 v32, vcc, s40, v8
	s_nop 1
	v_addc_co_u32_e32 v33, vcc, 0, v9, vcc
	v_add_co_u32_e32 v34, vcc, s41, v8
	s_nop 1
	v_addc_co_u32_e32 v35, vcc, 0, v9, vcc
	v_add_co_u32_e32 v40, vcc, s42, v8
	s_nop 1
	v_addc_co_u32_e32 v41, vcc, 0, v9, vcc
	v_add_co_u32_e32 v42, vcc, s43, v8
	s_nop 1
	v_addc_co_u32_e32 v43, vcc, 0, v9, vcc
	v_add_co_u32_e32 v44, vcc, s44, v8
	s_nop 1
	v_addc_co_u32_e32 v45, vcc, 0, v9, vcc
	v_add_co_u32_e32 v46, vcc, s45, v8
	s_nop 1
	v_addc_co_u32_e32 v47, vcc, 0, v9, vcc
	v_add_co_u32_e32 v48, vcc, s46, v8
	s_nop 1
	v_addc_co_u32_e32 v49, vcc, 0, v9, vcc
	v_add_co_u32_e32 v8, vcc, s47, v8
	s_nop 1
	v_addc_co_u32_e32 v9, vcc, 0, v9, vcc
	global_load_dword v32, v[32:33], off
	s_nop 0
	global_load_dword v33, v[34:35], off
	s_nop 0
	global_load_dword v34, v[40:41], off
	global_load_dword v35, v[42:43], off
	s_nop 0
	global_load_dword v40, v[44:45], off
	global_load_dword v41, v[46:47], off
	global_load_dword v42, v[48:49], off
	s_nop 0
	global_load_dword v8, v[8:9], off
	s_waitcnt vmcnt(30)
; #define LAS __attribute__((address_space(3)))
; #define GAS __attribute__((address_space(1)))
; __device__ __forceinline__ unsigned cvt_pk_bf16(float lo, float hi) { unsigned r; asm volatile("v_cvt_pk_bf16_f32 %0, %1, %2" : "=v"(r) : "v"(lo), "v"(hi)); return r; }
; __device__ __forceinline__ void transpose_item(const float* W, int ldw, int k0, int n0, bf16_t* WT, int ldt, int drow0, int dk0, LAS float* scr, int lane) {
;     ...
; #pragma unroll
;     for (int i = 0; i < 32; ++i) { const int kk = 2 * i + (lane >> 5); scr[kk * 33 + (lane & 31)] = tv[i]; }
;     asm volatile("s_waitcnt lgkmcnt(0)" ::: "memory");
;     const int c = lane & 7;
; #pragma unroll
;     for (int j = 0; j < 4; ++j) { const int n = (lane >> 3) + 8 * j; const LAS float* s = scr + (8 * c) * 33 + n;
;         u32x4 o; o.x = cvt_pk_bf16(s[0 * 33], s[1 * 33]); o.y = cvt_pk_bf16(s[2 * 33], s[3 * 33]); o.z = cvt_pk_bf16(s[4 * 33], s[5 * 33]); o.w = cvt_pk_bf16(s[6 * 33], s[7 * 33]);
;         *(GAS u32x4*)((GAS bf16_t*)WT + (size_t)(drow0 + n) * ldt + dk0 + 8 * c) = o; }
;     asm volatile("s_waitcnt lgkmcnt(0)" ::: "memory");
	ds_write2_b32 v20, v31, v37 offset1:66
	s_waitcnt vmcnt(28)
	ds_write2_b32 v20, v39, v52 offset0:132 offset1:198
	s_waitcnt vmcnt(26)
	ds_write2_b32 v21, v53, v54 offset0:8 offset1:74
	s_waitcnt vmcnt(24)
	ds_write2_b32 v21, v55, v56 offset0:140 offset1:206
	s_waitcnt vmcnt(22)
	ds_write2_b32 v22, v57, v58 offset0:16 offset1:82
	s_waitcnt vmcnt(20)
	ds_write2_b32 v22, v59, v60 offset0:148 offset1:214
	s_waitcnt vmcnt(18)
	ds_write2_b32 v23, v61, v62 offset0:24 offset1:90
	s_waitcnt vmcnt(16)
	ds_write2_b32 v23, v63, v64 offset0:156 offset1:222
	s_waitcnt vmcnt(14)
	ds_write2_b32 v24, v65, v66 offset0:32 offset1:98
	s_waitcnt vmcnt(12)
	ds_write2_b32 v24, v67, v68 offset0:164 offset1:230
	s_waitcnt vmcnt(10)
	ds_write2_b32 v25, v69, v70 offset0:40 offset1:106
	s_waitcnt vmcnt(8)
	ds_write2_b32 v25, v71, v50 offset0:172 offset1:238
	s_waitcnt vmcnt(6)
	ds_write2_b32 v26, v32, v33 offset0:48 offset1:114
	s_waitcnt vmcnt(4)
	ds_write2_b32 v26, v34, v35 offset0:180 offset1:246
	s_waitcnt vmcnt(2)
	ds_write2_b32 v27, v40, v41 offset0:56 offset1:122
	s_waitcnt vmcnt(0)
	ds_write2_b32 v27, v42, v8 offset0:188 offset1:254
	s_waitcnt lgkmcnt(0)
	ds_read2_b32 v[8:9], v14 offset1:33
	s_waitcnt lgkmcnt(0)
	v_cvt_pk_bf16_f32 v32, v8, v9
	ds_read2_b32 v[8:9], v14 offset0:66 offset1:99
	s_waitcnt lgkmcnt(0)
	v_cvt_pk_bf16_f32 v33, v8, v9
	ds_read2_b32 v[8:9], v14 offset0:132 offset1:165
	v_mov_b64_e32 v[34:35], s[92:93]
	v_mad_i64_i32 v[40:41], s[16:17], v7, s14, v[34:35]
	s_waitcnt lgkmcnt(0)
	v_cvt_pk_bf16_f32 v34, v8, v9
	ds_read2_b32 v[8:9], v14 offset0:198 offset1:231
	v_ashrrev_i32_e32 v39, 31, v38
	s_waitcnt lgkmcnt(0)
	v_cvt_pk_bf16_f32 v35, v8, v9
	v_add_u32_e32 v8, v30, v13
	v_lshl_add_u64 v[38:39], v[38:39], 1, v[40:41]
	v_mov_b32_e32 v7, v1
	v_ashrrev_i32_e32 v9, 31, v8
	v_lshl_add_u64 v[38:39], v[38:39], 0, v[6:7]
	v_lshlrev_b64 v[8:9], 11, v[8:9]
	v_lshl_add_u64 v[8:9], v[38:39], 0, v[8:9]
	ds_read2_b32 v[40:41], v14 offset0:8 offset1:41
	global_store_dwordx4 v[8:9], v[32:35], off sc1
	s_waitcnt lgkmcnt(0)
	s_nop 0
	v_cvt_pk_bf16_f32 v32, v40, v41
	ds_read2_b32 v[8:9], v14 offset0:74 offset1:107
	s_waitcnt lgkmcnt(0)
	v_cvt_pk_bf16_f32 v33, v8, v9
	ds_read2_b32 v[8:9], v14 offset0:140 offset1:173
	s_waitcnt lgkmcnt(0)
	v_cvt_pk_bf16_f32 v34, v8, v9
	ds_read2_b32 v[8:9], v14 offset0:206 offset1:239
	s_waitcnt lgkmcnt(0)
	v_cvt_pk_bf16_f32 v35, v8, v9
	v_add_u32_e32 v8, v30, v15
	v_ashrrev_i32_e32 v9, 31, v8
	v_lshlrev_b64 v[8:9], 11, v[8:9]
	v_lshl_add_u64 v[8:9], v[38:39], 0, v[8:9]
	ds_read2_b32 v[40:41], v14 offset0:16 offset1:49
	global_store_dwordx4 v[8:9], v[32:35], off sc1
	s_waitcnt lgkmcnt(0)
	s_nop 0
	v_cvt_pk_bf16_f32 v32, v40, v41
	ds_read2_b32 v[8:9], v14 offset0:82 offset1:115
	s_waitcnt lgkmcnt(0)
	v_cvt_pk_bf16_f32 v33, v8, v9
	ds_read2_b32 v[8:9], v14 offset0:148 offset1:181
	s_waitcnt lgkmcnt(0)
	v_cvt_pk_bf16_f32 v34, v8, v9
	ds_read2_b32 v[8:9], v14 offset0:214 offset1:247
	s_waitcnt lgkmcnt(0)
	v_cvt_pk_bf16_f32 v35, v8, v9
	v_add_u32_e32 v8, v30, v16
	v_ashrrev_i32_e32 v9, 31, v8
	v_lshlrev_b64 v[8:9], 11, v[8:9]
	v_lshl_add_u64 v[8:9], v[38:39], 0, v[8:9]
	ds_read2_b32 v[40:41], v14 offset0:24 offset1:57
	global_store_dwordx4 v[8:9], v[32:35], off sc1
	s_waitcnt lgkmcnt(0)
	s_nop 0
	v_cvt_pk_bf16_f32 v32, v40, v41
	ds_read2_b32 v[8:9], v14 offset0:90 offset1:123
	s_waitcnt lgkmcnt(0)
	v_cvt_pk_bf16_f32 v33, v8, v9
	ds_read2_b32 v[8:9], v14 offset0:156 offset1:189
	s_waitcnt lgkmcnt(0)
	v_cvt_pk_bf16_f32 v34, v8, v9
	ds_read2_b32 v[8:9], v14 offset0:222 offset1:255
	s_waitcnt lgkmcnt(0)
	v_cvt_pk_bf16_f32 v35, v8, v9
	v_add_u32_e32 v8, v30, v17
	v_ashrrev_i32_e32 v9, 31, v8
	v_lshlrev_b64 v[8:9], 11, v[8:9]
	v_lshl_add_u64 v[8:9], v[38:39], 0, v[8:9]
	global_store_dwordx4 v[8:9], v[32:35], off sc1
	s_waitcnt lgkmcnt(0)

; #define LAS __attribute__((address_space(3)))
; __device__ __forceinline__ void transpose_item(const float* W, int ldw, int k0, int n0, bf16_t* WT, int ldt, int drow0, int dk0, LAS float* scr, int lane) {
;     float tv[32];
; #pragma unroll
;     for (int i = 0; i < 32; ++i) { const int kk = 2 * i + (lane >> 5); tv[i] = W[(size_t)(k0 + kk) * ldw + n0 + (lane & 31)]; }
; __device__ __forceinline__ void prep_weights(const Params& P, LAS unsigned char* lds, int lay, int bid, int G, int sel) {
;     ...
;           if (r < 2 * I_DN) { if (!((sel >> (2 + r / I_DN)) & 1)) continue; const int mat = lay * 2 + r / I_DN, ii = r % I_DN, kb = ii / 32, nb = ii % 32;
;               transpose_item(P.w_down + (size_t)mat * DFF * 1024, 1024, kb * 64, nb * 32, (bf16_t*)(ws + OFF_WDN + mat * SZ_WDN1), DFF, nb * 32, kb * 64, scr, lane); continue; }
.LBB0_27:
	s_movk_i32 s8, 0x15ff
	v_cmp_lt_i32_e32 vcc, s8, v11
	s_and_saveexec_b64 s[8:9], vcc
	s_xor_b64 s[8:9], exec, s[8:9]
	s_cbranch_execz .LBB0_31
	v_add_u32_e32 v7, 0xffffe480, v11
	s_movk_i32 s10, 0xfa7f
	v_cmp_lt_u32_e32 vcc, s10, v7
	s_and_saveexec_b64 s[10:11], vcc
	s_cbranch_execz .LBB0_30
	v_and_b32_e32 v7, 0xfc0, v19
	v_and_b32_e32 v37, 0x3e0, v18
	v_or_b32_e32 v30, v7, v12
	v_lshlrev_b32_e32 v8, 2, v37
	v_mov_b32_e32 v9, v1
	v_lshl_add_u64 v[8:9], v[4:5], 0, v[8:9]
	v_lshlrev_b32_e32 v30, 12, v30
	v_mov_b32_e32 v31, v1
	v_lshl_add_u64 v[8:9], v[8:9], 0, v[30:31]
	v_add_co_u32_e32 v30, vcc, 0x2000, v8
	s_nop 1
	v_addc_co_u32_e32 v31, vcc, 0, v9, vcc
	v_add_co_u32_e32 v32, vcc, 0x4000, v8
	s_nop 1
	v_addc_co_u32_e32 v33, vcc, 0, v9, vcc
	v_add_co_u32_e32 v34, vcc, 0x6000, v8
	s_nop 1
	v_addc_co_u32_e32 v35, vcc, 0, v9, vcc
	v_add_co_u32_e32 v38, vcc, 0x8000, v8
	s_nop 1
	v_addc_co_u32_e32 v39, vcc, 0, v9, vcc
	v_add_co_u32_e32 v40, vcc, 0xa000, v8
	s_nop 1
	v_addc_co_u32_e32 v41, vcc, 0, v9, vcc
	v_add_co_u32_e32 v42, vcc, 0xc000, v8
	s_nop 1
	v_addc_co_u32_e32 v43, vcc, 0, v9, vcc
	v_add_co_u32_e32 v44, vcc, 0xe000, v8
	s_nop 1
	v_addc_co_u32_e32 v45, vcc, 0, v9, vcc
	global_load_dword v48, v[8:9], off
	global_load_dword v49, v[30:31], off
	global_load_dword v50, v[32:33], off
	global_load_dword v51, v[34:35], off
	global_load_dword v52, v[38:39], off
	global_load_dword v53, v[40:41], off
	global_load_dword v54, v[42:43], off
	global_load_dword v55, v[44:45], off
	v_add_co_u32_e32 v30, vcc, 0x10000, v8
	s_nop 1
	v_addc_co_u32_e32 v31, vcc, 0, v9, vcc
	v_add_co_u32_e32 v32, vcc, 0x12000, v8
	s_nop 1
	v_addc_co_u32_e32 v33, vcc, 0, v9, vcc
	v_add_co_u32_e32 v34, vcc, 0x14000, v8
	s_nop 1
	v_addc_co_u32_e32 v35, vcc, 0, v9, vcc
	v_add_co_u32_e32 v38, vcc, 0x16000, v8
	s_nop 1
	v_addc_co_u32_e32 v39, vcc, 0, v9, vcc
	v_add_co_u32_e32 v40, vcc, 0x18000, v8
	s_nop 1
	v_addc_co_u32_e32 v41, vcc, 0, v9, vcc
	v_add_co_u32_e32 v42, vcc, 0x1a000, v8
	s_nop 1
	v_addc_co_u32_e32 v43, vcc, 0, v9, vcc
	v_add_co_u32_e32 v44, vcc, 0x1c000, v8
	s_nop 1
	v_addc_co_u32_e32 v45, vcc, 0, v9, vcc
	v_add_co_u32_e32 v46, vcc, 0x1e000, v8
	s_nop 1
	v_addc_co_u32_e32 v47, vcc, 0, v9, vcc
	global_load_dword v56, v[30:31], off
	global_load_dword v57, v[32:33], off
	global_load_dword v58, v[34:35], off
	global_load_dword v59, v[38:39], off
	global_load_dword v60, v[40:41], off
	global_load_dword v61, v[42:43], off
	global_load_dword v62, v[44:45], off
	global_load_dword v63, v[46:47], off
	v_add_co_u32_e32 v30, vcc, 0x20000, v8
	s_nop 1
	v_addc_co_u32_e32 v31, vcc, 0, v9, vcc
	v_add_co_u32_e32 v32, vcc, 0x22000, v8
	s_nop 1
	v_addc_co_u32_e32 v33, vcc, 0, v9, vcc
	v_add_co_u32_e32 v34, vcc, 0x24000, v8
	s_nop 1
	v_addc_co_u32_e32 v35, vcc, 0, v9, vcc
	v_add_co_u32_e32 v38, vcc, 0x26000, v8
	s_nop 1
	v_addc_co_u32_e32 v39, vcc, 0, v9, vcc
	v_add_co_u32_e32 v40, vcc, 0x28000, v8
	s_nop 1
	v_addc_co_u32_e32 v41, vcc, 0, v9, vcc
	v_add_co_u32_e32 v42, vcc, 0x2a000, v8
	s_nop 1
	v_addc_co_u32_e32 v43, vcc, 0, v9, vcc
	v_add_co_u32_e32 v44, vcc, 0x2c000, v8
	s_nop 1
	v_addc_co_u32_e32 v45, vcc, 0, v9, vcc
	v_add_co_u32_e32 v46, vcc, 0x2e000, v8
	s_nop 1
	v_addc_co_u32_e32 v47, vcc, 0, v9, vcc
	global_load_dword v64, v[30:31], off
	global_load_dword v65, v[32:33], off
	global_load_dword v66, v[34:35], off
	global_load_dword v67, v[38:39], off
	global_load_dword v68, v[40:41], off
	global_load_dword v69, v[42:43], off
	global_load_dword v70, v[44:45], off
	s_nop 0
	global_load_dword v46, v[46:47], off
	v_add_co_u32_e32 v30, vcc, 0x30000, v8
	s_nop 1
	v_addc_co_u32_e32 v31, vcc, 0, v9, vcc
	v_add_co_u32_e32 v32, vcc, 0x32000, v8
	s_nop 1
	v_addc_co_u32_e32 v33, vcc, 0, v9, vcc
	v_add_co_u32_e32 v34, vcc, 0x34000, v8
	s_nop 1
	v_addc_co_u32_e32 v35, vcc, 0, v9, vcc
	v_add_co_u32_e32 v38, vcc, 0x36000, v8
	s_nop 1
	v_addc_co_u32_e32 v39, vcc, 0, v9, vcc
	v_add_co_u32_e32 v40, vcc, 0x38000, v8
	s_nop 1
	v_addc_co_u32_e32 v41, vcc, 0, v9, vcc
	v_add_co_u32_e32 v42, vcc, 0x3a000, v8
	s_nop 1
	v_addc_co_u32_e32 v43, vcc, 0, v9, vcc
	v_add_co_u32_e32 v44, vcc, 0x3c000, v8
	s_nop 1
	v_addc_co_u32_e32 v45, vcc, 0, v9, vcc
	v_add_co_u32_e32 v8, vcc, 0x3e000, v8
	s_nop 1
	v_addc_co_u32_e32 v9, vcc, 0, v9, vcc
	global_load_dword v30, v[30:31], off
	s_nop 0
	global_load_dword v31, v[32:33], off
	s_nop 0
	global_load_dword v32, v[34:35], off
	global_load_dword v33, v[38:39], off
	s_nop 0
	global_load_dword v34, v[40:41], off
	global_load_dword v35, v[42:43], off
	global_load_dword v38, v[44:45], off
	s_nop 0
	global_load_dword v8, v[8:9], off
	s_waitcnt vmcnt(30)
; #define LAS __attribute__((address_space(3)))
; #define GAS __attribute__((address_space(1)))
; __device__ __forceinline__ unsigned cvt_pk_bf16(float lo, float hi) { unsigned r; asm volatile("v_cvt_pk_bf16_f32 %0, %1, %2" : "=v"(r) : "v"(lo), "v"(hi)); return r; }
; __device__ __forceinline__ void transpose_item(const float* W, int ldw, int k0, int n0, bf16_t* WT, int ldt, int drow0, int dk0, LAS float* scr, int lane) {
;     ...
; #pragma unroll
;     for (int i = 0; i < 32; ++i) { const int kk = 2 * i + (lane >> 5); scr[kk * 33 + (lane & 31)] = tv[i]; }
;     asm volatile("s_waitcnt lgkmcnt(0)" ::: "memory");
;     const int c = lane & 7;
; #pragma unroll
;     for (int j = 0; j < 4; ++j) { const int n = (lane >> 3) + 8 * j; const LAS float* s = scr + (8 * c) * 33 + n;
;         u32x4 o; o.x = cvt_pk_bf16(s[0 * 33], s[1 * 33]); o.y = cvt_pk_bf16(s[2 * 33], s[3 * 33]); o.z = cvt_pk_bf16(s[4 * 33], s[5 * 33]); o.w = cvt_pk_bf16(s[6 * 33], s[7 * 33]);
;         *(GAS u32x4*)((GAS bf16_t*)WT + (size_t)(drow0 + n) * ldt + dk0 + 8 * c) = o; }
;     asm volatile("s_waitcnt lgkmcnt(0)" ::: "memory");
	ds_write2_b32 v20, v48, v49 offset1:66
	s_waitcnt vmcnt(28)
	ds_write2_b32 v20, v50, v51 offset0:132 offset1:198
	s_waitcnt vmcnt(26)
	ds_write2_b32 v21, v52, v53 offset0:8 offset1:74
	s_waitcnt vmcnt(24)
	ds_write2_b32 v21, v54, v55 offset0:140 offset1:206
	s_waitcnt vmcnt(22)
	ds_write2_b32 v22, v56, v57 offset0:16 offset1:82
	s_waitcnt vmcnt(20)
	ds_write2_b32 v22, v58, v59 offset0:148 offset1:214
	s_waitcnt vmcnt(18)
	ds_write2_b32 v23, v60, v61 offset0:24 offset1:90
	s_waitcnt vmcnt(16)
	ds_write2_b32 v23, v62, v63 offset0:156 offset1:222
	s_waitcnt vmcnt(14)
	ds_write2_b32 v24, v64, v65 offset0:32 offset1:98
	s_waitcnt vmcnt(12)
	ds_write2_b32 v24, v66, v67 offset0:164 offset1:230
	s_waitcnt vmcnt(10)
	ds_write2_b32 v25, v68, v69 offset0:40 offset1:106
	s_waitcnt vmcnt(8)
	ds_write2_b32 v25, v70, v46 offset0:172 offset1:238
	s_waitcnt vmcnt(6)
	ds_write2_b32 v26, v30, v31 offset0:48 offset1:114
	s_waitcnt vmcnt(4)
	ds_write2_b32 v26, v32, v33 offset0:180 offset1:246
	s_waitcnt vmcnt(2)
	ds_write2_b32 v27, v34, v35 offset0:56 offset1:122
	s_waitcnt vmcnt(0)
	ds_write2_b32 v27, v38, v8 offset0:188 offset1:254
	s_waitcnt lgkmcnt(0)
	ds_read2_b32 v[8:9], v14 offset1:33
	s_waitcnt lgkmcnt(0)
	v_cvt_pk_bf16_f32 v30, v8, v9
	ds_read2_b32 v[8:9], v14 offset0:66 offset1:99
	v_lshlrev_b32_e32 v34, 1, v7
	v_or_b32_e32 v7, v37, v13
	s_waitcnt lgkmcnt(0)
	v_cvt_pk_bf16_f32 v31, v8, v9
	ds_read2_b32 v[8:9], v14 offset0:132 offset1:165
	v_mov_b32_e32 v35, v1
	v_mul_u32_u24_e32 v7, 0xb00, v7
	s_waitcnt lgkmcnt(0)
	v_cvt_pk_bf16_f32 v32, v8, v9
	ds_read2_b32 v[8:9], v14 offset0:198 offset1:231
	v_lshl_add_u64 v[34:35], v[2:3], 0, v[34:35]
	v_lshlrev_b32_e32 v38, 1, v7
	v_mov_b32_e32 v39, v1
	s_waitcnt lgkmcnt(0)
	v_cvt_pk_bf16_f32 v33, v8, v9
	ds_read2_b32 v[8:9], v14 offset0:8 offset1:41
	v_lshl_add_u64 v[38:39], v[34:35], 0, v[38:39]
	global_store_dwordx4 v[38:39], v[30:33], off sc1
	v_or_b32_e32 v7, v37, v15
	v_mul_u32_u24_e32 v7, 0xb00, v7
	s_waitcnt lgkmcnt(0)
	v_cvt_pk_bf16_f32 v30, v8, v9
	ds_read2_b32 v[8:9], v14 offset0:74 offset1:107
	s_waitcnt lgkmcnt(0)
	v_cvt_pk_bf16_f32 v31, v8, v9
	ds_read2_b32 v[8:9], v14 offset0:140 offset1:173
	s_waitcnt lgkmcnt(0)
	v_cvt_pk_bf16_f32 v32, v8, v9
	ds_read2_b32 v[8:9], v14 offset0:206 offset1:239
	v_lshlrev_b32_e32 v38, 1, v7
	v_mov_b32_e32 v39, v1
	s_waitcnt lgkmcnt(0)
	v_cvt_pk_bf16_f32 v33, v8, v9
	ds_read2_b32 v[8:9], v14 offset0:16 offset1:49
	v_lshl_add_u64 v[38:39], v[34:35], 0, v[38:39]
	global_store_dwordx4 v[38:39], v[30:33], off sc1
	v_or_b32_e32 v7, v37, v16
	v_mul_u32_u24_e32 v7, 0xb00, v7
	s_waitcnt lgkmcnt(0)
	v_cvt_pk_bf16_f32 v30, v8, v9
	ds_read2_b32 v[8:9], v14 offset0:82 offset1:115
	s_waitcnt lgkmcnt(0)
	v_cvt_pk_bf16_f32 v31, v8, v9
	ds_read2_b32 v[8:9], v14 offset0:148 offset1:181
	s_waitcnt lgkmcnt(0)
	v_cvt_pk_bf16_f32 v32, v8, v9
	ds_read2_b32 v[8:9], v14 offset0:214 offset1:247
	v_lshlrev_b32_e32 v38, 1, v7
	v_mov_b32_e32 v39, v1
	s_waitcnt lgkmcnt(0)
	v_cvt_pk_bf16_f32 v33, v8, v9
	ds_read2_b32 v[8:9], v14 offset0:24 offset1:57
	v_lshl_add_u64 v[38:39], v[34:35], 0, v[38:39]
	global_store_dwordx4 v[38:39], v[30:33], off sc1
	v_or_b32_e32 v7, v37, v17
	v_mul_u32_u24_e32 v7, 0xb00, v7
	s_waitcnt lgkmcnt(0)
	v_cvt_pk_bf16_f32 v30, v8, v9
	ds_read2_b32 v[8:9], v14 offset0:90 offset1:123
	s_waitcnt lgkmcnt(0)
	v_cvt_pk_bf16_f32 v31, v8, v9
	ds_read2_b32 v[8:9], v14 offset0:156 offset1:189
	s_waitcnt lgkmcnt(0)
	v_cvt_pk_bf16_f32 v32, v8, v9
	ds_read2_b32 v[8:9], v14 offset0:222 offset1:255
	s_waitcnt lgkmcnt(0)
	v_cvt_pk_bf16_f32 v33, v8, v9
	v_lshlrev_b32_e32 v8, 1, v7
	v_mov_b32_e32 v9, v1
	v_lshl_add_u64 v[8:9], v[34:35], 0, v[8:9]
	global_store_dwordx4 v[8:9], v[30:33], off sc1
	s_waitcnt lgkmcnt(0)

; __device__ __forceinline__ void prep_weights(const Params& P, LAS unsigned char* lds, int lay, int bid, int G, int sel) {
;     ...
;       for (int idx = gt; idx < ((sel & 32) ? 256 * 1024 : 0); idx += NGT) { const int n = idx & 1023, gj = (idx >> 10) & 255, g = gj >> 6, j = gj & 63;
;           const float* wp = P.w_out + (size_t)l * 1024 * 1024 + (size_t)(768 + g * 64) * 1024 + n; float cs = 0.f, sn = 0.f;
; #pragma unroll 1
;           for (int m0 = 0; m0 < 64; m0 += 32) { float wv[32];
; #pragma unroll
;               for (int m = 0; m < 32; ++m) wv[m] = wp[(size_t)(m0 + m) * 1024];
; #pragma unroll
;               for (int m = 0; m < 32; ++m) { const int t = ((m0 + m) * j) & 63; cs += tab64[t] * wv[m]; sn += tab64[(t + 48) & 63] * wv[m]; } }
.LBB0_40:
	s_lshl_b32 s10, s13, 10
	v_lshl_add_u64 v[22:23], s[10:11], 2, v[4:5]
	v_mul_u32_u24_e32 v2, s13, v19
	v_mad_u32_u24 v8, s13, v19, 48
	v_mad_u32_u24 v9, s13, v19, v19
	v_add_co_u32_e32 v14, vcc, 0x1000, v22
	v_and_b32_e32 v10, 32, v2
	v_and_b32_e32 v8, 48, v8
	v_and_b32_e32 v11, 63, v9
	v_add_u32_e32 v12, 48, v9
	v_add_u32_e32 v9, v9, v19
	v_addc_co_u32_e32 v15, vcc, 0, v23, vcc
	v_lshl_add_u32 v10, v10, 2, s3
	v_lshl_add_u32 v16, v8, 2, s3
	v_and_b32_e32 v17, 62, v9
	v_add_u32_e32 v18, 48, v9
	v_add_u32_e32 v21, v9, v19
	v_add_co_u32_e32 v20, vcc, 0x2000, v22
	global_load_dword v2, v[22:23], off
	v_lshl_add_u32 v11, v11, 2, s3
	ds_read_b32 v8, v10
	ds_read_b32 v9, v16
	ds_read_b32 v10, v11
	v_lshl_add_u32 v16, v17, 2, s3
	v_and_b32_e32 v17, 62, v18
	v_and_b32_e32 v18, 63, v21
	v_add_u32_e32 v25, 48, v21
	v_add_u32_e32 v26, v21, v19
	v_addc_co_u32_e32 v21, vcc, 0, v23, vcc
	v_and_b32_e32 v12, 63, v12
	v_add_co_u32_e32 v24, vcc, 0x3000, v22
	v_lshl_add_u32 v11, v12, 2, s3
	global_load_dword v12, v[14:15], off
	v_lshl_add_u32 v15, v17, 2, s3
	v_and_b32_e32 v17, 63, v25
	v_addc_co_u32_e32 v25, vcc, 0, v23, vcc
	v_add_co_u32_e32 v28, vcc, 0x4000, v22
	ds_read_b32 v11, v11
	ds_read_b32 v14, v16
	v_lshl_add_u32 v16, v18, 2, s3
	v_and_b32_e32 v18, 60, v26
	v_addc_co_u32_e32 v29, vcc, 0, v23, vcc
	v_lshl_add_u32 v17, v17, 2, s3
	v_lshl_add_u32 v31, v18, 2, s3
	v_add_co_u32_e32 v30, vcc, 0x5000, v22
	ds_read_b32 v15, v15
	ds_read_b32 v16, v16
	global_load_dword v18, v[20:21], off
	s_nop 0
	global_load_dword v20, v[24:25], off
	ds_read_b32 v17, v17
	ds_read_b32 v24, v31
	v_addc_co_u32_e32 v31, vcc, 0, v23, vcc
	v_add_co_u32_e32 v38, vcc, 0x6000, v22
	v_add_u32_e32 v27, 48, v26
	s_nop 0
	v_addc_co_u32_e32 v39, vcc, 0, v23, vcc
	v_add_co_u32_e32 v40, vcc, 0x7000, v22
	v_add_u32_e32 v26, v26, v19
	s_nop 0
	v_addc_co_u32_e32 v41, vcc, 0, v23, vcc
	v_add_co_u32_e32 v46, vcc, 0x8000, v22
	v_and_b32_e32 v27, 60, v27
	s_nop 0
	v_addc_co_u32_e32 v47, vcc, 0, v23, vcc
	v_add_co_u32_e32 v48, vcc, 0x9000, v22
	v_and_b32_e32 v32, 63, v26
	s_nop 0
	v_addc_co_u32_e32 v49, vcc, 0, v23, vcc
	v_add_co_u32_e32 v54, vcc, 0xa000, v22
	v_add_u32_e32 v33, 48, v26
	s_nop 0
	v_addc_co_u32_e32 v55, vcc, 0, v23, vcc
	v_add_co_u32_e32 v56, vcc, 0xb000, v22
	v_add_u32_e32 v26, v26, v19
	s_nop 0
	v_addc_co_u32_e32 v57, vcc, 0, v23, vcc
	v_add_co_u32_e32 v62, vcc, 0xc000, v22
	v_lshl_add_u32 v21, v27, 2, s3
	s_nop 0
	v_addc_co_u32_e32 v63, vcc, 0, v23, vcc
	v_add_co_u32_e32 v64, vcc, 0xd000, v22
	v_lshl_add_u32 v27, v32, 2, s3
	s_nop 0
	v_addc_co_u32_e32 v65, vcc, 0, v23, vcc
	v_add_co_u32_e32 v70, vcc, 0xe000, v22
	v_and_b32_e32 v32, 63, v33
	s_nop 0
	v_addc_co_u32_e32 v71, vcc, 0, v23, vcc
	v_add_co_u32_e32 v72, vcc, 0xf000, v22
	v_and_b32_e32 v33, 62, v26
	s_nop 0
	v_addc_co_u32_e32 v73, vcc, 0, v23, vcc
	v_add_co_u32_e32 v74, vcc, 0x10000, v22
	v_add_u32_e32 v34, 48, v26
	s_nop 0
	v_addc_co_u32_e32 v75, vcc, 0, v23, vcc
	v_add_co_u32_e32 v76, vcc, 0x11000, v22
	v_add_u32_e32 v35, v26, v19
	s_nop 0
	v_addc_co_u32_e32 v77, vcc, 0, v23, vcc
	v_add_co_u32_e32 v80, vcc, 0x12000, v22
	ds_read_b32 v25, v21
	ds_read_b32 v26, v27
	v_lshl_add_u32 v21, v32, 2, s3
	v_lshl_add_u32 v32, v33, 2, s3
	v_and_b32_e32 v33, 62, v34
	v_and_b32_e32 v34, 63, v35
	v_add_u32_e32 v37, 48, v35
	v_add_u32_e32 v35, v35, v19
	global_load_dword v28, v[28:29], off
	s_nop 0
	global_load_dword v30, v[30:31], off
	v_addc_co_u32_e32 v81, vcc, 0, v23, vcc
	ds_read_b32 v27, v21
	ds_read_b32 v32, v32
	v_lshl_add_u32 v21, v33, 2, s3
	v_lshl_add_u32 v29, v34, 2, s3
	v_and_b32_e32 v31, 63, v37
	v_and_b32_e32 v37, 56, v35
	v_add_u32_e32 v42, 48, v35
	v_add_u32_e32 v35, v35, v19
	v_add_co_u32_e32 v84, vcc, 0x13000, v22
	ds_read_b32 v33, v21
	ds_read_b32 v34, v29
	v_lshl_add_u32 v21, v31, 2, s3
	v_lshl_add_u32 v29, v37, 2, s3
	v_and_b32_e32 v31, 56, v42
	v_and_b32_e32 v37, 63, v35
	v_add_u32_e32 v43, 48, v35
	v_add_u32_e32 v44, v35, v19
	global_load_dword v38, v[38:39], off
	s_nop 0
	global_load_dword v40, v[40:41], off
	v_addc_co_u32_e32 v85, vcc, 0, v23, vcc
	ds_read_b32 v35, v21
	ds_read_b32 v42, v29
	v_lshl_add_u32 v21, v31, 2, s3
	v_lshl_add_u32 v29, v37, 2, s3
	v_and_b32_e32 v31, 63, v43
	v_and_b32_e32 v37, 62, v44
	v_add_u32_e32 v39, 48, v44
	v_add_u32_e32 v41, v44, v19
	v_add_co_u32_e32 v88, vcc, 0x14000, v22
	ds_read_b32 v43, v21
	ds_read_b32 v44, v29
	v_lshl_add_u32 v21, v31, 2, s3
	v_lshl_add_u32 v29, v37, 2, s3
	v_and_b32_e32 v31, 62, v39
	v_and_b32_e32 v37, 63, v41
	v_add_u32_e32 v39, 48, v41
	v_add_u32_e32 v41, v41, v19
	global_load_dword v46, v[46:47], off
	s_nop 0
	global_load_dword v48, v[48:49], off
	v_addc_co_u32_e32 v89, vcc, 0, v23, vcc
	ds_read_b32 v45, v21
	ds_read_b32 v50, v29
	v_lshl_add_u32 v21, v31, 2, s3
	v_lshl_add_u32 v29, v37, 2, s3
	v_and_b32_e32 v31, 63, v39
	v_and_b32_e32 v37, 60, v41
	v_add_u32_e32 v39, 48, v41
	v_add_u32_e32 v41, v41, v19
	v_add_co_u32_e32 v92, vcc, 0x15000, v22
	ds_read_b32 v51, v21
	ds_read_b32 v52, v29
	v_lshl_add_u32 v21, v31, 2, s3
	v_lshl_add_u32 v29, v37, 2, s3
	v_and_b32_e32 v31, 60, v39
	v_and_b32_e32 v37, 63, v41
	v_add_u32_e32 v39, 48, v41
	v_add_u32_e32 v41, v41, v19
	global_load_dword v54, v[54:55], off
	s_nop 0
	global_load_dword v56, v[56:57], off
	v_addc_co_u32_e32 v93, vcc, 0, v23, vcc
	ds_read_b32 v53, v21
	ds_read_b32 v58, v29
	v_lshl_add_u32 v21, v31, 2, s3
	v_lshl_add_u32 v29, v37, 2, s3
	v_and_b32_e32 v31, 63, v39
	v_and_b32_e32 v37, 62, v41
	v_add_u32_e32 v39, 48, v41
	v_add_u32_e32 v41, v41, v19
	v_add_co_u32_e32 v96, vcc, 0x16000, v22
	ds_read_b32 v59, v21
	ds_read_b32 v60, v29
	v_lshl_add_u32 v21, v31, 2, s3
	v_lshl_add_u32 v29, v37, 2, s3
; __device__ __forceinline__ void prep_weights(const Params& P, LAS unsigned char* lds, int lay, int bid, int G, int sel) {
;     ...
;           for (int m0 = 0; m0 < 64; m0 += 32) { float wv[32];
; #pragma unroll
;               for (int m = 0; m < 32; ++m) wv[m] = wp[(size_t)(m0 + m) * 1024];
; #pragma unroll
;               for (int m = 0; m < 32; ++m) { const int t = ((m0 + m) * j) & 63; cs += tab64[t] * wv[m]; sn += tab64[(t + 48) & 63] * wv[m]; } }
	v_and_b32_e32 v31, 62, v39
	v_and_b32_e32 v37, 63, v41
	v_add_u32_e32 v39, 48, v41
	v_add_u32_e32 v41, v41, v19
	global_load_dword v62, v[62:63], off
	s_nop 0
	global_load_dword v64, v[64:65], off
	v_addc_co_u32_e32 v97, vcc, 0, v23, vcc
	ds_read_b32 v61, v21
	ds_read_b32 v66, v29
	v_lshl_add_u32 v21, v31, 2, s3
	v_lshl_add_u32 v29, v37, 2, s3
	v_and_b32_e32 v31, 63, v39
	v_and_b32_e32 v37, 48, v41
	v_add_u32_e32 v39, 48, v41
	v_add_u32_e32 v41, v41, v19
	v_add_co_u32_e32 v100, vcc, 0x17000, v22
	ds_read_b32 v67, v21
	ds_read_b32 v68, v29
	v_lshl_add_u32 v21, v31, 2, s3
	v_lshl_add_u32 v29, v37, 2, s3
	v_and_b32_e32 v31, 48, v39
	v_and_b32_e32 v37, 63, v41
	v_add_u32_e32 v39, 48, v41
	v_add_u32_e32 v41, v41, v19
	global_load_dword v70, v[70:71], off
	s_nop 0
	global_load_dword v72, v[72:73], off
	v_addc_co_u32_e32 v101, vcc, 0, v23, vcc
	ds_read_b32 v69, v21
	ds_read_b32 v78, v29
	v_lshl_add_u32 v21, v31, 2, s3
	v_lshl_add_u32 v29, v37, 2, s3
	v_and_b32_e32 v31, 63, v39
	v_and_b32_e32 v37, 62, v41
	v_add_u32_e32 v39, 48, v41
	v_add_u32_e32 v41, v41, v19
	v_add_co_u32_e32 v104, vcc, 0x18000, v22
	ds_read_b32 v79, v21
	ds_read_b32 v82, v29
	v_lshl_add_u32 v21, v31, 2, s3
	v_lshl_add_u32 v29, v37, 2, s3
	v_and_b32_e32 v31, 62, v39
	v_and_b32_e32 v37, 63, v41
	v_add_u32_e32 v39, 48, v41
	v_add_u32_e32 v41, v41, v19
	global_load_dword v74, v[74:75], off
	s_nop 0
	global_load_dword v76, v[76:77], off
	v_addc_co_u32_e32 v105, vcc, 0, v23, vcc
	ds_read_b32 v83, v21
	ds_read_b32 v86, v29
	v_lshl_add_u32 v21, v31, 2, s3
	v_lshl_add_u32 v29, v37, 2, s3
	v_and_b32_e32 v31, 63, v39
	v_and_b32_e32 v37, 60, v41
	v_add_u32_e32 v39, 48, v41
	v_add_u32_e32 v41, v41, v19
	v_add_co_u32_e32 v108, vcc, 0x19000, v22
	ds_read_b32 v87, v21
	ds_read_b32 v90, v29
	v_lshl_add_u32 v21, v31, 2, s3
	v_lshl_add_u32 v29, v37, 2, s3
	v_and_b32_e32 v31, 60, v39
	v_and_b32_e32 v37, 63, v41
	v_add_u32_e32 v39, 48, v41
	v_add_u32_e32 v41, v41, v19
	global_load_dword v80, v[80:81], off
	s_nop 0
	global_load_dword v84, v[84:85], off
	v_addc_co_u32_e32 v109, vcc, 0, v23, vcc
	ds_read_b32 v91, v21
	ds_read_b32 v94, v29
	v_lshl_add_u32 v21, v31, 2, s3
	v_lshl_add_u32 v29, v37, 2, s3
	v_and_b32_e32 v31, 63, v39
	v_and_b32_e32 v37, 62, v41
	v_add_u32_e32 v39, 48, v41
	v_add_u32_e32 v41, v41, v19
	v_add_co_u32_e32 v112, vcc, 0x1a000, v22
	ds_read_b32 v95, v21
	ds_read_b32 v98, v29
	v_lshl_add_u32 v21, v31, 2, s3
	v_and_b32_e32 v31, 62, v39
	v_add_u32_e32 v39, 48, v41
	global_load_dword v88, v[88:89], off
	s_nop 0
	global_load_dword v92, v[92:93], off
	v_addc_co_u32_e32 v113, vcc, 0, v23, vcc
	v_lshl_add_u32 v29, v37, 2, s3
	v_and_b32_e32 v37, 63, v41
	v_add_u32_e32 v41, v41, v19
	ds_read_b32 v99, v21
	ds_read_b32 v102, v29
	v_lshl_add_u32 v21, v31, 2, s3
	v_and_b32_e32 v31, 63, v39
	global_load_dword v96, v[96:97], off
	v_add_co_u32_e32 v114, vcc, 0x1b000, v22
	v_lshl_add_u32 v29, v37, 2, s3
	v_and_b32_e32 v37, 56, v41
	v_lshl_add_u32 v31, v31, 2, s3
	ds_read_b32 v103, v21
	ds_read_b32 v106, v29
	global_load_dword v100, v[100:101], off
	v_addc_co_u32_e32 v115, vcc, 0, v23, vcc
	v_lshl_add_u32 v37, v37, 2, s3
	ds_read_b32 v107, v31
	ds_read_b32 v110, v37
	global_load_dword v104, v[104:105], off
	v_add_co_u32_e32 v116, vcc, 0x1c000, v22
	global_load_dword v108, v[108:109], off
	s_nop 0
	v_addc_co_u32_e32 v117, vcc, 0, v23, vcc
	global_load_dword v112, v[112:113], off
	v_add_co_u32_e32 v118, vcc, 0x1d000, v22
	global_load_dword v114, v[114:115], off
	s_nop 0
	v_addc_co_u32_e32 v119, vcc, 0, v23, vcc
	v_add_co_u32_e32 v120, vcc, 0x1e000, v22
	global_load_dword v116, v[116:117], off
	s_nop 0
	v_addc_co_u32_e32 v121, vcc, 0, v23, vcc
	global_load_dword v118, v[118:119], off
	v_add_co_u32_e32 v22, vcc, 0x1f000, v22
	v_add_u32_e32 v39, 48, v41
	s_nop 0
	v_addc_co_u32_e32 v23, vcc, 0, v23, vcc
	global_load_dword v120, v[120:121], off
	s_nop 0
	global_load_dword v22, v[22:23], off
	v_add_u32_e32 v41, v41, v19
	v_and_b32_e32 v39, 56, v39
	v_and_b32_e32 v47, 63, v41
	v_add_u32_e32 v49, 48, v41
	v_add_u32_e32 v41, v41, v19
	v_lshl_add_u32 v21, v39, 2, s3
	v_and_b32_e32 v31, 63, v49
	v_and_b32_e32 v37, 62, v41
	v_add_u32_e32 v39, 48, v41
	v_add_u32_e32 v41, v41, v19
	v_lshl_add_u32 v29, v47, 2, s3
	v_lshl_add_u32 v31, v31, 2, s3
	v_lshl_add_u32 v37, v37, 2, s3
	v_and_b32_e32 v23, 62, v39
	v_and_b32_e32 v39, 63, v41
	v_add_u32_e32 v47, 48, v41
	v_add_u32_e32 v41, v41, v19
	ds_read_b32 v111, v21
	ds_read_b32 v122, v29
	ds_read_b32 v123, v31
	ds_read_b32 v124, v37
	v_lshl_add_u32 v21, v23, 2, s3
	v_lshl_add_u32 v23, v39, 2, s3
	v_and_b32_e32 v29, 63, v47
	v_and_b32_e32 v31, 60, v41
	v_add_u32_e32 v37, 48, v41
	v_add_u32_e32 v39, v41, v19
	v_lshl_add_u32 v29, v29, 2, s3
	v_lshl_add_u32 v31, v31, 2, s3
	v_and_b32_e32 v37, 60, v37
	v_and_b32_e32 v41, 63, v39
	v_add_u32_e32 v47, 48, v39
	v_add_u32_e32 v39, v39, v19
	ds_read_b32 v125, v21
	ds_read_b32 v126, v23
	ds_read_b32 v127, v29
	ds_read_b32 v128, v31
	v_lshl_add_u32 v21, v37, 2, s3
	v_and_b32_e32 v29, 63, v47
	v_and_b32_e32 v31, 62, v39
	v_add_u32_e32 v37, 48, v39
	v_add_u32_e32 v39, v39, v19
	s_waitcnt vmcnt(31) lgkmcnt(14)
	v_pk_fma_f32 v[6:7], v[2:3], v[8:9], v[6:7] op_sel_hi:[0,1,1]
	v_lshl_add_u32 v23, v41, 2, s3
	v_lshl_add_u32 v29, v29, 2, s3
	v_and_b32_e32 v37, 62, v37
	v_and_b32_e32 v41, 63, v39
	v_add_u32_e32 v39, 48, v39
	s_waitcnt vmcnt(30)
	v_pk_fma_f32 v[6:7], v[12:13], v[10:11], v[6:7] op_sel_hi:[0,1,1]
	v_lshl_add_u32 v31, v31, 2, s3
	ds_read_b32 v129, v21
	ds_read_b32 v130, v23
	ds_read_b32 v131, v29
	ds_read_b32 v132, v31
	v_lshl_add_u32 v21, v37, 2, s3
	v_and_b32_e32 v29, 63, v39
	s_waitcnt vmcnt(29)
; __device__ __forceinline__ unsigned f2bf(float f) { unsigned u = __float_as_uint(f); return (u + 0x7fffu + ((u >> 16) & 1u)) >> 16; }
; __device__ __forceinline__ void prep_weights(const Params& P, LAS unsigned char* lds, int lay, int bid, int G, int sel) {
;     ...
;           for (int m0 = 0; m0 < 64; m0 += 32) { float wv[32];
; #pragma unroll
;               for (int m = 0; m < 32; ++m) wv[m] = wp[(size_t)(m0 + m) * 1024];
; #pragma unroll
;               for (int m = 0; m < 32; ++m) { const int t = ((m0 + m) * j) & 63; cs += tab64[t] * wv[m]; sn += tab64[(t + 48) & 63] * wv[m]; } }
;           bf16_t* o = (bf16_t*)(ws + OFF_WOUT + l * SZ_WOUT1) + (size_t)n * 1280; o[768 + gj] = (bf16_t)f2bf(cs); o[1024 + gj] = (bf16_t)f2bf(-sn); }
;       for (int i0 = gt; i0 < ((sel & 64) ? 131072 : 0); i0 += NGT) { const int idx = l * 131072 + i0; const int i = idx & 63, j = (idx >> 6) & 63, hi = idx >> 12;
;           ((bf16_t*)(ws + OFF_WGT))[idx] = (bf16_t)f2bf(P.lru_wg[(size_t)hi * 4096 + i * 64 + j]); }
	v_pk_fma_f32 v[6:7], v[18:19], v[14:15], v[6:7] op_sel_hi:[0,1,1]
	v_lshl_add_u32 v29, v29, 2, s3
	s_waitcnt vmcnt(28)
	v_pk_fma_f32 v[6:7], v[20:21], v[16:17], v[6:7] op_sel_hi:[0,1,1]
	s_waitcnt vmcnt(27)
	v_pk_fma_f32 v[6:7], v[28:29], v[24:25], v[6:7] op_sel_hi:[0,1,1]
	s_waitcnt vmcnt(26)
	v_pk_fma_f32 v[6:7], v[30:31], v[26:27], v[6:7] op_sel_hi:[0,1,1]
	s_waitcnt vmcnt(25)
	v_pk_fma_f32 v[6:7], v[38:39], v[32:33], v[6:7] op_sel_hi:[0,1,1]
	s_waitcnt vmcnt(24)
	v_pk_fma_f32 v[6:7], v[40:41], v[34:35], v[6:7] op_sel_hi:[0,1,1]
	s_waitcnt vmcnt(23)
	v_pk_fma_f32 v[6:7], v[46:47], v[42:43], v[6:7] op_sel_hi:[0,1,1]
	s_waitcnt vmcnt(22)
	v_pk_fma_f32 v[6:7], v[48:49], v[44:45], v[6:7] op_sel_hi:[0,1,1]
	s_waitcnt vmcnt(21)
	v_pk_fma_f32 v[6:7], v[54:55], v[50:51], v[6:7] op_sel_hi:[0,1,1]
	s_waitcnt vmcnt(20)
	v_pk_fma_f32 v[6:7], v[56:57], v[52:53], v[6:7] op_sel_hi:[0,1,1]
	s_waitcnt vmcnt(19)
	v_pk_fma_f32 v[6:7], v[62:63], v[58:59], v[6:7] op_sel_hi:[0,1,1]
	s_waitcnt vmcnt(18)
	v_pk_fma_f32 v[6:7], v[64:65], v[60:61], v[6:7] op_sel_hi:[0,1,1]
	s_waitcnt vmcnt(17)
	v_pk_fma_f32 v[6:7], v[70:71], v[66:67], v[6:7] op_sel_hi:[0,1,1]
	s_waitcnt vmcnt(16)
	v_pk_fma_f32 v[6:7], v[72:73], v[68:69], v[6:7] op_sel_hi:[0,1,1]
	s_waitcnt vmcnt(15)
	v_pk_fma_f32 v[6:7], v[74:75], v[78:79], v[6:7] op_sel_hi:[0,1,1]
	s_waitcnt vmcnt(14)
	v_pk_fma_f32 v[6:7], v[76:77], v[82:83], v[6:7] op_sel_hi:[0,1,1]
	s_waitcnt vmcnt(13)
	v_pk_fma_f32 v[6:7], v[80:81], v[86:87], v[6:7] op_sel_hi:[0,1,1]
	s_waitcnt vmcnt(12)
	v_pk_fma_f32 v[6:7], v[84:85], v[90:91], v[6:7] op_sel_hi:[0,1,1]
	s_waitcnt vmcnt(11)
	v_pk_fma_f32 v[6:7], v[88:89], v[94:95], v[6:7] op_sel_hi:[0,1,1]
	s_waitcnt vmcnt(10) lgkmcnt(14)
	v_pk_fma_f32 v[6:7], v[92:93], v[98:99], v[6:7] op_sel_hi:[0,1,1]
	s_waitcnt vmcnt(9)
	v_pk_fma_f32 v[6:7], v[96:97], v[102:103], v[6:7] op_sel_hi:[0,1,1]
	s_waitcnt vmcnt(8) lgkmcnt(13)
	v_pk_fma_f32 v[6:7], v[100:101], v[106:107], v[6:7] op_sel_hi:[0,1,1]
	s_waitcnt vmcnt(7) lgkmcnt(11)
	v_pk_fma_f32 v[6:7], v[104:105], v[110:111], v[6:7] op_sel_hi:[0,1,1]
	s_waitcnt vmcnt(6) lgkmcnt(9)
	v_pk_fma_f32 v[6:7], v[108:109], v[122:123], v[6:7] op_sel_hi:[0,1,1]
	v_lshl_add_u32 v23, v41, 2, s3
	ds_read_b32 v133, v21
	ds_read_b32 v134, v23
	ds_read_b32 v135, v29
	s_waitcnt vmcnt(5) lgkmcnt(10)
	v_pk_fma_f32 v[6:7], v[112:113], v[124:125], v[6:7] op_sel_hi:[0,1,1]
	s_waitcnt vmcnt(4) lgkmcnt(8)
	v_pk_fma_f32 v[6:7], v[114:115], v[126:127], v[6:7] op_sel_hi:[0,1,1]
	s_waitcnt vmcnt(3) lgkmcnt(6)
	v_pk_fma_f32 v[6:7], v[116:117], v[128:129], v[6:7] op_sel_hi:[0,1,1]
	s_waitcnt vmcnt(2) lgkmcnt(4)
	v_pk_fma_f32 v[6:7], v[118:119], v[130:131], v[6:7] op_sel_hi:[0,1,1]
	s_and_b64 s[4:5], exec, s[22:23]
	s_waitcnt vmcnt(1) lgkmcnt(2)
	v_pk_fma_f32 v[6:7], v[120:121], v[132:133], v[6:7] op_sel_hi:[0,1,1]
	s_mov_b64 s[22:23], 0
	s_mov_b32 s13, 32
	s_waitcnt vmcnt(0) lgkmcnt(0)
	v_pk_fma_f32 v[6:7], v[22:23], v[134:135], v[6:7] op_sel_hi:[0,1,1]
	s_mov_b64 vcc, s[4:5]
	s_cbranch_vccnz .LBB0_40
	v_bfe_u32 v2, v6, 16, 1
	v_mov_b64_e32 v[4:5], s[16:17]
	v_add3_u32 v6, v6, v2, s12
	v_lshrrev_b32_e32 v2, 9, v1
	v_mad_u64_u32 v[4:5], s[4:5], v13, s7, v[4:5]
	v_and_b32_e32 v2, 0x1fe, v2
	v_lshl_add_u64 v[4:5], v[4:5], 0, v[2:3]
	v_xor_b32_e32 v2, 0x80000000, v7
	v_add_u32_e32 v1, s6, v1
	global_store_short_d16_hi v[4:5], v6, off offset:1536 sc1
	v_bfe_u32 v6, v2, 16, 1
	v_cmp_lt_i32_e32 vcc, -1, v1
	v_add3_u32 v2, v2, v6, s12
	s_or_b64 s[18:19], vcc, s[18:19]
	global_store_short_d16_hi v[4:5], v2, off offset:2048 sc1
	s_andn2_b64 exec, exec, s[18:19]
	s_cbranch_execnz .LBB0_39
	s_or_b64 exec, exec, s[18:19]
	v_cvt_f32_u32_e32 v1, s6
	s_sub_i32 s3, 0, s6
	s_mov_b64 s[4:5], -1
	v_rcp_iflag_f32_e32 v2, v1
	v_add_u32_e32 v1, s6, v0
	v_lshrrev_b32_e32 v4, 31, v1
	v_max_i32_e32 v3, 0, v1
	v_mul_f32_e32 v2, 0x4f7ffffe, v2
	v_cvt_u32_f32_e32 v2, v2
	v_add_u32_e32 v5, v4, v1
	v_sub_u32_e32 v3, v3, v5
	v_mul_lo_u32 v5, s3, v2
	v_mul_hi_u32 v5, v2, v5
	v_add_u32_e32 v2, v2, v5
	v_mul_hi_u32 v2, v3, v2
	v_mul_lo_u32 v5, v2, s6
	v_sub_u32_e32 v3, v3, v5
	v_add_u32_e32 v6, 1, v2
	v_cmp_le_u32_e32 vcc, s6, v3
	v_subrev_u32_e32 v5, s6, v3
	s_nop 0
	v_cndmask_b32_e32 v2, v2, v6, vcc
	v_cndmask_b32_e32 v3, v3, v5, vcc
	v_add_u32_e32 v5, 1, v2
	v_cmp_le_u32_e32 vcc, s6, v3
	s_nop 1
	v_cndmask_b32_e32 v2, v2, v5, vcc
	v_add3_u32 v8, v4, v2, 1
	v_cmp_lt_u32_e32 vcc, 1, v8
	v_and_b32_e32 v9, -2, v8
	v_mov_b32_e32 v2, v0
	s_and_saveexec_b64 s[10:11], vcc
	s_cbranch_execz .LBB0_46
	s_add_u32 s16, s92, 0x4e00000
	s_addc_u32 s17, s93, 0
	v_and_b32_e32 v6, -2, v8
	s_lshl_b32 s3, s90, 10
	v_readlane_b32 s36, v250, 0
	s_mov_b32 s7, s3
	s_mov_b64 s[18:19], 0
	v_mov_b32_e32 v3, 0
	s_movk_i32 s12, 0x7fff
	v_mov_b32_e32 v7, 1
	v_mov_b32_e32 v10, v6
	v_mov_b64_e32 v[4:5], v[0:1]
	v_readlane_b32 s46, v250, 10
	v_readlane_b32 s47, v250, 11
	v_readlane_b32 s37, v250, 1
	v_readlane_b32 s38, v250, 2
	v_readlane_b32 s39, v250, 3
	v_readlane_b32 s40, v250, 4
	v_readlane_b32 s41, v250, 5
	v_readlane_b32 s42, v250, 6
	v_readlane_b32 s43, v250, 7
	v_readlane_b32 s44, v250, 8
	v_readlane_b32 s45, v250, 9
	v_readlane_b32 s48, v250, 12
	v_readlane_b32 s49, v250, 13
	v_readlane_b32 s50, v250, 14
	v_readlane_b32 s51, v250, 15
; __device__ __forceinline__ unsigned f2bf(float f) { unsigned u = __float_as_uint(f); return (u + 0x7fffu + ((u >> 16) & 1u)) >> 16; }
; __device__ __forceinline__ void prep_weights(const Params& P, LAS unsigned char* lds, int lay, int bid, int G, int sel) {
;     ...
;       for (int i0 = gt; i0 < ((sel & 64) ? 131072 : 0); i0 += NGT) { const int idx = l * 131072 + i0; const int i = idx & 63, j = (idx >> 6) & 63, hi = idx >> 12;
;           ((bf16_t*)(ws + OFF_WGT))[idx] = (bf16_t)f2bf(P.lru_wg[(size_t)hi * 4096 + i * 64 + j]); }
.LBB0_44:
	v_ashrrev_i32_e32 v14, 12, v4
	v_lshrrev_b32_e32 v2, 6, v5
	v_ashrrev_i32_e32 v12, 12, v5
	v_lshlrev_b32_e32 v17, 6, v4
	v_ashrrev_i32_e32 v15, 31, v14
	v_lshlrev_b32_e32 v16, 6, v5
	v_and_b32_e32 v18, 63, v2
	v_ashrrev_i32_e32 v13, 31, v12
	v_and_b32_e32 v2, 0xfc0, v17
	v_lshlrev_b64 v[14:15], 14, v[14:15]
	v_lshrrev_b32_e32 v11, 6, v4
	v_and_b32_e32 v16, 0xfc0, v16
	v_lshlrev_b64 v[12:13], 14, v[12:13]
	v_lshlrev_b32_e32 v2, 2, v2
	v_lshl_add_u64 v[14:15], s[46:47], 0, v[14:15]
	v_and_b32_e32 v11, 63, v11
	v_lshl_add_u64 v[12:13], s[46:47], 0, v[12:13]
	v_lshl_add_u64 v[14:15], v[14:15], 0, v[2:3]
	v_lshlrev_b32_e32 v2, 2, v16
	v_lshl_add_u64 v[12:13], v[12:13], 0, v[2:3]
	v_lshlrev_b32_e32 v2, 2, v11
	v_lshl_add_u64 v[14:15], v[14:15], 0, v[2:3]
	v_lshlrev_b32_e32 v2, 2, v18
	v_lshl_add_u64 v[12:13], v[12:13], 0, v[2:3]
	global_load_dword v2, v[14:15], off
	global_load_dword v11, v[12:13], off
	v_add_u32_e32 v10, -2, v10
	v_ashrrev_i32_e32 v15, 31, v4
	v_mov_b32_e32 v14, v4
	v_cmp_eq_u32_e64 s[4:5], 0, v10
	v_ashrrev_i32_e32 v13, 31, v5
	v_mov_b32_e32 v12, v5
	v_add_u32_e32 v5, s7, v5
	v_add_u32_e32 v4, s3, v4
	v_lshl_add_u64 v[14:15], v[14:15], 1, s[16:17]
	s_or_b64 s[18:19], s[4:5], s[18:19]
	v_lshl_add_u64 v[12:13], v[12:13], 1, s[16:17]
	s_waitcnt vmcnt(1)
	v_and_b32_sdwa v16, v2, v7 dst_sel:DWORD dst_unused:UNUSED_PAD src0_sel:WORD_1 src1_sel:DWORD
	s_waitcnt vmcnt(0)
	v_and_b32_sdwa v17, v11, v7 dst_sel:DWORD dst_unused:UNUSED_PAD src0_sel:WORD_1 src1_sel:DWORD
	v_add3_u32 v2, v2, v16, s12
	v_add3_u32 v11, v11, v17, s12
	global_store_short_d16_hi v[14:15], v2, off sc1
	global_store_short_d16_hi v[12:13], v11, off sc1
	s_andn2_b64 exec, exec, s[18:19]
	s_cbranch_execnz .LBB0_44
	s_or_b64 exec, exec, s[18:19]
	v_mad_u64_u32 v[2:3], s[4:5], v6, s6, v[0:1]
	v_cmp_ne_u32_e64 s[4:5], v8, v6
	s_orn2_b64 s[4:5], s[4:5], exec

; __device__ __forceinline__ unsigned f2bf(float f) { unsigned u = __float_as_uint(f); return (u + 0x7fffu + ((u >> 16) & 1u)) >> 16; }
; __device__ __forceinline__ void prep_weights(const Params& P, LAS unsigned char* lds, int lay, int bid, int G, int sel) {
;     ...
;       for (int i0 = gt; i0 < ((sel & 64) ? 131072 : 0); i0 += NGT) { const int idx = l * 131072 + i0; const int i = idx & 63, j = (idx >> 6) & 63, hi = idx >> 12;
;           ((bf16_t*)(ws + OFF_WGT))[idx] = (bf16_t)f2bf(P.lru_wg[(size_t)hi * 4096 + i * 64 + j]); }
.LBB0_48:
	v_ashrrev_i32_e32 v10, 12, v2
	v_ashrrev_i32_e32 v11, 31, v10
	v_and_b32_e32 v6, 0xfc0, v3
	v_lshlrev_b64 v[10:11], 14, v[10:11]
	v_lshrrev_b32_e32 v12, 4, v2
	v_lshlrev_b32_e32 v6, 2, v6
	v_lshl_add_u64 v[10:11], s[22:23], 0, v[10:11]
	v_lshl_add_u64 v[10:11], v[10:11], 0, v[6:7]
	v_and_b32_e32 v6, 0xfc, v12
	v_lshl_add_u64 v[10:11], v[10:11], 0, v[6:7]
	global_load_dword v6, v[10:11], off
	v_add_u32_e32 v2, s6, v2
	v_cmp_lt_i32_e64 s[4:5], -1, v2
	v_add_u32_e32 v3, s3, v3
	s_or_b64 s[18:19], s[4:5], s[18:19]
	s_waitcnt vmcnt(0)
	v_bfe_u32 v10, v6, 16, 1
	v_add3_u32 v6, v6, v10, s7
	global_store_short_d16_hi v[4:5], v6, off sc1
	v_lshl_add_u64 v[4:5], v[4:5], 0, s[16:17]
	s_andn2_b64 exec, exec, s[18:19]
	s_cbranch_execnz .LBB0_48

; __device__ __forceinline__ unsigned f2bf(float f) { unsigned u = __float_as_uint(f); return (u + 0x7fffu + ((u >> 16) & 1u)) >> 16; }
; __device__ __forceinline__ void prep_weights(const Params& P, LAS unsigned char* lds, int lay, int bid, int G, int sel) {
;     ...
;       for (int i0 = gt; i0 < ((sel & 64) ? 65536 : 0); i0 += NGT) { const int idx = l * 65536 + i0; ((bf16_t*)(ws + OFF_GWS))[idx] = (bf16_t)f2bf(P.gmlp_ws[idx]); } }
.LBB0_51:
	v_ashrrev_i32_e32 v7, 31, v3
	v_mov_b32_e32 v6, v3
	v_ashrrev_i32_e32 v11, 31, v2
	v_mov_b32_e32 v10, v2
	v_lshl_add_u64 v[12:13], v[10:11], 2, s[80:81]
	v_lshl_add_u64 v[14:15], v[6:7], 2, s[80:81]
	global_load_dword v1, v[14:15], off
	s_nop 0
	global_load_dword v12, v[12:13], off
	v_add_u32_e32 v5, -2, v5
	v_cmp_eq_u32_e32 vcc, 0, v5
	v_add_u32_e32 v3, s7, v3
	v_add_u32_e32 v2, s3, v2
	v_lshl_add_u64 v[10:11], v[10:11], 1, s[10:11]
	s_or_b64 s[16:17], vcc, s[16:17]
	v_lshl_add_u64 v[6:7], v[6:7], 1, s[10:11]
	s_waitcnt vmcnt(1)
	v_and_b32_sdwa v13, v1, v4 dst_sel:DWORD dst_unused:UNUSED_PAD src0_sel:WORD_1 src1_sel:DWORD
	s_waitcnt vmcnt(0)
	v_and_b32_sdwa v14, v12, v4 dst_sel:DWORD dst_unused:UNUSED_PAD src0_sel:WORD_1 src1_sel:DWORD
	v_add3_u32 v12, v12, v14, s12
	v_add3_u32 v1, v1, v13, s12
	global_store_short_d16_hi v[10:11], v12, off sc1
	global_store_short_d16_hi v[6:7], v1, off sc1
	s_andn2_b64 exec, exec, s[16:17]
	s_cbranch_execnz .LBB0_51
	s_or_b64 exec, exec, s[16:17]
	v_mad_u64_u32 v[0:1], s[10:11], v9, s6, v[0:1]
	v_cmp_ne_u32_e32 vcc, v8, v9
	s_orn2_b64 s[10:11], vcc, exec

; __device__ __forceinline__ unsigned f2bf(float f) { unsigned u = __float_as_uint(f); return (u + 0x7fffu + ((u >> 16) & 1u)) >> 16; }
; __device__ __forceinline__ void prep_weights(const Params& P, LAS unsigned char* lds, int lay, int bid, int G, int sel) {
;     ...
;       for (int i0 = gt; i0 < ((sel & 64) ? 65536 : 0); i0 += NGT) { const int idx = l * 65536 + i0; ((bf16_t*)(ws + OFF_GWS))[idx] = (bf16_t)f2bf(P.gmlp_ws[idx]); } }
.LBB0_55:
	global_load_dword v1, v[2:3], off
	v_add_u32_e32 v0, s6, v0
	v_cmp_lt_i32_e32 vcc, -1, v0
	v_lshl_add_u64 v[2:3], v[2:3], 0, s[4:5]
	s_or_b64 s[16:17], vcc, s[16:17]
	s_waitcnt vmcnt(0)
	v_bfe_u32 v6, v1, 16, 1
	v_add3_u32 v1, v1, v6, s3
	global_store_short_d16_hi v[4:5], v1, off sc1
	v_lshl_add_u64 v[4:5], v[4:5], 0, s[10:11]
	s_andn2_b64 exec, exec, s[16:17]
	s_cbranch_execnz .LBB0_55

; __device__ __forceinline__ void phase_prep(const Params& P, LAS unsigned char* lds) {
;     ...
;     { const int gt = bid * 512 + tid, NGT = G * 512;
;       for (int idx = gt; idx < 2048; idx += NGT) ((float*)(ws + OFF_SP8))[idx] = 8.0f * log1pf(expf(-P.lru_lam[idx])); }
.LBB0_58:
	v_lshl_add_u64 v[8:9], s[22:23], 0, v[2:3]
	global_load_dword v5, v[8:9], off
	v_add_u32_e32 v0, s6, v0
	v_cmp_lt_i32_e32 vcc, s18, v0
	s_or_b64 s[16:17], vcc, s[16:17]
	v_lshl_add_u64 v[8:9], s[8:9], 0, v[2:3]
	v_lshl_add_u64 v[2:3], v[2:3], 0, s[10:11]
	s_waitcnt vmcnt(0)
	v_mul_f32_e32 v7, 0xbfb8aa3b, v5
	v_fma_f32 v10, v5, s2, -v7
	v_rndne_f32_e32 v11, v7
	v_fmac_f32_e32 v10, 0xb2a5705f, v5
	v_sub_f32_e32 v7, v7, v11
	v_add_f32_e32 v7, v7, v10
	v_cvt_i32_f32_e32 v11, v11
	v_exp_f32_e32 v7, v7
	v_cmp_nlt_f32_e32 vcc, s3, v5
	v_ldexp_f32 v7, v7, v11
	s_nop 0
	v_cndmask_b32_e32 v7, 0, v7, vcc
	v_cmp_ngt_f32_e32 vcc, s7, v5
	s_nop 1
	v_cndmask_b32_e32 v7, v1, v7, vcc
	v_add_f32_e32 v5, 1.0, v7
	v_add_f32_e32 v12, -1.0, v5
	v_frexp_mant_f32_e32 v13, v5
	v_cvt_f64_f32_e32 v[10:11], v5
	v_sub_f32_e32 v14, v12, v5
	v_frexp_exp_i32_f64_e32 v10, v[10:11]
	v_cmp_gt_f32_e32 vcc, s13, v13
	v_sub_f32_e32 v12, v7, v12
	v_add_f32_e32 v11, 1.0, v14
	v_subbrev_co_u32_e32 v10, vcc, 0, v10, vcc
	v_add_f32_e32 v11, v12, v11
	v_sub_u32_e32 v12, 0, v10
	v_ldexp_f32 v5, v5, v12
	v_ldexp_f32 v11, v11, v12
	v_add_f32_e32 v12, -1.0, v5
	v_add_f32_e32 v14, 1.0, v5
	v_add_f32_e32 v13, 1.0, v12
	v_add_f32_e32 v15, -1.0, v14
	v_sub_f32_e32 v13, v5, v13
	v_sub_f32_e32 v5, v5, v15
	v_add_f32_e32 v5, v11, v5
	v_add_f32_e32 v15, v11, v13
	v_add_f32_e32 v11, v14, v5
	v_rcp_f32_e32 v18, v11
	v_add_f32_e32 v13, v12, v15
	v_sub_f32_e32 v14, v14, v11
	v_add_f32_e32 v5, v5, v14
	v_mul_f32_e32 v20, v13, v18
	v_mul_f32_e32 v14, v11, v20
	v_fma_f32 v16, v20, v11, -v14
	v_sub_f32_e32 v12, v12, v13
	v_fmac_f32_e32 v16, v20, v5
	v_add_f32_e32 v19, v15, v12
	v_add_f32_e32 v12, v14, v16
	v_sub_f32_e32 v15, v13, v12
	v_mov_b32_e32 v17, v12
	v_pk_add_f32 v[12:13], v[12:13], v[14:15] neg_lo:[0,1] neg_hi:[0,1]
	v_cvt_f32_i32_e32 v10, v10
	v_pk_add_f32 v[12:13], v[12:13], v[16:17] neg_lo:[0,1] neg_hi:[0,1]
	v_cmp_neq_f32_e32 vcc, s12, v7
	v_add_f32_e32 v13, v19, v13
	v_add_f32_e32 v12, v12, v13
	v_add_f32_e32 v13, v15, v12
	v_mul_f32_e32 v17, v18, v13
	v_mul_f32_e32 v14, v11, v17
	v_fma_f32 v16, v17, v11, -v14
	v_sub_f32_e32 v15, v15, v13
	v_fmac_f32_e32 v16, v17, v5
	v_add_f32_e32 v19, v12, v15
	v_add_f32_e32 v21, v20, v17
	v_add_f32_e32 v12, v14, v16
	v_sub_f32_e32 v11, v21, v20
	v_sub_f32_e32 v15, v13, v12
	v_sub_f32_e32 v5, v17, v11
	v_mov_b32_e32 v17, v12
	v_pk_add_f32 v[12:13], v[12:13], v[14:15] neg_lo:[0,1] neg_hi:[0,1]
	s_nop 0
	v_pk_add_f32 v[12:13], v[12:13], v[16:17] neg_lo:[0,1] neg_hi:[0,1]
	s_nop 0
	v_add_f32_e32 v11, v19, v13
	v_add_f32_e32 v11, v12, v11
	v_add_f32_e32 v11, v15, v11
	v_mul_f32_e32 v11, v18, v11
	v_add_f32_e32 v5, v5, v11
	v_add_f32_e32 v11, v21, v5
	v_mul_f32_e32 v12, v11, v11
	v_sub_f32_e32 v14, v11, v21
	v_fmamk_f32 v15, v12, 0x3e9b6dac, v6
	v_ldexp_f32 v13, v11, 1
	v_sub_f32_e32 v14, v5, v14
	v_mul_f32_e32 v11, v11, v12
	v_fmaak_f32 v5, v12, v15, 0x3f2aaada
	v_ldexp_f32 v17, v14, 1
	v_pk_mul_f32 v[14:15], v[10:11], v[4:5]
	s_nop 0
	v_fma_f32 v12, v10, s14, -v14
	v_fmac_f32_e32 v12, 0xb102e308, v10
	v_pk_add_f32 v[10:11], v[14:15], v[12:13]
	v_mov_b32_e32 v16, v14
	v_sub_f32_e32 v5, v11, v13
	v_sub_f32_e32 v5, v15, v5
	v_add_f32_e32 v17, v17, v5
	v_pk_add_f32 v[18:19], v[10:11], v[14:15] neg_lo:[0,1] neg_hi:[0,1]
	v_pk_add_f32 v[14:15], v[10:11], v[16:17]
	v_mov_b32_e32 v13, v10
	v_mov_b32_e32 v19, v15
	v_pk_add_f32 v[22:23], v[12:13], v[18:19] neg_lo:[0,1] neg_hi:[0,1]
	v_pk_add_f32 v[12:13], v[12:13], v[18:19]
	v_mov_b32_e32 v21, v10
	v_pk_add_f32 v[18:19], v[12:13], v[10:11] op_sel:[1,0] op_sel_hi:[0,1] neg_lo:[0,1] neg_hi:[0,1]
	v_mov_b32_e32 v20, v17
	v_mov_b32_e32 v16, v15
	v_mov_b32_e32 v17, v13
	v_pk_mov_b32 v[10:11], v[10:11], v[18:19] op_sel:[1,0]
	v_pk_add_f32 v[14:15], v[14:15], v[18:19] op_sel_hi:[1,0] neg_lo:[0,1] neg_hi:[0,1]
	v_pk_add_f32 v[10:11], v[16:17], v[10:11] neg_lo:[0,1] neg_hi:[0,1]
	v_mov_b32_e32 v14, v22
	v_pk_add_f32 v[10:11], v[20:21], v[10:11] neg_lo:[0,1] neg_hi:[0,1]
	v_mov_b32_e32 v23, v13
	v_pk_add_f32 v[14:15], v[14:15], v[10:11]
	s_nop 0
	v_pk_add_f32 v[16:17], v[14:15], v[14:15] op_sel:[0,1] op_sel_hi:[1,0]
	s_nop 0
	v_pk_add_f32 v[12:13], v[12:13], v[16:17] op_sel:[1,0] op_sel_hi:[0,1]
	v_mov_b32_e32 v15, v12
	v_mov_b32_e32 v11, v16
	v_pk_add_f32 v[16:17], v[14:15], v[22:23] neg_lo:[0,1] neg_hi:[0,1]
	s_nop 0
	v_sub_f32_e32 v5, v14, v16
	v_pk_add_f32 v[10:11], v[10:11], v[16:17] neg_lo:[0,1] neg_hi:[0,1]
	v_sub_f32_e32 v5, v22, v5
	v_add_f32_e32 v5, v10, v5
	v_add_f32_e32 v5, v5, v11
	v_add_f32_e32 v5, v12, v5
	v_cndmask_b32_e32 v5, v1, v5, vcc
	v_cmp_lt_f32_e64 vcc, |v7|, s15
	s_nop 1
	v_cndmask_b32_e32 v5, v5, v7, vcc
	v_mul_f32_e32 v5, 0x41000000, v5
	global_store_dword v[8:9], v5, off sc1
	s_andn2_b64 exec, exec, s[16:17]
	s_cbranch_execnz .LBB0_58

; __device__ __forceinline__ void phase_prep(const Params& P, LAS unsigned char* lds) {
;     ...
;           for (int o = tid; o < 9 * 64; o += 512) { const int v = o >> 6, cc = o & 63; float s = P.b_mod[l * 9216 + col0 + cc];
; #pragma unroll
;               for (int q = 0; q < 32; ++q) s += red[(q * 9 + v) * 64 + cc];
;               MOD[(size_t)(l * 9 + v) * 9216 + col0 + cc] = s; }
.LBB0_78:
	global_load_dword v5, v[0:1], off
	v_ashrrev_i32_e32 v6, 6, v4
	v_add_u32_e32 v7, 0x200, v4
	v_lshl_add_u32 v18, v6, 8, v55
	v_cmp_lt_i32_e32 vcc, 63, v4
	v_add_u32_e32 v19, s34, v6
	v_mov_b32_e32 v4, v7
	ds_read2st64_b32 v[6:7], v18 offset0:144 offset1:153
	ds_read2st64_b32 v[8:9], v18 offset0:162 offset1:171
	ds_read2st64_b32 v[10:11], v18 offset0:180 offset1:189
	ds_read2st64_b32 v[12:13], v18 offset0:198 offset1:207
	ds_read2st64_b32 v[14:15], v18 offset0:216 offset1:225
	ds_read2st64_b32 v[16:17], v18 offset0:234 offset1:243
	ds_read_b32 v44, v18 offset:64512
	v_add_u32_e32 v34, 0x9000, v18
	v_add_u32_e32 v45, 0x19500, v18
	v_add_u32_e32 v46, 0x19e00, v18
	v_add_u32_e32 v47, 0x1a700, v18
	ds_read2st64_b32 v[20:21], v34 offset0:117 offset1:126
	ds_read2st64_b32 v[22:23], v34 offset0:135 offset1:144
	ds_read2st64_b32 v[24:25], v34 offset0:153 offset1:162
	ds_read2st64_b32 v[26:27], v34 offset0:171 offset1:180
	ds_read2st64_b32 v[28:29], v34 offset0:189 offset1:198
	ds_read2st64_b32 v[30:31], v34 offset0:207 offset1:216
	ds_read2st64_b32 v[32:33], v34 offset0:225 offset1:234
	ds_read2st64_b32 v[34:35], v34 offset0:243 offset1:252
	ds_read_b32 v45, v45
	ds_read_b32 v46, v46
	ds_read_b32 v47, v47
	s_or_b64 s[8:9], vcc, s[8:9]
	v_mad_i64_i32 v[18:19], s[2:3], v19, s16, v[2:3]
	s_waitcnt vmcnt(0) lgkmcnt(14)
	v_add_f32_e32 v5, v5, v6
	v_add_f32_e32 v5, v5, v7
	v_add_f32_e32 v5, v5, v8
	v_add_f32_e32 v5, v5, v9
	v_add_f32_e32 v5, v5, v10
	v_add_f32_e32 v5, v5, v11
	v_add_f32_e32 v5, v5, v12
	v_add_f32_e32 v5, v5, v13
	s_waitcnt lgkmcnt(13)
	v_add_f32_e32 v5, v5, v14
	v_add_f32_e32 v5, v5, v15
	s_waitcnt lgkmcnt(12)
	v_add_f32_e32 v5, v5, v16
	v_add_f32_e32 v5, v5, v17
	s_waitcnt lgkmcnt(11)
	v_add_f32_e32 v5, v5, v44
	s_waitcnt lgkmcnt(10)
	v_add_f32_e32 v5, v5, v20
	v_add_f32_e32 v5, v5, v21
	s_waitcnt lgkmcnt(9)
	v_add_f32_e32 v5, v5, v22
	v_add_f32_e32 v5, v5, v23
	s_waitcnt lgkmcnt(8)
	v_add_f32_e32 v5, v5, v24
	v_add_f32_e32 v5, v5, v25
	s_waitcnt lgkmcnt(7)
	v_add_f32_e32 v5, v5, v26
	v_add_f32_e32 v5, v5, v27
	s_waitcnt lgkmcnt(6)
	v_add_f32_e32 v5, v5, v28
	v_add_f32_e32 v5, v5, v29
	s_waitcnt lgkmcnt(5)
	v_add_f32_e32 v5, v5, v30
	v_add_f32_e32 v5, v5, v31
	s_waitcnt lgkmcnt(4)
	v_add_f32_e32 v5, v5, v32
	v_add_f32_e32 v5, v5, v33
	s_waitcnt lgkmcnt(3)
	v_add_f32_e32 v5, v5, v34
	v_add_f32_e32 v5, v5, v35
	s_waitcnt lgkmcnt(2)
	v_add_f32_e32 v5, v5, v45
	s_waitcnt lgkmcnt(1)
	v_add_f32_e32 v5, v5, v46
	s_waitcnt lgkmcnt(0)
	v_add_f32_e32 v5, v5, v47
	global_store_dword v[18:19], v5, off sc1
	s_andn2_b64 exec, exec, s[8:9]
	s_cbranch_execnz .LBB0_78
	s_branch .LBB0_73

; #define GAS __attribute__((address_space(1)))
; __device__ __forceinline__ unsigned cvt_pk_bf16(float lo, float hi) { unsigned r; asm volatile("v_cvt_pk_bf16_f32 %0, %1, %2" : "=v"(r) : "v"(lo), "v"(hi)); return r; }
; __device__ __forceinline__ void phase_init(const Params& P) {
;     ...
;         float ss = 0.f;
; #pragma unroll
;         for (int j = 0; j < 4; ++j) { *(f32x4*)(hr + 4 * lane + 256 * j) = v[j]; ss += (v[j].x * v[j].x + v[j].y * v[j].y) + (v[j].z * v[j].z + v[j].w * v[j].w); }
;         const float rstd = 1.0f / sqrtf(wave_sum(ss) * (1.0f / 1024.0f) + 1e-6f);
; #pragma unroll
;         for (int j = 0; j < 4; ++j) { const f32x4 y = v[j] * rstd * gg[j] * (sc[j] + 1.0f) + sh[j];
;             u32x2 w; w.x = cvt_pk_bf16(y.x, y.y); w.y = cvt_pk_bf16(y.z, y.w); *(GAS u32x2*)((GAS bf16_t*)XN + (size_t)r * 1024 + 4 * lane + 256 * j) = w; }
;         if (rn < T) {
; #pragma unroll
;             for (int j = 0; j < 4; ++j) { v[j] = vn[j]; sc[j] = scn[j]; sh[j] = shn[j]; } }
.LBB0_251:
	s_or_b64 exec, exec, s[34:35]
	v_pk_mul_f32 v[190:191], v[2:3], v[2:3]
	v_pk_mul_f32 v[192:193], v[0:1], v[0:1]
	v_pk_mul_f32 v[186:187], v[6:7], v[6:7]
	v_pk_mul_f32 v[188:189], v[4:5], v[4:5]
	v_pk_mov_b32 v[194:195], v[192:193], v[190:191] op_sel:[1,0]
	v_mov_b32_e32 v193, v191
	v_pk_add_f32 v[190:191], v[194:195], v[192:193]
	v_pk_mov_b32 v[192:193], v[188:189], v[186:187] op_sel:[1,0]
	v_mov_b32_e32 v189, v187
	v_pk_add_f32 v[186:187], v[192:193], v[188:189]
	v_pk_add_f32 v[190:191], v[190:191], v[190:191] op_sel_hi:[0,1]
	v_pk_add_f32 v[186:187], v[186:187], v[186:187] op_sel_hi:[0,1]
	v_mul_f32_e32 v186, v8, v8
	v_pk_fma_f32 v[188:189], v[8:9], v[8:9], v[186:187] op_sel_hi:[1,1,0]
	v_mul_f32_e32 v186, v10, v10
	v_pk_fma_f32 v[192:193], v[10:11], v[10:11], v[186:187] op_sel_hi:[1,1,0]
	v_mul_f32_e32 v188, v12, v12
	v_mul_f32_e32 v192, v13, v13
	v_mul_f32_e32 v190, v14, v14
	v_mul_f32_e32 v186, v15, v15
	v_pk_add_f32 v[188:189], v[188:189], v[192:193]
	v_pk_add_f32 v[186:187], v[190:191], v[186:187]
	s_and_b64 s[2:3], exec, vcc
	v_pk_add_f32 v[186:187], v[188:189], v[186:187]
	s_or_b64 s[24:25], s[2:3], s[24:25]
	v_add_f32_e32 v155, v186, v187
	ds_bpermute_b32 v157, v174, v155
	v_lshl_add_u64 v[162:163], v[162:163], 0, v[116:117]
	global_store_dwordx4 v[162:163], v[0:3], off sc1
	global_store_dwordx4 v[162:163], v[4:7], off offset:1024 sc1
	global_store_dwordx4 v[162:163], v[8:11], off offset:2048 sc1
	global_store_dwordx4 v[162:163], v[12:15], off offset:3072 sc1
	v_pk_add_f32 v[192:193], v[48:49], 1.0 op_sel_hi:[1,0]
	s_waitcnt lgkmcnt(0)
	v_add_f32_e32 v155, v155, v157
	ds_bpermute_b32 v157, v175, v155
	v_lshlrev_b64 v[160:161], 11, v[160:161]
	v_pk_add_f32 v[190:191], v[50:51], 1.0 op_sel_hi:[1,0]
	v_lshl_add_u64 v[160:161], v[150:151], 0, v[160:161]
	s_waitcnt lgkmcnt(0)
	v_add_f32_e32 v155, v155, v157
	ds_bpermute_b32 v157, v176, v155
	s_waitcnt lgkmcnt(0)
	v_add_f32_e32 v155, v155, v157
	ds_bpermute_b32 v157, v177, v155
	s_waitcnt lgkmcnt(0)
	v_add_f32_e32 v155, v155, v157
	ds_bpermute_b32 v157, v178, v155
	s_waitcnt lgkmcnt(0)
	v_add_f32_e32 v155, v155, v157
	ds_bpermute_b32 v157, v179, v155
	s_waitcnt lgkmcnt(0)
	v_add_f32_e32 v155, v155, v157
	v_fmamk_f32 v155, v155, 0x3a800000, v180
	v_mul_f32_e32 v157, 0x4f800000, v155
	v_cmp_gt_f32_e32 vcc, s60, v155
	s_nop 1
	v_cndmask_b32_e32 v155, v155, v157, vcc
	v_sqrt_f32_e32 v157, v155
	s_nop 0
	v_add_u32_e32 v159, -1, v157
	v_add_u32_e32 v185, 1, v157
	v_fma_f32 v186, -v159, v157, v155
	v_fma_f32 v187, -v185, v157, v155
	v_cmp_ge_f32_e64 s[6:7], 0, v186
	s_nop 1
	v_cndmask_b32_e64 v157, v157, v159, s[6:7]
	v_cmp_lt_f32_e64 s[6:7], 0, v187
	s_nop 1
	v_cndmask_b32_e64 v157, v157, v185, s[6:7]
	v_mul_f32_e32 v159, 0x37800000, v157
	v_cndmask_b32_e32 v157, v157, v159, vcc
	v_cmp_class_f32_e32 vcc, v155, v181
	s_nop 1
	v_cndmask_b32_e32 v155, v157, v155, vcc
	v_div_scale_f32 v157, s[2:3], v155, v155, 1.0
	v_rcp_f32_e32 v159, v157
	v_div_scale_f32 v162, vcc, 1.0, v155, 1.0
	v_fma_f32 v163, -v157, v159, 1.0
	v_fmac_f32_e32 v159, v163, v159
	v_mul_f32_e32 v163, v162, v159
	v_fma_f32 v185, -v157, v163, v162
	v_fmac_f32_e32 v163, v185, v159
	v_fma_f32 v157, -v157, v163, v162
	v_div_fmas_f32 v157, v157, v159, v163
	v_div_fixup_f32 v162, v157, v155, 1.0
	v_pk_mul_f32 v[188:189], v[0:1], v[162:163] op_sel_hi:[1,0]
	v_pk_mul_f32 v[186:187], v[2:3], v[162:163] op_sel_hi:[1,0]
	s_waitcnt vmcnt(7)
	v_pk_mul_f32 v[188:189], v[32:33], v[188:189]
	v_pk_mul_f32 v[186:187], v[34:35], v[186:187]
	v_pk_fma_f32 v[188:189], v[192:193], v[188:189], v[52:53]
	v_pk_fma_f32 v[186:187], v[190:191], v[186:187], v[54:55]
	v_cvt_pk_bf16_f32 v188, v188, v189
	s_waitcnt vmcnt(5)
	v_pk_add_f32 v[192:193], v[72:73], 1.0 op_sel_hi:[1,0]
	v_cvt_pk_bf16_f32 v189, v186, v187
	global_store_dwordx2 v[160:161], v[188:189], off sc1
	v_pk_mul_f32 v[188:189], v[4:5], v[162:163] op_sel_hi:[1,0]
	v_pk_mul_f32 v[186:187], v[6:7], v[162:163] op_sel_hi:[1,0]
	v_pk_mul_f32 v[188:189], v[36:37], v[188:189]
	v_pk_mul_f32 v[186:187], v[38:39], v[186:187]
	v_pk_add_f32 v[190:191], v[74:75], 1.0 op_sel_hi:[1,0]
	v_pk_fma_f32 v[188:189], v[192:193], v[188:189], v[60:61]
	v_pk_fma_f32 v[186:187], v[190:191], v[186:187], v[62:63]
	v_cvt_pk_bf16_f32 v188, v188, v189
	v_pk_add_f32 v[190:191], v[70:71], 1.0 op_sel_hi:[1,0]
	v_cvt_pk_bf16_f32 v189, v186, v187
	global_store_dwordx2 v[160:161], v[188:189], off offset:512 sc1
	v_pk_mul_f32 v[186:187], v[10:11], v[162:163] op_sel_hi:[1,0]
	v_pk_mul_f32 v[188:189], v[8:9], v[162:163] op_sel_hi:[1,0]
	v_pk_mul_f32 v[186:187], v[42:43], v[186:187]
	v_pk_mul_f32 v[188:189], v[40:41], v[188:189]
	v_pk_add_f32 v[192:193], v[68:69], 1.0 op_sel_hi:[1,0]
	v_pk_fma_f32 v[186:187], v[190:191], v[186:187], v[58:59]
	v_pk_fma_f32 v[188:189], v[192:193], v[188:189], v[56:57]
	v_pk_add_f32 v[190:191], v[64:65], 1.0 op_sel_hi:[1,0]
	v_cvt_pk_bf16_f32 v188, v188, v189
	v_cvt_pk_bf16_f32 v189, v186, v187
	v_pk_mul_f32 v[186:187], v[14:15], v[162:163] op_sel_hi:[1,0]
	v_pk_mul_f32 v[162:163], v[12:13], v[162:163] op_sel_hi:[1,0]
	global_store_dwordx2 v[160:161], v[188:189], off offset:1024 sc1
	s_waitcnt vmcnt(7)
	v_pk_mul_f32 v[162:163], v[44:45], v[162:163]
	v_pk_mul_f32 v[186:187], v[46:47], v[186:187]
	v_pk_add_f32 v[188:189], v[66:67], 1.0 op_sel_hi:[1,0]
	v_pk_fma_f32 v[162:163], v[190:191], v[162:163], v[76:77]
	v_pk_fma_f32 v[186:187], v[188:189], v[186:187], v[78:79]
	v_cvt_pk_bf16_f32 v162, v162, v163
	s_nop 0
	v_cvt_pk_bf16_f32 v163, v186, v187
	global_store_dwordx2 v[160:161], v[162:163], off offset:1536 sc1
	s_and_saveexec_b64 s[6:7], s[4:5]
	s_cbranch_execz .LBB0_204
	v_mov_b64_e32 v[64:65], v[96:97]
	v_mov_b64_e32 v[68:69], v[100:101]
	v_mov_b64_e32 v[72:73], v[104:105]
	v_mov_b64_e32 v[48:49], v[80:81]
	v_mov_b64_e32 v[76:77], v[108:109]
	v_mov_b64_e32 v[56:57], v[92:93]
	v_mov_b64_e32 v[60:61], v[88:89]
	v_mov_b64_e32 v[52:53], v[84:85]
	v_mov_b64_e32 v[0:1], v[16:17]
	v_mov_b64_e32 v[66:67], v[98:99]
	v_mov_b64_e32 v[70:71], v[102:103]
	v_mov_b64_e32 v[74:75], v[106:107]
	v_mov_b64_e32 v[50:51], v[82:83]
	v_mov_b64_e32 v[78:79], v[110:111]
	v_mov_b64_e32 v[58:59], v[94:95]
	v_mov_b64_e32 v[62:63], v[90:91]
	v_mov_b64_e32 v[54:55], v[86:87]
	v_mov_b64_e32 v[2:3], v[18:19]
	v_mov_b64_e32 v[4:5], v[20:21]
	v_mov_b64_e32 v[6:7], v[22:23]
	v_mov_b64_e32 v[8:9], v[24:25]
	v_mov_b64_e32 v[10:11], v[26:27]
	v_mov_b64_e32 v[12:13], v[28:29]
	v_mov_b64_e32 v[14:15], v[30:31]
	s_branch .LBB0_204

; #define GAS __attribute__((address_space(1)))
; __device__ __forceinline__ unsigned cvt_pk_bf16(float lo, float hi) { unsigned r; asm volatile("v_cvt_pk_bf16_f32 %0, %1, %2" : "=v"(r) : "v"(lo), "v"(hi)); return r; }
; __device__ __forceinline__ void phase_norm(const Params& P, int l, int sub, int addpart) {
;     ...
;         float ss = 0.f;
; #pragma unroll
;         for (int j = 0; j < 4; ++j) ss += (v[j].x * v[j].x + v[j].y * v[j].y) + (v[j].z * v[j].z + v[j].w * v[j].w);
;         const float rstd = 1.0f / sqrtf(wave_sum(ss) * (1.0f / 1024.0f) + 1e-6f);
; #pragma unroll
;         for (int j = 0; j < 4; ++j) { const f32x4 y = v[j] * rstd * gg[j] * (sc[j] + 1.0f) + sh[j];
;             u32x2 w; w.x = cvt_pk_bf16(y.x, y.y); w.y = cvt_pk_bf16(y.z, y.w); *(GAS u32x2*)((GAS bf16_t*)XN + (size_t)r * 1024 + 4 * lane + 256 * j) = w; }
;         if (rn < rend) {
; #pragma unroll
;             for (int j = 0; j < 4; ++j) { v[j] = vn[j]; sc[j] = scn[j]; sh[j] = shn[j]; } }
.LBB0_319:
	s_or_b64 exec, exec, s[42:43]
	v_mov_b32_e32 v142, v58
	v_mov_b32_e32 v143, v56
	v_mov_b32_e32 v150, v59
	v_mov_b32_e32 v151, v57
	v_pk_mul_f32 v[142:143], v[142:143], v[142:143]
	v_pk_mul_f32 v[152:153], v[140:141], v[140:141]
	v_pk_fma_f32 v[142:143], v[150:151], v[150:151], v[142:143]
	v_pk_fma_f32 v[152:153], v[60:61], v[60:61], v[152:153]
	v_pk_add_f32 v[142:143], v[142:143], v[142:143] op_sel_hi:[0,1]
	v_pk_add_f32 v[152:153], v[152:153], v[152:153] op_sel_hi:[0,1]
	v_mul_f32_e32 v142, v52, v52
	v_mul_f32_e32 v155, v54, v54
	v_mul_f32_e32 v63, v55, v55
	v_mov_b32_e32 v154, v62
	v_pk_fma_f32 v[150:151], v[52:53], v[52:53], v[142:143] op_sel_hi:[1,1,0]
	v_mul_f32_e32 v152, v40, v40
	v_mul_f32_e32 v142, v41, v41
	v_pk_add_f32 v[154:155], v[62:63], v[154:155]
	v_mul_f32_e32 v150, v42, v42
	v_pk_add_f32 v[142:143], v[142:143], v[152:153]
	v_mul_f32_e32 v152, v62, v62
	v_mov_b32_e32 v153, v155
	v_pk_add_f32 v[150:151], v[152:153], v[150:151]
	s_and_b64 s[0:1], exec, s[38:39]
	v_pk_add_f32 v[142:143], v[150:151], v[142:143]
	s_or_b64 s[8:9], s[0:1], s[8:9]
	v_add_f32_e32 v43, v142, v143
	ds_bpermute_b32 v63, v144, v43
	s_mov_b32 s0, 0xf800000
	v_mov_b32_e32 v150, v140
	v_mov_b32_e32 v151, v60
	v_mov_b32_e32 v60, v141
	s_waitcnt lgkmcnt(0)
	v_add_f32_e32 v43, v43, v63
	ds_bpermute_b32 v63, v145, v43
	v_pk_add_f32 v[46:47], v[46:47], 1.0 op_sel_hi:[1,0]
	v_pk_add_f32 v[44:45], v[44:45], 1.0 op_sel_hi:[1,0]
	v_pk_add_f32 v[32:33], v[32:33], 1.0 op_sel_hi:[1,0]
	v_pk_add_f32 v[34:35], v[34:35], 1.0 op_sel_hi:[1,0]
	s_waitcnt lgkmcnt(0)
	v_add_f32_e32 v43, v43, v63
	ds_bpermute_b32 v63, v146, v43
	v_pk_add_f32 v[26:27], v[26:27], 1.0 op_sel_hi:[1,0]
	v_pk_add_f32 v[24:25], v[24:25], 1.0 op_sel_hi:[1,0]
	s_waitcnt vmcnt(1)
	v_pk_add_f32 v[16:17], v[16:17], 1.0 op_sel_hi:[1,0]
	v_pk_add_f32 v[18:19], v[18:19], 1.0 op_sel_hi:[1,0]
	s_waitcnt lgkmcnt(0)
	v_add_f32_e32 v43, v43, v63
	ds_bpermute_b32 v63, v147, v43
	s_waitcnt lgkmcnt(0)
	v_add_f32_e32 v43, v43, v63
	ds_bpermute_b32 v63, v148, v43
	s_waitcnt lgkmcnt(0)
	v_add_f32_e32 v43, v43, v63
	ds_bpermute_b32 v63, v149, v43
	s_waitcnt lgkmcnt(0)
	v_add_f32_e32 v43, v43, v63
	v_fmamk_f32 v43, v43, 0x3a800000, v137
	v_cmp_gt_f32_e32 vcc, s0, v43
	v_mul_f32_e32 v63, 0x4f800000, v43
	s_nop 0
	v_cndmask_b32_e32 v43, v43, v63, vcc
	v_sqrt_f32_e32 v63, v43
	s_nop 0
	v_add_u32_e32 v113, -1, v63
	v_fma_f32 v115, -v113, v63, v43
	v_cmp_ge_f32_e64 s[38:39], 0, v115
	v_add_u32_e32 v115, 1, v63
	s_nop 0
	v_cndmask_b32_e64 v113, v63, v113, s[38:39]
	v_fma_f32 v63, -v115, v63, v43
	v_cmp_lt_f32_e64 s[38:39], 0, v63
	s_nop 1
	v_cndmask_b32_e64 v63, v113, v115, s[38:39]
	v_mul_f32_e32 v113, 0x37800000, v63
	v_cndmask_b32_e32 v63, v63, v113, vcc
	v_cmp_class_f32_e32 vcc, v43, v169
	s_nop 1
	v_cndmask_b32_e32 v43, v63, v43, vcc
	v_div_scale_f32 v63, s[0:1], v43, v43, 1.0
	v_rcp_f32_e32 v113, v63
	v_readlane_b32 s0, v253, 34
	v_readlane_b32 s1, v253, 35
	v_fma_f32 v115, -v63, v113, 1.0
	v_fmac_f32_e32 v113, v115, v113
	v_div_scale_f32 v115, vcc, 1.0, v43, 1.0
	v_mul_f32_e32 v117, v115, v113
	v_fma_f32 v119, -v63, v117, v115
	v_fmac_f32_e32 v117, v119, v113
	v_fma_f32 v63, -v63, v117, v115
	v_div_fmas_f32 v63, v63, v113, v117
	v_div_fixup_f32 v142, v63, v43, 1.0
	v_pk_mul_f32 v[150:151], v[150:151], v[142:143] op_sel_hi:[1,0]
	v_pk_mul_f32 v[60:61], v[60:61], v[142:143] op_sel_hi:[1,0]
	v_pk_mul_f32 v[140:141], v[2:3], v[150:151]
	v_pk_mul_f32 v[60:61], v[0:1], v[60:61]
	v_pk_fma_f32 v[46:47], v[46:47], v[140:141], v[50:51]
	v_pk_fma_f32 v[44:45], v[44:45], v[60:61], v[48:49]
	v_mov_b32_e32 v43, v62
	v_cvt_pk_bf16_f32 v44, v44, v45
	v_cvt_pk_bf16_f32 v45, v46, v47
	v_pk_mul_f32 v[46:47], v[56:57], v[142:143] op_sel_hi:[1,0]
	global_store_dwordx2 v[138:139], v[44:45], off offset:-1536 sc1
	v_pk_mul_f32 v[44:45], v[58:59], v[142:143] op_sel_hi:[1,0]
	v_pk_mul_f32 v[46:47], v[4:5], v[46:47]
	v_pk_mul_f32 v[44:45], v[6:7], v[44:45]
	v_pk_fma_f32 v[32:33], v[32:33], v[46:47], v[36:37]
	v_pk_fma_f32 v[34:35], v[34:35], v[44:45], v[38:39]
	v_cvt_pk_bf16_f32 v32, v32, v33
	v_mov_b64_e32 v[44:45], v[68:69]
	v_cvt_pk_bf16_f32 v33, v34, v35
	global_store_dwordx2 v[138:139], v[32:33], off offset:-1024 sc1
	v_pk_mul_f32 v[32:33], v[54:55], v[142:143] op_sel_hi:[1,0]
	v_pk_mul_f32 v[34:35], v[52:53], v[142:143] op_sel_hi:[1,0]
	v_pk_mul_f32 v[32:33], v[10:11], v[32:33]
	v_pk_mul_f32 v[34:35], v[8:9], v[34:35]
	v_pk_fma_f32 v[26:27], v[26:27], v[32:33], v[30:31]
	v_pk_fma_f32 v[24:25], v[24:25], v[34:35], v[28:29]
	v_mov_b64_e32 v[32:33], v[96:97]
	v_cvt_pk_bf16_f32 v24, v24, v25
	v_cvt_pk_bf16_f32 v25, v26, v27
	v_pk_mul_f32 v[26:27], v[40:41], v[142:143] op_sel_hi:[1,0]
	global_store_dwordx2 v[138:139], v[24:25], off offset:-512 sc1
	v_pk_mul_f32 v[24:25], v[42:43], v[142:143] op_sel_hi:[1,0]
	v_pk_mul_f32 v[26:27], v[12:13], v[26:27]
	v_pk_mul_f32 v[24:25], v[14:15], v[24:25]
	s_waitcnt vmcnt(3)
	v_pk_fma_f32 v[16:17], v[16:17], v[26:27], v[20:21]
	v_pk_fma_f32 v[18:19], v[18:19], v[24:25], v[22:23]
	v_cvt_pk_bf16_f32 v16, v16, v17
	v_mov_b64_e32 v[24:25], v[92:93]
	v_cvt_pk_bf16_f32 v17, v18, v19
	global_store_dwordx2 v[138:139], v[16:17], off sc1
	v_mov_b64_e32 v[16:17], v[88:89]
	v_mov_b64_e32 v[20:21], v[100:101]
	v_mov_b64_e32 v[28:29], v[84:85]
	v_mov_b64_e32 v[36:37], v[80:81]
	v_mov_b64_e32 v[48:49], v[72:73]
	v_lshl_add_u64 v[138:139], v[138:139], 0, s[0:1]
	v_mov_b32_e32 v142, v128
	v_mov_b64_e32 v[18:19], v[90:91]
	v_mov_b64_e32 v[26:27], v[94:95]
	v_mov_b64_e32 v[34:35], v[98:99]
	v_mov_b64_e32 v[46:47], v[70:71]
	v_mov_b64_e32 v[22:23], v[102:103]
	v_mov_b64_e32 v[30:31], v[86:87]
	v_mov_b64_e32 v[38:39], v[82:83]
	v_mov_b64_e32 v[50:51], v[74:75]
	v_mov_b32_e32 v141, v64
	v_mov_b32_e32 v61, v65
	v_mov_b32_e32 v140, v66
	v_mov_b32_e32 v60, v67
	v_mov_b32_e32 v56, v76
	v_mov_b32_e32 v57, v77
	v_mov_b32_e32 v58, v78
	v_mov_b32_e32 v59, v79
	v_mov_b32_e32 v52, v104
	v_mov_b32_e32 v53, v105
	v_mov_b32_e32 v54, v106
	v_mov_b32_e32 v55, v107
	v_mov_b32_e32 v40, v108
	v_mov_b32_e32 v41, v109
	v_mov_b32_e32 v42, v110
	v_mov_b32_e32 v62, v111
	s_andn2_b64 exec, exec, s[8:9]
	s_cbranch_execz .LBB0_330

; __device__ __forceinline__ void phase_norm(const Params& P, int l, int sub, int addpart) {
;     ...
;         if (addpart && r >= TL) { float* hw = (float*)(P.ws + OFF_HC) + (size_t)(r - TL) * 1024;
; #pragma unroll
;             for (int j = 0; j < 4; ++j) *(f32x4*)(hw + 4 * lane + 256 * j) = v[j]; }
.LBB0_325:
	s_or_b64 exec, exec, s[42:43]
	v_add_u32_e32 v43, 0x8000, v142
	v_cmp_gt_i32_e32 vcc, s25, v43
	s_and_saveexec_b64 s[0:1], vcc
	s_xor_b64 s[42:43], exec, s[0:1]
	s_andn2_saveexec_b64 s[42:43], s[42:43]
	s_cbranch_execz .LBB0_319
	v_mov_b32_e32 v143, v129
	v_lshlrev_b64 v[142:143], 12, v[142:143]
	v_lshl_add_u64 v[142:143], v[120:121], 0, v[142:143]
	v_mov_b32_e32 v150, v141
	v_mov_b32_e32 v151, v61
	v_mov_b32_e32 v152, v140
	v_mov_b32_e32 v153, v60
	v_mov_b32_e32 v43, v62
	global_store_dwordx4 v[142:143], v[150:153], off sc1
	global_store_dwordx4 v[142:143], v[56:59], off offset:1024 sc1
	global_store_dwordx4 v[142:143], v[52:55], off offset:2048 sc1
	global_store_dwordx4 v[142:143], v[40:43], off offset:3072 sc1
	s_branch .LBB0_319

; #define GAS __attribute__((address_space(1)))
; __device__ __forceinline__ unsigned f2bf(float f) { unsigned u = __float_as_uint(f); return (u + 0x7fffu + ((u >> 16) & 1u)) >> 16; }
; __device__ __forceinline__ void dft_nyquist(const Params& P) {
;     ...
;     for (int wi = blockIdx.x * 8 + (tid >> 6); wi < NB * 256; wi += gridDim.x * 8) { const int b = wi >> 8, ch = wi & 255; const GAS bf16_t* fp = FT + ((size_t)b * 256 + ch) * 4096; float a = 0.f;
;         u32x4 qv[8];
; #pragma unroll
;         for (int j = 0; j < 8; ++j) qv[j] = *(const GAS u32x4*)(fp + (size_t)(j * 64 + lane) * 8);
;         __builtin_amdgcn_sched_barrier(0);
; #pragma unroll
;         for (int j = 0; j < 8; ++j) {
; #pragma unroll
;             for (int e = 0; e < 4; ++e) a += __uint_as_float(qv[j][e] << 16) - __uint_as_float(qv[j][e] & 0xffff0000u); }
;         a = wave_sum(a);
;         if (lane == 0) { GAS bf16_t* yr = Y + (size_t)(b * 4096 + 2048) * YW; yr[768 + ch] = (bf16_t)f2bf(a * (1.0f / 512.0f)); yr[1024 + ch] = (bf16_t)0; } }
.LBB0_543:
	v_ashrrev_i32_e32 v2, 8, v4
	s_waitcnt lgkmcnt(0)
	v_ashrrev_i32_e32 v3, 31, v2
	v_readlane_b32 s0, v251, 61
	v_lshlrev_b64 v[12:13], 21, v[2:3]
	v_readlane_b32 s1, v251, 62
	v_lshlrev_b32_sdwa v128, v175, v4 dst_sel:DWORD dst_unused:UNUSED_PAD src0_sel:DWORD src1_sel:BYTE_0
	v_mov_b32_e32 v1, v129
	v_lshl_add_u64 v[12:13], s[0:1], 0, v[12:13]
	v_lshl_add_u64 v[12:13], v[12:13], 0, v[128:129]
	v_lshl_add_u64 v[28:29], v[12:13], 0, v[0:1]
	s_movk_i32 s0, 0x1000
	v_add_co_u32_e64 v40, s[38:39], s0, v28
	global_load_dwordx4 v[12:15], v[28:29], off
	global_load_dwordx4 v[16:19], v[28:29], off offset:1024
	global_load_dwordx4 v[20:23], v[28:29], off offset:2048
	global_load_dwordx4 v[24:27], v[28:29], off offset:3072
	v_addc_co_u32_e64 v41, s[38:39], 0, v29, s[38:39]
	global_load_dwordx4 v[28:31], v[40:41], off
	global_load_dwordx4 v[32:35], v[40:41], off offset:1024
	global_load_dwordx4 v[36:39], v[40:41], off offset:2048
	s_nop 0
	global_load_dwordx4 v[40:43], v[40:41], off offset:3072
	s_waitcnt vmcnt(7)
	v_lshlrev_b32_e32 v1, 16, v12
	v_and_b32_e32 v3, 0xffff0000, v12
	v_sub_f32_e32 v1, v1, v3
	v_lshlrev_b32_e32 v3, 16, v13
	v_and_b32_e32 v11, 0xffff0000, v13
	v_add_f32_e32 v1, 0, v1
	v_sub_f32_e32 v3, v3, v11
	v_add_f32_e32 v1, v3, v1
	v_lshlrev_b32_e32 v3, 16, v14
	v_and_b32_e32 v11, 0xffff0000, v14
	v_sub_f32_e32 v3, v3, v11
	v_add_f32_e32 v1, v3, v1
	v_lshlrev_b32_e32 v3, 16, v15
	v_and_b32_e32 v11, 0xffff0000, v15
	v_sub_f32_e32 v3, v3, v11
	v_add_f32_e32 v1, v3, v1
	s_waitcnt vmcnt(6)
	v_lshlrev_b32_e32 v3, 16, v16
	v_and_b32_e32 v11, 0xffff0000, v16
	v_sub_f32_e32 v3, v3, v11
	v_add_f32_e32 v1, v3, v1
	v_lshlrev_b32_e32 v3, 16, v17
	v_and_b32_e32 v11, 0xffff0000, v17
	v_sub_f32_e32 v3, v3, v11
	v_add_f32_e32 v1, v3, v1
	v_lshlrev_b32_e32 v3, 16, v18
	v_and_b32_e32 v11, 0xffff0000, v18
	v_sub_f32_e32 v3, v3, v11
	v_add_f32_e32 v1, v3, v1
	v_lshlrev_b32_e32 v3, 16, v19
	v_and_b32_e32 v11, 0xffff0000, v19
	v_sub_f32_e32 v3, v3, v11
	v_add_f32_e32 v1, v3, v1
	s_waitcnt vmcnt(5)
	v_lshlrev_b32_e32 v3, 16, v20
	v_and_b32_e32 v11, 0xffff0000, v20
	v_sub_f32_e32 v3, v3, v11
	v_add_f32_e32 v1, v3, v1
	v_lshlrev_b32_e32 v3, 16, v21
	v_and_b32_e32 v11, 0xffff0000, v21
	v_sub_f32_e32 v3, v3, v11
	v_add_f32_e32 v1, v3, v1
	v_lshlrev_b32_e32 v3, 16, v22
	v_and_b32_e32 v11, 0xffff0000, v22
	v_sub_f32_e32 v3, v3, v11
	v_add_f32_e32 v1, v3, v1
	v_lshlrev_b32_e32 v3, 16, v23
	v_and_b32_e32 v11, 0xffff0000, v23
	v_sub_f32_e32 v3, v3, v11
	v_add_f32_e32 v1, v3, v1
	s_waitcnt vmcnt(4)
	v_lshlrev_b32_e32 v3, 16, v24
	v_and_b32_e32 v11, 0xffff0000, v24
	v_sub_f32_e32 v3, v3, v11
	v_add_f32_e32 v1, v3, v1
	v_lshlrev_b32_e32 v3, 16, v25
	v_and_b32_e32 v11, 0xffff0000, v25
	v_sub_f32_e32 v3, v3, v11
	v_add_f32_e32 v1, v3, v1
	v_lshlrev_b32_e32 v3, 16, v26
	v_and_b32_e32 v11, 0xffff0000, v26
	v_sub_f32_e32 v3, v3, v11
	v_add_f32_e32 v1, v3, v1
	v_lshlrev_b32_e32 v3, 16, v27
	v_and_b32_e32 v11, 0xffff0000, v27
	v_sub_f32_e32 v3, v3, v11
	v_add_f32_e32 v1, v3, v1
	s_waitcnt vmcnt(3)
	v_lshlrev_b32_e32 v3, 16, v28
	v_and_b32_e32 v11, 0xffff0000, v28
	v_sub_f32_e32 v3, v3, v11
	v_add_f32_e32 v1, v3, v1
	v_lshlrev_b32_e32 v3, 16, v29
	v_and_b32_e32 v11, 0xffff0000, v29
	v_sub_f32_e32 v3, v3, v11
	v_add_f32_e32 v1, v3, v1
	v_lshlrev_b32_e32 v3, 16, v30
	v_and_b32_e32 v11, 0xffff0000, v30
	v_sub_f32_e32 v3, v3, v11
	v_add_f32_e32 v1, v3, v1
	v_lshlrev_b32_e32 v3, 16, v31
	v_and_b32_e32 v11, 0xffff0000, v31
	v_sub_f32_e32 v3, v3, v11
	v_add_f32_e32 v1, v3, v1
	s_waitcnt vmcnt(2)
	v_lshlrev_b32_e32 v3, 16, v32
	v_and_b32_e32 v11, 0xffff0000, v32
	v_sub_f32_e32 v3, v3, v11
	v_add_f32_e32 v1, v3, v1
	v_lshlrev_b32_e32 v3, 16, v33
	v_and_b32_e32 v11, 0xffff0000, v33
	v_sub_f32_e32 v3, v3, v11
	v_add_f32_e32 v1, v3, v1
	v_lshlrev_b32_e32 v3, 16, v34
	v_and_b32_e32 v11, 0xffff0000, v34
	v_sub_f32_e32 v3, v3, v11
	v_add_f32_e32 v1, v3, v1
	v_lshlrev_b32_e32 v3, 16, v35
	v_and_b32_e32 v11, 0xffff0000, v35
	v_sub_f32_e32 v3, v3, v11
	v_add_f32_e32 v1, v3, v1
	s_waitcnt vmcnt(1)
	v_lshlrev_b32_e32 v3, 16, v36
	v_and_b32_e32 v11, 0xffff0000, v36
	v_sub_f32_e32 v3, v3, v11
	v_add_f32_e32 v1, v3, v1
	v_lshlrev_b32_e32 v3, 16, v37
	v_and_b32_e32 v11, 0xffff0000, v37
	v_sub_f32_e32 v3, v3, v11
	v_add_f32_e32 v1, v3, v1
	v_lshlrev_b32_e32 v3, 16, v38
	v_and_b32_e32 v11, 0xffff0000, v38
	v_sub_f32_e32 v3, v3, v11
	v_add_f32_e32 v1, v3, v1
	v_lshlrev_b32_e32 v3, 16, v39
	v_and_b32_e32 v11, 0xffff0000, v39
	v_sub_f32_e32 v3, v3, v11
	v_add_f32_e32 v1, v3, v1
	s_waitcnt vmcnt(0)
	v_lshlrev_b32_e32 v3, 16, v40
	v_and_b32_e32 v11, 0xffff0000, v40
	v_sub_f32_e32 v3, v3, v11
	v_add_f32_e32 v1, v3, v1
	v_lshlrev_b32_e32 v3, 16, v41
	v_and_b32_e32 v11, 0xffff0000, v41
	v_sub_f32_e32 v3, v3, v11
	v_add_f32_e32 v1, v3, v1
	v_lshlrev_b32_e32 v3, 16, v42
	v_and_b32_e32 v11, 0xffff0000, v42
	v_sub_f32_e32 v3, v3, v11
	v_add_f32_e32 v1, v3, v1
	v_lshlrev_b32_e32 v3, 16, v43
	v_and_b32_e32 v11, 0xffff0000, v43
	v_sub_f32_e32 v3, v3, v11
	v_add_f32_e32 v1, v3, v1
	ds_bpermute_b32 v3, v5, v1
	s_waitcnt lgkmcnt(0)
	v_add_f32_e32 v1, v1, v3
	ds_bpermute_b32 v3, v6, v1
	s_waitcnt lgkmcnt(0)
	v_add_f32_e32 v1, v1, v3
	ds_bpermute_b32 v3, v7, v1
	s_waitcnt lgkmcnt(0)
	v_add_f32_e32 v1, v1, v3
	ds_bpermute_b32 v3, v8, v1
	s_waitcnt lgkmcnt(0)
	v_add_f32_e32 v1, v1, v3
	ds_bpermute_b32 v3, v9, v1
	s_waitcnt lgkmcnt(0)
	v_add_f32_e32 v1, v1, v3
	ds_bpermute_b32 v3, v10, v1
	s_and_saveexec_b64 s[38:39], vcc
	s_cbranch_execz .LBB0_542
	v_readlane_b32 s0, v253, 20
	s_waitcnt lgkmcnt(0)
	v_add_f32_e32 v1, v1, v3
	v_readlane_b32 s1, v253, 21
	v_lshl_or_b32 v11, v2, 12, v176
	v_mul_f32_e32 v1, 0x3b000000, v1
	v_mov_b64_e32 v[2:3], s[0:1]
	v_mad_i64_i32 v[2:3], s[0:1], v11, s23, v[2:3]
	v_bfe_u32 v11, v1, 16, 1
	v_lshlrev_b32_sdwa v128, v170, v4 dst_sel:DWORD dst_unused:UNUSED_PAD src0_sel:DWORD src1_sel:BYTE_0
	v_add3_u32 v1, v1, v11, s19
	v_lshl_add_u64 v[2:3], v[2:3], 0, v[128:129]
	global_store_short_d16_hi v[2:3], v1, off offset:1536 sc1
	global_store_short v[2:3], v129, off offset:2048 sc1
	s_branch .LBB0_542

; #define GAS __attribute__((address_space(1)))
; __device__ __forceinline__ int lru_pass1(const Params& P, int l, LAS unsigned char* lds, unsigned* qw) {
;     ...
; #pragma unroll
;             for (int idx = 0; idx < 16; ++idx) *(GAS u32x2*)(AB + ((size_t)(r0 + 16 * fq + idx) * 512 + c) * 2) = abw[idx];
;         }
.LBB0_556:
	s_or_b64 exec, exec, s[8:9]
	s_waitcnt lgkmcnt(6)
	v_or_b32_e32 v33, v105, v157
	s_waitcnt lgkmcnt(0)
	v_or_b32_e32 v32, v104, v156
	v_lshl_add_u64 v[32:33], v[32:33], 2, s[6:7]
	global_store_dwordx2 v[32:33], v[92:93], off sc1
	v_or_b32_e32 v33, v107, v157
	v_or_b32_e32 v32, v106, v156
	v_lshl_add_u64 v[32:33], v[32:33], 2, s[6:7]
	global_store_dwordx2 v[32:33], v[88:89], off sc1
	v_or_b32_e32 v33, v109, v157
	v_or_b32_e32 v32, v108, v156
	v_lshl_add_u64 v[32:33], v[32:33], 2, s[6:7]
	global_store_dwordx2 v[32:33], v[90:91], off sc1
	v_or_b32_e32 v33, v111, v157
	v_or_b32_e32 v32, v110, v156
	v_lshl_add_u64 v[32:33], v[32:33], 2, s[6:7]
	global_store_dwordx2 v[32:33], v[84:85], off sc1
	v_or_b32_e32 v33, v113, v157
	v_or_b32_e32 v32, v112, v156
	v_lshl_add_u64 v[32:33], v[32:33], 2, s[6:7]
	global_store_dwordx2 v[32:33], v[86:87], off sc1
	v_or_b32_e32 v33, v115, v157
	v_or_b32_e32 v32, v114, v156
	v_lshl_add_u64 v[32:33], v[32:33], 2, s[6:7]
	global_store_dwordx2 v[32:33], v[80:81], off sc1
	v_or_b32_e32 v33, v117, v157
	v_or_b32_e32 v32, v116, v156
	v_lshl_add_u64 v[32:33], v[32:33], 2, s[6:7]
	global_store_dwordx2 v[32:33], v[82:83], off sc1
	v_or_b32_e32 v33, v119, v157
	v_or_b32_e32 v32, v118, v156
	v_lshl_add_u64 v[32:33], v[32:33], 2, s[6:7]
	global_store_dwordx2 v[32:33], v[76:77], off sc1
	v_or_b32_e32 v33, v121, v157
	v_or_b32_e32 v32, v120, v156
	v_lshl_add_u64 v[32:33], v[32:33], 2, s[6:7]
	global_store_dwordx2 v[32:33], v[78:79], off sc1
	v_or_b32_e32 v33, v123, v157
	v_or_b32_e32 v32, v122, v156
	v_lshl_add_u64 v[32:33], v[32:33], 2, s[6:7]
	global_store_dwordx2 v[32:33], v[72:73], off sc1
	v_or_b32_e32 v33, v125, v157
	v_or_b32_e32 v32, v124, v156
	v_lshl_add_u64 v[32:33], v[32:33], 2, s[6:7]
	global_store_dwordx2 v[32:33], v[74:75], off sc1
	v_or_b32_e32 v33, v127, v157
	v_or_b32_e32 v32, v126, v156
	v_lshl_add_u64 v[32:33], v[32:33], 2, s[6:7]
	global_store_dwordx2 v[32:33], v[68:69], off sc1
	v_or_b32_e32 v33, v139, v157
	v_or_b32_e32 v32, v138, v156
	v_lshl_add_u64 v[32:33], v[32:33], 2, s[6:7]
	global_store_dwordx2 v[32:33], v[70:71], off sc1
	v_or_b32_e32 v33, v141, v157
	v_or_b32_e32 v32, v140, v156
	v_lshl_add_u64 v[32:33], v[32:33], 2, s[6:7]
	global_store_dwordx2 v[32:33], v[64:65], off sc1
	v_or_b32_e32 v33, v143, v157
	v_or_b32_e32 v32, v142, v156
	v_lshl_add_u64 v[32:33], v[32:33], 2, s[6:7]
	s_add_u32 s50, s50, 64
	global_store_dwordx2 v[32:33], v[94:95], off sc1
	v_or_b32_e32 v33, v145, v157
	v_or_b32_e32 v32, v144, v156
	s_addc_u32 s51, s51, 0
	v_lshl_add_u64 v[32:33], v[32:33], 2, s[6:7]
	v_add_u32_e32 v213, 32, v213
	v_lshl_add_u64 v[156:157], v[156:157], 0, 32
	v_lshl_add_u64 v[146:147], v[146:147], 0, 64
	v_lshl_add_u64 v[148:149], v[148:149], 0, s[64:65]
	v_lshl_add_u64 v[152:153], v[152:153], 0, 64
	s_cmpk_eq_i32 s50, 0x100
	v_lshl_add_u64 v[102:103], v[102:103], 0, 64
	global_store_dwordx2 v[32:33], v[66:67], off sc1
	s_cbranch_scc1 .LBB0_625

; __device__ __forceinline__ int lru_pass1(const Params& P, int l, LAS unsigned char* lds, unsigned* qw) {
;     ...
;                         const f32x2 tr = ((f32x2){acc[mt][2 * d][2 * ip], acc[mt][2 * d][2 * ip + 1]} + bgr) * (-1.4426950408889634f);
;                         const f32x2 ti = ((f32x2){acc[mt][2 * d + 1][2 * ip], acc[mt][2 * d + 1][2 * ip + 1]} + bgi) * (-1.4426950408889634f);
;                         const f32x2 dr = (f32x2){__builtin_amdgcn_exp2f(tr.x), __builtin_amdgcn_exp2f(tr.y)} + 1.0f, di = (f32x2){__builtin_amdgcn_exp2f(ti.x), __builtin_amdgcn_exp2f(ti.y)} + 1.0f;
;                         const f32x2 r = (f32x2){__builtin_amdgcn_rcpf(dr.x), __builtin_amdgcn_rcpf(dr.y)}, ig = (f32x2){__builtin_amdgcn_rcpf(di.x), __builtin_amdgcn_rcpf(di.y)};
;                         const f32x2 la = r * (-sp8), x2 = la + la;
;                         f32x2 q5 = x2 * 0.0083333333f + 0.041666668f; q5 = q5 * x2 + 0.16666667f; q5 = q5 * x2 + 0.5f; q5 = q5 * x2 + 1.0f; f32x2 em = -(x2 * q5);
;                         if (__builtin_expect(__any((x2.x < -0.25f) || (x2.y < -0.25f)), 0)) {
;                             if (x2.x < -0.25f) em.x = 1.0f - __expf(x2.x);
;                             if (x2.y < -0.25f) em.y = 1.0f - __expf(x2.y); }
;                         const f32x2 tl = la * 1.4426950408889634f; const f32x2 om = 1.0f - (f32x2){__builtin_amdgcn_exp2f(tl.x), __builtin_amdgcn_exp2f(tl.y)};
;                         const f32x2 bvv = (f32x2){__builtin_amdgcn_sqrtf(em.x), __builtin_amdgcn_sqrtf(em.y)} * ig * xcv;
;                         const unsigned wq0 = cvt_pk_bf16(om.x, bvv.x), wq1 = cvt_pk_bf16(om.y, bvv.y);
;                         acc[mt][2 * d][2 * ip] = 1.0f - __uint_as_float(wq0 << 16); acc[mt][2 * d + 1][2 * ip] = __uint_as_float(wq0 & 0xffff0000u);
;                         acc[mt][2 * d][2 * ip + 1] = 1.0f - __uint_as_float(wq1 << 16); acc[mt][2 * d + 1][2 * ip + 1] = __uint_as_float(wq1 & 0xffff0000u);
;                         abw[mt * 4 + 2 * ip][d] = wq0; abw[mt * 4 + 2 * ip + 1][d] = wq1; }
;                 float Ar = 1.f, Br = 0.f;
; #pragma unroll
;                 for (int s = 0; s < 16; ++s) { const int idx = d == 0 ? s : 15 - s; const float a = acc[idx >> 2][2 * d][idx & 3], bb = acc[idx >> 2][2 * d + 1][idx & 3]; Br = a * Br + bb; Ar *= a; }
;                 float Ac = 1.f, Bc = 0.f;
; #pragma unroll
.LBB0_565:
	v_pk_add_f32 v[66:67], v[66:67], v[158:159]
	v_sqrt_f32_e32 v160, v160
	v_pk_mul_f32 v[66:67], v[66:67], s[18:19] op_sel_hi:[1,0]
	v_sqrt_f32_e32 v161, v161
	v_exp_f32_e32 v66, v66
	v_exp_f32_e32 v67, v67
	v_lshlrev_b32_e32 v183, 16, v92
	v_sub_f32_e32 v183, 1.0, v183
	v_and_b32_e32 v214, 0xffff0000, v92
	v_pk_add_f32 v[66:67], v[66:67], 1.0 op_sel_hi:[1,0]
	v_lshlrev_b32_e32 v215, 16, v88
	v_rcp_f32_e32 v66, v66
	v_rcp_f32_e32 v67, v67
	v_lshlrev_b32_e32 v167, 16, v90
	v_sub_f32_e32 v215, 1.0, v215
	v_and_b32_e32 v216, 0xffff0000, v88
	v_fmac_f32_e32 v214, 0, v183
	v_sub_f32_e32 v167, 1.0, v167
	v_and_b32_e32 v180, 0xffff0000, v90
	v_lshlrev_b32_e32 v181, 16, v84
	v_pk_mul_f32 v[66:67], v[66:67], v[160:161]
	v_fmac_f32_e32 v216, v215, v214
	v_mul_f32_e32 v160, v183, v215
	v_lshlrev_b32_e32 v163, 16, v86
	v_sub_f32_e32 v181, 1.0, v181
	v_and_b32_e32 v182, 0xffff0000, v84
	v_fmac_f32_e32 v180, v216, v167
	v_mul_f32_e32 v160, v160, v167
	v_sub_f32_e32 v163, 1.0, v163
	v_and_b32_e32 v164, 0xffff0000, v86
	v_lshlrev_b32_e32 v165, 16, v80
	v_fmac_f32_e32 v182, v181, v180
	v_mul_f32_e32 v160, v160, v181
	v_lshlrev_b32_e32 v91, 16, v82
	v_sub_f32_e32 v165, 1.0, v165
	v_and_b32_e32 v166, 0xffff0000, v80
	v_fmac_f32_e32 v164, v182, v163
	v_mul_f32_e32 v160, v160, v163
	v_sub_f32_e32 v91, 1.0, v91
	v_and_b32_e32 v93, 0xffff0000, v82
	v_lshlrev_b32_e32 v128, 16, v76
	v_fmac_f32_e32 v166, v165, v164
	v_mul_f32_e32 v160, v160, v165
	v_lshlrev_b32_e32 v83, 16, v78
	v_sub_f32_e32 v128, 1.0, v128
	v_and_b32_e32 v162, 0xffff0000, v76
	v_pk_mul_f32 v[94:95], v[94:95], s[24:25] op_sel_hi:[1,0]
	v_fmac_f32_e32 v93, v166, v91
	v_mul_f32_e32 v91, v160, v91
	v_sub_f32_e32 v83, 1.0, v83
	v_and_b32_e32 v85, 0xffff0000, v78
	v_lshlrev_b32_e32 v87, 16, v72
	v_exp_f32_e32 v94, v94
	v_exp_f32_e32 v95, v95
	v_fmac_f32_e32 v162, v128, v93
	v_mul_f32_e32 v91, v91, v128
	s_waitcnt lgkmcnt(1)
	v_lshlrev_b32_e32 v158, 16, v65
	v_lshlrev_b32_e32 v65, 16, v74
	v_sub_f32_e32 v87, 1.0, v87
	v_and_b32_e32 v89, 0xffff0000, v72
	v_fmac_f32_e32 v85, v162, v83
	v_mul_f32_e32 v83, v91, v83
	s_waitcnt lgkmcnt(0)
	v_lshlrev_b32_e32 v159, 16, v69
	v_sub_f32_e32 v65, 1.0, v65
	v_and_b32_e32 v69, 0xffff0000, v74
	v_lshlrev_b32_e32 v79, 16, v68
	v_fmac_f32_e32 v89, v87, v85
	v_mul_f32_e32 v83, v83, v87
	v_lshlrev_b32_e32 v71, 16, v70
	v_sub_f32_e32 v79, 1.0, v79
	v_and_b32_e32 v81, 0xffff0000, v68
	v_fmac_f32_e32 v69, v89, v65
	v_mul_f32_e32 v65, v83, v65
	v_sub_f32_e32 v71, 1.0, v71
	v_and_b32_e32 v73, 0xffff0000, v70
	v_lshlrev_b32_e32 v75, 16, v64
	v_pk_add_f32 v[94:95], v[94:95], 1.0 op_sel_hi:[1,0] neg_lo:[1,0] neg_hi:[1,0]
	v_pk_mul_f32 v[66:67], v[66:67], v[158:159]
	v_fmac_f32_e32 v81, v79, v69
	v_mul_f32_e32 v65, v65, v79
	v_sub_f32_e32 v75, 1.0, v75
	v_and_b32_e32 v77, 0xffff0000, v64
	v_cvt_pk_bf16_f32 v94, v94, v66
	v_cvt_pk_bf16_f32 v66, v95, v67
	v_fmac_f32_e32 v73, v81, v71
	v_lshlrev_b32_e32 v67, 16, v94
	v_mul_f32_e32 v65, v65, v71
	v_sub_f32_e32 v67, 1.0, v67
	v_and_b32_e32 v95, 0xffff0000, v94
	v_lshlrev_b32_e32 v158, 16, v66
	v_fmac_f32_e32 v77, v75, v73
	v_mul_f32_e32 v65, v65, v75
	v_sub_f32_e32 v158, 1.0, v158
	v_and_b32_e32 v159, 0xffff0000, v66
	v_fmac_f32_e32 v95, v77, v67
	v_mul_f32_e32 v65, v65, v67
	v_and_or_b32 v67, v174, 64, v185
	v_fmac_f32_e32 v159, v158, v95
	v_mul_f32_e32 v65, v65, v158
	v_lshlrev_b32_e32 v214, 2, v67
	ds_bpermute_b32 v73, v214, v65
	ds_bpermute_b32 v67, v214, v159
	ds_bpermute_b32 v75, v214, v65 offset:64
	ds_bpermute_b32 v69, v214, v159 offset:64
	ds_bpermute_b32 v77, v214, v65 offset:128
	ds_bpermute_b32 v71, v214, v159 offset:128
	ds_bpermute_b32 v79, v214, v65 offset:192
	ds_bpermute_b32 v65, v214, v159 offset:192
	v_lshl_add_u64 v[158:159], s[92:93], 0, v[102:103]
	s_and_saveexec_b64 s[8:9], s[38:39]
	s_cbranch_execz .LBB0_567
	s_waitcnt lgkmcnt(5)
	v_mul_f32_e32 v81, v73, v75
	v_fmac_f32_e32 v67, 0, v73
	s_waitcnt lgkmcnt(3)
	v_mul_f32_e32 v81, v81, v77
	v_fmac_f32_e32 v69, v67, v75
	v_add_co_u32_e32 v160, vcc, 0x11fa2000, v158
	s_waitcnt lgkmcnt(1)
	v_mul_f32_e32 v81, v81, v79
	v_fmac_f32_e32 v71, v69, v77
	v_addc_co_u32_e32 v161, vcc, 0, v159, vcc
	s_waitcnt lgkmcnt(0)
	v_fmac_f32_e32 v65, v71, v79
	global_store_dword v[160:161], v81, off sc1
	global_store_dword v[160:161], v65, off offset:2048 sc1

; __device__ __forceinline__ int lru_pass1(const Params& P, int l, LAS unsigned char* lds, unsigned* qw) {
;     ...
;                         const f32x2 tr = ((f32x2){acc[mt][2 * d][2 * ip], acc[mt][2 * d][2 * ip + 1]} + bgr) * (-1.4426950408889634f);
;                         const f32x2 ti = ((f32x2){acc[mt][2 * d + 1][2 * ip], acc[mt][2 * d + 1][2 * ip + 1]} + bgi) * (-1.4426950408889634f);
;                         const f32x2 dr = (f32x2){__builtin_amdgcn_exp2f(tr.x), __builtin_amdgcn_exp2f(tr.y)} + 1.0f, di = (f32x2){__builtin_amdgcn_exp2f(ti.x), __builtin_amdgcn_exp2f(ti.y)} + 1.0f;
;                         const f32x2 r = (f32x2){__builtin_amdgcn_rcpf(dr.x), __builtin_amdgcn_rcpf(dr.y)}, ig = (f32x2){__builtin_amdgcn_rcpf(di.x), __builtin_amdgcn_rcpf(di.y)};
;                         const f32x2 la = r * (-sp8), x2 = la + la;
;                         f32x2 q5 = x2 * 0.0083333333f + 0.041666668f; q5 = q5 * x2 + 0.16666667f; q5 = q5 * x2 + 0.5f; q5 = q5 * x2 + 1.0f; f32x2 em = -(x2 * q5);
;                         if (__builtin_expect(__any((x2.x < -0.25f) || (x2.y < -0.25f)), 0)) {
;                             if (x2.x < -0.25f) em.x = 1.0f - __expf(x2.x);
;                             if (x2.y < -0.25f) em.y = 1.0f - __expf(x2.y); }
;                         const f32x2 tl = la * 1.4426950408889634f; const f32x2 om = 1.0f - (f32x2){__builtin_amdgcn_exp2f(tl.x), __builtin_amdgcn_exp2f(tl.y)};
;                         const f32x2 bvv = (f32x2){__builtin_amdgcn_sqrtf(em.x), __builtin_amdgcn_sqrtf(em.y)} * ig * xcv;
;                         const unsigned wq0 = cvt_pk_bf16(om.x, bvv.x), wq1 = cvt_pk_bf16(om.y, bvv.y);
;                         acc[mt][2 * d][2 * ip] = 1.0f - __uint_as_float(wq0 << 16); acc[mt][2 * d + 1][2 * ip] = __uint_as_float(wq0 & 0xffff0000u);
;                         acc[mt][2 * d][2 * ip + 1] = 1.0f - __uint_as_float(wq1 << 16); acc[mt][2 * d + 1][2 * ip + 1] = __uint_as_float(wq1 & 0xffff0000u);
;                         abw[mt * 4 + 2 * ip][d] = wq0; abw[mt * 4 + 2 * ip + 1][d] = wq1; }
;                 float Ar = 1.f, Br = 0.f;
; #pragma unroll
;                 for (int s = 0; s < 16; ++s) { const int idx = d == 0 ? s : 15 - s; const float a = acc[idx >> 2][2 * d][idx & 3], bb = acc[idx >> 2][2 * d + 1][idx & 3]; Br = a * Br + bb; Ar *= a; }
;                 float Ac = 1.f, Bc = 0.f;
; #pragma unroll
.LBB0_575:
	v_pk_add_f32 v[34:35], v[34:35], v[160:161]
	v_sqrt_f32_e32 v36, v36
	v_pk_mul_f32 v[34:35], v[34:35], s[18:19] op_sel_hi:[1,0]
	v_sqrt_f32_e32 v37, v37
	v_exp_f32_e32 v34, v34
	v_exp_f32_e32 v35, v35
	v_pk_mul_f32 v[32:33], v[32:33], s[24:25] op_sel_hi:[1,0]
	v_lshlrev_b32_e32 v38, 16, v71
	v_exp_f32_e32 v32, v32
	v_pk_add_f32 v[34:35], v[34:35], 1.0 op_sel_hi:[1,0]
	v_exp_f32_e32 v33, v33
	v_rcp_f32_e32 v34, v34
	v_rcp_f32_e32 v35, v35
	v_sub_f32_e32 v45, 1.0, v38
	v_lshlrev_b32_e32 v38, 16, v65
	v_lshlrev_b32_e32 v67, 16, v85
	v_sub_f32_e32 v47, 1.0, v38
	s_waitcnt lgkmcnt(1)
	v_lshlrev_b32_e32 v38, 16, v40
	s_waitcnt lgkmcnt(0)
	v_lshlrev_b32_e32 v39, 16, v41
	v_sub_f32_e32 v160, 1.0, v67
	v_lshlrev_b32_e32 v67, 16, v93
	v_pk_mul_f32 v[34:35], v[34:35], v[36:37]
	v_sub_f32_e32 v162, 1.0, v67
	v_lshlrev_b32_e32 v67, 16, v89
	v_pk_mul_f32 v[34:35], v[34:35], v[38:39]
	v_sub_f32_e32 v164, 1.0, v67
	v_pk_add_f32 v[32:33], v[32:33], 1.0 op_sel_hi:[1,0] neg_lo:[1,0] neg_hi:[1,0]
	v_and_b32_e32 v48, 0xffff0000, v65
	v_cvt_pk_bf16_f32 v95, v32, v34
	v_cvt_pk_bf16_f32 v67, v33, v35
	v_and_b32_e32 v46, 0xffff0000, v71
	v_lshlrev_b32_e32 v34, 16, v67
	v_lshlrev_b32_e32 v32, 16, v95
	v_sub_f32_e32 v34, 1.0, v34
	v_and_b32_e32 v35, 0xffff0000, v67
	v_sub_f32_e32 v32, 1.0, v32
	v_and_b32_e32 v33, 0xffff0000, v95
	v_fmac_f32_e32 v35, 0, v34
	v_fmac_f32_e32 v33, v32, v35
	v_mul_f32_e32 v32, v32, v34
	v_lshlrev_b32_e32 v49, 16, v69
	v_fmac_f32_e32 v48, v47, v33
	v_mul_f32_e32 v32, v47, v32
	v_lshlrev_b32_e32 v40, 16, v75
	v_sub_f32_e32 v49, 1.0, v49
	v_and_b32_e32 v50, 0xffff0000, v69
	v_fmac_f32_e32 v46, v45, v48
	v_mul_f32_e32 v32, v45, v32
	v_sub_f32_e32 v40, 1.0, v40
	v_and_b32_e32 v41, 0xffff0000, v75
	v_lshlrev_b32_e32 v53, 16, v73
	v_fmac_f32_e32 v50, v49, v46
	v_mul_f32_e32 v32, v49, v32
	v_lshlrev_b32_e32 v51, 16, v79
	v_sub_f32_e32 v53, 1.0, v53
	v_and_b32_e32 v54, 0xffff0000, v73
	v_fmac_f32_e32 v41, v40, v50
	v_mul_f32_e32 v32, v40, v32
	v_sub_f32_e32 v51, 1.0, v51
	v_and_b32_e32 v52, 0xffff0000, v79
	v_lshlrev_b32_e32 v57, 16, v77
	v_fmac_f32_e32 v54, v53, v41
	v_mul_f32_e32 v32, v53, v32
	v_lshlrev_b32_e32 v55, 16, v83
	v_sub_f32_e32 v57, 1.0, v57
	v_and_b32_e32 v58, 0xffff0000, v77
	v_fmac_f32_e32 v52, v51, v54
	v_mul_f32_e32 v32, v51, v32
	v_sub_f32_e32 v55, 1.0, v55
	v_and_b32_e32 v56, 0xffff0000, v83
	v_lshlrev_b32_e32 v61, 16, v81
	v_fmac_f32_e32 v58, v57, v52
	v_mul_f32_e32 v32, v57, v32
	v_lshlrev_b32_e32 v59, 16, v87
	v_sub_f32_e32 v61, 1.0, v61
	v_and_b32_e32 v62, 0xffff0000, v81
	v_fmac_f32_e32 v56, v55, v58
	v_mul_f32_e32 v32, v55, v32
	v_sub_f32_e32 v59, 1.0, v59
	v_and_b32_e32 v60, 0xffff0000, v87
	v_fmac_f32_e32 v62, v61, v56
	v_mul_f32_e32 v32, v61, v32
	v_lshlrev_b32_e32 v63, 16, v91
	v_and_b32_e32 v161, 0xffff0000, v85
	v_fmac_f32_e32 v60, v59, v62
	v_mul_f32_e32 v32, v59, v32
	v_sub_f32_e32 v63, 1.0, v63
	v_and_b32_e32 v128, 0xffff0000, v91
	v_fmac_f32_e32 v161, v160, v60
	v_mul_f32_e32 v32, v160, v32
	v_and_b32_e32 v165, 0xffff0000, v89
	v_fmac_f32_e32 v128, v63, v161
	v_mul_f32_e32 v32, v63, v32
	v_and_b32_e32 v163, 0xffff0000, v93
	v_fmac_f32_e32 v165, v164, v128
	v_mul_f32_e32 v32, v164, v32
	v_or_b32_e32 v42, 64, v214
	v_or_b32_e32 v43, 0x80, v214
	v_or_b32_e32 v44, 0xc0, v214
	v_fmac_f32_e32 v163, v162, v165
	v_mul_f32_e32 v32, v162, v32
	ds_bpermute_b32 v36, v44, v32
	ds_bpermute_b32 v33, v44, v163
	ds_bpermute_b32 v37, v43, v32
	ds_bpermute_b32 v34, v43, v163
	ds_bpermute_b32 v38, v42, v32
	ds_bpermute_b32 v35, v42, v163
	ds_bpermute_b32 v39, v214, v32
	ds_bpermute_b32 v32, v214, v163
	s_and_saveexec_b64 s[8:9], s[38:39]
	s_cbranch_execz .LBB0_556
	s_waitcnt lgkmcnt(6)
	v_fmac_f32_e32 v33, 0, v36
	s_waitcnt lgkmcnt(5)
	v_mul_f32_e32 v40, v36, v37
	s_waitcnt lgkmcnt(4)
	v_fmac_f32_e32 v34, v33, v37
	s_waitcnt lgkmcnt(3)
	v_mul_f32_e32 v40, v40, v38
	s_waitcnt lgkmcnt(2)
	v_fmac_f32_e32 v35, v34, v38
	v_add_co_u32_e32 v34, vcc, 0x11fa3000, v158
	s_waitcnt lgkmcnt(1)
	v_mul_f32_e32 v40, v40, v39
	s_waitcnt lgkmcnt(0)
	v_fmac_f32_e32 v32, v35, v39
	v_addc_co_u32_e32 v35, vcc, 0, v159, vcc
	global_store_dword v[34:35], v40, off sc1
	global_store_dword v[34:35], v32, off offset:2048 sc1
	s_branch .LBB0_556

; #define GAS __attribute__((address_space(1)))
; __device__ __forceinline__ unsigned cvt_pk_bf16(float lo, float hi) { unsigned r; asm volatile("v_cvt_pk_bf16_f32 %0, %1, %2" : "=v"(r) : "v"(lo), "v"(hi)); return r; }
; __device__ __forceinline__ void gmlp_items(const Params& P, int l, int local, unsigned* q) {
;     ...
;             for (int q = 0; q < 4; ++q) { const int p = 16 * (4 * half + q) + fr; const size_t row = (size_t)ch * 128 + p; bsv[q] = P.gmlp_bs[(l * 4 + g) * 128 + p];
; #pragma unroll
;                 for (int kk = 0; kk < 4; ++kk) Bfv[q][kk] = *(const GAS bf16x8*)(GWS + ((size_t)(g * 128 + p)) * 128 + kk * 32 + 8 * fq);
; #pragma unroll
;                 for (int mt = 0; mt < 4; ++mt) uua[q][mt] = *(const GAS u32x2*)(Z + row * ZW + 1024 + g * 64 + mt * 16 + 4 * fq); }
;             __builtin_amdgcn_sched_barrier(0);
; #pragma unroll
;             for (int q = 0; q < 4; ++q) { const int p = 16 * (4 * half + q) + fr; const size_t row = (size_t)ch * 128 + p;
;                 f32x4 acc[4];
; #pragma unroll
;                 for (int mt = 0; mt < 4; ++mt) acc[mt] = (f32x4){0.f, 0.f, 0.f, 0.f};
; #pragma unroll
;                 for (int kk = 0; kk < 4; ++kk)
; #pragma unroll
;                     for (int mt = 0; mt < 4; ++mt) acc[mt] = __builtin_amdgcn_mfma_f32_16x16x32_bf16(Afv[kk][mt], Bfv[q][kk], acc[mt], 0, 0, 0);
; #pragma unroll
;                 for (int mt = 0; mt < 4; ++mt) { const int d0 = mt * 16 + 4 * fq; const u32x2 uu = uua[q][mt];
;                     const float u0 = __uint_as_float(uu.x << 16), u1 = __uint_as_float(uu.x & 0xffff0000u), u2 = __uint_as_float(uu.y << 16), u3 = __uint_as_float(uu.y & 0xffff0000u);
;                     u32x2 o; o.x = cvt_pk_bf16(u0 * (acc[mt][0] + bsv[q]), u1 * (acc[mt][1] + bsv[q])); o.y = cvt_pk_bf16(u2 * (acc[mt][2] + bsv[q]), u3 * (acc[mt][3] + bsv[q]));
;                     *(GAS u32x2*)(Y + row * YW + 512 + g * 64 + d0) = o; } }
.LBB0_638:
	v_or_b32_e32 v68, s0, v140
	v_or_b32_e32 v128, v68, v103
	v_lshl_add_u64 v[64:65], v[128:129], 2, s[82:83]
	v_lshl_or_b32 v128, v68, 7, v144
	global_load_dword v145, v[64:65], off
	v_lshl_add_u64 v[64:65], v[128:129], 1, v[96:97]
	v_or_b32_e32 v200, v104, v68
	global_load_dwordx4 v[146:149], v[64:65], off
	global_load_dwordx4 v[150:153], v[64:65], off offset:64
	global_load_dwordx4 v[154:157], v[64:65], off offset:128
	global_load_dwordx4 v[158:161], v[64:65], off offset:192
	v_mad_u64_u32 v[64:65], s[0:1], v200, s23, v[106:107]
	v_mad_i32_i24 v65, v105, s23, v65
	v_or_b32_e32 v69, 16, v68
	v_add_u32_e32 v128, v68, v103
	global_load_dwordx2 v[166:167], v[64:65], off offset:2048
	global_load_dwordx2 v[180:181], v[64:65], off offset:2080
	global_load_dwordx2 v[182:183], v[64:65], off offset:2112
	global_load_dwordx2 v[204:205], v[64:65], off offset:2144
	v_lshl_add_u64 v[64:65], v[128:129], 2, s[82:83]
	v_lshl_or_b32 v128, v69, 7, v144
	v_lshl_add_u64 v[66:67], v[128:129], 1, v[96:97]
	v_or_b32_e32 v212, v104, v69
	global_load_dwordx4 v[162:165], v[66:67], off
	global_load_dwordx4 v[184:187], v[66:67], off offset:64
	global_load_dwordx4 v[188:191], v[66:67], off offset:128
	global_load_dwordx4 v[192:195], v[66:67], off offset:192
	v_mad_u64_u32 v[66:67], s[0:1], v212, s23, v[106:107]
	v_or_b32_e32 v69, 32, v68
	v_mad_i32_i24 v67, v105, s23, v67
	v_lshl_or_b32 v128, v69, 7, v144
	global_load_dwordx2 v[206:207], v[66:67], off offset:2048
	global_load_dwordx2 v[208:209], v[66:67], off offset:2080
	global_load_dwordx2 v[138:139], v[66:67], off offset:2112
	global_load_dwordx2 v[126:127], v[66:67], off offset:2144
	v_lshl_add_u64 v[66:67], v[128:129], 1, v[96:97]
	v_or_b32_e32 v213, v104, v69
	global_load_dwordx4 v[92:95], v[66:67], off
	global_load_dwordx4 v[88:91], v[66:67], off offset:64
	global_load_dwordx4 v[84:87], v[66:67], off offset:128
	global_load_dwordx4 v[80:83], v[66:67], off offset:192
	v_mad_u64_u32 v[66:67], s[0:1], v213, s23, v[106:107]
	v_or_b32_e32 v110, 48, v68
	v_mad_i32_i24 v67, v105, s23, v67
	v_lshl_or_b32 v128, v110, 7, v144
	global_load_dwordx2 v[124:125], v[66:67], off offset:2048
	global_load_dwordx2 v[122:123], v[66:67], off offset:2080
	global_load_dwordx2 v[120:121], v[66:67], off offset:2112
	global_load_dwordx2 v[118:119], v[66:67], off offset:2144
	global_load_dword v214, v[64:65], off offset:64
	global_load_dword v215, v[64:65], off offset:128
	global_load_dword v216, v[64:65], off offset:192
	v_lshl_add_u64 v[64:65], v[128:129], 1, v[96:97]
	v_or_b32_e32 v128, v104, v110
	v_mad_u64_u32 v[110:111], s[0:1], v128, s23, v[106:107]
	v_mad_i32_i24 v111, v105, s23, v111
	global_load_dwordx4 v[76:79], v[64:65], off
	global_load_dwordx4 v[72:75], v[64:65], off offset:64
	global_load_dwordx4 v[68:71], v[64:65], off offset:128
	s_nop 0
	global_load_dwordx4 v[64:67], v[64:65], off offset:192
	s_nop 0
	global_load_dwordx2 v[116:117], v[110:111], off offset:2048
	global_load_dwordx2 v[114:115], v[110:111], off offset:2080
	global_load_dwordx2 v[112:113], v[110:111], off offset:2112
	s_nop 0
	global_load_dwordx2 v[110:111], v[110:111], off offset:2144
	s_waitcnt vmcnt(34)
	v_mfma_f32_16x16x32_bf16 v[196:199], v[0:3], v[146:149], 0
	s_waitcnt vmcnt(30)
	v_lshlrev_b32_e32 v201, 16, v166
	v_and_b32_e32 v166, 0xffff0000, v166
	v_lshlrev_b32_e32 v202, 16, v167
	v_mfma_f32_16x16x32_bf16 v[196:199], v[4:7], v[150:153], v[196:199]
	v_and_b32_e32 v167, 0xffff0000, v167
	v_mad_u64_u32 v[210:211], s[0:1], v200, s23, v[108:109]
	v_mfma_f32_16x16x32_bf16 v[196:199], v[32:35], v[154:157], v[196:199]
	v_mad_i32_i24 v211, v105, s23, v211
	s_andn2_b64 vcc, exec, s[40:41]
	s_mov_b64 s[40:41], 0
	v_mfma_f32_16x16x32_bf16 v[196:199], v[36:39], v[158:161], v[196:199]
	s_nop 7
	v_add_f32_e32 v196, v145, v196
	v_add_f32_e32 v197, v145, v197
	v_add_f32_e32 v198, v145, v198
	v_add_f32_e32 v199, v145, v199
	v_mul_f32_e32 v196, v196, v201
	v_mul_f32_e32 v166, v197, v166
	v_mul_f32_e32 v201, v198, v202
	v_mul_f32_e32 v167, v199, v167
	v_cvt_pk_bf16_f32 v166, v196, v166
	v_mfma_f32_16x16x32_bf16 v[196:199], v[8:11], v[146:149], 0
	v_cvt_pk_bf16_f32 v167, v201, v167
	global_store_dwordx2 v[210:211], v[166:167], off offset:1024 sc1
	s_waitcnt vmcnt(30)
	v_lshlrev_b32_e32 v166, 16, v180
	v_mfma_f32_16x16x32_bf16 v[196:199], v[12:15], v[150:153], v[196:199]
	v_and_b32_e32 v167, 0xffff0000, v180
	v_lshlrev_b32_e32 v180, 16, v181
	v_and_b32_e32 v181, 0xffff0000, v181
	v_mfma_f32_16x16x32_bf16 v[196:199], v[40:43], v[154:157], v[196:199]
	v_mfma_f32_16x16x32_bf16 v[196:199], v[44:47], v[158:161], v[196:199]
	v_mfma_f32_16x16x32_bf16 v[200:203], v[16:19], v[146:149], 0
	v_mfma_f32_16x16x32_bf16 v[200:203], v[20:23], v[150:153], v[200:203]
	s_nop 5
	v_add_f32_e32 v196, v145, v196
	v_mul_f32_e32 v166, v196, v166
	v_add_f32_e32 v196, v145, v197
	v_mul_f32_e32 v167, v196, v167
	v_cvt_pk_bf16_f32 v166, v166, v167
	v_add_f32_e32 v167, v145, v198
	v_mfma_f32_16x16x32_bf16 v[146:149], v[24:27], v[146:149], 0
	v_mul_f32_e32 v167, v167, v180
	v_add_f32_e32 v180, v145, v199
	v_mul_f32_e32 v180, v180, v181
	v_mfma_f32_16x16x32_bf16 v[196:199], v[48:51], v[154:157], v[200:203]
	v_cvt_pk_bf16_f32 v167, v167, v180
	global_store_dwordx2 v[210:211], v[166:167], off offset:1056 sc1
	s_waitcnt vmcnt(30)
; #define GAS __attribute__((address_space(1)))
; __device__ __forceinline__ unsigned cvt_pk_bf16(float lo, float hi) { unsigned r; asm volatile("v_cvt_pk_bf16_f32 %0, %1, %2" : "=v"(r) : "v"(lo), "v"(hi)); return r; }
; __device__ __forceinline__ void gmlp_items(const Params& P, int l, int local, unsigned* q) {
;     ...
;             for (int q = 0; q < 4; ++q) { const int p = 16 * (4 * half + q) + fr; const size_t row = (size_t)ch * 128 + p;
;                 f32x4 acc[4];
; #pragma unroll
;                 for (int mt = 0; mt < 4; ++mt) acc[mt] = (f32x4){0.f, 0.f, 0.f, 0.f};
; #pragma unroll
;                 for (int kk = 0; kk < 4; ++kk)
; #pragma unroll
;                     for (int mt = 0; mt < 4; ++mt) acc[mt] = __builtin_amdgcn_mfma_f32_16x16x32_bf16(Afv[kk][mt], Bfv[q][kk], acc[mt], 0, 0, 0);
; #pragma unroll
;                 for (int mt = 0; mt < 4; ++mt) { const int d0 = mt * 16 + 4 * fq; const u32x2 uu = uua[q][mt];
;                     const float u0 = __uint_as_float(uu.x << 16), u1 = __uint_as_float(uu.x & 0xffff0000u), u2 = __uint_as_float(uu.y << 16), u3 = __uint_as_float(uu.y & 0xffff0000u);
;                     u32x2 o; o.x = cvt_pk_bf16(u0 * (acc[mt][0] + bsv[q]), u1 * (acc[mt][1] + bsv[q])); o.y = cvt_pk_bf16(u2 * (acc[mt][2] + bsv[q]), u3 * (acc[mt][3] + bsv[q]));
;                     *(GAS u32x2*)(Y + row * YW + 512 + g * 64 + d0) = o; } }
	v_lshlrev_b32_e32 v166, 16, v182
	v_mfma_f32_16x16x32_bf16 v[146:149], v[28:31], v[150:153], v[146:149]
	v_and_b32_e32 v167, 0xffff0000, v182
	v_lshlrev_b32_e32 v180, 16, v183
	v_and_b32_e32 v181, 0xffff0000, v183
	v_mfma_f32_16x16x32_bf16 v[196:199], v[52:55], v[158:161], v[196:199]
	v_mfma_f32_16x16x32_bf16 v[146:149], v[56:59], v[154:157], v[146:149]
	v_mfma_f32_16x16x32_bf16 v[146:149], v[60:63], v[158:161], v[146:149]
	s_nop 5
	v_add_f32_e32 v182, v145, v196
	v_add_f32_e32 v151, v145, v198
	v_mul_f32_e32 v166, v182, v166
	v_add_f32_e32 v182, v145, v197
	v_mul_f32_e32 v151, v151, v180
	v_add_f32_e32 v152, v145, v199
	v_mul_f32_e32 v167, v182, v167
	v_cvt_pk_bf16_f32 v150, v166, v167
	v_mul_f32_e32 v152, v152, v181
	v_cvt_pk_bf16_f32 v151, v151, v152
	global_store_dwordx2 v[210:211], v[150:151], off offset:1088 sc1
	s_waitcnt vmcnt(29)
	v_mfma_f32_16x16x32_bf16 v[150:153], v[0:3], v[162:165], 0
	v_lshlrev_b32_e32 v158, 16, v204
	v_add_f32_e32 v146, v145, v146
	v_and_b32_e32 v159, 0xffff0000, v204
	s_waitcnt vmcnt(28)
	v_mfma_f32_16x16x32_bf16 v[150:153], v[4:7], v[184:187], v[150:153]
	v_mul_f32_e32 v146, v146, v158
	v_add_f32_e32 v147, v145, v147
	v_lshlrev_b32_e32 v167, 16, v205
	v_mul_f32_e32 v147, v147, v159
	v_cvt_pk_bf16_f32 v166, v146, v147
	v_add_f32_e32 v146, v145, v148
	v_and_b32_e32 v180, 0xffff0000, v205
	v_mul_f32_e32 v146, v146, v167
	v_add_f32_e32 v145, v145, v149
	v_mul_f32_e32 v145, v145, v180
	v_cvt_pk_bf16_f32 v167, v146, v145
	s_waitcnt vmcnt(27)
	v_mfma_f32_16x16x32_bf16 v[146:149], v[32:35], v[188:191], v[150:153]
	s_waitcnt vmcnt(25)
	v_lshlrev_b32_e32 v145, 16, v206
	global_store_dwordx2 v[210:211], v[166:167], off offset:1120 sc1
	v_and_b32_e32 v166, 0xffff0000, v206
	v_mfma_f32_16x16x32_bf16 v[146:149], v[36:39], v[192:195], v[146:149]
	v_and_b32_e32 v180, 0xffff0000, v207
	v_lshlrev_b32_e32 v167, 16, v207
	v_mfma_f32_16x16x32_bf16 v[154:157], v[8:11], v[162:165], 0
	v_mfma_f32_16x16x32_bf16 v[150:153], v[24:27], v[162:165], 0
	s_waitcnt vmcnt(14)
	s_nop 2
	v_add_f32_e32 v146, v214, v146
	v_mul_f32_e32 v145, v146, v145
	v_add_f32_e32 v146, v214, v147
	v_mfma_f32_16x16x32_bf16 v[154:157], v[12:15], v[184:187], v[154:157]
	v_mul_f32_e32 v146, v146, v166
	v_mfma_f32_16x16x32_bf16 v[158:161], v[16:19], v[162:165], 0
	v_cvt_pk_bf16_f32 v162, v145, v146
	v_add_f32_e32 v146, v214, v149
	v_add_f32_e32 v145, v214, v148
	v_mul_f32_e32 v146, v146, v180
	v_mul_f32_e32 v145, v145, v167
	v_cvt_pk_bf16_f32 v163, v145, v146
	v_mfma_f32_16x16x32_bf16 v[146:149], v[28:31], v[184:187], v[150:153]
	v_mad_u64_u32 v[166:167], s[0:1], v212, s23, v[108:109]
	v_mad_i32_i24 v167, v105, s23, v167
	v_mfma_f32_16x16x32_bf16 v[150:153], v[40:43], v[188:191], v[154:157]
	v_lshlrev_b32_e32 v145, 16, v208
	global_store_dwordx2 v[166:167], v[162:163], off offset:1024 sc1
	v_and_b32_e32 v162, 0xffff0000, v208
	v_mfma_f32_16x16x32_bf16 v[158:161], v[20:23], v[184:187], v[158:161]
	v_and_b32_e32 v164, 0xffff0000, v209
	v_lshlrev_b32_e32 v163, 16, v209
	v_lshlrev_b32_e32 v180, 16, v139
	v_mfma_f32_16x16x32_bf16 v[150:153], v[44:47], v[192:195], v[150:153]
	v_and_b32_e32 v139, 0xffff0000, v139
	v_mfma_f32_16x16x32_bf16 v[154:157], v[48:51], v[188:191], v[158:161]
	v_mfma_f32_16x16x32_bf16 v[154:157], v[52:55], v[192:195], v[154:157]
	s_nop 4
	v_add_f32_e32 v150, v214, v150
	v_mul_f32_e32 v145, v150, v145
	v_add_f32_e32 v150, v214, v151
	v_mul_f32_e32 v150, v150, v162
	v_mfma_f32_16x16x32_bf16 v[146:149], v[56:59], v[188:191], v[146:149]
	v_add_f32_e32 v151, v214, v153
	v_cvt_pk_bf16_f32 v150, v145, v150
	v_add_f32_e32 v145, v214, v152
	v_mul_f32_e32 v151, v151, v164
	v_mul_f32_e32 v145, v145, v163
	v_cvt_pk_bf16_f32 v151, v145, v151
	global_store_dwordx2 v[166:167], v[150:151], off offset:1056 sc1
	v_lshlrev_b32_e32 v145, 16, v138
	v_mfma_f32_16x16x32_bf16 v[150:153], v[0:3], v[92:95], 0
	v_add_f32_e32 v154, v214, v154
	v_and_b32_e32 v138, 0xffff0000, v138
	v_mul_f32_e32 v145, v154, v145
	v_mfma_f32_16x16x32_bf16 v[146:149], v[60:63], v[192:195], v[146:149]
	v_add_f32_e32 v154, v214, v155
	v_mul_f32_e32 v138, v154, v138
	v_cvt_pk_bf16_f32 v138, v145, v138
	v_mfma_f32_16x16x32_bf16 v[158:161], v[8:11], v[92:95], 0
	v_add_f32_e32 v145, v214, v156
	v_add_f32_e32 v154, v214, v157
	v_mul_f32_e32 v145, v145, v180
	v_mfma_f32_16x16x32_bf16 v[162:165], v[16:19], v[92:95], 0
	v_mul_f32_e32 v139, v154, v139
	v_cvt_pk_bf16_f32 v139, v145, v139
	global_store_dwordx2 v[166:167], v[138:139], off offset:1088 sc1
	v_mfma_f32_16x16x32_bf16 v[92:95], v[24:27], v[92:95], 0
	v_lshlrev_b32_e32 v138, 16, v126
	v_add_f32_e32 v145, v214, v146
	v_and_b32_e32 v126, 0xffff0000, v126
	v_mfma_f32_16x16x32_bf16 v[150:153], v[4:7], v[88:91], v[150:153]
	v_mul_f32_e32 v138, v145, v138
	v_add_f32_e32 v145, v214, v147
	v_lshlrev_b32_e32 v139, 16, v127
	v_mfma_f32_16x16x32_bf16 v[154:157], v[12:15], v[88:91], v[158:161]
	v_mul_f32_e32 v126, v145, v126
	v_cvt_pk_bf16_f32 v126, v138, v126
	v_and_b32_e32 v127, 0xffff0000, v127
	v_mfma_f32_16x16x32_bf16 v[158:161], v[20:23], v[88:91], v[162:165]
	v_lshlrev_b32_e32 v145, 16, v125
	v_mfma_f32_16x16x32_bf16 v[88:91], v[28:31], v[88:91], v[92:95]
	s_nop 2
	v_add_f32_e32 v92, v214, v148
	v_mul_f32_e32 v138, v92, v139
	v_mfma_f32_16x16x32_bf16 v[92:95], v[32:35], v[84:87], v[150:153]
	v_add_f32_e32 v139, v214, v149
	v_mul_f32_e32 v127, v139, v127
	v_cvt_pk_bf16_f32 v127, v138, v127
	v_mfma_f32_16x16x32_bf16 v[92:95], v[36:39], v[80:83], v[92:95]
	global_store_dwordx2 v[166:167], v[126:127], off offset:1120 sc1
	v_lshlrev_b32_e32 v138, 16, v124
	v_and_b32_e32 v139, 0xffff0000, v124
	v_mfma_f32_16x16x32_bf16 v[146:149], v[40:43], v[84:87], v[154:157]
	v_and_b32_e32 v150, 0xffff0000, v125
	s_waitcnt vmcnt(17)
; #define GAS __attribute__((address_space(1)))
; __device__ __forceinline__ unsigned cvt_pk_bf16(float lo, float hi) { unsigned r; asm volatile("v_cvt_pk_bf16_f32 %0, %1, %2" : "=v"(r) : "v"(lo), "v"(hi)); return r; }
; __device__ __forceinline__ int queue_pull(unsigned* q, int lane) { unsigned nx = 0; if (lane == 0) nx = __hip_atomic_fetch_add(q, 1u, __ATOMIC_RELAXED, __HIP_MEMORY_SCOPE_AGENT); return 256 + (int)__builtin_amdgcn_readfirstlane(nx); }
; __device__ __forceinline__ void gmlp_items(const Params& P, int l, int local, unsigned* q) {
;     int tid = threadIdx.x; asm volatile("" : "+v"(tid)); const int lane = tid & 63, wslot = tid >> 6, fr = lane & 15, fq = lane >> 4;
;     const GAS bf16_t* GWS = (const GAS bf16_t*)(P.ws + OFF_GWS + l * SZ_GWS1); const GAS bf16_t* Z = (const GAS bf16_t*)(P.ws + OFF_Z); GAS bf16_t* Y = (GAS bf16_t*)(P.ws + OFF_Y);
;     const int xq = blockIdx.x & 7;
;     for (; local < 680; local = queue_pull(q, lane)) { const int it = xq * 136 + (local - 544); const int ch = it >> 2, g = it & 3; const GAS bf16_t* VTb; int ldv;
;     ...
;             for (int q = 0; q < 4; ++q) { const int p = 16 * (4 * half + q) + fr; const size_t row = (size_t)ch * 128 + p;
;                 f32x4 acc[4];
; #pragma unroll
;                 for (int mt = 0; mt < 4; ++mt) acc[mt] = (f32x4){0.f, 0.f, 0.f, 0.f};
; #pragma unroll
;                 for (int kk = 0; kk < 4; ++kk)
; #pragma unroll
;                     for (int mt = 0; mt < 4; ++mt) acc[mt] = __builtin_amdgcn_mfma_f32_16x16x32_bf16(Afv[kk][mt], Bfv[q][kk], acc[mt], 0, 0, 0);
; #pragma unroll
;                 for (int mt = 0; mt < 4; ++mt) { const int d0 = mt * 16 + 4 * fq; const u32x2 uu = uua[q][mt];
;                     const float u0 = __uint_as_float(uu.x << 16), u1 = __uint_as_float(uu.x & 0xffff0000u), u2 = __uint_as_float(uu.y << 16), u3 = __uint_as_float(uu.y & 0xffff0000u);
;                     u32x2 o; o.x = cvt_pk_bf16(u0 * (acc[mt][0] + bsv[q]), u1 * (acc[mt][1] + bsv[q])); o.y = cvt_pk_bf16(u2 * (acc[mt][2] + bsv[q]), u3 * (acc[mt][3] + bsv[q]));
;                     *(GAS u32x2*)(Y + row * YW + 512 + g * 64 + d0) = o; } }
	s_nop 1
	v_add_f32_e32 v92, v215, v92
	v_add_f32_e32 v93, v215, v93
	v_mfma_f32_16x16x32_bf16 v[124:127], v[48:51], v[84:87], v[158:161]
	v_mul_f32_e32 v92, v92, v138
	v_mul_f32_e32 v93, v93, v139
	v_cvt_pk_bf16_f32 v138, v92, v93
	v_mfma_f32_16x16x32_bf16 v[84:87], v[56:59], v[84:87], v[88:91]
	v_add_f32_e32 v93, v215, v95
	v_mul_f32_e32 v93, v93, v150
	v_and_b32_e32 v150, 0xffff0000, v123
	v_add_f32_e32 v88, v215, v94
	v_mul_f32_e32 v92, v88, v145
	v_mfma_f32_16x16x32_bf16 v[88:91], v[44:47], v[80:83], v[146:149]
	v_cvt_pk_bf16_f32 v139, v92, v93
	v_lshlrev_b32_e32 v145, 16, v123
	v_mfma_f32_16x16x32_bf16 v[92:95], v[52:55], v[80:83], v[124:127]
	s_nop 2
	v_mad_u64_u32 v[126:127], s[0:1], v213, s23, v[108:109]
	v_mfma_f32_16x16x32_bf16 v[80:83], v[60:63], v[80:83], v[84:87]
	v_mad_i32_i24 v127, v105, s23, v127
	global_store_dwordx2 v[126:127], v[138:139], off offset:1024 sc1
	v_lshlrev_b32_e32 v138, 16, v122
	s_waitcnt vmcnt(16)
	v_mfma_f32_16x16x32_bf16 v[84:87], v[0:3], v[76:79], 0
	v_and_b32_e32 v139, 0xffff0000, v122
	v_add_f32_e32 v88, v215, v88
	v_add_f32_e32 v89, v215, v89
	v_mfma_f32_16x16x32_bf16 v[122:125], v[8:11], v[76:79], 0
	v_mul_f32_e32 v88, v88, v138
	v_mul_f32_e32 v89, v89, v139
	v_cvt_pk_bf16_f32 v88, v88, v89
	v_mfma_f32_16x16x32_bf16 v[146:149], v[16:19], v[76:79], 0
	v_add_f32_e32 v89, v215, v90
	v_mul_f32_e32 v89, v89, v145
	v_add_f32_e32 v90, v215, v91
	v_mfma_f32_16x16x32_bf16 v[76:79], v[24:27], v[76:79], 0
	v_mul_f32_e32 v90, v90, v150
	v_cvt_pk_bf16_f32 v89, v89, v90
	v_lshlrev_b32_e32 v138, 16, v120
	s_waitcnt vmcnt(15)
	v_mfma_f32_16x16x32_bf16 v[84:87], v[4:7], v[72:75], v[84:87]
	v_and_b32_e32 v139, 0xffff0000, v120
	v_add_f32_e32 v92, v215, v92
	v_add_f32_e32 v93, v215, v93
	global_store_dwordx2 v[126:127], v[88:89], off offset:1056 sc1
	v_mfma_f32_16x16x32_bf16 v[88:91], v[12:15], v[72:75], v[122:125]
	v_mul_f32_e32 v92, v92, v138
	v_mul_f32_e32 v93, v93, v139
	v_cvt_pk_bf16_f32 v92, v92, v93
	v_add_f32_e32 v80, v215, v80
	v_lshlrev_b32_e32 v124, 16, v121
	v_and_b32_e32 v125, 0xffff0000, v121
	v_mfma_f32_16x16x32_bf16 v[120:123], v[20:23], v[72:75], v[146:149]
	v_mfma_f32_16x16x32_bf16 v[72:75], v[28:31], v[72:75], v[76:79]
	s_nop 2
	v_add_f32_e32 v76, v215, v94
	v_mul_f32_e32 v93, v76, v124
	s_waitcnt vmcnt(15)
	v_mfma_f32_16x16x32_bf16 v[76:79], v[32:35], v[68:71], v[84:87]
	v_lshlrev_b32_e32 v94, 16, v119
	s_nop 1
	v_add_f32_e32 v84, v215, v95
	v_mul_f32_e32 v84, v84, v125
	v_cvt_pk_bf16_f32 v93, v93, v84
	v_mfma_f32_16x16x32_bf16 v[84:87], v[40:43], v[68:71], v[88:91]
	global_store_dwordx2 v[126:127], v[92:93], off offset:1088 sc1
	v_and_b32_e32 v93, 0xffff0000, v118
	v_lshlrev_b32_e32 v92, 16, v118
	v_mfma_f32_16x16x32_bf16 v[88:91], v[48:51], v[68:71], v[120:123]
	v_and_b32_e32 v95, 0xffff0000, v119
	v_mul_f32_e32 v80, v80, v92
	v_mfma_f32_16x16x32_bf16 v[68:71], v[56:59], v[68:71], v[72:75]
	s_nop 2
	v_add_f32_e32 v72, v215, v81
	v_mul_f32_e32 v81, v72, v93
	s_waitcnt vmcnt(15)
	v_mfma_f32_16x16x32_bf16 v[72:75], v[36:39], v[64:67], v[76:79]
	v_cvt_pk_bf16_f32 v92, v80, v81
	v_add_f32_e32 v81, v215, v83
	v_mul_f32_e32 v81, v81, v95
	s_nop 0
	v_add_f32_e32 v76, v215, v82
	v_mul_f32_e32 v80, v76, v94
	v_mfma_f32_16x16x32_bf16 v[76:79], v[44:47], v[64:67], v[84:87]
	v_cvt_pk_bf16_f32 v93, v80, v81
	global_store_dwordx2 v[126:127], v[92:93], off offset:1120 sc1
	v_mfma_f32_16x16x32_bf16 v[80:83], v[52:55], v[64:67], v[88:91]
	s_waitcnt vmcnt(15)
	v_lshlrev_b32_e32 v84, 16, v116
	v_and_b32_e32 v85, 0xffff0000, v116
	v_mfma_f32_16x16x32_bf16 v[64:67], v[60:63], v[64:67], v[68:71]
	s_nop 2
	v_add_f32_e32 v68, v216, v72
	v_add_f32_e32 v71, v216, v73
	v_mul_f32_e32 v68, v68, v84
	v_mul_f32_e32 v71, v71, v85
	v_lshlrev_b32_e32 v69, 16, v117
	v_cvt_pk_bf16_f32 v68, v68, v71
	v_add_f32_e32 v71, v216, v74
	v_and_b32_e32 v70, 0xffff0000, v117
	v_mul_f32_e32 v69, v71, v69
	v_add_f32_e32 v71, v216, v75
	v_mul_f32_e32 v70, v71, v70
	v_cvt_pk_bf16_f32 v69, v69, v70
	v_mad_u64_u32 v[70:71], s[0:1], v128, s23, v[108:109]
	v_mad_i32_i24 v71, v105, s23, v71
	global_store_dwordx2 v[70:71], v[68:69], off offset:1024 sc1
	s_waitcnt vmcnt(15)
	v_lshlrev_b32_e32 v68, 16, v114
	v_add_f32_e32 v74, v216, v76
	v_and_b32_e32 v69, 0xffff0000, v114
	v_mul_f32_e32 v68, v74, v68
	v_add_f32_e32 v74, v216, v77
	v_mul_f32_e32 v69, v74, v69
	v_lshlrev_b32_e32 v72, 16, v115
	v_cvt_pk_bf16_f32 v68, v68, v69
	v_add_f32_e32 v69, v216, v78
	v_and_b32_e32 v73, 0xffff0000, v115
	v_mul_f32_e32 v69, v69, v72
	v_add_f32_e32 v72, v216, v79
	v_mul_f32_e32 v72, v72, v73
	v_cvt_pk_bf16_f32 v69, v69, v72
	global_store_dwordx2 v[70:71], v[68:69], off offset:1056 sc1
	s_waitcnt vmcnt(15)
	v_lshlrev_b32_e32 v68, 16, v112
	v_add_f32_e32 v74, v216, v80
	v_and_b32_e32 v69, 0xffff0000, v112
	v_mul_f32_e32 v68, v74, v68
	v_add_f32_e32 v74, v216, v81
	v_mul_f32_e32 v69, v74, v69
	v_lshlrev_b32_e32 v72, 16, v113
	v_cvt_pk_bf16_f32 v68, v68, v69
	v_add_f32_e32 v69, v216, v82
	v_and_b32_e32 v73, 0xffff0000, v113
	v_mul_f32_e32 v69, v69, v72
	v_add_f32_e32 v72, v216, v83
	v_mul_f32_e32 v72, v72, v73
	v_cvt_pk_bf16_f32 v69, v69, v72
	global_store_dwordx2 v[70:71], v[68:69], off offset:1088 sc1
	s_waitcnt vmcnt(15)
	v_lshlrev_b32_e32 v68, 16, v110
	v_and_b32_e32 v69, 0xffff0000, v110
	v_add_f32_e32 v64, v216, v64
	v_add_f32_e32 v65, v216, v65
	v_mul_f32_e32 v64, v64, v68
	v_mul_f32_e32 v65, v65, v69
	v_lshlrev_b32_e32 v72, 16, v111
	v_cvt_pk_bf16_f32 v64, v64, v65
	v_add_f32_e32 v65, v216, v66
	v_and_b32_e32 v73, 0xffff0000, v111
	v_mul_f32_e32 v65, v65, v72
	v_add_f32_e32 v66, v216, v67
	s_mov_b32 s0, 64
	v_mul_f32_e32 v66, v66, v73
	v_cvt_pk_bf16_f32 v65, v65, v66
	global_store_dwordx2 v[70:71], v[64:65], off offset:1120 sc1
	s_cbranch_vccz .LBB0_638
	v_mov_b32_e32 v0, 0
	s_and_saveexec_b64 s[40:41], s[38:39]
	s_cbranch_execz .LBB0_632
	s_mov_b64 s[44:45], exec
	v_mbcnt_lo_u32_b32 v0, s44, 0
	v_mbcnt_hi_u32_b32 v0, s45, v0
	v_cmp_eq_u32_e32 vcc, 0, v0
	s_and_saveexec_b64 s[42:43], vcc
	s_cbranch_execz .LBB0_631
	s_bcnt1_i32_b64 s0, s[44:45]
	v_mov_b32_e32 v1, s0
	v_readlane_b32 s0, v254, 50
	v_readlane_b32 s1, v254, 51
	s_nop 4
	global_atomic_add v1, v129, v1, s[0:1] sc0
	s_branch .LBB0_631

; #define GAS __attribute__((address_space(1)))
; __device__ __forceinline__ void lru_scan(const Params& P, int l) {
;     ...
;         const GAS u32x2* abp = (const GAS u32x2*)(AB + ((size_t)r0 * 512 + c) * 2);
;         u32x2 w[64];
; #pragma unroll
;         for (int p = 0; p < 64; ++p) w[p] = abp[(size_t)p * 512];
;         float hf[64]; { float hh = hin[0];
; #pragma unroll
;             for (int p = 0; p < 64; ++p) { const float om = __uint_as_float(w[p].x << 16), bb = __uint_as_float(w[p].x & 0xffff0000u); hh = (hh - om * hh) + bb; hf[p] = hh; } }
.LBB0_702:
	v_readlane_b32 s1, v255, 36
	s_lshl_b32 s0, s19, 6
	s_add_i32 s38, s0, s1
	s_ashr_i32 s39, s38, 31
	s_lshl_b64 s[0:1], s[38:39], 12
	v_lshl_add_u64 v[138:139], v[2:3], 0, s[0:1]
	v_add_co_u32_e32 v10, vcc, 0x1000, v138
	s_mov_b32 s2, 0x9000
	s_nop 0
	v_addc_co_u32_e32 v11, vcc, 0, v139, vcc
	v_add_co_u32_e32 v12, vcc, 0x2000, v138
	s_mov_b32 s0, 0x21000
	s_nop 0
	v_addc_co_u32_e32 v13, vcc, 0, v139, vcc
	v_add_co_u32_e32 v14, vcc, 0x3000, v138
	s_add_i32 s72, s38, 63
	s_nop 0
	v_addc_co_u32_e32 v15, vcc, 0, v139, vcc
	global_load_dwordx2 v[8:9], v[138:139], off
	s_nop 0
	global_load_dwordx2 v[10:11], v[10:11], off
	s_nop 0
	global_load_dwordx2 v[12:13], v[12:13], off
	s_nop 0
	global_load_dwordx2 v[14:15], v[14:15], off
	v_add_co_u32_e32 v16, vcc, 0x4000, v138
	s_add_i32 s76, s38, 62
	s_nop 0
	v_addc_co_u32_e32 v17, vcc, 0, v139, vcc
	v_add_co_u32_e32 v18, vcc, 0x5000, v138
	s_add_i32 s75, s38, 61
	s_nop 0
	v_addc_co_u32_e32 v19, vcc, 0, v139, vcc
	v_add_co_u32_e32 v20, vcc, 0x6000, v138
	s_add_i32 s73, s38, 59
	s_nop 0
	v_addc_co_u32_e32 v21, vcc, 0, v139, vcc
	v_add_co_u32_e32 v22, vcc, 0x7000, v138
	s_add_i32 s74, s38, 60
	s_nop 0
	v_addc_co_u32_e32 v23, vcc, 0, v139, vcc
	global_load_dwordx2 v[16:17], v[16:17], off
	s_nop 0
	global_load_dwordx2 v[18:19], v[18:19], off
	s_nop 0
	global_load_dwordx2 v[20:21], v[20:21], off
	s_nop 0
	global_load_dwordx2 v[22:23], v[22:23], off
	v_add_co_u32_e32 v26, vcc, s2, v138
	v_mad_i64_i32 v[214:215], s[28:29], s73, v178, v[6:7]
	s_nop 0
	v_addc_co_u32_e32 v27, vcc, 0, v139, vcc
	v_add_co_u32_e32 v30, vcc, s4, v138
	s_add_i32 s70, s38, 57
	s_nop 0
	v_addc_co_u32_e32 v31, vcc, 0, v139, vcc
	global_load_dwordx2 v[24:25], v[26:27], off offset:-4096
	s_nop 0
	global_load_dwordx2 v[26:27], v[26:27], off
	s_nop 0
	global_load_dwordx2 v[28:29], v[30:31], off offset:-4096
	s_nop 0
	global_load_dwordx2 v[30:31], v[30:31], off
	s_waitcnt vmcnt(0)
	v_add_co_u32_e32 v34, vcc, s5, v138
	s_add_i32 s71, s38, 58
	s_nop 0
	v_addc_co_u32_e32 v35, vcc, 0, v139, vcc
	v_add_co_u32_e32 v38, vcc, s8, v138
	v_mad_i64_i32 v[212:213], s[28:29], s70, v178, v[6:7]
	s_nop 0
	v_addc_co_u32_e32 v39, vcc, 0, v139, vcc
	global_load_dwordx2 v[32:33], v[34:35], off offset:-4096
	s_nop 0
	global_load_dwordx2 v[34:35], v[34:35], off
	s_nop 0
	global_load_dwordx2 v[36:37], v[38:39], off offset:-4096
	s_nop 0
	global_load_dwordx2 v[38:39], v[38:39], off
	v_add_co_u32_e32 v42, vcc, s9, v138
	s_add_i32 s68, s38, 55
	s_nop 0
	v_addc_co_u32_e32 v43, vcc, 0, v139, vcc
	v_add_co_u32_e32 v46, vcc, s10, v138
	s_add_i32 s69, s38, 56
	s_nop 0
	v_addc_co_u32_e32 v47, vcc, 0, v139, vcc
	global_load_dwordx2 v[40:41], v[42:43], off offset:-4096
	s_nop 0
	global_load_dwordx2 v[42:43], v[42:43], off
	s_nop 0
	global_load_dwordx2 v[44:45], v[46:47], off offset:-4096
	s_nop 0
	global_load_dwordx2 v[46:47], v[46:47], off
	v_add_co_u32_e32 v50, vcc, s11, v138
	s_add_i32 s3, s38, 19
	s_nop 0
	v_addc_co_u32_e32 v51, vcc, 0, v139, vcc
	v_add_co_u32_e32 v54, vcc, s12, v138
	v_mad_i64_i32 v[210:211], s[28:29], s68, v178, v[6:7]
	s_nop 0
	v_addc_co_u32_e32 v55, vcc, 0, v139, vcc
	global_load_dwordx2 v[48:49], v[50:51], off offset:-4096
	s_nop 0
	global_load_dwordx2 v[50:51], v[50:51], off
	s_nop 0
	global_load_dwordx2 v[52:53], v[54:55], off offset:-4096
	s_nop 0
	global_load_dwordx2 v[54:55], v[54:55], off
	v_add_co_u32_e32 v58, vcc, s13, v138
	s_add_i32 s66, s38, 53
	s_nop 0
	v_addc_co_u32_e32 v59, vcc, 0, v139, vcc
	v_add_co_u32_e32 v62, vcc, s14, v138
	s_add_i32 s67, s38, 54
	s_nop 0
	v_addc_co_u32_e32 v63, vcc, 0, v139, vcc
	global_load_dwordx2 v[56:57], v[58:59], off offset:-4096
	s_nop 0
	global_load_dwordx2 v[58:59], v[58:59], off
	s_nop 0
	global_load_dwordx2 v[60:61], v[62:63], off offset:-4096
	s_nop 0
	global_load_dwordx2 v[62:63], v[62:63], off
	v_add_co_u32_e32 v66, vcc, s15, v138
	v_lshlrev_b32_e32 v146, 16, v8
	s_nop 0
	v_addc_co_u32_e32 v67, vcc, 0, v139, vcc
	v_add_co_u32_e32 v70, vcc, s16, v138
	v_and_b32_e32 v8, 0xffff0000, v8
	s_nop 0
	v_addc_co_u32_e32 v71, vcc, 0, v139, vcc
	global_load_dwordx2 v[64:65], v[66:67], off offset:-4096
	s_nop 0
	global_load_dwordx2 v[66:67], v[66:67], off
	s_nop 0
	global_load_dwordx2 v[68:69], v[70:71], off offset:-4096
	s_nop 0
	global_load_dwordx2 v[70:71], v[70:71], off
	v_add_co_u32_e32 v74, vcc, s0, v138
	s_mov_b32 s0, 0x23000
	s_nop 0
	v_addc_co_u32_e32 v75, vcc, 0, v139, vcc
	v_add_co_u32_e32 v78, vcc, s0, v138
	s_mov_b32 s0, 0x25000
	s_nop 0
	v_addc_co_u32_e32 v79, vcc, 0, v139, vcc
	global_load_dwordx2 v[72:73], v[74:75], off offset:-4096
	s_nop 0
	global_load_dwordx2 v[74:75], v[74:75], off
	s_nop 0
	global_load_dwordx2 v[76:77], v[78:79], off offset:-4096
	s_nop 0
	global_load_dwordx2 v[78:79], v[78:79], off
	v_add_co_u32_e32 v82, vcc, s0, v138
	s_mov_b32 s0, 0x27000
	s_nop 0
	v_addc_co_u32_e32 v83, vcc, 0, v139, vcc
	v_add_co_u32_e32 v86, vcc, s0, v138
	s_mov_b32 s0, 0x29000
	s_nop 0
	v_addc_co_u32_e32 v87, vcc, 0, v139, vcc
	global_load_dwordx2 v[80:81], v[82:83], off offset:-4096
	s_nop 0
	global_load_dwordx2 v[82:83], v[82:83], off
	s_nop 0
	global_load_dwordx2 v[84:85], v[86:87], off offset:-4096
	s_nop 0
	global_load_dwordx2 v[86:87], v[86:87], off
	v_add_co_u32_e32 v90, vcc, s0, v138
	s_mov_b32 s0, 0x2b000
	s_nop 0
	v_addc_co_u32_e32 v91, vcc, 0, v139, vcc
	v_add_co_u32_e32 v94, vcc, s0, v138
	v_fma_f32 v128, -v128, v146, v128
	s_nop 0
	v_addc_co_u32_e32 v95, vcc, 0, v139, vcc
	v_add_f32_e32 v8, v128, v8
	v_lshlrev_b32_e32 v128, 16, v10
	global_load_dwordx2 v[88:89], v[90:91], off offset:-4096
	s_nop 0
	global_load_dwordx2 v[90:91], v[90:91], off
	s_nop 0
; __device__ __forceinline__ void lru_scan(const Params& P, int l) {
;     ...
;         for (int p = 0; p < 64; ++p) w[p] = abp[(size_t)p * 512];
;         float hf[64]; { float hh = hin[0];
; #pragma unroll
;             for (int p = 0; p < 64; ++p) { const float om = __uint_as_float(w[p].x << 16), bb = __uint_as_float(w[p].x & 0xffff0000u); hh = (hh - om * hh) + bb; hf[p] = hh; } }
	global_load_dwordx2 v[92:93], v[94:95], off offset:-4096
	s_nop 0
	global_load_dwordx2 v[94:95], v[94:95], off
	v_and_b32_e32 v10, 0xffff0000, v10
	v_fma_f32 v128, -v8, v128, v8
	v_add_f32_e32 v10, v128, v10
	v_lshlrev_b32_e32 v128, 16, v12
	v_and_b32_e32 v12, 0xffff0000, v12
	v_fma_f32 v128, -v10, v128, v10
	s_mov_b32 s0, 0x2d000
	v_add_f32_e32 v12, v128, v12
	v_lshlrev_b32_e32 v128, 16, v14
	v_add_co_u32_e32 v98, vcc, s0, v138
	v_and_b32_e32 v14, 0xffff0000, v14
	v_fma_f32 v128, -v12, v128, v12
	v_addc_co_u32_e32 v99, vcc, 0, v139, vcc
	s_mov_b32 s0, 0x2f000
	v_add_f32_e32 v14, v128, v14
	v_lshlrev_b32_e32 v128, 16, v16
	v_add_co_u32_e32 v102, vcc, s0, v138
	v_and_b32_e32 v16, 0xffff0000, v16
	v_fma_f32 v128, -v14, v128, v14
	v_addc_co_u32_e32 v103, vcc, 0, v139, vcc
	v_add_f32_e32 v16, v128, v16
	v_lshlrev_b32_e32 v128, 16, v18
	global_load_dwordx2 v[96:97], v[98:99], off offset:-4096
	s_nop 0
	global_load_dwordx2 v[98:99], v[98:99], off
	s_nop 0
	global_load_dwordx2 v[100:101], v[102:103], off offset:-4096
	s_nop 0
	global_load_dwordx2 v[102:103], v[102:103], off
	v_and_b32_e32 v18, 0xffff0000, v18
	v_fma_f32 v128, -v16, v128, v16
	v_add_f32_e32 v18, v128, v18
	v_lshlrev_b32_e32 v128, 16, v20
	v_and_b32_e32 v20, 0xffff0000, v20
	v_fma_f32 v128, -v18, v128, v18
	s_mov_b32 s0, 0x31000
	v_add_f32_e32 v20, v128, v20
	v_lshlrev_b32_e32 v128, 16, v22
	v_add_co_u32_e32 v106, vcc, s0, v138
	v_and_b32_e32 v22, 0xffff0000, v22
	v_fma_f32 v128, -v20, v128, v20
	v_addc_co_u32_e32 v107, vcc, 0, v139, vcc
	s_mov_b32 s0, 0x33000
	v_add_f32_e32 v22, v128, v22
	v_lshlrev_b32_e32 v128, 16, v24
	v_add_co_u32_e32 v110, vcc, s0, v138
	v_and_b32_e32 v24, 0xffff0000, v24
	v_fma_f32 v128, -v22, v128, v22
	v_addc_co_u32_e32 v111, vcc, 0, v139, vcc
	v_add_f32_e32 v24, v128, v24
	v_lshlrev_b32_e32 v128, 16, v26
	global_load_dwordx2 v[104:105], v[106:107], off offset:-4096
	s_nop 0
	global_load_dwordx2 v[106:107], v[106:107], off
	s_nop 0
	global_load_dwordx2 v[108:109], v[110:111], off offset:-4096
	s_nop 0
	global_load_dwordx2 v[110:111], v[110:111], off
	v_and_b32_e32 v26, 0xffff0000, v26
	v_fma_f32 v128, -v24, v128, v24
	v_add_f32_e32 v26, v128, v26
	v_lshlrev_b32_e32 v128, 16, v28
	v_and_b32_e32 v28, 0xffff0000, v28
	v_fma_f32 v128, -v26, v128, v26
	s_mov_b32 s0, 0x35000
	v_add_f32_e32 v28, v128, v28
	v_lshlrev_b32_e32 v128, 16, v30
	v_add_co_u32_e32 v114, vcc, s0, v138
	v_and_b32_e32 v30, 0xffff0000, v30
	v_fma_f32 v128, -v28, v128, v28
	v_addc_co_u32_e32 v115, vcc, 0, v139, vcc
	s_mov_b32 s0, 0x37000
	v_add_f32_e32 v30, v128, v30
	s_waitcnt vmcnt(39)
	v_lshlrev_b32_e32 v128, 16, v32
	v_add_co_u32_e32 v118, vcc, s0, v138
	v_and_b32_e32 v32, 0xffff0000, v32
	v_fma_f32 v128, -v30, v128, v30
	v_addc_co_u32_e32 v119, vcc, 0, v139, vcc
	v_add_f32_e32 v32, v128, v32
	s_waitcnt vmcnt(38)
	v_lshlrev_b32_e32 v128, 16, v34
	global_load_dwordx2 v[112:113], v[114:115], off offset:-4096
	s_nop 0
	global_load_dwordx2 v[114:115], v[114:115], off
	s_nop 0
	global_load_dwordx2 v[116:117], v[118:119], off offset:-4096
	s_nop 0
	global_load_dwordx2 v[118:119], v[118:119], off
	v_and_b32_e32 v34, 0xffff0000, v34
	v_fma_f32 v128, -v32, v128, v32
	v_add_f32_e32 v34, v128, v34
	s_waitcnt vmcnt(41)
	v_lshlrev_b32_e32 v128, 16, v36
	v_and_b32_e32 v36, 0xffff0000, v36
	v_fma_f32 v128, -v34, v128, v34
	s_mov_b32 s0, 0x39000
	v_add_f32_e32 v36, v128, v36
	s_waitcnt vmcnt(40)
	v_lshlrev_b32_e32 v128, 16, v38
	v_add_co_u32_e32 v122, vcc, s0, v138
	v_and_b32_e32 v38, 0xffff0000, v38
	v_fma_f32 v128, -v36, v128, v36
	v_addc_co_u32_e32 v123, vcc, 0, v139, vcc
	s_mov_b32 s0, 0x3b000
	v_add_f32_e32 v38, v128, v38
	s_waitcnt vmcnt(39)
	v_lshlrev_b32_e32 v128, 16, v40
	v_add_co_u32_e32 v126, vcc, s0, v138
	v_and_b32_e32 v40, 0xffff0000, v40
	v_fma_f32 v128, -v38, v128, v38
	v_addc_co_u32_e32 v127, vcc, 0, v139, vcc
	v_add_f32_e32 v40, v128, v40
	s_waitcnt vmcnt(38)
	v_lshlrev_b32_e32 v128, 16, v42
	global_load_dwordx2 v[120:121], v[122:123], off offset:-4096
	s_nop 0
	global_load_dwordx2 v[122:123], v[122:123], off
	s_nop 0
	global_load_dwordx2 v[124:125], v[126:127], off offset:-4096
	s_nop 0
	global_load_dwordx2 v[126:127], v[126:127], off
	v_and_b32_e32 v42, 0xffff0000, v42
	v_fma_f32 v128, -v40, v128, v40
	v_add_f32_e32 v42, v128, v42
	s_waitcnt vmcnt(41)
	v_lshlrev_b32_e32 v128, 16, v44
	v_and_b32_e32 v44, 0xffff0000, v44
	v_fma_f32 v128, -v42, v128, v42
	s_mov_b32 s0, 0x3d000
	v_add_f32_e32 v44, v128, v44
	s_waitcnt vmcnt(40)
	v_lshlrev_b32_e32 v128, 16, v46
	v_add_co_u32_e32 v140, vcc, s0, v138
	v_and_b32_e32 v46, 0xffff0000, v46
	v_fma_f32 v128, -v44, v128, v44
	v_addc_co_u32_e32 v141, vcc, 0, v139, vcc
	s_mov_b32 s0, 0x3f000
	v_add_f32_e32 v46, v128, v46
	s_waitcnt vmcnt(39)
	v_lshlrev_b32_e32 v128, 16, v48
	v_add_co_u32_e32 v144, vcc, s0, v138
	v_and_b32_e32 v48, 0xffff0000, v48
	v_fma_f32 v128, -v46, v128, v46
	v_addc_co_u32_e32 v145, vcc, 0, v139, vcc
	v_add_f32_e32 v48, v128, v48
	s_waitcnt vmcnt(38)
	v_lshlrev_b32_e32 v128, 16, v50
	global_load_dwordx2 v[138:139], v[140:141], off offset:-4096
	s_nop 0
	global_load_dwordx2 v[140:141], v[140:141], off
	s_nop 0
	global_load_dwordx2 v[142:143], v[144:145], off offset:-4096
	s_nop 0
	global_load_dwordx2 v[144:145], v[144:145], off
	v_and_b32_e32 v50, 0xffff0000, v50
	v_fma_f32 v128, -v48, v128, v48
	v_add_f32_e32 v50, v128, v50
	s_waitcnt vmcnt(41)
	v_lshlrev_b32_e32 v128, 16, v52
	v_and_b32_e32 v52, 0xffff0000, v52
	v_fma_f32 v128, -v50, v128, v50
	v_add_f32_e32 v52, v128, v52
	s_waitcnt vmcnt(40)
	v_lshlrev_b32_e32 v128, 16, v54
	v_and_b32_e32 v54, 0xffff0000, v54
	v_fma_f32 v128, -v52, v128, v52
	v_add_f32_e32 v54, v128, v54
	s_waitcnt vmcnt(39)
; __device__ __forceinline__ void lru_scan(const Params& P, int l) {
;     ...
;             for (int p = 0; p < 64; ++p) { const float om = __uint_as_float(w[p].x << 16), bb = __uint_as_float(w[p].x & 0xffff0000u); hh = (hh - om * hh) + bb; hf[p] = hh; } }
	v_lshlrev_b32_e32 v128, 16, v56
	v_and_b32_e32 v56, 0xffff0000, v56
	v_fma_f32 v128, -v54, v128, v54
	v_add_f32_e32 v56, v128, v56
	s_waitcnt vmcnt(38)
	v_lshlrev_b32_e32 v128, 16, v58
	v_and_b32_e32 v58, 0xffff0000, v58
	v_fma_f32 v128, -v56, v128, v56
	v_add_f32_e32 v58, v128, v58
	s_waitcnt vmcnt(37)
	v_lshlrev_b32_e32 v128, 16, v60
	v_and_b32_e32 v60, 0xffff0000, v60
	v_fma_f32 v128, -v58, v128, v58
	v_add_f32_e32 v60, v128, v60
	s_waitcnt vmcnt(36)
	v_lshlrev_b32_e32 v128, 16, v62
	v_and_b32_e32 v62, 0xffff0000, v62
	v_fma_f32 v128, -v60, v128, v60
	v_add_f32_e32 v62, v128, v62
	s_waitcnt vmcnt(35)
	v_lshlrev_b32_e32 v128, 16, v64
	v_and_b32_e32 v64, 0xffff0000, v64
	v_fma_f32 v128, -v62, v128, v62
	v_add_f32_e32 v64, v128, v64
	s_waitcnt vmcnt(34)
	v_lshlrev_b32_e32 v128, 16, v66
	v_and_b32_e32 v66, 0xffff0000, v66
	v_fma_f32 v128, -v64, v128, v64
	v_add_f32_e32 v66, v128, v66
	s_waitcnt vmcnt(33)
	v_lshlrev_b32_e32 v128, 16, v68
	v_and_b32_e32 v68, 0xffff0000, v68
	v_fma_f32 v128, -v66, v128, v66
	v_add_f32_e32 v68, v128, v68
	s_waitcnt vmcnt(32)
	v_lshlrev_b32_e32 v128, 16, v70
	v_and_b32_e32 v70, 0xffff0000, v70
	v_fma_f32 v128, -v68, v128, v68
	v_add_f32_e32 v70, v128, v70
	s_waitcnt vmcnt(31)
	v_lshlrev_b32_e32 v128, 16, v72
	v_and_b32_e32 v72, 0xffff0000, v72
	v_fma_f32 v128, -v70, v128, v70
	v_add_f32_e32 v72, v128, v72
	s_waitcnt vmcnt(30)
	v_lshlrev_b32_e32 v128, 16, v74
	v_and_b32_e32 v74, 0xffff0000, v74
	v_fma_f32 v128, -v72, v128, v72
	v_add_f32_e32 v74, v128, v74
	s_waitcnt vmcnt(29)
	v_lshlrev_b32_e32 v128, 16, v76
	v_and_b32_e32 v76, 0xffff0000, v76
	v_fma_f32 v128, -v74, v128, v74
	v_add_f32_e32 v76, v128, v76
	s_waitcnt vmcnt(28)
	v_lshlrev_b32_e32 v128, 16, v78
	v_and_b32_e32 v78, 0xffff0000, v78
	v_fma_f32 v128, -v76, v128, v76
	v_add_f32_e32 v78, v128, v78
	s_waitcnt vmcnt(27)
	v_lshlrev_b32_e32 v128, 16, v80
	v_and_b32_e32 v80, 0xffff0000, v80
	v_fma_f32 v128, -v78, v128, v78
	v_add_f32_e32 v80, v128, v80
	s_waitcnt vmcnt(26)
	v_lshlrev_b32_e32 v128, 16, v82
	v_and_b32_e32 v82, 0xffff0000, v82
	v_fma_f32 v128, -v80, v128, v80
	v_add_f32_e32 v82, v128, v82
	s_waitcnt vmcnt(25)
	v_lshlrev_b32_e32 v128, 16, v84
	v_and_b32_e32 v84, 0xffff0000, v84
	v_fma_f32 v128, -v82, v128, v82
	v_add_f32_e32 v84, v128, v84
	s_waitcnt vmcnt(24)
	v_lshlrev_b32_e32 v128, 16, v86
	v_and_b32_e32 v86, 0xffff0000, v86
	v_fma_f32 v128, -v84, v128, v84
	v_add_f32_e32 v86, v128, v86
	s_waitcnt vmcnt(23)
	v_lshlrev_b32_e32 v128, 16, v88
	v_and_b32_e32 v88, 0xffff0000, v88
	v_fma_f32 v128, -v86, v128, v86
	v_add_f32_e32 v88, v128, v88
	s_waitcnt vmcnt(22)
	v_lshlrev_b32_e32 v128, 16, v90
	v_and_b32_e32 v90, 0xffff0000, v90
	v_fma_f32 v128, -v88, v128, v88
	v_add_f32_e32 v90, v128, v90
	s_waitcnt vmcnt(21)
	v_lshlrev_b32_e32 v128, 16, v92
	v_and_b32_e32 v92, 0xffff0000, v92
	v_fma_f32 v128, -v90, v128, v90
	v_add_f32_e32 v92, v128, v92
	s_waitcnt vmcnt(20)
	v_lshlrev_b32_e32 v128, 16, v94
	v_and_b32_e32 v94, 0xffff0000, v94
	v_fma_f32 v128, -v92, v128, v92
	v_add_f32_e32 v94, v128, v94
	s_waitcnt vmcnt(19)
	v_lshlrev_b32_e32 v128, 16, v96
	v_and_b32_e32 v96, 0xffff0000, v96
	v_fma_f32 v128, -v94, v128, v94
	v_add_f32_e32 v96, v128, v96
	s_waitcnt vmcnt(18)
	v_lshlrev_b32_e32 v128, 16, v98
	v_and_b32_e32 v98, 0xffff0000, v98
	v_fma_f32 v128, -v96, v128, v96
	v_add_f32_e32 v98, v128, v98
	s_waitcnt vmcnt(17)
	v_lshlrev_b32_e32 v128, 16, v100
	v_and_b32_e32 v100, 0xffff0000, v100
	v_fma_f32 v128, -v98, v128, v98
	v_add_f32_e32 v100, v128, v100
	s_waitcnt vmcnt(16)
	v_lshlrev_b32_e32 v128, 16, v102
	v_and_b32_e32 v102, 0xffff0000, v102
	v_fma_f32 v128, -v100, v128, v100
	v_add_f32_e32 v102, v128, v102
	s_waitcnt vmcnt(15)
	v_lshlrev_b32_e32 v128, 16, v104
	v_and_b32_e32 v104, 0xffff0000, v104
	v_fma_f32 v128, -v102, v128, v102
	v_add_f32_e32 v104, v128, v104
	s_waitcnt vmcnt(14)
	v_lshlrev_b32_e32 v128, 16, v106
	v_and_b32_e32 v106, 0xffff0000, v106
	v_fma_f32 v128, -v104, v128, v104
	v_add_f32_e32 v128, v128, v106
	s_waitcnt vmcnt(13)
	v_lshlrev_b32_e32 v106, 16, v108
	v_and_b32_e32 v108, 0xffff0000, v108
	v_fma_f32 v106, -v128, v106, v128
	v_add_f32_e32 v155, v106, v108
	s_waitcnt vmcnt(12)
	v_lshlrev_b32_e32 v106, 16, v110
	v_and_b32_e32 v108, 0xffff0000, v110
	v_fma_f32 v106, -v155, v106, v155
	v_add_f32_e32 v156, v106, v108
	s_waitcnt vmcnt(11)
	v_lshlrev_b32_e32 v106, 16, v112
	v_and_b32_e32 v108, 0xffff0000, v112
	v_fma_f32 v106, -v156, v106, v156
	v_add_f32_e32 v157, v106, v108
	s_waitcnt vmcnt(10)
	v_lshlrev_b32_e32 v106, 16, v114
	v_and_b32_e32 v108, 0xffff0000, v114
	v_fma_f32 v106, -v157, v106, v157
	v_add_f32_e32 v158, v106, v108
	s_waitcnt vmcnt(9)
	v_lshlrev_b32_e32 v106, 16, v116
	v_and_b32_e32 v108, 0xffff0000, v116
	v_fma_f32 v106, -v158, v106, v158
	v_add_f32_e32 v159, v106, v108
	s_waitcnt vmcnt(8)
	v_lshlrev_b32_e32 v106, 16, v118
	v_and_b32_e32 v108, 0xffff0000, v118
	v_fma_f32 v106, -v159, v106, v159
	v_add_f32_e32 v160, v106, v108
	s_waitcnt vmcnt(7)
	v_lshlrev_b32_e32 v106, 16, v120
	v_and_b32_e32 v108, 0xffff0000, v120
	v_fma_f32 v106, -v160, v106, v160
	v_add_f32_e32 v161, v106, v108
	s_waitcnt vmcnt(6)
	v_lshlrev_b32_e32 v106, 16, v122
	v_and_b32_e32 v108, 0xffff0000, v122
	v_fma_f32 v106, -v161, v106, v161
	v_add_f32_e32 v162, v106, v108
	s_waitcnt vmcnt(5)
	v_lshlrev_b32_e32 v106, 16, v124
	v_and_b32_e32 v108, 0xffff0000, v124
	v_fma_f32 v106, -v162, v106, v162
	v_add_f32_e32 v163, v106, v108
	s_waitcnt vmcnt(4)
	v_lshlrev_b32_e32 v106, 16, v126
	v_and_b32_e32 v108, 0xffff0000, v126
	v_fma_f32 v106, -v163, v106, v163
	v_add_f32_e32 v167, v106, v108
	s_waitcnt vmcnt(3)
; __device__ __forceinline__ void lru_scan(const Params& P, int l) {
;     ...
;             for (int p = 0; p < 64; ++p) { const float om = __uint_as_float(w[p].x << 16), bb = __uint_as_float(w[p].x & 0xffff0000u); hh = (hh - om * hh) + bb; hf[p] = hh; } }
;     ...
;         for (int p = 0; p < 64; ++p) gar[p] = Z[(size_t)(r0 + p) * ZW + 512 + c];
	v_lshlrev_b32_e32 v106, 16, v138
	v_and_b32_e32 v108, 0xffff0000, v138
	v_fma_f32 v106, -v167, v106, v167
	v_add_f32_e32 v186, v106, v108
	s_waitcnt vmcnt(2)
	v_lshlrev_b32_e32 v106, 16, v140
	v_and_b32_e32 v108, 0xffff0000, v140
	v_fma_f32 v106, -v186, v106, v186
	v_add_f32_e32 v190, v106, v108
	s_waitcnt vmcnt(1)
	v_lshlrev_b32_e32 v106, 16, v142
	v_and_b32_e32 v108, 0xffff0000, v142
	v_fma_f32 v106, -v190, v106, v190
	v_add_f32_e32 v216, v106, v108
	s_waitcnt vmcnt(0)
	v_lshlrev_b32_e32 v106, 16, v144
	v_and_b32_e32 v108, 0xffff0000, v144
	v_fma_f32 v106, -v216, v106, v216
	v_mad_i64_i32 v[164:165], s[14:15], s72, v178, v[6:7]
	v_add_f32_e32 v106, v106, v108
	global_load_ushort v108, v[164:165], off offset:1024
	v_lshlrev_b32_e32 v110, 16, v145
	v_and_b32_e32 v112, 0xffff0000, v145
	v_mad_i64_i32 v[144:145], s[28:29], s76, v178, v[6:7]
	global_load_ushort v218, v[144:145], off offset:1024
	v_mad_i64_i32 v[144:145], s[28:29], s75, v178, v[6:7]
	global_load_ushort v220, v[144:145], off offset:1024
	v_mad_i64_i32 v[144:145], s[28:29], s74, v178, v[6:7]
	global_load_ushort v221, v[144:145], off offset:1024
	s_nop 0
	global_load_ushort v214, v[214:215], off offset:1024
	v_mad_i64_i32 v[144:145], s[28:29], s71, v178, v[6:7]
	global_load_ushort v215, v[144:145], off offset:1024
	s_nop 0
	global_load_ushort v212, v[212:213], off offset:1024
	v_mad_i64_i32 v[144:145], s[28:29], s69, v178, v[6:7]
	v_mad_i64_i32 v[146:147], s[4:5], s3, v178, v[6:7]
	global_load_ushort v213, v[144:145], off offset:1024
	s_nop 0
	global_load_ushort v210, v[210:211], off offset:1024
	s_add_i32 s5, s38, 21
	v_mad_i64_i32 v[148:149], s[8:9], s5, v178, v[6:7]
	s_add_i32 s9, s38, 23
	s_add_i32 s64, s38, 51
	s_add_i32 s65, s38, 52
	v_mad_i64_i32 v[208:209], s[28:29], s66, v178, v[6:7]
	v_mad_i64_i32 v[144:145], s[28:29], s67, v178, v[6:7]
	v_mad_i64_i32 v[150:151], s[10:11], s9, v178, v[6:7]
	s_add_i32 s62, s38, 49
	s_add_i32 s63, s38, 50
	v_mad_i64_i32 v[206:207], s[28:29], s64, v178, v[6:7]
	global_load_ushort v211, v[144:145], off offset:1024
	s_nop 0
	global_load_ushort v208, v[208:209], off offset:1024
	v_mad_i64_i32 v[144:145], s[28:29], s65, v178, v[6:7]
	s_add_i32 s11, s38, 25
	s_add_i32 s60, s38, 47
	s_add_i32 s61, s38, 48
	v_mad_i64_i32 v[204:205], s[28:29], s62, v178, v[6:7]
	global_load_ushort v209, v[144:145], off offset:1024
	s_nop 0
	global_load_ushort v206, v[206:207], off offset:1024
	v_mad_i64_i32 v[144:145], s[28:29], s63, v178, v[6:7]
	v_mad_i64_i32 v[152:153], s[12:13], s11, v178, v[6:7]
	s_add_i32 s58, s38, 45
	s_add_i32 s59, s38, 46
	v_mad_i64_i32 v[202:203], s[28:29], s60, v178, v[6:7]
	global_load_ushort v207, v[144:145], off offset:1024
	s_nop 0
	global_load_ushort v204, v[204:205], off offset:1024
	v_mad_i64_i32 v[144:145], s[28:29], s61, v178, v[6:7]
	s_add_i32 s13, s38, 27
	s_add_i32 s56, s38, 43
	s_add_i32 s57, s38, 44
	v_mad_i64_i32 v[200:201], s[28:29], s58, v178, v[6:7]
	global_load_ushort v205, v[144:145], off offset:1024
	s_nop 0
	global_load_ushort v202, v[202:203], off offset:1024
	v_mad_i64_i32 v[144:145], s[28:29], s59, v178, v[6:7]
	v_mad_i64_i32 v[164:165], s[14:15], s13, v178, v[6:7]
	s_add_i32 s54, s38, 41
	s_add_i32 s55, s38, 42
	v_mad_i64_i32 v[198:199], s[28:29], s56, v178, v[6:7]
	global_load_ushort v203, v[144:145], off offset:1024
	s_nop 0
	global_load_ushort v200, v[200:201], off offset:1024
	v_mad_i64_i32 v[144:145], s[28:29], s57, v178, v[6:7]
	s_add_i32 s15, s38, 29
	s_add_i32 s53, s38, 40
	v_mad_i64_i32 v[196:197], s[28:29], s54, v178, v[6:7]
	global_load_ushort v201, v[144:145], off offset:1024
	s_nop 0
	global_load_ushort v198, v[198:199], off offset:1024
	v_mad_i64_i32 v[144:145], s[28:29], s55, v178, v[6:7]
	v_mad_i64_i32 v[180:181], s[16:17], s15, v178, v[6:7]
	s_add_i32 s47, s38, 38
	s_add_i32 s50, s38, 39
	global_load_ushort v199, v[144:145], off offset:1024
	s_nop 0
	global_load_ushort v196, v[196:197], off offset:1024
	v_mad_i64_i32 v[144:145], s[28:29], s53, v178, v[6:7]
	s_add_i32 s17, s38, 31
	s_add_i32 s41, s38, 36
	s_add_i32 s44, s38, 37
	v_mad_i64_i32 v[194:195], s[28:29], s50, v178, v[6:7]
	global_load_ushort v197, v[144:145], off offset:1024
	global_load_ushort v222, v[194:195], off offset:1024
	v_mad_i64_i32 v[144:145], s[28:29], s47, v178, v[6:7]
	v_mad_i64_i32 v[182:183], s[26:27], s17, v178, v[6:7]
	s_add_i32 s31, s38, 34
	s_add_i32 s39, s38, 35
	v_mad_i64_i32 v[192:193], s[28:29], s44, v178, v[6:7]
	global_load_ushort v223, v[144:145], off offset:1024
	global_load_ushort v224, v[192:193], off offset:1024
	v_mad_i64_i32 v[144:145], s[28:29], s41, v178, v[6:7]
	s_add_i32 s21, s38, 32
	s_add_i32 s27, s38, 33
	v_mad_i64_i32 v[188:189], s[28:29], s39, v178, v[6:7]
	global_load_ushort v225, v[144:145], off offset:1024
	global_load_ushort v193, v[188:189], off offset:1024
	v_mad_i64_i32 v[144:145], s[28:29], s31, v178, v[6:7]
	s_add_i32 s16, s38, 30
	v_mad_i64_i32 v[184:185], s[28:29], s27, v178, v[6:7]
	global_load_ushort v192, v[144:145], off offset:1024
	global_load_ushort v189, v[184:185], off offset:1024
	v_mad_i64_i32 v[144:145], s[28:29], s21, v178, v[6:7]
	s_add_i32 s14, s38, 28
	global_load_ushort v191, v[144:145], off offset:1024
	global_load_ushort v188, v[182:183], off offset:1024
	v_mad_i64_i32 v[144:145], s[28:29], s16, v178, v[6:7]
	s_add_i32 s12, s38, 26
	global_load_ushort v187, v[144:145], off offset:1024
	global_load_ushort v185, v[180:181], off offset:1024
	v_mad_i64_i32 v[144:145], s[28:29], s14, v178, v[6:7]
	s_add_i32 s10, s38, 24
	global_load_ushort v184, v[144:145], off offset:1024
	global_load_ushort v166, v[164:165], off offset:1024
	v_mad_i64_i32 v[144:145], s[28:29], s12, v178, v[6:7]
; __device__ __forceinline__ float bf2f(unsigned short b) { return __uint_as_float(((unsigned)b) << 16); }
; __device__ __forceinline__ unsigned cvt_pk_bf16(float lo, float hi) { unsigned r; asm volatile("v_cvt_pk_bf16_f32 %0, %1, %2" : "=v"(r) : "v"(lo), "v"(hi)); return r; }
; __device__ __forceinline__ void lru_scan(const Params& P, int l) {
;     ...
;         { float hh = hin[1];
; #pragma unroll
;             for (int p = 63; p >= 0; --p) { const float om = __uint_as_float(w[p].y << 16), bb = __uint_as_float(w[p].y & 0xffff0000u); hh = (hh - om * hh) + bb;
;                 const float yo = (hf[p] + hh) * bf2f(gar[p]); Y[(size_t)(r0 + p) * YW + c] = (bf16_t)cvt_pk_bf16(yo, yo); } }
	s_add_i32 s8, s38, 22
	v_fma_f32 v110, -v154, v110, v154
	global_load_ushort v165, v[144:145], off offset:1024
	global_load_ushort v154, v[152:153], off offset:1024
	v_mad_i64_i32 v[144:145], s[28:29], s10, v178, v[6:7]
	s_add_i32 s4, s38, 20
	global_load_ushort v164, v[144:145], off offset:1024
	global_load_ushort v153, v[150:151], off offset:1024
	v_mad_i64_i32 v[144:145], s[28:29], s8, v178, v[6:7]
	s_add_i32 s2, s38, 18
	global_load_ushort v152, v[144:145], off offset:1024
	global_load_ushort v151, v[148:149], off offset:1024
	v_mad_i64_i32 v[144:145], s[28:29], s4, v178, v[6:7]
	s_add_i32 s1, s38, 17
	global_load_ushort v150, v[144:145], off offset:1024
	global_load_ushort v149, v[146:147], off offset:1024
	v_mad_i64_i32 v[144:145], s[28:29], s2, v178, v[6:7]
	s_add_i32 s0, s38, 16
	global_load_ushort v148, v[144:145], off offset:1024
	v_mad_i64_i32 v[144:145], s[28:29], s1, v178, v[6:7]
	global_load_ushort v146, v[144:145], off offset:1024
	v_mad_i64_i32 v[144:145], s[28:29], s0, v178, v[6:7]
	s_add_i32 s52, s38, 15
	s_add_i32 s51, s38, 14
	global_load_ushort v147, v[144:145], off offset:1024
	v_mad_i64_i32 v[144:145], s[28:29], s52, v178, v[6:7]
	v_mad_i64_i32 v[180:181], s[28:29], s51, v178, v[6:7]
	s_add_i32 s49, s38, 13
	global_load_ushort v145, v[144:145], off offset:1024
	s_add_i32 s48, s38, 12
	global_load_ushort v144, v[180:181], off offset:1024
	v_mad_i64_i32 v[180:181], s[28:29], s49, v178, v[6:7]
	global_load_ushort v142, v[180:181], off offset:1024
	v_mad_i64_i32 v[180:181], s[28:29], s48, v178, v[6:7]
	s_add_i32 s46, s38, 11
	global_load_ushort v140, v[180:181], off offset:1024
	v_mad_i64_i32 v[180:181], s[28:29], s46, v178, v[6:7]
	s_add_i32 s45, s38, 10
	global_load_ushort v138, v[180:181], off offset:1024
	v_mad_i64_i32 v[180:181], s[28:29], s45, v178, v[6:7]
	s_add_i32 s43, s38, 9
	global_load_ushort v126, v[180:181], off offset:1024
	v_mad_i64_i32 v[180:181], s[28:29], s43, v178, v[6:7]
	s_add_i32 s42, s38, 8
	global_load_ushort v124, v[180:181], off offset:1024
	v_mad_i64_i32 v[180:181], s[28:29], s42, v178, v[6:7]
	s_add_i32 s40, s38, 7
	global_load_ushort v122, v[180:181], off offset:1024
	v_mad_i64_i32 v[180:181], s[28:29], s40, v178, v[6:7]
	s_add_i32 s35, s38, 6
	global_load_ushort v120, v[180:181], off offset:1024
	v_mad_i64_i32 v[180:181], s[28:29], s35, v178, v[6:7]
	s_add_i32 s34, s38, 5
	global_load_ushort v118, v[180:181], off offset:1024
	v_mad_i64_i32 v[180:181], s[28:29], s34, v178, v[6:7]
	s_add_i32 s30, s38, 4
	global_load_ushort v116, v[180:181], off offset:1024
	v_mad_i64_i32 v[180:181], s[28:29], s30, v178, v[6:7]
	s_add_i32 s26, s38, 3
	global_load_ushort v114, v[180:181], off offset:1024
	v_mad_i64_i32 v[180:181], s[28:29], s26, v178, v[6:7]
	s_add_i32 s25, s38, 2
	v_add_f32_e32 v217, v110, v112
	global_load_ushort v112, v[180:181], off offset:1024
	v_mad_i64_i32 v[180:181], s[28:29], s25, v178, v[6:7]
	s_add_i32 s19, s38, 1
	v_add_f32_e32 v106, v217, v106
	s_waitcnt vmcnt(60)
	v_lshlrev_b32_e32 v108, 16, v108
	global_load_ushort v110, v[180:181], off offset:1024
	v_mad_i64_i32 v[180:181], s[28:29], s19, v178, v[6:7]
	v_mul_f32_e32 v219, v106, v108
	global_load_ushort v108, v[180:181], off offset:1024
	v_mad_i64_i32 v[180:181], s[28:29], s38, v178, v[6:7]
	global_load_ushort v106, v[180:181], off offset:1024
	v_mad_i64_i32 v[180:181], s[28:29], s72, v178, v[4:5]
	v_cvt_pk_bf16_f32 v182, v219, v219
	global_store_short v[180:181], v182, off sc1
	v_lshlrev_b32_e32 v180, 16, v143
	v_and_b32_e32 v143, 0xffff0000, v143
	v_fma_f32 v180, -v217, v180, v217
	v_add_f32_e32 v143, v180, v143
	v_add_f32_e32 v180, v143, v216
	s_waitcnt vmcnt(62)
	v_lshlrev_b32_e32 v181, 16, v218
	v_mul_f32_e32 v180, v180, v181
	v_cvt_pk_bf16_f32 v182, v180, v180
	v_mad_i64_i32 v[180:181], s[28:29], s76, v178, v[4:5]
	global_store_short v[180:181], v182, off sc1
	v_lshlrev_b32_e32 v180, 16, v141
	v_and_b32_e32 v141, 0xffff0000, v141
	v_fma_f32 v143, -v143, v180, v143
	v_add_f32_e32 v141, v143, v141
	v_add_f32_e32 v143, v141, v190
	v_lshlrev_b32_e32 v180, 16, v220
	v_mul_f32_e32 v143, v143, v180
	v_cvt_pk_bf16_f32 v143, v143, v143
	v_mad_i64_i32 v[180:181], s[28:29], s75, v178, v[4:5]
	global_store_short v[180:181], v143, off sc1
	v_lshlrev_b32_e32 v143, 16, v139
	v_and_b32_e32 v139, 0xffff0000, v139
	v_fma_f32 v141, -v141, v143, v141
	v_add_f32_e32 v139, v141, v139
	v_add_f32_e32 v141, v139, v186
	s_waitcnt vmcnt(62)
	v_lshlrev_b32_e32 v143, 16, v221
	v_mul_f32_e32 v141, v141, v143
	v_cvt_pk_bf16_f32 v141, v141, v141
	v_mad_i64_i32 v[180:181], s[28:29], s74, v178, v[4:5]
	global_store_short v[180:181], v141, off sc1
	v_lshlrev_b32_e32 v141, 16, v127
	v_and_b32_e32 v127, 0xffff0000, v127
	v_fma_f32 v139, -v139, v141, v139
	v_add_f32_e32 v127, v139, v127
	v_add_f32_e32 v139, v127, v167
	v_lshlrev_b32_e32 v141, 16, v214
	v_mul_f32_e32 v139, v139, v141
	v_cvt_pk_bf16_f32 v139, v139, v139
	v_mad_i64_i32 v[180:181], s[28:29], s73, v178, v[4:5]
	global_store_short v[180:181], v139, off sc1
	v_lshlrev_b32_e32 v139, 16, v125
	v_and_b32_e32 v125, 0xffff0000, v125
	v_fma_f32 v127, -v127, v139, v127
	v_add_f32_e32 v125, v127, v125
	v_add_f32_e32 v127, v125, v163
	s_waitcnt vmcnt(62)
	v_lshlrev_b32_e32 v139, 16, v215
	v_mul_f32_e32 v127, v127, v139
	v_mad_i64_i32 v[180:181], s[28:29], s71, v178, v[4:5]
	v_cvt_pk_bf16_f32 v127, v127, v127
	global_store_short v[180:181], v127, off sc1
	v_lshlrev_b32_e32 v127, 16, v123
	v_and_b32_e32 v123, 0xffff0000, v123
	v_fma_f32 v125, -v125, v127, v125
	v_add_f32_e32 v123, v125, v123
	v_add_f32_e32 v125, v123, v162
	v_lshlrev_b32_e32 v127, 16, v212
	v_mul_f32_e32 v125, v125, v127
	v_mad_i64_i32 v[182:183], s[28:29], s70, v178, v[4:5]
	v_cvt_pk_bf16_f32 v125, v125, v125
	global_store_short v[182:183], v125, off sc1
	v_lshlrev_b32_e32 v125, 16, v121
	v_and_b32_e32 v121, 0xffff0000, v121
	v_fma_f32 v123, -v123, v125, v123
	v_add_f32_e32 v121, v123, v121
	v_add_f32_e32 v123, v121, v161
	s_waitcnt vmcnt(62)
; __device__ __forceinline__ float bf2f(unsigned short b) { return __uint_as_float(((unsigned)b) << 16); }
; __device__ __forceinline__ unsigned cvt_pk_bf16(float lo, float hi) { unsigned r; asm volatile("v_cvt_pk_bf16_f32 %0, %1, %2" : "=v"(r) : "v"(lo), "v"(hi)); return r; }
; __device__ __forceinline__ void lru_scan(const Params& P, int l) {
;     ...
;         { float hh = hin[1];
; #pragma unroll
;             for (int p = 63; p >= 0; --p) { const float om = __uint_as_float(w[p].y << 16), bb = __uint_as_float(w[p].y & 0xffff0000u); hh = (hh - om * hh) + bb;
;                 const float yo = (hf[p] + hh) * bf2f(gar[p]); Y[(size_t)(r0 + p) * YW + c] = (bf16_t)cvt_pk_bf16(yo, yo); } }
	v_lshlrev_b32_e32 v125, 16, v213
	v_mul_f32_e32 v123, v123, v125
	v_mad_i64_i32 v[180:181], s[28:29], s69, v178, v[4:5]
	v_cvt_pk_bf16_f32 v123, v123, v123
	global_store_short v[180:181], v123, off sc1
	v_lshlrev_b32_e32 v123, 16, v119
	v_and_b32_e32 v119, 0xffff0000, v119
	v_fma_f32 v121, -v121, v123, v121
	v_add_f32_e32 v119, v121, v119
	v_add_f32_e32 v121, v119, v160
	v_lshlrev_b32_e32 v123, 16, v210
	v_mul_f32_e32 v121, v121, v123
	v_mad_i64_i32 v[194:195], s[28:29], s68, v178, v[4:5]
	v_cvt_pk_bf16_f32 v121, v121, v121
	global_store_short v[194:195], v121, off sc1
	v_lshlrev_b32_e32 v121, 16, v117
	v_and_b32_e32 v117, 0xffff0000, v117
	v_fma_f32 v119, -v119, v121, v119
	v_add_f32_e32 v117, v119, v117
	v_add_f32_e32 v119, v117, v159
	s_waitcnt vmcnt(62)
	v_lshlrev_b32_e32 v121, 16, v211
	v_mul_f32_e32 v119, v119, v121
	v_cvt_pk_bf16_f32 v119, v119, v119
	v_mad_i64_i32 v[160:161], s[28:29], s67, v178, v[4:5]
	global_store_short v[160:161], v119, off sc1
	v_lshlrev_b32_e32 v119, 16, v115
	v_and_b32_e32 v115, 0xffff0000, v115
	v_fma_f32 v117, -v117, v119, v117
	v_add_f32_e32 v115, v117, v115
	v_add_f32_e32 v117, v115, v158
	v_lshlrev_b32_e32 v119, 16, v208
	v_mul_f32_e32 v117, v117, v119
	v_cvt_pk_bf16_f32 v117, v117, v117
	v_mad_i64_i32 v[158:159], s[28:29], s66, v178, v[4:5]
	global_store_short v[158:159], v117, off sc1
	v_lshlrev_b32_e32 v117, 16, v113
	v_and_b32_e32 v113, 0xffff0000, v113
	v_fma_f32 v115, -v115, v117, v115
	v_add_f32_e32 v113, v115, v113
	v_add_f32_e32 v115, v113, v157
	s_waitcnt vmcnt(62)
	v_lshlrev_b32_e32 v117, 16, v209
	v_mul_f32_e32 v115, v115, v117
	v_cvt_pk_bf16_f32 v115, v115, v115
	v_mad_i64_i32 v[158:159], s[28:29], s65, v178, v[4:5]
	global_store_short v[158:159], v115, off sc1
	v_lshlrev_b32_e32 v115, 16, v111
	v_and_b32_e32 v111, 0xffff0000, v111
	v_fma_f32 v113, -v113, v115, v113
	v_add_f32_e32 v111, v113, v111
	v_add_f32_e32 v113, v111, v156
	v_lshlrev_b32_e32 v115, 16, v206
	v_mul_f32_e32 v113, v113, v115
	v_cvt_pk_bf16_f32 v113, v113, v113
	v_mad_i64_i32 v[156:157], s[28:29], s64, v178, v[4:5]
	global_store_short v[156:157], v113, off sc1
	v_lshlrev_b32_e32 v113, 16, v109
	v_and_b32_e32 v109, 0xffff0000, v109
	v_fma_f32 v111, -v111, v113, v111
	v_add_f32_e32 v109, v111, v109
	v_add_f32_e32 v111, v109, v155
	s_waitcnt vmcnt(62)
	v_lshlrev_b32_e32 v113, 16, v207
	v_mul_f32_e32 v111, v111, v113
	v_cvt_pk_bf16_f32 v111, v111, v111
	v_mad_i64_i32 v[156:157], s[28:29], s63, v178, v[4:5]
	global_store_short v[156:157], v111, off sc1
	v_lshlrev_b32_e32 v111, 16, v107
	v_and_b32_e32 v107, 0xffff0000, v107
	v_fma_f32 v109, -v109, v111, v109
	v_add_f32_e32 v107, v109, v107
	v_add_f32_e32 v109, v107, v128
	v_lshlrev_b32_e32 v111, 16, v204
	v_mul_f32_e32 v109, v109, v111
	v_cvt_pk_bf16_f32 v109, v109, v109
	v_mad_i64_i32 v[156:157], s[28:29], s62, v178, v[4:5]
	global_store_short v[156:157], v109, off sc1
	v_lshlrev_b32_e32 v109, 16, v105
	v_and_b32_e32 v105, 0xffff0000, v105
	v_fma_f32 v107, -v107, v109, v107
	v_add_f32_e32 v107, v107, v105
	v_add_f32_e32 v104, v107, v104
	s_waitcnt vmcnt(62)
	v_lshlrev_b32_e32 v105, 16, v205
	v_mul_f32_e32 v104, v104, v105
	v_cvt_pk_bf16_f32 v109, v104, v104
	v_mad_i64_i32 v[104:105], s[28:29], s61, v178, v[4:5]
	global_store_short v[104:105], v109, off sc1
	v_lshlrev_b32_e32 v104, 16, v103
	v_and_b32_e32 v103, 0xffff0000, v103
	v_fma_f32 v104, -v107, v104, v107
	v_add_f32_e32 v104, v104, v103
	v_add_f32_e32 v102, v104, v102
	v_lshlrev_b32_e32 v103, 16, v202
	v_mul_f32_e32 v102, v102, v103
	v_cvt_pk_bf16_f32 v105, v102, v102
	v_mad_i64_i32 v[102:103], s[28:29], s60, v178, v[4:5]
	global_store_short v[102:103], v105, off sc1
	v_lshlrev_b32_e32 v102, 16, v101
	v_and_b32_e32 v101, 0xffff0000, v101
	v_fma_f32 v102, -v104, v102, v104
	v_add_f32_e32 v102, v102, v101
	v_add_f32_e32 v100, v102, v100
	s_waitcnt vmcnt(62)
	v_lshlrev_b32_e32 v101, 16, v203
	v_mul_f32_e32 v100, v100, v101
	v_cvt_pk_bf16_f32 v103, v100, v100
	v_mad_i64_i32 v[100:101], s[28:29], s59, v178, v[4:5]
	global_store_short v[100:101], v103, off sc1
	v_lshlrev_b32_e32 v100, 16, v99
	v_and_b32_e32 v99, 0xffff0000, v99
	v_fma_f32 v100, -v102, v100, v102
	v_add_f32_e32 v100, v100, v99
	v_add_f32_e32 v98, v100, v98
	v_lshlrev_b32_e32 v99, 16, v200
	v_mul_f32_e32 v98, v98, v99
	v_cvt_pk_bf16_f32 v101, v98, v98
	v_mad_i64_i32 v[98:99], s[28:29], s58, v178, v[4:5]
	global_store_short v[98:99], v101, off sc1
	v_lshlrev_b32_e32 v98, 16, v97
	v_and_b32_e32 v97, 0xffff0000, v97
	v_fma_f32 v98, -v100, v98, v100
	v_add_f32_e32 v98, v98, v97
	v_add_f32_e32 v96, v98, v96
	s_waitcnt vmcnt(62)
	v_lshlrev_b32_e32 v97, 16, v201
	v_mul_f32_e32 v96, v96, v97
	v_cvt_pk_bf16_f32 v99, v96, v96
	v_mad_i64_i32 v[96:97], s[28:29], s57, v178, v[4:5]
	global_store_short v[96:97], v99, off sc1
	v_lshlrev_b32_e32 v96, 16, v95
	v_and_b32_e32 v95, 0xffff0000, v95
	v_fma_f32 v96, -v98, v96, v98
	v_add_f32_e32 v96, v96, v95
	v_add_f32_e32 v94, v96, v94
	v_lshlrev_b32_e32 v95, 16, v198
	v_mul_f32_e32 v94, v94, v95
	v_cvt_pk_bf16_f32 v97, v94, v94
	v_mad_i64_i32 v[94:95], s[28:29], s56, v178, v[4:5]
	global_store_short v[94:95], v97, off sc1
	v_lshlrev_b32_e32 v94, 16, v93
	v_and_b32_e32 v93, 0xffff0000, v93
	v_fma_f32 v94, -v96, v94, v96
	v_add_f32_e32 v94, v94, v93
	v_add_f32_e32 v92, v92, v94
	s_waitcnt vmcnt(62)
; __device__ __forceinline__ float bf2f(unsigned short b) { return __uint_as_float(((unsigned)b) << 16); }
; __device__ __forceinline__ unsigned cvt_pk_bf16(float lo, float hi) { unsigned r; asm volatile("v_cvt_pk_bf16_f32 %0, %1, %2" : "=v"(r) : "v"(lo), "v"(hi)); return r; }
; __device__ __forceinline__ void lru_scan(const Params& P, int l) {
;     ...
;         { float hh = hin[1];
; #pragma unroll
;             for (int p = 63; p >= 0; --p) { const float om = __uint_as_float(w[p].y << 16), bb = __uint_as_float(w[p].y & 0xffff0000u); hh = (hh - om * hh) + bb;
;                 const float yo = (hf[p] + hh) * bf2f(gar[p]); Y[(size_t)(r0 + p) * YW + c] = (bf16_t)cvt_pk_bf16(yo, yo); } }
	v_lshlrev_b32_e32 v93, 16, v199
	v_mul_f32_e32 v92, v92, v93
	v_cvt_pk_bf16_f32 v95, v92, v92
	v_mad_i64_i32 v[92:93], s[28:29], s55, v178, v[4:5]
	global_store_short v[92:93], v95, off sc1
	v_lshlrev_b32_e32 v92, 16, v91
	v_and_b32_e32 v91, 0xffff0000, v91
	v_fma_f32 v92, -v94, v92, v94
	v_add_f32_e32 v92, v92, v91
	v_add_f32_e32 v90, v90, v92
	v_lshlrev_b32_e32 v91, 16, v196
	v_mul_f32_e32 v90, v90, v91
	v_cvt_pk_bf16_f32 v93, v90, v90
	v_mad_i64_i32 v[90:91], s[28:29], s54, v178, v[4:5]
	global_store_short v[90:91], v93, off sc1
	v_lshlrev_b32_e32 v90, 16, v89
	v_and_b32_e32 v89, 0xffff0000, v89
	v_fma_f32 v90, -v92, v90, v92
	v_add_f32_e32 v90, v90, v89
	v_add_f32_e32 v88, v88, v90
	s_waitcnt vmcnt(62)
	v_lshlrev_b32_e32 v89, 16, v197
	v_mul_f32_e32 v88, v88, v89
	v_cvt_pk_bf16_f32 v91, v88, v88
	v_mad_i64_i32 v[88:89], s[28:29], s53, v178, v[4:5]
	global_store_short v[88:89], v91, off sc1
	v_lshlrev_b32_e32 v88, 16, v87
	v_and_b32_e32 v87, 0xffff0000, v87
	v_fma_f32 v88, -v90, v88, v90
	v_add_f32_e32 v88, v88, v87
	v_add_f32_e32 v86, v86, v88
	v_lshlrev_b32_e32 v87, 16, v222
	v_mul_f32_e32 v86, v86, v87
	v_cvt_pk_bf16_f32 v89, v86, v86
	v_mad_i64_i32 v[86:87], s[28:29], s50, v178, v[4:5]
	global_store_short v[86:87], v89, off sc1
	v_lshlrev_b32_e32 v86, 16, v85
	v_and_b32_e32 v85, 0xffff0000, v85
	v_fma_f32 v86, -v88, v86, v88
	v_add_f32_e32 v86, v86, v85
	v_add_f32_e32 v84, v84, v86
	s_waitcnt vmcnt(62)
	v_lshlrev_b32_e32 v85, 16, v223
	v_mul_f32_e32 v84, v84, v85
	v_cvt_pk_bf16_f32 v87, v84, v84
	v_mad_i64_i32 v[84:85], s[28:29], s47, v178, v[4:5]
	global_store_short v[84:85], v87, off sc1
	v_lshlrev_b32_e32 v84, 16, v83
	v_and_b32_e32 v83, 0xffff0000, v83
	v_fma_f32 v84, -v86, v84, v86
	v_add_f32_e32 v84, v84, v83
	v_add_f32_e32 v82, v82, v84
	v_lshlrev_b32_e32 v83, 16, v224
	v_mul_f32_e32 v82, v82, v83
	v_cvt_pk_bf16_f32 v85, v82, v82
	v_mad_i64_i32 v[82:83], s[28:29], s44, v178, v[4:5]
	global_store_short v[82:83], v85, off sc1
	v_lshlrev_b32_e32 v82, 16, v81
	v_and_b32_e32 v81, 0xffff0000, v81
	v_fma_f32 v82, -v84, v82, v84
	v_add_f32_e32 v82, v82, v81
	v_add_f32_e32 v80, v80, v82
	s_waitcnt vmcnt(62)
	v_lshlrev_b32_e32 v81, 16, v225
	v_mul_f32_e32 v80, v80, v81
	v_cvt_pk_bf16_f32 v83, v80, v80
	v_mad_i64_i32 v[80:81], s[28:29], s41, v178, v[4:5]
	global_store_short v[80:81], v83, off sc1
	v_lshlrev_b32_e32 v80, 16, v79
	v_and_b32_e32 v79, 0xffff0000, v79
	v_fma_f32 v80, -v82, v80, v82
	v_add_f32_e32 v80, v80, v79
	v_add_f32_e32 v78, v78, v80
	v_lshlrev_b32_e32 v79, 16, v193
	v_mul_f32_e32 v78, v78, v79
	v_cvt_pk_bf16_f32 v81, v78, v78
	v_mad_i64_i32 v[78:79], s[28:29], s39, v178, v[4:5]
	global_store_short v[78:79], v81, off sc1
	v_lshlrev_b32_e32 v78, 16, v77
	v_and_b32_e32 v77, 0xffff0000, v77
	v_fma_f32 v78, -v80, v78, v80
	v_add_f32_e32 v78, v78, v77
	v_add_f32_e32 v76, v76, v78
	s_waitcnt vmcnt(62)
	v_lshlrev_b32_e32 v77, 16, v192
	v_mul_f32_e32 v76, v76, v77
	v_cvt_pk_bf16_f32 v79, v76, v76
	v_mad_i64_i32 v[76:77], s[28:29], s31, v178, v[4:5]
	global_store_short v[76:77], v79, off sc1
	v_lshlrev_b32_e32 v76, 16, v75
	v_and_b32_e32 v75, 0xffff0000, v75
	v_fma_f32 v76, -v78, v76, v78
	v_add_f32_e32 v76, v76, v75
	v_add_f32_e32 v74, v74, v76
	v_lshlrev_b32_e32 v75, 16, v189
	v_mul_f32_e32 v74, v74, v75
	v_cvt_pk_bf16_f32 v77, v74, v74
	v_mad_i64_i32 v[74:75], s[28:29], s27, v178, v[4:5]
	global_store_short v[74:75], v77, off sc1
	v_lshlrev_b32_e32 v74, 16, v73
	v_and_b32_e32 v73, 0xffff0000, v73
	v_fma_f32 v74, -v76, v74, v76
	v_add_f32_e32 v74, v74, v73
	v_add_f32_e32 v72, v72, v74
	s_waitcnt vmcnt(62)
	v_lshlrev_b32_e32 v73, 16, v191
	v_mul_f32_e32 v72, v72, v73
	v_cvt_pk_bf16_f32 v75, v72, v72
	v_mad_i64_i32 v[72:73], s[28:29], s21, v178, v[4:5]
	global_store_short v[72:73], v75, off sc1
	v_lshlrev_b32_e32 v72, 16, v71
	v_and_b32_e32 v71, 0xffff0000, v71
	v_fma_f32 v72, -v74, v72, v74
	v_add_f32_e32 v72, v72, v71
	v_add_f32_e32 v70, v70, v72
	v_lshlrev_b32_e32 v71, 16, v188
	v_mul_f32_e32 v70, v70, v71
	v_cvt_pk_bf16_f32 v73, v70, v70
	v_mad_i64_i32 v[70:71], s[28:29], s17, v178, v[4:5]
	global_store_short v[70:71], v73, off sc1
	v_lshlrev_b32_e32 v70, 16, v69
	v_and_b32_e32 v69, 0xffff0000, v69
	v_fma_f32 v70, -v72, v70, v72
	v_add_f32_e32 v70, v70, v69
	v_add_f32_e32 v68, v68, v70
	s_waitcnt vmcnt(62)
	v_lshlrev_b32_e32 v69, 16, v187
	v_mul_f32_e32 v68, v68, v69
	v_cvt_pk_bf16_f32 v71, v68, v68
	v_mad_i64_i32 v[68:69], s[16:17], s16, v178, v[4:5]
	global_store_short v[68:69], v71, off sc1
	v_lshlrev_b32_e32 v68, 16, v67
	v_and_b32_e32 v67, 0xffff0000, v67
	v_fma_f32 v68, -v70, v68, v70
	v_add_f32_e32 v68, v68, v67
	v_add_f32_e32 v66, v66, v68
	v_lshlrev_b32_e32 v67, 16, v185
	v_mul_f32_e32 v66, v66, v67
	v_cvt_pk_bf16_f32 v69, v66, v66
	v_mad_i64_i32 v[66:67], s[16:17], s15, v178, v[4:5]
	global_store_short v[66:67], v69, off sc1
	v_lshlrev_b32_e32 v66, 16, v65
	v_and_b32_e32 v65, 0xffff0000, v65
	v_fma_f32 v66, -v68, v66, v68
	v_add_f32_e32 v66, v66, v65
	v_add_f32_e32 v64, v64, v66
	s_waitcnt vmcnt(62)
	v_lshlrev_b32_e32 v65, 16, v184
	v_mul_f32_e32 v64, v64, v65
	v_cvt_pk_bf16_f32 v67, v64, v64
	v_mad_i64_i32 v[64:65], s[14:15], s14, v178, v[4:5]
	global_store_short v[64:65], v67, off sc1
	v_lshlrev_b32_e32 v64, 16, v63
	v_and_b32_e32 v63, 0xffff0000, v63
	v_fma_f32 v64, -v66, v64, v66
	v_add_f32_e32 v64, v64, v63
	v_add_f32_e32 v62, v62, v64
	v_lshlrev_b32_e32 v63, 16, v166
	v_mul_f32_e32 v62, v62, v63
	v_cvt_pk_bf16_f32 v65, v62, v62
	v_mad_i64_i32 v[62:63], s[14:15], s13, v178, v[4:5]
	global_store_short v[62:63], v65, off sc1
	v_lshlrev_b32_e32 v62, 16, v61
	v_and_b32_e32 v61, 0xffff0000, v61
	v_fma_f32 v62, -v64, v62, v64
	v_add_f32_e32 v62, v62, v61
	v_add_f32_e32 v60, v60, v62
	s_waitcnt vmcnt(62)
; __device__ __forceinline__ float bf2f(unsigned short b) { return __uint_as_float(((unsigned)b) << 16); }
; __device__ __forceinline__ unsigned cvt_pk_bf16(float lo, float hi) { unsigned r; asm volatile("v_cvt_pk_bf16_f32 %0, %1, %2" : "=v"(r) : "v"(lo), "v"(hi)); return r; }
; __device__ __forceinline__ void lru_scan(const Params& P, int l) {
;     ...
;         { float hh = hin[1];
; #pragma unroll
;             for (int p = 63; p >= 0; --p) { const float om = __uint_as_float(w[p].y << 16), bb = __uint_as_float(w[p].y & 0xffff0000u); hh = (hh - om * hh) + bb;
;                 const float yo = (hf[p] + hh) * bf2f(gar[p]); Y[(size_t)(r0 + p) * YW + c] = (bf16_t)cvt_pk_bf16(yo, yo); } }
	v_lshlrev_b32_e32 v61, 16, v165
	v_mul_f32_e32 v60, v60, v61
	v_cvt_pk_bf16_f32 v63, v60, v60
	v_mad_i64_i32 v[60:61], s[12:13], s12, v178, v[4:5]
	global_store_short v[60:61], v63, off sc1
	v_lshlrev_b32_e32 v60, 16, v59
	v_and_b32_e32 v59, 0xffff0000, v59
	v_fma_f32 v60, -v62, v60, v62
	v_add_f32_e32 v60, v60, v59
	v_add_f32_e32 v58, v58, v60
	v_lshlrev_b32_e32 v59, 16, v154
	v_mul_f32_e32 v58, v58, v59
	v_cvt_pk_bf16_f32 v61, v58, v58
	v_mad_i64_i32 v[58:59], s[12:13], s11, v178, v[4:5]
	global_store_short v[58:59], v61, off sc1
	v_lshlrev_b32_e32 v58, 16, v57
	v_and_b32_e32 v57, 0xffff0000, v57
	v_fma_f32 v58, -v60, v58, v60
	v_add_f32_e32 v58, v58, v57
	v_add_f32_e32 v56, v56, v58
	s_waitcnt vmcnt(62)
	v_lshlrev_b32_e32 v57, 16, v164
	v_mul_f32_e32 v56, v56, v57
	v_cvt_pk_bf16_f32 v59, v56, v56
	v_mad_i64_i32 v[56:57], s[10:11], s10, v178, v[4:5]
	global_store_short v[56:57], v59, off sc1
	v_lshlrev_b32_e32 v56, 16, v55
	v_and_b32_e32 v55, 0xffff0000, v55
	v_fma_f32 v56, -v58, v56, v58
	v_add_f32_e32 v56, v56, v55
	v_add_f32_e32 v54, v54, v56
	v_lshlrev_b32_e32 v55, 16, v153
	v_mul_f32_e32 v54, v54, v55
	v_cvt_pk_bf16_f32 v57, v54, v54
	v_mad_i64_i32 v[54:55], s[10:11], s9, v178, v[4:5]
	global_store_short v[54:55], v57, off sc1
	v_lshlrev_b32_e32 v54, 16, v53
	v_and_b32_e32 v53, 0xffff0000, v53
	v_fma_f32 v54, -v56, v54, v56
	v_add_f32_e32 v54, v54, v53
	v_add_f32_e32 v52, v52, v54
	s_waitcnt vmcnt(62)
	v_lshlrev_b32_e32 v53, 16, v152
	v_mul_f32_e32 v52, v52, v53
	v_cvt_pk_bf16_f32 v55, v52, v52
	v_mad_i64_i32 v[52:53], s[8:9], s8, v178, v[4:5]
	global_store_short v[52:53], v55, off sc1
	v_lshlrev_b32_e32 v52, 16, v51
	v_and_b32_e32 v51, 0xffff0000, v51
	v_fma_f32 v52, -v54, v52, v54
	v_add_f32_e32 v52, v52, v51
	v_add_f32_e32 v50, v50, v52
	v_lshlrev_b32_e32 v51, 16, v151
	v_mul_f32_e32 v50, v50, v51
	v_cvt_pk_bf16_f32 v53, v50, v50
	v_mad_i64_i32 v[50:51], s[8:9], s5, v178, v[4:5]
	global_store_short v[50:51], v53, off sc1
	v_lshlrev_b32_e32 v50, 16, v49
	v_and_b32_e32 v49, 0xffff0000, v49
	v_fma_f32 v50, -v52, v50, v52
	v_add_f32_e32 v50, v50, v49
	v_add_f32_e32 v48, v48, v50
	s_waitcnt vmcnt(62)
	v_lshlrev_b32_e32 v49, 16, v150
	v_mul_f32_e32 v48, v48, v49
	v_cvt_pk_bf16_f32 v51, v48, v48
	v_mad_i64_i32 v[48:49], s[4:5], s4, v178, v[4:5]
	global_store_short v[48:49], v51, off sc1
	v_lshlrev_b32_e32 v48, 16, v47
	v_and_b32_e32 v47, 0xffff0000, v47
	v_fma_f32 v48, -v50, v48, v50
	v_add_f32_e32 v48, v48, v47
	v_add_f32_e32 v46, v46, v48
	v_lshlrev_b32_e32 v47, 16, v149
	v_mul_f32_e32 v46, v46, v47
	v_cvt_pk_bf16_f32 v49, v46, v46
	v_mad_i64_i32 v[46:47], s[4:5], s3, v178, v[4:5]
	global_store_short v[46:47], v49, off sc1
	v_lshlrev_b32_e32 v46, 16, v45
	v_and_b32_e32 v45, 0xffff0000, v45
	v_fma_f32 v46, -v48, v46, v48
	v_add_f32_e32 v46, v46, v45
	v_add_f32_e32 v44, v44, v46
	s_waitcnt vmcnt(62)
	v_lshlrev_b32_e32 v45, 16, v148
	v_mul_f32_e32 v44, v44, v45
	v_cvt_pk_bf16_f32 v47, v44, v44
	v_mad_i64_i32 v[44:45], s[2:3], s2, v178, v[4:5]
	global_store_short v[44:45], v47, off sc1
	v_lshlrev_b32_e32 v44, 16, v43
	v_and_b32_e32 v43, 0xffff0000, v43
	v_fma_f32 v44, -v46, v44, v46
	v_add_f32_e32 v44, v44, v43
	v_add_f32_e32 v42, v42, v44
	v_lshlrev_b32_e32 v43, 16, v146
	v_mul_f32_e32 v42, v42, v43
	v_cvt_pk_bf16_f32 v45, v42, v42
	v_mad_i64_i32 v[42:43], s[2:3], s1, v178, v[4:5]
	global_store_short v[42:43], v45, off sc1
	v_lshlrev_b32_e32 v42, 16, v41
	v_and_b32_e32 v41, 0xffff0000, v41
	v_fma_f32 v42, -v44, v42, v44
	v_add_f32_e32 v42, v42, v41
	v_add_f32_e32 v40, v40, v42
	s_waitcnt vmcnt(62)
	v_lshlrev_b32_e32 v41, 16, v147
	v_mul_f32_e32 v40, v40, v41
	v_cvt_pk_bf16_f32 v43, v40, v40
	v_mad_i64_i32 v[40:41], s[0:1], s0, v178, v[4:5]
	global_store_short v[40:41], v43, off sc1
	v_lshlrev_b32_e32 v40, 16, v39
	v_and_b32_e32 v39, 0xffff0000, v39
	v_fma_f32 v40, -v42, v40, v42
	v_add_f32_e32 v40, v40, v39
	v_add_f32_e32 v38, v38, v40
	v_lshlrev_b32_e32 v39, 16, v145
	v_mul_f32_e32 v38, v38, v39
	v_cvt_pk_bf16_f32 v41, v38, v38
	v_mad_i64_i32 v[38:39], s[0:1], s52, v178, v[4:5]
	global_store_short v[38:39], v41, off sc1
	v_lshlrev_b32_e32 v38, 16, v37
	v_and_b32_e32 v37, 0xffff0000, v37
	v_fma_f32 v38, -v40, v38, v40
	v_add_f32_e32 v38, v38, v37
	v_add_f32_e32 v36, v36, v38
	s_waitcnt vmcnt(62)
	v_lshlrev_b32_e32 v37, 16, v144
	v_mul_f32_e32 v36, v36, v37
	v_cvt_pk_bf16_f32 v39, v36, v36
	v_mad_i64_i32 v[36:37], s[0:1], s51, v178, v[4:5]
	global_store_short v[36:37], v39, off sc1
	v_lshlrev_b32_e32 v36, 16, v35
	v_and_b32_e32 v35, 0xffff0000, v35
	v_fma_f32 v36, -v38, v36, v38
	v_add_f32_e32 v36, v36, v35
	v_add_f32_e32 v34, v34, v36
	v_lshlrev_b32_e32 v35, 16, v142
	v_mul_f32_e32 v34, v34, v35
	v_cvt_pk_bf16_f32 v37, v34, v34
	v_mad_i64_i32 v[34:35], s[0:1], s49, v178, v[4:5]
	global_store_short v[34:35], v37, off sc1
	v_lshlrev_b32_e32 v34, 16, v33
	v_and_b32_e32 v33, 0xffff0000, v33
	v_fma_f32 v34, -v36, v34, v36
	v_add_f32_e32 v34, v34, v33
	v_add_f32_e32 v32, v32, v34
	s_waitcnt vmcnt(62)
	v_lshlrev_b32_e32 v33, 16, v140
	v_mul_f32_e32 v32, v32, v33
	v_cvt_pk_bf16_f32 v35, v32, v32
	v_mad_i64_i32 v[32:33], s[0:1], s48, v178, v[4:5]
	global_store_short v[32:33], v35, off sc1
	v_lshlrev_b32_e32 v32, 16, v31
	v_and_b32_e32 v31, 0xffff0000, v31
	v_fma_f32 v32, -v34, v32, v34
	v_add_f32_e32 v32, v32, v31
	v_add_f32_e32 v30, v30, v32
	v_lshlrev_b32_e32 v31, 16, v138
	v_mul_f32_e32 v30, v30, v31
	v_cvt_pk_bf16_f32 v33, v30, v30
	v_mad_i64_i32 v[30:31], s[0:1], s46, v178, v[4:5]
	global_store_short v[30:31], v33, off sc1
	v_lshlrev_b32_e32 v30, 16, v29
	v_and_b32_e32 v29, 0xffff0000, v29
	v_fma_f32 v30, -v32, v30, v32
	v_add_f32_e32 v30, v30, v29
	v_add_f32_e32 v28, v28, v30
	s_waitcnt vmcnt(62)
; __device__ __forceinline__ float bf2f(unsigned short b) { return __uint_as_float(((unsigned)b) << 16); }
; __device__ __forceinline__ unsigned cvt_pk_bf16(float lo, float hi) { unsigned r; asm volatile("v_cvt_pk_bf16_f32 %0, %1, %2" : "=v"(r) : "v"(lo), "v"(hi)); return r; }
; __device__ __forceinline__ void lru_scan(const Params& P, int l) {
;     ...
;         { float hh = hin[1];
; #pragma unroll
;             for (int p = 63; p >= 0; --p) { const float om = __uint_as_float(w[p].y << 16), bb = __uint_as_float(w[p].y & 0xffff0000u); hh = (hh - om * hh) + bb;
;                 const float yo = (hf[p] + hh) * bf2f(gar[p]); Y[(size_t)(r0 + p) * YW + c] = (bf16_t)cvt_pk_bf16(yo, yo); } }
;     }
	v_lshlrev_b32_e32 v29, 16, v126
	v_mul_f32_e32 v28, v28, v29
	v_cvt_pk_bf16_f32 v31, v28, v28
	v_mad_i64_i32 v[28:29], s[0:1], s45, v178, v[4:5]
	global_store_short v[28:29], v31, off sc1
	v_lshlrev_b32_e32 v28, 16, v27
	v_and_b32_e32 v27, 0xffff0000, v27
	v_fma_f32 v28, -v30, v28, v30
	v_add_f32_e32 v28, v28, v27
	v_add_f32_e32 v26, v26, v28
	v_lshlrev_b32_e32 v27, 16, v124
	v_mul_f32_e32 v26, v26, v27
	v_cvt_pk_bf16_f32 v29, v26, v26
	v_mad_i64_i32 v[26:27], s[0:1], s43, v178, v[4:5]
	global_store_short v[26:27], v29, off sc1
	v_lshlrev_b32_e32 v26, 16, v25
	v_and_b32_e32 v25, 0xffff0000, v25
	v_fma_f32 v26, -v28, v26, v28
	v_add_f32_e32 v26, v26, v25
	v_add_f32_e32 v24, v24, v26
	s_waitcnt vmcnt(62)
	v_lshlrev_b32_e32 v25, 16, v122
	v_mul_f32_e32 v24, v24, v25
	v_cvt_pk_bf16_f32 v27, v24, v24
	v_mad_i64_i32 v[24:25], s[0:1], s42, v178, v[4:5]
	global_store_short v[24:25], v27, off sc1
	v_lshlrev_b32_e32 v24, 16, v23
	v_and_b32_e32 v23, 0xffff0000, v23
	v_fma_f32 v24, -v26, v24, v26
	v_add_f32_e32 v24, v24, v23
	v_add_f32_e32 v22, v22, v24
	v_lshlrev_b32_e32 v23, 16, v120
	v_mul_f32_e32 v22, v22, v23
	v_cvt_pk_bf16_f32 v25, v22, v22
	v_mad_i64_i32 v[22:23], s[0:1], s40, v178, v[4:5]
	global_store_short v[22:23], v25, off sc1
	v_lshlrev_b32_e32 v22, 16, v21
	v_and_b32_e32 v21, 0xffff0000, v21
	v_fma_f32 v22, -v24, v22, v24
	v_add_f32_e32 v22, v22, v21
	v_add_f32_e32 v20, v20, v22
	s_waitcnt vmcnt(62)
	v_lshlrev_b32_e32 v21, 16, v118
	v_mul_f32_e32 v20, v20, v21
	v_cvt_pk_bf16_f32 v23, v20, v20
	v_mad_i64_i32 v[20:21], s[0:1], s35, v178, v[4:5]
	global_store_short v[20:21], v23, off sc1
	v_lshlrev_b32_e32 v20, 16, v19
	v_and_b32_e32 v19, 0xffff0000, v19
	v_fma_f32 v20, -v22, v20, v22
	v_add_f32_e32 v20, v20, v19
	v_add_f32_e32 v18, v18, v20
	v_lshlrev_b32_e32 v19, 16, v116
	v_mul_f32_e32 v18, v18, v19
	v_cvt_pk_bf16_f32 v21, v18, v18
	v_mad_i64_i32 v[18:19], s[0:1], s34, v178, v[4:5]
	global_store_short v[18:19], v21, off sc1
	v_lshlrev_b32_e32 v18, 16, v17
	v_and_b32_e32 v17, 0xffff0000, v17
	v_fma_f32 v18, -v20, v18, v20
	v_add_f32_e32 v18, v18, v17
	v_add_f32_e32 v16, v16, v18
	s_waitcnt vmcnt(62)
	v_lshlrev_b32_e32 v17, 16, v114
	v_mul_f32_e32 v16, v16, v17
	v_cvt_pk_bf16_f32 v19, v16, v16
	v_mad_i64_i32 v[16:17], s[0:1], s30, v178, v[4:5]
	global_store_short v[16:17], v19, off sc1
	v_lshlrev_b32_e32 v16, 16, v15
	v_and_b32_e32 v15, 0xffff0000, v15
	v_fma_f32 v16, -v18, v16, v18
	v_add_f32_e32 v16, v16, v15
	v_add_f32_e32 v14, v14, v16
	v_lshlrev_b32_e32 v15, 16, v112
	v_mul_f32_e32 v14, v14, v15
	v_cvt_pk_bf16_f32 v17, v14, v14
	v_mad_i64_i32 v[14:15], s[0:1], s26, v178, v[4:5]
	global_store_short v[14:15], v17, off sc1
	v_lshlrev_b32_e32 v14, 16, v13
	v_and_b32_e32 v13, 0xffff0000, v13
	v_fma_f32 v14, -v16, v14, v16
	v_add_f32_e32 v14, v14, v13
	v_add_f32_e32 v12, v12, v14
	s_waitcnt vmcnt(62)
	v_lshlrev_b32_e32 v13, 16, v110
	v_mul_f32_e32 v12, v12, v13
	v_cvt_pk_bf16_f32 v15, v12, v12
	v_mad_i64_i32 v[12:13], s[0:1], s25, v178, v[4:5]
	global_store_short v[12:13], v15, off sc1
	v_lshlrev_b32_e32 v12, 16, v11
	v_and_b32_e32 v11, 0xffff0000, v11
	v_fma_f32 v12, -v14, v12, v14
	v_add_f32_e32 v12, v12, v11
	v_add_f32_e32 v10, v10, v12
	v_lshlrev_b32_e32 v11, 16, v108
	v_mul_f32_e32 v10, v10, v11
	v_cvt_pk_bf16_f32 v13, v10, v10
	v_mad_i64_i32 v[10:11], s[0:1], s19, v178, v[4:5]
	global_store_short v[10:11], v13, off sc1
	v_lshlrev_b32_e32 v10, 16, v9
	v_and_b32_e32 v9, 0xffff0000, v9
	v_fma_f32 v10, -v12, v10, v12
	v_add_f32_e32 v9, v10, v9
	v_add_f32_e32 v8, v8, v9
	s_waitcnt vmcnt(62)
	v_lshlrev_b32_e32 v9, 16, v106
	v_mul_f32_e32 v8, v8, v9
	v_readlane_b32 s64, v254, 2
	v_readlane_b32 s90, v254, 30
	v_cvt_pk_bf16_f32 v10, v8, v8
	v_mad_i64_i32 v[8:9], s[0:1], s38, v178, v[4:5]
	v_readlane_b32 s17, v255, 37
	v_readlane_b32 s74, v254, 12
	v_readlane_b32 s75, v254, 13
	v_readlane_b32 s88, v254, 24
	v_readlane_b32 s92, v254, 26
	s_add_i32 s17, s17, s90
	v_readlane_b32 s0, v254, 58
	v_readlane_b32 s65, v254, 3
	v_readlane_b32 s30, v254, 34
	v_readlane_b32 s28, v254, 18
	v_readlane_b32 s34, v254, 20
	v_readlane_b32 s60, v254, 22
	v_readlane_b32 s74, v255, 34
	v_readlane_b32 s26, v255, 32
	v_readlane_b32 s89, v254, 25
	v_readlane_b32 s93, v254, 27
	v_readlane_b32 s94, v254, 28
	v_readlane_b32 s95, v254, 29
	v_readlane_b32 s96, v254, 32
	s_cmp_ge_i32 s17, s0
	v_readlane_b32 s76, v254, 14
	v_readlane_b32 s77, v254, 15
	v_readlane_b32 s31, v254, 35
	v_readlane_b32 s29, v254, 19
	v_readlane_b32 s35, v254, 21
	v_readlane_b32 s61, v254, 23
	s_mov_b32 s25, 0x8000
	s_movk_i32 s19, 0x7fff
	v_readlane_b32 s75, v255, 35
	s_mov_b64 s[64:65], 0x800
	v_readlane_b32 s27, v255, 33
	v_readlane_b32 s91, v254, 31
	v_readlane_b32 s97, v254, 33
	global_store_short v[8:9], v10, off sc1
	v_readlane_b32 s66, v254, 4
	v_readlane_b32 s67, v254, 5
	v_readlane_b32 s68, v254, 6
	v_readlane_b32 s69, v254, 7
	v_readlane_b32 s70, v254, 8
	v_readlane_b32 s71, v254, 9
	v_readlane_b32 s72, v254, 10
	v_readlane_b32 s73, v254, 11
	v_readlane_b32 s78, v254, 16
	v_readlane_b32 s79, v254, 17
	s_cbranch_scc1 .LBB0_716

; #define GAS __attribute__((address_space(1)))
;     __device__ __forceinline__ void operator()(const f32x4 (&acc)[2][2][4][2], const Unit& u, int wr, int wc, int fr, int fq) const {
;     ...
;         if (u.kind >= 2) {
; #pragma unroll
;             for (int bj = 0; bj < 2; ++bj)
; #pragma unroll
;                 for (int n = 0; n < 2; ++n) { const f32x4 gv = *(const GAS f32x4*)(gp + bj * HALF + n * 16) * mul;
; #pragma unroll
;                     for (int ai = 0; ai < 2; ++ai)
; #pragma unroll
;                         for (int m = 0; m < 4; ++m) *(GAS f32x4*)(row0 + (size_t)(ai * HALF + m * 16) * 1024 + bj * HALF + n * 16) = gv * acc[ai][bj][m][n]; }
;             return; }
.LBB0_823:
	global_load_dwordx4 v[150:153], v[148:149], off
	s_waitcnt vmcnt(0)
	v_pk_mul_f32 v[126:127], v[126:127], v[152:153]
	v_pk_mul_f32 v[124:125], v[124:125], v[150:151]
	global_store_dwordx4 v[146:147], v[124:127], off sc1
	s_nop 1
	v_pk_mul_f32 v[124:125], v[122:123], v[152:153]
	v_pk_mul_f32 v[122:123], v[120:121], v[150:151]
	v_add_co_u32_e32 v120, vcc, 0x10000, v146
	s_nop 1
	v_addc_co_u32_e32 v121, vcc, 0, v147, vcc
	global_store_dwordx4 v[120:121], v[122:125], off sc1
	s_nop 1
	v_pk_mul_f32 v[122:123], v[116:117], v[150:151]
	v_add_co_u32_e32 v116, vcc, s19, v146
	v_pk_mul_f32 v[124:125], v[118:119], v[152:153]
	s_nop 0
	v_addc_co_u32_e32 v117, vcc, 0, v147, vcc
	global_store_dwordx4 v[116:117], v[122:125], off sc1
	s_nop 1
	v_pk_mul_f32 v[122:123], v[112:113], v[150:151]
	v_add_co_u32_e32 v112, vcc, s65, v146
	v_pk_mul_f32 v[124:125], v[114:115], v[152:153]
	s_nop 0
	v_addc_co_u32_e32 v113, vcc, 0, v147, vcc
	global_store_dwordx4 v[112:113], v[122:125], off sc1
	s_nop 1
	v_pk_mul_f32 v[122:123], v[108:109], v[150:151]
	v_add_co_u32_e32 v108, vcc, s66, v146
	v_pk_mul_f32 v[124:125], v[110:111], v[152:153]
	s_nop 0
	v_addc_co_u32_e32 v109, vcc, 0, v147, vcc
	global_store_dwordx4 v[108:109], v[122:125], off sc1
	s_nop 1
	v_pk_mul_f32 v[122:123], v[104:105], v[150:151]
	v_add_co_u32_e32 v104, vcc, s67, v146
	v_pk_mul_f32 v[124:125], v[106:107], v[152:153]
	s_nop 0
	v_addc_co_u32_e32 v105, vcc, 0, v147, vcc
	global_store_dwordx4 v[104:105], v[122:125], off sc1
	s_nop 1
	v_pk_mul_f32 v[122:123], v[100:101], v[150:151]
	v_add_co_u32_e32 v100, vcc, s21, v146
	v_pk_mul_f32 v[124:125], v[102:103], v[152:153]
	s_nop 0
	v_addc_co_u32_e32 v101, vcc, 0, v147, vcc
	global_store_dwordx4 v[100:101], v[122:125], off sc1
	s_nop 1
	v_pk_mul_f32 v[122:123], v[96:97], v[150:151]
	v_add_co_u32_e32 v96, vcc, s68, v146
	v_pk_mul_f32 v[124:125], v[98:99], v[152:153]
	s_nop 0
	v_addc_co_u32_e32 v97, vcc, 0, v147, vcc
	global_store_dwordx4 v[96:97], v[122:125], off sc1
	global_load_dwordx4 v[122:125], v[148:149], off offset:64
	s_waitcnt vmcnt(0)
	v_pk_mul_f32 v[94:95], v[94:95], v[124:125]
	v_pk_mul_f32 v[92:93], v[92:93], v[122:123]
	v_pk_mul_f32 v[90:91], v[90:91], v[124:125]
	v_pk_mul_f32 v[88:89], v[88:89], v[122:123]
	v_pk_mul_f32 v[86:87], v[86:87], v[124:125]
	v_pk_mul_f32 v[84:85], v[84:85], v[122:123]
	v_pk_mul_f32 v[82:83], v[82:83], v[124:125]
	v_pk_mul_f32 v[80:81], v[80:81], v[122:123]
	v_pk_mul_f32 v[78:79], v[78:79], v[124:125]
	v_pk_mul_f32 v[76:77], v[76:77], v[122:123]
	v_pk_mul_f32 v[74:75], v[74:75], v[124:125]
	v_pk_mul_f32 v[72:73], v[72:73], v[122:123]
	v_pk_mul_f32 v[70:71], v[70:71], v[124:125]
	v_pk_mul_f32 v[68:69], v[68:69], v[122:123]
	v_pk_mul_f32 v[62:63], v[62:63], v[124:125]
	v_pk_mul_f32 v[60:61], v[60:61], v[122:123]
	global_store_dwordx4 v[146:147], v[92:95], off offset:64 sc1
	global_store_dwordx4 v[120:121], v[88:91], off offset:64 sc1
	global_store_dwordx4 v[116:117], v[84:87], off offset:64 sc1
	global_store_dwordx4 v[112:113], v[80:83], off offset:64 sc1
	global_store_dwordx4 v[108:109], v[76:79], off offset:64 sc1
	global_store_dwordx4 v[104:105], v[72:75], off offset:64 sc1
	global_store_dwordx4 v[100:101], v[68:71], off offset:64 sc1
	global_store_dwordx4 v[96:97], v[60:63], off offset:64 sc1
	global_load_dwordx4 v[60:63], v[148:149], off offset:512
	s_waitcnt vmcnt(0)
	v_pk_mul_f32 v[66:67], v[66:67], v[62:63]
	v_pk_mul_f32 v[64:65], v[64:65], v[60:61]
	v_pk_mul_f32 v[58:59], v[58:59], v[62:63]
	v_pk_mul_f32 v[56:57], v[56:57], v[60:61]
	v_pk_mul_f32 v[54:55], v[54:55], v[62:63]
	v_pk_mul_f32 v[52:53], v[52:53], v[60:61]
	v_pk_mul_f32 v[50:51], v[50:51], v[62:63]
	v_pk_mul_f32 v[48:49], v[48:49], v[60:61]
	v_pk_mul_f32 v[46:47], v[46:47], v[62:63]
	v_pk_mul_f32 v[44:45], v[44:45], v[60:61]
	v_pk_mul_f32 v[38:39], v[38:39], v[62:63]
	v_pk_mul_f32 v[36:37], v[36:37], v[60:61]
	v_pk_mul_f32 v[30:31], v[30:31], v[62:63]
	v_pk_mul_f32 v[28:29], v[28:29], v[60:61]
	v_pk_mul_f32 v[22:23], v[22:23], v[62:63]
	v_pk_mul_f32 v[20:21], v[20:21], v[60:61]
	global_store_dwordx4 v[146:147], v[64:67], off offset:512 sc1
	global_store_dwordx4 v[120:121], v[56:59], off offset:512 sc1
	global_store_dwordx4 v[116:117], v[52:55], off offset:512 sc1
	global_store_dwordx4 v[112:113], v[48:51], off offset:512 sc1
	global_store_dwordx4 v[108:109], v[44:47], off offset:512 sc1
	global_store_dwordx4 v[104:105], v[36:39], off offset:512 sc1
	global_store_dwordx4 v[100:101], v[28:31], off offset:512 sc1
	global_store_dwordx4 v[96:97], v[20:23], off offset:512 sc1
	global_load_dwordx4 v[20:23], v[148:149], off offset:576
	s_waitcnt vmcnt(0)
	v_pk_mul_f32 v[30:31], v[42:43], v[22:23]
	v_pk_mul_f32 v[28:29], v[40:41], v[20:21]
	global_store_dwordx4 v[146:147], v[28:31], off offset:576 sc1
	v_pk_mul_f32 v[26:27], v[26:27], v[22:23]
	v_pk_mul_f32 v[24:25], v[24:25], v[20:21]
	v_pk_mul_f32 v[30:31], v[34:35], v[22:23]
	v_pk_mul_f32 v[28:29], v[32:33], v[20:21]
	v_pk_mul_f32 v[18:19], v[18:19], v[22:23]
	v_pk_mul_f32 v[16:17], v[16:17], v[20:21]
	v_pk_mul_f32 v[14:15], v[14:15], v[22:23]
	v_pk_mul_f32 v[12:13], v[12:13], v[20:21]
	v_pk_mul_f32 v[10:11], v[10:11], v[22:23]
	v_pk_mul_f32 v[8:9], v[8:9], v[20:21]
	v_pk_mul_f32 v[6:7], v[6:7], v[22:23]
	v_pk_mul_f32 v[4:5], v[4:5], v[20:21]
	v_pk_mul_f32 v[2:3], v[2:3], v[22:23]
	v_pk_mul_f32 v[0:1], v[0:1], v[20:21]
	global_store_dwordx4 v[120:121], v[28:31], off offset:576 sc1
	global_store_dwordx4 v[116:117], v[24:27], off offset:576 sc1
	global_store_dwordx4 v[112:113], v[16:19], off offset:576 sc1
	global_store_dwordx4 v[108:109], v[12:15], off offset:576 sc1
	global_store_dwordx4 v[104:105], v[8:11], off offset:576 sc1
	global_store_dwordx4 v[100:101], v[4:7], off offset:576 sc1
	global_store_dwordx4 v[96:97], v[0:3], off offset:576 sc1
	s_andn2_b64 vcc, exec, s[46:47]
	s_mov_b64 s[8:9], -1
	s_cbranch_vccnz .LBB0_792

; #define GAS __attribute__((address_space(1)))
; __device__ __forceinline__ unsigned cvt_pk_bf16(float lo, float hi) { unsigned r; asm volatile("v_cvt_pk_bf16_f32 %0, %1, %2" : "=v"(r) : "v"(lo), "v"(hi)); return r; }
; __device__ __forceinline__ void phase_norm(const Params& P, int l, int sub, int addpart) {
;     ...
;         float ss = 0.f;
; #pragma unroll
;         for (int j = 0; j < 4; ++j) ss += (v[j].x * v[j].x + v[j].y * v[j].y) + (v[j].z * v[j].z + v[j].w * v[j].w);
;         const float rstd = 1.0f / sqrtf(wave_sum(ss) * (1.0f / 1024.0f) + 1e-6f);
; #pragma unroll
;         for (int j = 0; j < 4; ++j) { const f32x4 y = v[j] * rstd * gg[j] * (sc[j] + 1.0f) + sh[j];
;             u32x2 w; w.x = cvt_pk_bf16(y.x, y.y); w.y = cvt_pk_bf16(y.z, y.w); *(GAS u32x2*)((GAS bf16_t*)XN + (size_t)r * 1024 + 4 * lane + 256 * j) = w; }
;         if (rn < rend) {
; #pragma unroll
;             for (int j = 0; j < 4; ++j) { v[j] = vn[j]; sc[j] = scn[j]; sh[j] = shn[j]; } }
.LBB0_888:
	s_or_b64 exec, exec, s[38:39]
	v_mov_b32_e32 v142, v58
	v_mov_b32_e32 v143, v56
	v_mov_b32_e32 v150, v59
	v_mov_b32_e32 v151, v57
	v_pk_mul_f32 v[142:143], v[142:143], v[142:143]
	v_pk_mul_f32 v[152:153], v[140:141], v[140:141]
	v_pk_fma_f32 v[142:143], v[150:151], v[150:151], v[142:143]
	v_pk_fma_f32 v[152:153], v[60:61], v[60:61], v[152:153]
	v_pk_add_f32 v[142:143], v[142:143], v[142:143] op_sel_hi:[0,1]
	v_pk_add_f32 v[152:153], v[152:153], v[152:153] op_sel_hi:[0,1]
	v_mul_f32_e32 v142, v52, v52
	v_mul_f32_e32 v155, v54, v54
	v_mul_f32_e32 v63, v55, v55
	v_mov_b32_e32 v154, v62
	v_pk_fma_f32 v[150:151], v[52:53], v[52:53], v[142:143] op_sel_hi:[1,1,0]
	v_mul_f32_e32 v152, v48, v48
	v_mul_f32_e32 v142, v49, v49
	v_pk_add_f32 v[154:155], v[62:63], v[154:155]
	v_mul_f32_e32 v150, v50, v50
	v_pk_add_f32 v[142:143], v[142:143], v[152:153]
	v_mul_f32_e32 v152, v62, v62
	v_mov_b32_e32 v153, v155
	v_pk_add_f32 v[150:151], v[152:153], v[150:151]
	s_and_b64 s[0:1], exec, vcc
	v_pk_add_f32 v[142:143], v[150:151], v[142:143]
	s_or_b64 s[40:41], s[0:1], s[40:41]
	v_add_f32_e32 v51, v142, v143
	ds_bpermute_b32 v63, v144, v51
	s_mov_b32 s0, 0xf800000
	v_mov_b32_e32 v150, v140
	v_mov_b32_e32 v151, v60
	v_mov_b32_e32 v60, v141
	s_waitcnt lgkmcnt(0)
	v_add_f32_e32 v51, v51, v63
	ds_bpermute_b32 v63, v145, v51
	v_pk_add_f32 v[42:43], v[42:43], 1.0 op_sel_hi:[1,0]
	v_pk_add_f32 v[40:41], v[40:41], 1.0 op_sel_hi:[1,0]
	v_pk_add_f32 v[32:33], v[32:33], 1.0 op_sel_hi:[1,0]
	v_pk_add_f32 v[34:35], v[34:35], 1.0 op_sel_hi:[1,0]
	s_waitcnt lgkmcnt(0)
	v_add_f32_e32 v51, v51, v63
	ds_bpermute_b32 v63, v146, v51
	v_pk_add_f32 v[26:27], v[26:27], 1.0 op_sel_hi:[1,0]
	v_pk_add_f32 v[24:25], v[24:25], 1.0 op_sel_hi:[1,0]
	s_waitcnt vmcnt(1)
	v_pk_add_f32 v[16:17], v[16:17], 1.0 op_sel_hi:[1,0]
	v_pk_add_f32 v[18:19], v[18:19], 1.0 op_sel_hi:[1,0]
	s_waitcnt lgkmcnt(0)
	v_add_f32_e32 v51, v51, v63
	ds_bpermute_b32 v63, v147, v51
	s_waitcnt lgkmcnt(0)
	v_add_f32_e32 v51, v51, v63
	ds_bpermute_b32 v63, v148, v51
	s_waitcnt lgkmcnt(0)
	v_add_f32_e32 v51, v51, v63
	ds_bpermute_b32 v63, v149, v51
	s_waitcnt lgkmcnt(0)
	v_add_f32_e32 v51, v51, v63
	v_fmamk_f32 v51, v51, 0x3a800000, v137
	v_cmp_gt_f32_e32 vcc, s0, v51
	v_mul_f32_e32 v63, 0x4f800000, v51
	s_nop 0
	v_cndmask_b32_e32 v51, v51, v63, vcc
	v_sqrt_f32_e32 v63, v51
	s_nop 0
	v_add_u32_e32 v113, -1, v63
	v_fma_f32 v115, -v113, v63, v51
	v_cmp_ge_f32_e64 s[38:39], 0, v115
	v_add_u32_e32 v115, 1, v63
	s_nop 0
	v_cndmask_b32_e64 v113, v63, v113, s[38:39]
	v_fma_f32 v63, -v115, v63, v51
	v_cmp_lt_f32_e64 s[38:39], 0, v63
	s_nop 1
	v_cndmask_b32_e64 v63, v113, v115, s[38:39]
	v_mul_f32_e32 v113, 0x37800000, v63
	v_cndmask_b32_e32 v63, v63, v113, vcc
	v_cmp_class_f32_e32 vcc, v51, v169
	s_nop 1
	v_cndmask_b32_e32 v51, v63, v51, vcc
	v_div_scale_f32 v63, s[0:1], v51, v51, 1.0
	v_rcp_f32_e32 v113, v63
	v_readlane_b32 s0, v253, 34
	v_readlane_b32 s1, v253, 35
	v_fma_f32 v115, -v63, v113, 1.0
	v_fmac_f32_e32 v113, v115, v113
	v_div_scale_f32 v115, vcc, 1.0, v51, 1.0
	v_mul_f32_e32 v117, v115, v113
	v_fma_f32 v119, -v63, v117, v115
	v_fmac_f32_e32 v117, v119, v113
	v_fma_f32 v63, -v63, v117, v115
	v_div_fmas_f32 v63, v63, v113, v117
	v_div_fixup_f32 v142, v63, v51, 1.0
	v_pk_mul_f32 v[150:151], v[150:151], v[142:143] op_sel_hi:[1,0]
	v_pk_mul_f32 v[60:61], v[60:61], v[142:143] op_sel_hi:[1,0]
	v_pk_mul_f32 v[140:141], v[2:3], v[150:151]
	v_pk_mul_f32 v[60:61], v[0:1], v[60:61]
	v_pk_fma_f32 v[42:43], v[42:43], v[140:141], v[46:47]
	v_pk_fma_f32 v[40:41], v[40:41], v[60:61], v[44:45]
	v_mov_b32_e32 v51, v62
	v_cvt_pk_bf16_f32 v40, v40, v41
	v_cvt_pk_bf16_f32 v41, v42, v43
	v_pk_mul_f32 v[42:43], v[56:57], v[142:143] op_sel_hi:[1,0]
	global_store_dwordx2 v[138:139], v[40:41], off offset:-1536 sc1
	v_pk_mul_f32 v[40:41], v[58:59], v[142:143] op_sel_hi:[1,0]
	v_pk_mul_f32 v[42:43], v[4:5], v[42:43]
	v_pk_mul_f32 v[40:41], v[6:7], v[40:41]
	v_pk_fma_f32 v[32:33], v[32:33], v[42:43], v[36:37]
	v_pk_fma_f32 v[34:35], v[34:35], v[40:41], v[38:39]
	v_cvt_pk_bf16_f32 v32, v32, v33
	v_mov_b64_e32 v[40:41], v[64:65]
	v_cvt_pk_bf16_f32 v33, v34, v35
	global_store_dwordx2 v[138:139], v[32:33], off offset:-1024 sc1
	v_pk_mul_f32 v[32:33], v[54:55], v[142:143] op_sel_hi:[1,0]
	v_pk_mul_f32 v[34:35], v[52:53], v[142:143] op_sel_hi:[1,0]
	v_pk_mul_f32 v[32:33], v[10:11], v[32:33]
	v_pk_mul_f32 v[34:35], v[8:9], v[34:35]
	v_pk_fma_f32 v[26:27], v[26:27], v[32:33], v[30:31]
	v_pk_fma_f32 v[24:25], v[24:25], v[34:35], v[28:29]
	v_mov_b64_e32 v[32:33], v[88:89]
	v_cvt_pk_bf16_f32 v24, v24, v25
	v_cvt_pk_bf16_f32 v25, v26, v27
	v_pk_mul_f32 v[26:27], v[48:49], v[142:143] op_sel_hi:[1,0]
	global_store_dwordx2 v[138:139], v[24:25], off offset:-512 sc1
	v_pk_mul_f32 v[24:25], v[50:51], v[142:143] op_sel_hi:[1,0]
	v_pk_mul_f32 v[26:27], v[12:13], v[26:27]
	v_pk_mul_f32 v[24:25], v[14:15], v[24:25]
	s_waitcnt vmcnt(3)
	v_pk_fma_f32 v[16:17], v[16:17], v[26:27], v[20:21]
	v_pk_fma_f32 v[18:19], v[18:19], v[24:25], v[22:23]
	v_cvt_pk_bf16_f32 v16, v16, v17
	v_mov_b64_e32 v[24:25], v[84:85]
	v_cvt_pk_bf16_f32 v17, v18, v19
	global_store_dwordx2 v[138:139], v[16:17], off sc1
	v_mov_b64_e32 v[16:17], v[80:81]
	v_mov_b64_e32 v[20:21], v[92:93]
	v_mov_b64_e32 v[28:29], v[76:77]
	v_mov_b64_e32 v[36:37], v[72:73]
	v_mov_b64_e32 v[44:45], v[68:69]
	v_lshl_add_u64 v[138:139], v[138:139], 0, s[0:1]
	v_mov_b32_e32 v142, v128
	v_mov_b64_e32 v[18:19], v[82:83]
	v_mov_b64_e32 v[26:27], v[86:87]
	v_mov_b64_e32 v[34:35], v[90:91]
	v_mov_b64_e32 v[42:43], v[66:67]
	v_mov_b64_e32 v[22:23], v[94:95]
	v_mov_b64_e32 v[30:31], v[78:79]
	v_mov_b64_e32 v[38:39], v[74:75]
	v_mov_b64_e32 v[46:47], v[70:71]
	v_mov_b32_e32 v141, v96
	v_mov_b32_e32 v61, v97
	v_mov_b32_e32 v140, v98
	v_mov_b32_e32 v60, v99
	v_mov_b32_e32 v56, v100
	v_mov_b32_e32 v57, v101
	v_mov_b32_e32 v58, v102
	v_mov_b32_e32 v59, v103
	v_mov_b32_e32 v52, v104
	v_mov_b32_e32 v53, v105
	v_mov_b32_e32 v54, v106
	v_mov_b32_e32 v55, v107
	v_mov_b32_e32 v48, v108
	v_mov_b32_e32 v49, v109
	v_mov_b32_e32 v50, v110
	v_mov_b32_e32 v62, v111
	s_andn2_b64 exec, exec, s[40:41]
	s_cbranch_execz .LBB0_897

; __device__ __forceinline__ void phase_norm(const Params& P, int l, int sub, int addpart) {
;     ...
;         if (addpart && r >= TL) { float* hw = (float*)(P.ws + OFF_HC) + (size_t)(r - TL) * 1024;
; #pragma unroll
;             for (int j = 0; j < 4; ++j) *(f32x4*)(hw + 4 * lane + 256 * j) = v[j]; }
.LBB0_893:
	s_or_b64 exec, exec, s[42:43]
	v_add_u32_e32 v51, 0x8000, v142
	v_readlane_b32 s0, v254, 38
	v_cmp_gt_i32_e64 s[38:39], s25, v51
	v_readlane_b32 s1, v254, 39
	s_or_b64 s[0:1], s[0:1], s[38:39]
	s_and_saveexec_b64 s[2:3], s[0:1]
	s_xor_b64 s[38:39], exec, s[2:3]
	s_andn2_saveexec_b64 s[38:39], s[38:39]
	s_cbranch_execz .LBB0_888
	v_mov_b32_e32 v143, v129
	v_lshlrev_b64 v[142:143], 12, v[142:143]
	v_lshl_add_u64 v[142:143], v[120:121], 0, v[142:143]
	v_mov_b32_e32 v150, v141
	v_mov_b32_e32 v151, v61
	v_mov_b32_e32 v152, v140
	v_mov_b32_e32 v153, v60
	v_mov_b32_e32 v51, v62
	global_store_dwordx4 v[142:143], v[150:153], off sc1
	global_store_dwordx4 v[142:143], v[56:59], off offset:1024 sc1
	global_store_dwordx4 v[142:143], v[52:55], off offset:2048 sc1
	global_store_dwordx4 v[142:143], v[48:51], off offset:3072 sc1
	s_branch .LBB0_888

; #define GAS __attribute__((address_space(1)))
;     __device__ __forceinline__ void operator()(const f32x4 (&acc)[2][2][4][2], const Unit& u, int wr, int wc, int fr, int fq) const {
;     ...
;         GAS float* base = (GAS float*)(u.pm < 128 ? Hl + (size_t)u.pm * 256 * 1024 : (u.kind >= 2 ? PART + (u.kind == 3 ? (size_t)((OFF_PART2 - OFF_PART) / 4) : u.kind == 4 ? (size_t)((OFF_PART3 - OFF_PART) / 4) : (size_t)0) : Hc) + (size_t)(u.pm - 128) * 256 * 1024);
;         const int col0 = u.pn * BM + wc * 32 + 4 * fq; const GAS float* gp = (const GAS float*)gate + vb * 9216 + col0;
;         GAS float* row0 = base + (size_t)(wr * 64 + fr) * 1024 + col0;
;         if (u.kind >= 2) {
; #pragma unroll
;             for (int bj = 0; bj < 2; ++bj)
; #pragma unroll
;                 for (int n = 0; n < 2; ++n) { const f32x4 gv = *(const GAS f32x4*)(gp + bj * HALF + n * 16) * mul;
; #pragma unroll
;                     for (int ai = 0; ai < 2; ++ai)
; #pragma unroll
;                         for (int m = 0; m < 4; ++m) *(GAS f32x4*)(row0 + (size_t)(ai * HALF + m * 16) * 1024 + bj * HALF + n * 16) = gv * acc[ai][bj][m][n]; }
;             return; }
.LBB0_1084:
	global_load_dwordx4 v[150:153], v[148:149], off
	s_waitcnt vmcnt(0)
	v_pk_mul_f32 v[152:153], v[152:153], 0.5 op_sel_hi:[1,0]
	v_pk_mul_f32 v[150:151], v[150:151], 0.5 op_sel_hi:[1,0]
	v_pk_mul_f32 v[126:127], v[126:127], v[152:153]
	v_pk_mul_f32 v[124:125], v[124:125], v[150:151]
	global_store_dwordx4 v[146:147], v[124:127], off sc1
	s_nop 1
	v_pk_mul_f32 v[124:125], v[122:123], v[152:153]
	v_pk_mul_f32 v[122:123], v[120:121], v[150:151]
	v_add_co_u32_e32 v120, vcc, s44, v146
	s_nop 1
	v_addc_co_u32_e32 v121, vcc, 0, v147, vcc
	global_store_dwordx4 v[120:121], v[122:125], off sc1
	s_nop 1
	v_pk_mul_f32 v[122:123], v[116:117], v[150:151]
	v_add_co_u32_e32 v116, vcc, s15, v146
	v_pk_mul_f32 v[124:125], v[118:119], v[152:153]
	s_nop 0
	v_addc_co_u32_e32 v117, vcc, 0, v147, vcc
	global_store_dwordx4 v[116:117], v[122:125], off sc1
	s_nop 1
	v_pk_mul_f32 v[122:123], v[112:113], v[150:151]
	v_add_co_u32_e32 v112, vcc, s45, v146
	v_pk_mul_f32 v[124:125], v[114:115], v[152:153]
	s_nop 0
	v_addc_co_u32_e32 v113, vcc, 0, v147, vcc
	global_store_dwordx4 v[112:113], v[122:125], off sc1
	s_nop 1
	v_pk_mul_f32 v[122:123], v[108:109], v[150:151]
	v_add_co_u32_e32 v108, vcc, s75, v146
	v_pk_mul_f32 v[124:125], v[110:111], v[152:153]
	s_nop 0
	v_addc_co_u32_e32 v109, vcc, 0, v147, vcc
	global_store_dwordx4 v[108:109], v[122:125], off sc1
	s_nop 1
	v_pk_mul_f32 v[122:123], v[104:105], v[150:151]
	v_add_co_u32_e32 v104, vcc, s76, v146
	v_pk_mul_f32 v[124:125], v[106:107], v[152:153]
	s_nop 0
	v_addc_co_u32_e32 v105, vcc, 0, v147, vcc
	global_store_dwordx4 v[104:105], v[122:125], off sc1
	s_nop 1
	v_pk_mul_f32 v[122:123], v[100:101], v[150:151]
	v_add_co_u32_e32 v100, vcc, s19, v146
	v_pk_mul_f32 v[124:125], v[102:103], v[152:153]
	s_nop 0
	v_addc_co_u32_e32 v101, vcc, 0, v147, vcc
	global_store_dwordx4 v[100:101], v[122:125], off sc1
	s_nop 1
	v_pk_mul_f32 v[122:123], v[96:97], v[150:151]
	v_add_co_u32_e32 v96, vcc, s77, v146
	v_pk_mul_f32 v[124:125], v[98:99], v[152:153]
	s_nop 0
	v_addc_co_u32_e32 v97, vcc, 0, v147, vcc
	global_store_dwordx4 v[96:97], v[122:125], off sc1
	global_load_dwordx4 v[122:125], v[148:149], off offset:64
	s_waitcnt vmcnt(0)
	v_pk_mul_f32 v[98:99], v[124:125], 0.5 op_sel_hi:[1,0]
	v_pk_mul_f32 v[102:103], v[122:123], 0.5 op_sel_hi:[1,0]
	v_pk_mul_f32 v[94:95], v[94:95], v[98:99]
	v_pk_mul_f32 v[92:93], v[92:93], v[102:103]
	v_pk_mul_f32 v[90:91], v[90:91], v[98:99]
	v_pk_mul_f32 v[88:89], v[88:89], v[102:103]
	v_pk_mul_f32 v[86:87], v[86:87], v[98:99]
	v_pk_mul_f32 v[84:85], v[84:85], v[102:103]
	v_pk_mul_f32 v[82:83], v[82:83], v[98:99]
	v_pk_mul_f32 v[80:81], v[80:81], v[102:103]
	v_pk_mul_f32 v[78:79], v[78:79], v[98:99]
	v_pk_mul_f32 v[76:77], v[76:77], v[102:103]
	v_pk_mul_f32 v[74:75], v[74:75], v[98:99]
	v_pk_mul_f32 v[72:73], v[72:73], v[102:103]
	v_pk_mul_f32 v[70:71], v[70:71], v[98:99]
	v_pk_mul_f32 v[68:69], v[68:69], v[102:103]
	v_pk_mul_f32 v[66:67], v[66:67], v[98:99]
	v_pk_mul_f32 v[64:65], v[64:65], v[102:103]
	global_store_dwordx4 v[146:147], v[92:95], off offset:64 sc1
	global_store_dwordx4 v[120:121], v[88:91], off offset:64 sc1
	global_store_dwordx4 v[116:117], v[84:87], off offset:64 sc1
	global_store_dwordx4 v[112:113], v[80:83], off offset:64 sc1
	global_store_dwordx4 v[108:109], v[76:79], off offset:64 sc1
	global_store_dwordx4 v[104:105], v[72:75], off offset:64 sc1
	global_store_dwordx4 v[100:101], v[68:71], off offset:64 sc1
	global_store_dwordx4 v[96:97], v[64:67], off offset:64 sc1
	global_load_dwordx4 v[64:67], v[148:149], off offset:512
	s_waitcnt vmcnt(0)
	v_pk_mul_f32 v[66:67], v[66:67], 0.5 op_sel_hi:[1,0]
	v_pk_mul_f32 v[64:65], v[64:65], 0.5 op_sel_hi:[1,0]
	v_pk_mul_f32 v[62:63], v[62:63], v[66:67]
	v_pk_mul_f32 v[60:61], v[60:61], v[64:65]
	v_pk_mul_f32 v[58:59], v[58:59], v[66:67]
	v_pk_mul_f32 v[56:57], v[56:57], v[64:65]
	v_pk_mul_f32 v[54:55], v[54:55], v[66:67]
	v_pk_mul_f32 v[52:53], v[52:53], v[64:65]
	v_pk_mul_f32 v[50:51], v[50:51], v[66:67]
	v_pk_mul_f32 v[48:49], v[48:49], v[64:65]
	v_pk_mul_f32 v[46:47], v[46:47], v[66:67]
	v_pk_mul_f32 v[44:45], v[44:45], v[64:65]
	v_pk_mul_f32 v[42:43], v[42:43], v[66:67]
	v_pk_mul_f32 v[40:41], v[40:41], v[64:65]
	v_pk_mul_f32 v[38:39], v[38:39], v[66:67]
	v_pk_mul_f32 v[36:37], v[36:37], v[64:65]
	v_pk_mul_f32 v[34:35], v[34:35], v[66:67]
	v_pk_mul_f32 v[32:33], v[32:33], v[64:65]
	global_store_dwordx4 v[146:147], v[60:63], off offset:512 sc1
	global_store_dwordx4 v[120:121], v[56:59], off offset:512 sc1
	global_store_dwordx4 v[116:117], v[52:55], off offset:512 sc1
	global_store_dwordx4 v[112:113], v[48:51], off offset:512 sc1
	global_store_dwordx4 v[108:109], v[44:47], off offset:512 sc1
	global_store_dwordx4 v[104:105], v[40:43], off offset:512 sc1
	global_store_dwordx4 v[100:101], v[36:39], off offset:512 sc1
	global_store_dwordx4 v[96:97], v[32:35], off offset:512 sc1
	global_load_dwordx4 v[32:35], v[148:149], off offset:576
	s_waitcnt vmcnt(0)
	v_pk_mul_f32 v[34:35], v[34:35], 0.5 op_sel_hi:[1,0]
	v_pk_mul_f32 v[32:33], v[32:33], 0.5 op_sel_hi:[1,0]
	v_pk_mul_f32 v[30:31], v[30:31], v[34:35]
	v_pk_mul_f32 v[28:29], v[28:29], v[32:33]
	v_pk_mul_f32 v[26:27], v[26:27], v[34:35]
	v_pk_mul_f32 v[24:25], v[24:25], v[32:33]
	v_pk_mul_f32 v[22:23], v[22:23], v[34:35]
	v_pk_mul_f32 v[20:21], v[20:21], v[32:33]
	v_pk_mul_f32 v[18:19], v[18:19], v[34:35]
	v_pk_mul_f32 v[16:17], v[16:17], v[32:33]
	v_pk_mul_f32 v[14:15], v[14:15], v[34:35]
	v_pk_mul_f32 v[12:13], v[12:13], v[32:33]
	v_pk_mul_f32 v[10:11], v[10:11], v[34:35]
	v_pk_mul_f32 v[8:9], v[8:9], v[32:33]
	v_pk_mul_f32 v[6:7], v[6:7], v[34:35]
	v_pk_mul_f32 v[4:5], v[4:5], v[32:33]
	v_pk_mul_f32 v[2:3], v[2:3], v[34:35]
	v_pk_mul_f32 v[0:1], v[0:1], v[32:33]
	global_store_dwordx4 v[146:147], v[28:31], off offset:576 sc1
	global_store_dwordx4 v[120:121], v[24:27], off offset:576 sc1
	global_store_dwordx4 v[116:117], v[20:23], off offset:576 sc1
	global_store_dwordx4 v[112:113], v[16:19], off offset:576 sc1
	global_store_dwordx4 v[108:109], v[12:15], off offset:576 sc1
	global_store_dwordx4 v[104:105], v[8:11], off offset:576 sc1
	global_store_dwordx4 v[100:101], v[4:7], off offset:576 sc1
	global_store_dwordx4 v[96:97], v[0:3], off offset:576 sc1
	s_andn2_b64 vcc, exec, s[48:49]
	s_mov_b64 s[8:9], -1
	s_cbranch_vccnz .LBB0_1048

; __device__ __forceinline__ void transpose_item(const float* W, int ldw, int k0, int n0, bf16_t* WT, int ldt, int drow0, int dk0, LAS float* scr, int lane) {
;     ...
;     for (int i = 0; i < 32; ++i) { const int kk = 2 * i + (lane >> 5); tv[i] = W[(size_t)(k0 + kk) * ldw + n0 + (lane & 31)]; }
; __device__ __forceinline__ void prep_weights(const Params& P, LAS unsigned char* lds, int lay, int bid, int G, int sel) {
;     ...
;           if (r < 2 * I_GU) { if (!((sel >> (r / I_GU)) & 1)) continue; const int mat = lay * 2 + r / I_GU, ii = r % I_GU, kb = ii / 176, nb = ii % 176, n0 = nb * 32;
;               const int drow = n0 < DFF ? (n0 >> 7) * 256 + (n0 & 127) : ((n0 - DFF) >> 7) * 256 + 128 + ((n0 - DFF) & 127);
;               transpose_item(P.w_gu + (size_t)mat * 1024 * 5632, 5632, kb * 64, n0, (bf16_t*)(ws + OFF_WGU + mat * SZ_WGU1), 1024, drow, kb * 64, scr, lane); continue; }
.LBB0_1095:
	s_or_b64 exec, exec, s[46:47]
	v_add_u32_e32 v17, 2, v12
	v_mov_b64_e32 v[14:15], s[78:79]
	s_mov_b32 s0, 0x1600000
	v_mad_u64_u32 v[28:29], s[0:1], v17, s0, v[14:15]
	v_lshlrev_b32_sdwa v12, v249, sext(v13) dst_sel:DWORD dst_unused:UNUSED_PAD src0_sel:DWORD src1_sel:WORD_0
	v_mov_b64_e32 v[14:15], s[92:93]
	s_mov_b32 s0, 0xb00000
	v_mad_u64_u32 v[14:15], s[0:1], v17, s0, v[14:15]
	v_or_b32_e32 v13, v12, v18
	v_ashrrev_i32_e32 v17, 31, v16
	v_lshl_add_u64 v[16:17], v[16:17], 2, v[28:29]
	v_lshlrev_b32_e32 v128, 2, v0
	v_mul_i32_i24_e32 v28, 0x1600, v13
	v_lshl_add_u64 v[16:17], v[16:17], 0, v[128:129]
	v_ashrrev_i32_e32 v29, 31, v28
	v_lshl_add_u64 v[16:17], v[28:29], 2, v[16:17]
	v_add_co_u32_e32 v28, vcc, s14, v16
	s_mov_b32 s0, 0x16000
	s_nop 0
	v_addc_co_u32_e32 v29, vcc, 0, v17, vcc
	global_load_dword v13, v[16:17], off
	global_load_dword v30, v[28:29], off
	v_add_co_u32_e32 v28, vcc, s0, v16
	s_mov_b32 s0, 0x21000
	s_nop 0
	v_addc_co_u32_e32 v29, vcc, 0, v17, vcc
	global_load_dword v31, v[28:29], off
	v_add_co_u32_e32 v28, vcc, s0, v16
	s_mov_b32 s0, 0x2c000
	s_nop 0
	v_addc_co_u32_e32 v29, vcc, 0, v17, vcc
	global_load_dword v32, v[28:29], off
	v_add_co_u32_e32 v28, vcc, s0, v16
	s_mov_b32 s0, 0x37000
	s_nop 0
	v_addc_co_u32_e32 v29, vcc, 0, v17, vcc
	global_load_dword v33, v[28:29], off
	v_add_co_u32_e32 v28, vcc, s0, v16
	s_mov_b32 s0, 0x42000
	s_nop 0
	v_addc_co_u32_e32 v29, vcc, 0, v17, vcc
	global_load_dword v34, v[28:29], off
	v_add_co_u32_e32 v28, vcc, s0, v16
	s_mov_b32 s0, 0x4d000
	s_nop 0
	v_addc_co_u32_e32 v29, vcc, 0, v17, vcc
	global_load_dword v35, v[28:29], off
	v_add_co_u32_e32 v28, vcc, s0, v16
	s_mov_b32 s0, 0x58000
	s_nop 0
	v_addc_co_u32_e32 v29, vcc, 0, v17, vcc
	global_load_dword v36, v[28:29], off
	v_add_co_u32_e32 v28, vcc, s0, v16
	s_mov_b32 s0, 0x63000
	s_nop 0
	v_addc_co_u32_e32 v29, vcc, 0, v17, vcc
	global_load_dword v37, v[28:29], off
	v_add_co_u32_e32 v28, vcc, s0, v16
	s_mov_b32 s0, 0x6e000
	s_nop 0
	v_addc_co_u32_e32 v29, vcc, 0, v17, vcc
	global_load_dword v38, v[28:29], off
	v_add_co_u32_e32 v28, vcc, s0, v16
	s_mov_b32 s0, 0x79000
	s_nop 0
	v_addc_co_u32_e32 v29, vcc, 0, v17, vcc
	global_load_dword v39, v[28:29], off
	v_add_co_u32_e32 v28, vcc, s0, v16
	s_mov_b32 s0, 0x84000
	s_nop 0
	v_addc_co_u32_e32 v29, vcc, 0, v17, vcc
	global_load_dword v40, v[28:29], off
	v_add_co_u32_e32 v28, vcc, s0, v16
	s_mov_b32 s0, 0x8f000
	s_nop 0
	v_addc_co_u32_e32 v29, vcc, 0, v17, vcc
	global_load_dword v41, v[28:29], off
	v_add_co_u32_e32 v28, vcc, s0, v16
	s_mov_b32 s0, 0x9a000
	s_nop 0
	v_addc_co_u32_e32 v29, vcc, 0, v17, vcc
	global_load_dword v42, v[28:29], off
	v_add_co_u32_e32 v28, vcc, s0, v16
	s_mov_b32 s0, 0xa5000
	s_nop 0
	v_addc_co_u32_e32 v29, vcc, 0, v17, vcc
	global_load_dword v43, v[28:29], off
	v_add_co_u32_e32 v28, vcc, s0, v16
	s_mov_b32 s0, 0xb0000
	s_nop 0
	v_addc_co_u32_e32 v29, vcc, 0, v17, vcc
	global_load_dword v44, v[28:29], off
	v_add_co_u32_e32 v28, vcc, s0, v16
	s_mov_b32 s0, 0xbb000
	s_nop 0
	v_addc_co_u32_e32 v29, vcc, 0, v17, vcc
	global_load_dword v45, v[28:29], off
	v_add_co_u32_e32 v28, vcc, s0, v16
	s_mov_b32 s0, 0xc6000
	s_nop 0
	v_addc_co_u32_e32 v29, vcc, 0, v17, vcc
	global_load_dword v46, v[28:29], off
	v_add_co_u32_e32 v28, vcc, s0, v16
	s_mov_b32 s0, 0xd1000
	s_nop 0
	v_addc_co_u32_e32 v29, vcc, 0, v17, vcc
	global_load_dword v47, v[28:29], off
	v_add_co_u32_e32 v28, vcc, s0, v16
	s_mov_b32 s0, 0xdc000
	s_nop 0
	v_addc_co_u32_e32 v29, vcc, 0, v17, vcc
	global_load_dword v48, v[28:29], off
	v_add_co_u32_e32 v28, vcc, s0, v16
	s_mov_b32 s0, 0xe7000
	s_nop 0
	v_addc_co_u32_e32 v29, vcc, 0, v17, vcc
	global_load_dword v49, v[28:29], off
	v_add_co_u32_e32 v28, vcc, s0, v16
	s_mov_b32 s0, 0xf2000
	s_nop 0
	v_addc_co_u32_e32 v29, vcc, 0, v17, vcc
	global_load_dword v50, v[28:29], off
	v_add_co_u32_e32 v28, vcc, s0, v16
	s_mov_b32 s0, 0xfd000
	s_nop 0
	v_addc_co_u32_e32 v29, vcc, 0, v17, vcc
	global_load_dword v51, v[28:29], off
	v_add_co_u32_e32 v28, vcc, s0, v16
	s_mov_b32 s0, 0x108000
	s_nop 0
	v_addc_co_u32_e32 v29, vcc, 0, v17, vcc
	global_load_dword v52, v[28:29], off
	v_add_co_u32_e32 v28, vcc, s0, v16
	s_mov_b32 s0, 0x113000
	s_nop 0
	v_addc_co_u32_e32 v29, vcc, 0, v17, vcc
	global_load_dword v53, v[28:29], off
	v_add_co_u32_e32 v28, vcc, s0, v16
	s_mov_b32 s0, 0x11e000
	s_nop 0
	v_addc_co_u32_e32 v29, vcc, 0, v17, vcc
	global_load_dword v54, v[28:29], off
	v_add_co_u32_e32 v28, vcc, s0, v16
	s_mov_b32 s0, 0x129000
	s_nop 0
	v_addc_co_u32_e32 v29, vcc, 0, v17, vcc
	global_load_dword v55, v[28:29], off
	v_add_co_u32_e32 v28, vcc, s0, v16
	s_mov_b32 s0, 0x134000
	s_nop 0
	v_addc_co_u32_e32 v29, vcc, 0, v17, vcc
	global_load_dword v56, v[28:29], off
	v_add_co_u32_e32 v28, vcc, s0, v16
	s_mov_b32 s0, 0x13f000
	s_nop 0
	v_addc_co_u32_e32 v29, vcc, 0, v17, vcc
	global_load_dword v57, v[28:29], off
	v_add_co_u32_e32 v28, vcc, s0, v16
	s_mov_b32 s0, 0x14a000
	s_nop 0
	v_addc_co_u32_e32 v29, vcc, 0, v17, vcc
	global_load_dword v58, v[28:29], off
	v_add_co_u32_e32 v28, vcc, s0, v16
	s_mov_b32 s0, 0x155000
	s_nop 0
	v_addc_co_u32_e32 v29, vcc, 0, v17, vcc
	v_add_co_u32_e32 v16, vcc, s0, v16
	global_load_dword v28, v[28:29], off
	s_nop 0
	v_addc_co_u32_e32 v17, vcc, 0, v17, vcc
	global_load_dword v16, v[16:17], off
	s_waitcnt vmcnt(30)
; #define LAS __attribute__((address_space(3)))
; #define GAS __attribute__((address_space(1)))
; __device__ __forceinline__ unsigned cvt_pk_bf16(float lo, float hi) { unsigned r; asm volatile("v_cvt_pk_bf16_f32 %0, %1, %2" : "=v"(r) : "v"(lo), "v"(hi)); return r; }
; __device__ __forceinline__ void transpose_item(const float* W, int ldw, int k0, int n0, bf16_t* WT, int ldt, int drow0, int dk0, LAS float* scr, int lane) {
;     ...
;     for (int i = 0; i < 32; ++i) { const int kk = 2 * i + (lane >> 5); scr[kk * 33 + (lane & 31)] = tv[i]; }
;     asm volatile("s_waitcnt lgkmcnt(0)" ::: "memory");
;     const int c = lane & 7;
; #pragma unroll
;     for (int j = 0; j < 4; ++j) { const int n = (lane >> 3) + 8 * j; const LAS float* s = scr + (8 * c) * 33 + n;
;         u32x4 o; o.x = cvt_pk_bf16(s[0 * 33], s[1 * 33]); o.y = cvt_pk_bf16(s[2 * 33], s[3 * 33]); o.z = cvt_pk_bf16(s[4 * 33], s[5 * 33]); o.w = cvt_pk_bf16(s[6 * 33], s[7 * 33]);
;         *(GAS u32x4*)((GAS bf16_t*)WT + (size_t)(drow0 + n) * ldt + dk0 + 8 * c) = o; }
; __device__ __forceinline__ void prep_weights(const Params& P, LAS unsigned char* lds, int lay, int bid, int G, int sel) {
;     ...
;               const int drow = n0 < DFF ? (n0 >> 7) * 256 + (n0 & 127) : ((n0 - DFF) >> 7) * 256 + 128 + ((n0 - DFF) & 127);
;               transpose_item(P.w_gu + (size_t)mat * 1024 * 5632, 5632, kb * 64, n0, (bf16_t*)(ws + OFF_WGU + mat * SZ_WGU1), 1024, drow, kb * 64, scr, lane); continue; }
	ds_write2_b32 v19, v13, v30 offset1:66
	s_waitcnt vmcnt(28)
	ds_write2_b32 v19, v31, v32 offset0:132 offset1:198
	v_add_u32_e32 v13, 0x400, v19
	s_waitcnt vmcnt(26)
	ds_write2_b32 v13, v33, v34 offset0:8 offset1:74
	s_waitcnt vmcnt(24)
	ds_write2_b32 v13, v35, v36 offset0:140 offset1:206
	v_add_u32_e32 v13, 0x800, v19
	s_waitcnt vmcnt(22)
	ds_write2_b32 v13, v37, v38 offset0:16 offset1:82
	s_waitcnt vmcnt(20)
	ds_write2_b32 v13, v39, v40 offset0:148 offset1:214
	v_add_u32_e32 v13, 0xc00, v19
	s_waitcnt vmcnt(18)
	ds_write2_b32 v13, v41, v42 offset0:24 offset1:90
	s_waitcnt vmcnt(16)
	ds_write2_b32 v13, v43, v44 offset0:156 offset1:222
	v_add_u32_e32 v13, 0x1000, v19
	s_waitcnt vmcnt(14)
	ds_write2_b32 v13, v45, v46 offset0:32 offset1:98
	s_waitcnt vmcnt(12)
	ds_write2_b32 v13, v47, v48 offset0:164 offset1:230
	v_add_u32_e32 v13, 0x1400, v19
	s_waitcnt vmcnt(10)
	ds_write2_b32 v13, v49, v50 offset0:40 offset1:106
	s_waitcnt vmcnt(8)
	ds_write2_b32 v13, v51, v52 offset0:172 offset1:238
	v_add_u32_e32 v13, 0x1800, v19
	s_waitcnt vmcnt(6)
	ds_write2_b32 v13, v53, v54 offset0:48 offset1:114
	s_waitcnt vmcnt(4)
	ds_write2_b32 v13, v55, v56 offset0:180 offset1:246
	v_add_u32_e32 v13, 0x1c00, v19
	s_waitcnt vmcnt(2)
	ds_write2_b32 v13, v57, v58 offset0:56 offset1:122
	s_waitcnt vmcnt(0)
	ds_write2_b32 v13, v28, v16 offset0:188 offset1:254
	v_ashrrev_i32_e32 v13, 31, v12
	s_waitcnt lgkmcnt(0)
	v_lshl_add_u64 v[12:13], v[12:13], 1, v[14:15]
	v_lshlrev_b32_e32 v128, 1, v2
	v_lshl_add_u64 v[16:17], v[12:13], 0, v[128:129]
	ds_read2_b32 v[12:13], v21 offset1:33
	s_waitcnt lgkmcnt(0)
	v_cvt_pk_bf16_f32 v12, v12, v13
	ds_read2_b32 v[14:15], v21 offset0:66 offset1:99
	s_waitcnt lgkmcnt(0)
	v_cvt_pk_bf16_f32 v13, v14, v15
	ds_read2_b32 v[14:15], v21 offset0:132 offset1:165
	s_waitcnt lgkmcnt(0)
	v_cvt_pk_bf16_f32 v14, v14, v15
	ds_read2_b32 v[28:29], v21 offset0:198 offset1:231
	s_waitcnt lgkmcnt(0)
	v_cvt_pk_bf16_f32 v15, v28, v29
	v_add_u32_e32 v28, v27, v20
	v_ashrrev_i32_e32 v29, 31, v28
	v_lshlrev_b64 v[28:29], 11, v[28:29]
	v_lshl_add_u64 v[28:29], v[16:17], 0, v[28:29]
	global_store_dwordx4 v[28:29], v[12:15], off sc1
	ds_read2_b32 v[12:13], v21 offset0:8 offset1:41
	s_waitcnt lgkmcnt(0)
	v_cvt_pk_bf16_f32 v12, v12, v13
	ds_read2_b32 v[14:15], v21 offset0:74 offset1:107
	s_waitcnt lgkmcnt(0)
	v_cvt_pk_bf16_f32 v13, v14, v15
	ds_read2_b32 v[14:15], v21 offset0:140 offset1:173
	s_waitcnt lgkmcnt(0)
	v_cvt_pk_bf16_f32 v14, v14, v15
	ds_read2_b32 v[28:29], v21 offset0:206 offset1:239
	s_waitcnt lgkmcnt(0)
	v_cvt_pk_bf16_f32 v15, v28, v29
	v_add_u32_e32 v28, v27, v22
	v_ashrrev_i32_e32 v29, 31, v28
	v_lshlrev_b64 v[28:29], 11, v[28:29]
	v_lshl_add_u64 v[28:29], v[16:17], 0, v[28:29]
	global_store_dwordx4 v[28:29], v[12:15], off sc1
	ds_read2_b32 v[12:13], v21 offset0:16 offset1:49
	s_waitcnt lgkmcnt(0)
	v_cvt_pk_bf16_f32 v12, v12, v13
	ds_read2_b32 v[14:15], v21 offset0:82 offset1:115
	s_waitcnt lgkmcnt(0)
	v_cvt_pk_bf16_f32 v13, v14, v15
	ds_read2_b32 v[14:15], v21 offset0:148 offset1:181
	s_waitcnt lgkmcnt(0)
	v_cvt_pk_bf16_f32 v14, v14, v15
	ds_read2_b32 v[28:29], v21 offset0:214 offset1:247
	s_waitcnt lgkmcnt(0)
	v_cvt_pk_bf16_f32 v15, v28, v29
	v_add_u32_e32 v28, v27, v23
	v_ashrrev_i32_e32 v29, 31, v28
	v_lshlrev_b64 v[28:29], 11, v[28:29]
	v_lshl_add_u64 v[28:29], v[16:17], 0, v[28:29]
	global_store_dwordx4 v[28:29], v[12:15], off sc1
	ds_read2_b32 v[12:13], v21 offset0:24 offset1:57
	s_waitcnt lgkmcnt(0)
	v_cvt_pk_bf16_f32 v12, v12, v13
	ds_read2_b32 v[14:15], v21 offset0:90 offset1:123
	s_waitcnt lgkmcnt(0)
	v_cvt_pk_bf16_f32 v13, v14, v15
	ds_read2_b32 v[14:15], v21 offset0:156 offset1:189
	s_waitcnt lgkmcnt(0)
	v_cvt_pk_bf16_f32 v14, v14, v15
	ds_read2_b32 v[28:29], v21 offset0:222 offset1:255
	s_waitcnt lgkmcnt(0)
	v_cvt_pk_bf16_f32 v15, v28, v29
	v_add_u32_e32 v28, v27, v24
	v_ashrrev_i32_e32 v29, 31, v28
	v_lshlrev_b64 v[28:29], 11, v[28:29]
	v_lshl_add_u64 v[16:17], v[16:17], 0, v[28:29]
	global_store_dwordx4 v[16:17], v[12:15], off sc1
	s_waitcnt lgkmcnt(0)

; __device__ __forceinline__ void prep_weights(const Params& P, LAS unsigned char* lds, int lay, int bid, int G, int sel) {
;     ...
;       for (int it = gw; it < NIT; it += NGW) { int r = it;
;           if (r < 2 * I_GU) { if (!((sel >> (r / I_GU)) & 1)) continue; const int mat = lay * 2 + r / I_GU, ii = r % I_GU, kb = ii / 176, nb = ii % 176, n0 = nb * 32;
;               const int drow = n0 < DFF ? (n0 >> 7) * 256 + (n0 & 127) : ((n0 - DFF) >> 7) * 256 + 128 + ((n0 - DFF) & 127);
;               transpose_item(P.w_gu + (size_t)mat * 1024 * 5632, 5632, kb * 64, n0, (bf16_t*)(ws + OFF_WGU + mat * SZ_WGU1), 1024, drow, kb * 64, scr, lane); continue; }
;           r -= 2 * I_GU;
;           if (r < 2 * I_DN) { if (!((sel >> (2 + r / I_DN)) & 1)) continue; const int mat = lay * 2 + r / I_DN, ii = r % I_DN, kb = ii / 32, nb = ii % 32;
;               transpose_item(P.w_down + (size_t)mat * DFF * 1024, 1024, kb * 64, nb * 32, (bf16_t*)(ws + OFF_WDN + mat * SZ_WDN1), DFF, nb * 32, kb * 64, scr, lane); continue; }
;           r -= 2 * I_DN;
;           if (r < I_IN) { if (!(sel & 16)) continue; const int mat = lay, kb = r / 56, nb = r % 56;
;               transpose_item(P.w_in + (size_t)mat * 1024 * 1792, 1792, kb * 64, nb * 32, (bf16_t*)(ws + OFF_WIN + mat * SZ_WIN1), 1024, nb * 32, kb * 64, scr, lane); continue; }
;           r -= I_IN;
;           if (sel & 32) { const int mat = lay, kb = r / 32, nb = r % 32;
;               transpose_item(P.w_out + (size_t)mat * 1024 * 1024, 1024, kb * 64, nb * 32, (bf16_t*)(ws + OFF_WOUT + mat * SZ_WOUT1), 1280, nb * 32, kb * 64, scr, lane); } } }
.LBB0_1098:
	s_movk_i32 s0, 0x15ff
	v_cmp_lt_i32_e32 vcc, s0, v3
	s_and_saveexec_b64 s[0:1], vcc
	s_xor_b64 s[42:43], exec, s[0:1]
	s_cbranch_execz .LBB0_1108
	s_movk_i32 s0, 0x20ff
	v_cmp_lt_u32_e32 vcc, s0, v3
	s_and_saveexec_b64 s[0:1], vcc
	s_xor_b64 s[8:9], exec, s[0:1]
	s_cbranch_execz .LBB0_1105
	s_movk_i32 s0, 0x247f
	v_cmp_lt_u32_e32 vcc, s0, v3
	s_and_saveexec_b64 s[0:1], vcc
	s_xor_b64 s[46:47], exec, s[0:1]
	s_cbranch_execz .LBB0_1102
	v_and_b32_e32 v12, 0x7fffffc0, v25
	v_add_u32_e32 v12, 0xffffb700, v12
	v_and_b32_e32 v27, 0x3e0, v26
	v_or_b32_e32 v16, v12, v18
	v_lshlrev_b32_e32 v128, 2, v27
	v_mov_b32_e32 v17, v129
	v_lshl_add_u64 v[14:15], v[8:9], 0, v[128:129]
	v_lshlrev_b64 v[28:29], 12, v[16:17]
	v_lshl_add_u64 v[28:29], v[14:15], 0, v[28:29]
	v_or_b32_e32 v128, 2, v16
	global_load_dword v13, v[28:29], off
	v_lshlrev_b64 v[28:29], 12, v[128:129]
	v_lshl_add_u64 v[28:29], v[14:15], 0, v[28:29]
	v_or_b32_e32 v128, 4, v16
	global_load_dword v30, v[28:29], off
	v_lshlrev_b64 v[28:29], 12, v[128:129]
	v_lshl_add_u64 v[28:29], v[14:15], 0, v[28:29]
	v_or_b32_e32 v128, 6, v16
	global_load_dword v31, v[28:29], off
	v_lshlrev_b64 v[28:29], 12, v[128:129]
	v_lshl_add_u64 v[28:29], v[14:15], 0, v[28:29]
	v_or_b32_e32 v128, 8, v16
	global_load_dword v32, v[28:29], off
	v_lshlrev_b64 v[28:29], 12, v[128:129]
	v_lshl_add_u64 v[28:29], v[14:15], 0, v[28:29]
	v_or_b32_e32 v128, 10, v16
	global_load_dword v33, v[28:29], off
	v_lshlrev_b64 v[28:29], 12, v[128:129]
	v_lshl_add_u64 v[28:29], v[14:15], 0, v[28:29]
	v_or_b32_e32 v128, 12, v16
	global_load_dword v34, v[28:29], off
	v_lshlrev_b64 v[28:29], 12, v[128:129]
	v_lshl_add_u64 v[28:29], v[14:15], 0, v[28:29]
	v_or_b32_e32 v128, 14, v16
	global_load_dword v35, v[28:29], off
	v_lshlrev_b64 v[28:29], 12, v[128:129]
	v_lshl_add_u64 v[28:29], v[14:15], 0, v[28:29]
	v_or_b32_e32 v128, 16, v16
	global_load_dword v36, v[28:29], off
	v_lshlrev_b64 v[28:29], 12, v[128:129]
	v_lshl_add_u64 v[28:29], v[14:15], 0, v[28:29]
	v_or_b32_e32 v128, 18, v16
	global_load_dword v37, v[28:29], off
	v_lshlrev_b64 v[28:29], 12, v[128:129]
	v_lshl_add_u64 v[28:29], v[14:15], 0, v[28:29]
	v_or_b32_e32 v128, 20, v16
	global_load_dword v38, v[28:29], off
	v_lshlrev_b64 v[28:29], 12, v[128:129]
	v_lshl_add_u64 v[28:29], v[14:15], 0, v[28:29]
	v_or_b32_e32 v128, 22, v16
	global_load_dword v39, v[28:29], off
	v_lshlrev_b64 v[28:29], 12, v[128:129]
	v_lshl_add_u64 v[28:29], v[14:15], 0, v[28:29]
	v_or_b32_e32 v128, 24, v16
	global_load_dword v40, v[28:29], off
	v_lshlrev_b64 v[28:29], 12, v[128:129]
	v_lshl_add_u64 v[28:29], v[14:15], 0, v[28:29]
	v_or_b32_e32 v128, 26, v16
	global_load_dword v41, v[28:29], off
	v_lshlrev_b64 v[28:29], 12, v[128:129]
	v_lshl_add_u64 v[28:29], v[14:15], 0, v[28:29]
	v_or_b32_e32 v128, 28, v16
	global_load_dword v42, v[28:29], off
	v_lshlrev_b64 v[28:29], 12, v[128:129]
	v_lshl_add_u64 v[28:29], v[14:15], 0, v[28:29]
	v_or_b32_e32 v128, 30, v16
	global_load_dword v43, v[28:29], off
	v_lshlrev_b64 v[28:29], 12, v[128:129]
	v_lshl_add_u64 v[28:29], v[14:15], 0, v[28:29]
	v_or_b32_e32 v128, 32, v16
	global_load_dword v44, v[28:29], off
	v_lshlrev_b64 v[28:29], 12, v[128:129]
	v_lshl_add_u64 v[28:29], v[14:15], 0, v[28:29]
	v_or_b32_e32 v128, 34, v16
	global_load_dword v45, v[28:29], off
	v_lshlrev_b64 v[28:29], 12, v[128:129]
	v_lshl_add_u64 v[28:29], v[14:15], 0, v[28:29]
	v_or_b32_e32 v128, 36, v16
	global_load_dword v46, v[28:29], off
	v_lshlrev_b64 v[28:29], 12, v[128:129]
	v_lshl_add_u64 v[28:29], v[14:15], 0, v[28:29]
	v_or_b32_e32 v128, 38, v16
	global_load_dword v47, v[28:29], off
	v_lshlrev_b64 v[28:29], 12, v[128:129]
	v_lshl_add_u64 v[28:29], v[14:15], 0, v[28:29]
	v_or_b32_e32 v128, 40, v16
	global_load_dword v48, v[28:29], off
	v_lshlrev_b64 v[28:29], 12, v[128:129]
	v_lshl_add_u64 v[28:29], v[14:15], 0, v[28:29]
	v_or_b32_e32 v128, 42, v16
	global_load_dword v49, v[28:29], off
	v_lshlrev_b64 v[28:29], 12, v[128:129]
	v_lshl_add_u64 v[28:29], v[14:15], 0, v[28:29]
	v_or_b32_e32 v128, 44, v16
	global_load_dword v50, v[28:29], off
	v_lshlrev_b64 v[28:29], 12, v[128:129]
	v_lshl_add_u64 v[28:29], v[14:15], 0, v[28:29]
	v_or_b32_e32 v128, 46, v16
	global_load_dword v51, v[28:29], off
	v_lshlrev_b64 v[28:29], 12, v[128:129]
	v_lshl_add_u64 v[28:29], v[14:15], 0, v[28:29]
	v_or_b32_e32 v128, 48, v16
	global_load_dword v52, v[28:29], off
	v_lshlrev_b64 v[28:29], 12, v[128:129]
	v_lshl_add_u64 v[28:29], v[14:15], 0, v[28:29]
	v_or_b32_e32 v128, 50, v16
	global_load_dword v53, v[28:29], off
	v_lshlrev_b64 v[28:29], 12, v[128:129]
	v_lshl_add_u64 v[28:29], v[14:15], 0, v[28:29]
	v_or_b32_e32 v128, 52, v16
	global_load_dword v54, v[28:29], off
	v_lshlrev_b64 v[28:29], 12, v[128:129]
	v_lshl_add_u64 v[28:29], v[14:15], 0, v[28:29]
	v_or_b32_e32 v128, 54, v16
	global_load_dword v55, v[28:29], off
	v_lshlrev_b64 v[28:29], 12, v[128:129]
	v_lshl_add_u64 v[28:29], v[14:15], 0, v[28:29]
	v_or_b32_e32 v128, 56, v16
	global_load_dword v56, v[28:29], off
	v_lshlrev_b64 v[28:29], 12, v[128:129]
	v_lshl_add_u64 v[28:29], v[14:15], 0, v[28:29]
	v_or_b32_e32 v128, 58, v16
	global_load_dword v57, v[28:29], off
	v_lshlrev_b64 v[28:29], 12, v[128:129]
	v_lshl_add_u64 v[28:29], v[14:15], 0, v[28:29]
	v_or_b32_e32 v128, 60, v16
	global_load_dword v58, v[28:29], off
	v_lshlrev_b64 v[28:29], 12, v[128:129]
	v_or_b32_e32 v128, 62, v16
	v_lshlrev_b64 v[16:17], 12, v[128:129]
	v_lshl_add_u64 v[28:29], v[14:15], 0, v[28:29]
	v_lshl_add_u64 v[14:15], v[14:15], 0, v[16:17]
	global_load_dword v28, v[28:29], off
	s_nop 0
	global_load_dword v14, v[14:15], off
	s_waitcnt vmcnt(30)
; #define LAS __attribute__((address_space(3)))
; #define GAS __attribute__((address_space(1)))
; __device__ __forceinline__ unsigned cvt_pk_bf16(float lo, float hi) { unsigned r; asm volatile("v_cvt_pk_bf16_f32 %0, %1, %2" : "=v"(r) : "v"(lo), "v"(hi)); return r; }
; __device__ __forceinline__ void transpose_item(const float* W, int ldw, int k0, int n0, bf16_t* WT, int ldt, int drow0, int dk0, LAS float* scr, int lane) {
;     ...
;     for (int i = 0; i < 32; ++i) { const int kk = 2 * i + (lane >> 5); scr[kk * 33 + (lane & 31)] = tv[i]; }
;     asm volatile("s_waitcnt lgkmcnt(0)" ::: "memory");
;     const int c = lane & 7;
; #pragma unroll
;     for (int j = 0; j < 4; ++j) { const int n = (lane >> 3) + 8 * j; const LAS float* s = scr + (8 * c) * 33 + n;
;         u32x4 o; o.x = cvt_pk_bf16(s[0 * 33], s[1 * 33]); o.y = cvt_pk_bf16(s[2 * 33], s[3 * 33]); o.z = cvt_pk_bf16(s[4 * 33], s[5 * 33]); o.w = cvt_pk_bf16(s[6 * 33], s[7 * 33]);
;         *(GAS u32x4*)((GAS bf16_t*)WT + (size_t)(drow0 + n) * ldt + dk0 + 8 * c) = o; }
; __device__ __forceinline__ void prep_weights(const Params& P, LAS unsigned char* lds, int lay, int bid, int G, int sel) {
;     ...
;           if (r < I_IN) { if (!(sel & 16)) continue; const int mat = lay, kb = r / 56, nb = r % 56;
;               transpose_item(P.w_in + (size_t)mat * 1024 * 1792, 1792, kb * 64, nb * 32, (bf16_t*)(ws + OFF_WIN + mat * SZ_WIN1), 1024, nb * 32, kb * 64, scr, lane); continue; }
	ds_write2_b32 v19, v13, v30 offset1:66
	s_waitcnt vmcnt(28)
	ds_write2_b32 v19, v31, v32 offset0:132 offset1:198
	v_add_u32_e32 v13, 0x400, v19
	s_waitcnt vmcnt(26)
	ds_write2_b32 v13, v33, v34 offset0:8 offset1:74
	s_waitcnt vmcnt(24)
	ds_write2_b32 v13, v35, v36 offset0:140 offset1:206
	v_add_u32_e32 v13, 0x800, v19
	s_waitcnt vmcnt(22)
	ds_write2_b32 v13, v37, v38 offset0:16 offset1:82
	s_waitcnt vmcnt(20)
	ds_write2_b32 v13, v39, v40 offset0:148 offset1:214
	v_add_u32_e32 v13, 0xc00, v19
	s_waitcnt vmcnt(18)
	ds_write2_b32 v13, v41, v42 offset0:24 offset1:90
	s_waitcnt vmcnt(16)
	ds_write2_b32 v13, v43, v44 offset0:156 offset1:222
	v_add_u32_e32 v13, 0x1000, v19
	s_waitcnt vmcnt(14)
	ds_write2_b32 v13, v45, v46 offset0:32 offset1:98
	s_waitcnt vmcnt(12)
	ds_write2_b32 v13, v47, v48 offset0:164 offset1:230
	v_add_u32_e32 v13, 0x1400, v19
	s_waitcnt vmcnt(10)
	ds_write2_b32 v13, v49, v50 offset0:40 offset1:106
	s_waitcnt vmcnt(8)
	ds_write2_b32 v13, v51, v52 offset0:172 offset1:238
	v_add_u32_e32 v13, 0x1800, v19
	s_waitcnt vmcnt(6)
	ds_write2_b32 v13, v53, v54 offset0:48 offset1:114
	s_waitcnt vmcnt(4)
	ds_write2_b32 v13, v55, v56 offset0:180 offset1:246
	v_add_u32_e32 v13, 0x1c00, v19
	s_waitcnt vmcnt(2)
	ds_write2_b32 v13, v57, v58 offset0:56 offset1:122
	s_waitcnt vmcnt(0)
	ds_write2_b32 v13, v28, v14 offset0:188 offset1:254
	s_waitcnt lgkmcnt(0)
	v_mov_b32_e32 v13, v129
	v_lshl_add_u64 v[16:17], v[12:13], 1, v[4:5]
	ds_read2_b32 v[12:13], v21 offset1:33
	s_waitcnt lgkmcnt(0)
	v_cvt_pk_bf16_f32 v12, v12, v13
	ds_read2_b32 v[14:15], v21 offset0:66 offset1:99
	s_waitcnt lgkmcnt(0)
	v_cvt_pk_bf16_f32 v13, v14, v15
	ds_read2_b32 v[14:15], v21 offset0:132 offset1:165
	s_waitcnt lgkmcnt(0)
	v_cvt_pk_bf16_f32 v14, v14, v15
	ds_read2_b32 v[28:29], v21 offset0:198 offset1:231
	s_waitcnt lgkmcnt(0)
	v_cvt_pk_bf16_f32 v15, v28, v29
	v_or_b32_e32 v28, v27, v20
	v_mul_u32_u24_e32 v28, 0x500, v28
	v_lshlrev_b32_e32 v128, 1, v28
	v_lshl_add_u64 v[28:29], v[16:17], 0, v[128:129]
	global_store_dwordx4 v[28:29], v[12:15], off sc1
	ds_read2_b32 v[12:13], v21 offset0:8 offset1:41
	s_waitcnt lgkmcnt(0)
	v_cvt_pk_bf16_f32 v12, v12, v13
	ds_read2_b32 v[14:15], v21 offset0:74 offset1:107
	s_waitcnt lgkmcnt(0)
	v_cvt_pk_bf16_f32 v13, v14, v15
	ds_read2_b32 v[14:15], v21 offset0:140 offset1:173
	s_waitcnt lgkmcnt(0)
	v_cvt_pk_bf16_f32 v14, v14, v15
	ds_read2_b32 v[28:29], v21 offset0:206 offset1:239
	s_waitcnt lgkmcnt(0)
	v_cvt_pk_bf16_f32 v15, v28, v29
	v_or_b32_e32 v28, v27, v22
	v_mul_u32_u24_e32 v28, 0x500, v28
	v_lshlrev_b32_e32 v128, 1, v28
	v_lshl_add_u64 v[28:29], v[16:17], 0, v[128:129]
	global_store_dwordx4 v[28:29], v[12:15], off sc1
	ds_read2_b32 v[12:13], v21 offset0:16 offset1:49
	s_waitcnt lgkmcnt(0)
	v_cvt_pk_bf16_f32 v12, v12, v13
	ds_read2_b32 v[14:15], v21 offset0:82 offset1:115
	s_waitcnt lgkmcnt(0)
	v_cvt_pk_bf16_f32 v13, v14, v15
	ds_read2_b32 v[14:15], v21 offset0:148 offset1:181
	s_waitcnt lgkmcnt(0)
	v_cvt_pk_bf16_f32 v14, v14, v15
	ds_read2_b32 v[28:29], v21 offset0:214 offset1:247
	s_waitcnt lgkmcnt(0)
	v_cvt_pk_bf16_f32 v15, v28, v29
	v_or_b32_e32 v28, v27, v23
	v_mul_u32_u24_e32 v28, 0x500, v28
	v_lshlrev_b32_e32 v128, 1, v28
	v_lshl_add_u64 v[28:29], v[16:17], 0, v[128:129]
	v_or_b32_e32 v27, v27, v24
	global_store_dwordx4 v[28:29], v[12:15], off sc1
	ds_read2_b32 v[12:13], v21 offset0:24 offset1:57
	v_mul_u32_u24_e32 v27, 0x500, v27
	s_waitcnt lgkmcnt(0)
	v_cvt_pk_bf16_f32 v12, v12, v13
	ds_read2_b32 v[14:15], v21 offset0:90 offset1:123
	v_lshlrev_b32_e32 v128, 1, v27
	s_waitcnt lgkmcnt(0)
	v_cvt_pk_bf16_f32 v13, v14, v15
	ds_read2_b32 v[14:15], v21 offset0:156 offset1:189
	v_lshl_add_u64 v[16:17], v[16:17], 0, v[128:129]
	s_waitcnt lgkmcnt(0)
	v_cvt_pk_bf16_f32 v14, v14, v15
	ds_read2_b32 v[28:29], v21 offset0:222 offset1:255
	s_waitcnt lgkmcnt(0)
	v_cvt_pk_bf16_f32 v15, v28, v29
	global_store_dwordx4 v[16:17], v[12:15], off sc1
	s_waitcnt lgkmcnt(0)
.LBB0_1102:
	s_andn2_saveexec_b64 s[46:47], s[46:47]
	s_cbranch_execz .LBB0_1104
	v_add_u16_e32 v12, 0xdf00, v3
	v_lshrrev_b16_e32 v13, 3, v12
	v_mul_u32_u24_e32 v13, 0x2493, v13
	v_lshrrev_b32_e32 v15, 16, v13
	v_mul_lo_u16_e32 v13, 56, v15
	v_sub_u16_e32 v12, v12, v13
	v_lshlrev_b16_e32 v14, 5, v12
	v_lshl_or_b32 v16, v15, 6, v18
	v_lshlrev_b32_e32 v128, 2, v14
	v_lshl_add_u64 v[12:13], v[10:11], 0, v[128:129]
	v_mul_u32_u24_e32 v128, 0x700, v16
	v_lshl_add_u64 v[12:13], v[128:129], 2, v[12:13]
	v_add_co_u32_e32 v16, vcc, 0x3000, v12
	s_mov_b32 s0, 0xa000
	s_nop 0
	v_addc_co_u32_e32 v17, vcc, 0, v13, vcc
	global_load_dword v28, v[16:17], off offset:2048
	v_add_co_u32_e32 v16, vcc, 0x7000, v12
	global_load_dword v27, v[12:13], off
	s_nop 0
	v_addc_co_u32_e32 v17, vcc, 0, v13, vcc
	global_load_dword v29, v[16:17], off
	v_add_co_u32_e32 v16, vcc, s0, v12
	s_mov_b32 s0, 0xe000
	s_nop 0
	v_addc_co_u32_e32 v17, vcc, 0, v13, vcc
	global_load_dword v30, v[16:17], off offset:2048
	v_add_co_u32_e32 v16, vcc, s0, v12
	s_mov_b32 s0, 0x18000
	s_nop 0
	v_addc_co_u32_e32 v17, vcc, 0, v13, vcc
	global_load_dword v31, v[16:17], off
	v_add_co_u32_e32 v16, vcc, 0x11000, v12
	v_lshlrev_b32_e32 v128, 7, v15
	s_nop 0
	v_addc_co_u32_e32 v17, vcc, 0, v13, vcc
	global_load_dword v32, v[16:17], off offset:2048
	v_add_co_u32_e32 v16, vcc, 0x15000, v12
	v_or_b32_e32 v15, v20, v14
	s_nop 0
	v_addc_co_u32_e32 v17, vcc, 0, v13, vcc
	global_load_dword v33, v[16:17], off
	v_add_co_u32_e32 v16, vcc, s0, v12
	s_mov_b32 s0, 0x1c000
	s_nop 0
	v_addc_co_u32_e32 v17, vcc, 0, v13, vcc
	global_load_dword v34, v[16:17], off offset:2048
	v_add_co_u32_e32 v16, vcc, s0, v12
	s_mov_b32 s0, 0x50000
	s_nop 0
; #define LAS __attribute__((address_space(3)))
; #define GAS __attribute__((address_space(1)))
; __device__ __forceinline__ unsigned cvt_pk_bf16(float lo, float hi) { unsigned r; asm volatile("v_cvt_pk_bf16_f32 %0, %1, %2" : "=v"(r) : "v"(lo), "v"(hi)); return r; }
; __device__ __forceinline__ void transpose_item(const float* W, int ldw, int k0, int n0, bf16_t* WT, int ldt, int drow0, int dk0, LAS float* scr, int lane) {
;     ...
;     for (int i = 0; i < 32; ++i) { const int kk = 2 * i + (lane >> 5); tv[i] = W[(size_t)(k0 + kk) * ldw + n0 + (lane & 31)]; }
; #pragma unroll
;     for (int i = 0; i < 32; ++i) { const int kk = 2 * i + (lane >> 5); scr[kk * 33 + (lane & 31)] = tv[i]; }
;     asm volatile("s_waitcnt lgkmcnt(0)" ::: "memory");
;     const int c = lane & 7;
; #pragma unroll
;     for (int j = 0; j < 4; ++j) { const int n = (lane >> 3) + 8 * j; const LAS float* s = scr + (8 * c) * 33 + n;
;         u32x4 o; o.x = cvt_pk_bf16(s[0 * 33], s[1 * 33]); o.y = cvt_pk_bf16(s[2 * 33], s[3 * 33]); o.z = cvt_pk_bf16(s[4 * 33], s[5 * 33]); o.w = cvt_pk_bf16(s[6 * 33], s[7 * 33]);
;         *(GAS u32x4*)((GAS bf16_t*)WT + (size_t)(drow0 + n) * ldt + dk0 + 8 * c) = o; }
; __device__ __forceinline__ void prep_weights(const Params& P, LAS unsigned char* lds, int lay, int bid, int G, int sel) {
;     ...
;               transpose_item(P.w_in + (size_t)mat * 1024 * 1792, 1792, kb * 64, nb * 32, (bf16_t*)(ws + OFF_WIN + mat * SZ_WIN1), 1024, nb * 32, kb * 64, scr, lane); continue; }
	v_addc_co_u32_e32 v17, vcc, 0, v13, vcc
	global_load_dword v35, v[16:17], off
	v_add_co_u32_e32 v16, vcc, 0x1f000, v12
	s_nop 1
	v_addc_co_u32_e32 v17, vcc, 0, v13, vcc
	global_load_dword v36, v[16:17], off offset:2048
	v_add_co_u32_e32 v16, vcc, 0x23000, v12
	s_nop 1
	v_addc_co_u32_e32 v17, vcc, 0, v13, vcc
	global_load_dword v37, v[16:17], off
	v_add_co_u32_e32 v16, vcc, 0x26000, v12
	s_nop 1
	v_addc_co_u32_e32 v17, vcc, 0, v13, vcc
	global_load_dword v38, v[16:17], off offset:2048
	v_add_co_u32_e32 v16, vcc, 0x2a000, v12
	s_nop 1
	v_addc_co_u32_e32 v17, vcc, 0, v13, vcc
	global_load_dword v39, v[16:17], off
	v_add_co_u32_e32 v16, vcc, 0x2d000, v12
	s_nop 1
	v_addc_co_u32_e32 v17, vcc, 0, v13, vcc
	global_load_dword v40, v[16:17], off offset:2048
	v_add_co_u32_e32 v16, vcc, 0x31000, v12
	s_nop 1
	v_addc_co_u32_e32 v17, vcc, 0, v13, vcc
	global_load_dword v41, v[16:17], off
	v_add_co_u32_e32 v16, vcc, 0x34000, v12
	s_nop 1
	v_addc_co_u32_e32 v17, vcc, 0, v13, vcc
	global_load_dword v42, v[16:17], off offset:2048
	v_add_co_u32_e32 v16, vcc, 0x38000, v12
	s_nop 1
	v_addc_co_u32_e32 v17, vcc, 0, v13, vcc
	global_load_dword v43, v[16:17], off
	v_add_co_u32_e32 v16, vcc, 0x3b000, v12
	s_nop 1
	v_addc_co_u32_e32 v17, vcc, 0, v13, vcc
	global_load_dword v44, v[16:17], off offset:2048
	v_add_co_u32_e32 v16, vcc, 0x3f000, v12
	s_nop 1
	v_addc_co_u32_e32 v17, vcc, 0, v13, vcc
	global_load_dword v45, v[16:17], off
	v_add_co_u32_e32 v16, vcc, 0x42000, v12
	s_nop 1
	v_addc_co_u32_e32 v17, vcc, 0, v13, vcc
	global_load_dword v46, v[16:17], off offset:2048
	v_add_co_u32_e32 v16, vcc, 0x46000, v12
	s_nop 1
	v_addc_co_u32_e32 v17, vcc, 0, v13, vcc
	global_load_dword v47, v[16:17], off
	v_add_co_u32_e32 v16, vcc, 0x49000, v12
	s_nop 1
	v_addc_co_u32_e32 v17, vcc, 0, v13, vcc
	global_load_dword v48, v[16:17], off offset:2048
	v_add_co_u32_e32 v16, vcc, 0x4d000, v12
	s_nop 1
	v_addc_co_u32_e32 v17, vcc, 0, v13, vcc
	global_load_dword v49, v[16:17], off
	v_add_co_u32_e32 v16, vcc, s0, v12
	s_nop 1
	v_addc_co_u32_e32 v17, vcc, 0, v13, vcc
	global_load_dword v50, v[16:17], off offset:2048
	v_add_co_u32_e32 v16, vcc, 0x54000, v12
	s_nop 1
	v_addc_co_u32_e32 v17, vcc, 0, v13, vcc
	global_load_dword v51, v[16:17], off
	v_add_co_u32_e32 v16, vcc, 0x57000, v12
	s_nop 1
	v_addc_co_u32_e32 v17, vcc, 0, v13, vcc
	global_load_dword v52, v[16:17], off offset:2048
	v_add_co_u32_e32 v16, vcc, 0x5b000, v12
	s_nop 1
	v_addc_co_u32_e32 v17, vcc, 0, v13, vcc
	global_load_dword v53, v[16:17], off
	v_add_co_u32_e32 v16, vcc, 0x5e000, v12
	s_nop 1
	v_addc_co_u32_e32 v17, vcc, 0, v13, vcc
	global_load_dword v54, v[16:17], off offset:2048
	v_add_co_u32_e32 v16, vcc, 0x62000, v12
	s_nop 1
	v_addc_co_u32_e32 v17, vcc, 0, v13, vcc
	global_load_dword v55, v[16:17], off
	v_add_co_u32_e32 v16, vcc, 0x65000, v12
	s_nop 1
	v_addc_co_u32_e32 v17, vcc, 0, v13, vcc
	global_load_dword v56, v[16:17], off offset:2048
	v_add_co_u32_e32 v16, vcc, 0x69000, v12
	s_nop 1
	v_addc_co_u32_e32 v17, vcc, 0, v13, vcc
	v_add_co_u32_e32 v12, vcc, 0x6c000, v12
	global_load_dword v16, v[16:17], off
	s_nop 0
	v_addc_co_u32_e32 v13, vcc, 0, v13, vcc
	global_load_dword v12, v[12:13], off offset:2048
	v_add_u32_e32 v13, 0x400, v19
	s_waitcnt vmcnt(30)
	ds_write2_b32 v19, v27, v28 offset1:66
	s_waitcnt vmcnt(28)
	ds_write2_b32 v19, v29, v30 offset0:132 offset1:198
	s_waitcnt vmcnt(26)
	ds_write2_b32 v13, v31, v32 offset0:8 offset1:74
	s_waitcnt vmcnt(24)
	ds_write2_b32 v13, v33, v34 offset0:140 offset1:206
	v_add_u32_e32 v13, 0x800, v19
	s_waitcnt vmcnt(22)
	ds_write2_b32 v13, v35, v36 offset0:16 offset1:82
	s_waitcnt vmcnt(20)
	ds_write2_b32 v13, v37, v38 offset0:148 offset1:214
	v_add_u32_e32 v13, 0xc00, v19
	s_waitcnt vmcnt(18)
	ds_write2_b32 v13, v39, v40 offset0:24 offset1:90
	s_waitcnt vmcnt(16)
	ds_write2_b32 v13, v41, v42 offset0:156 offset1:222
	v_add_u32_e32 v13, 0x1000, v19
	s_waitcnt vmcnt(14)
	ds_write2_b32 v13, v43, v44 offset0:32 offset1:98
	s_waitcnt vmcnt(12)
	ds_write2_b32 v13, v45, v46 offset0:164 offset1:230
	v_add_u32_e32 v13, 0x1400, v19
	s_waitcnt vmcnt(10)
	ds_write2_b32 v13, v47, v48 offset0:40 offset1:106
	s_waitcnt vmcnt(8)
	ds_write2_b32 v13, v49, v50 offset0:172 offset1:238
	v_add_u32_e32 v13, 0x1800, v19
	s_waitcnt vmcnt(6)
	ds_write2_b32 v13, v51, v52 offset0:48 offset1:114
	s_waitcnt vmcnt(4)
	ds_write2_b32 v13, v53, v54 offset0:180 offset1:246
	v_add_u32_e32 v13, 0x1c00, v19
	s_waitcnt vmcnt(2)
	ds_write2_b32 v13, v55, v56 offset0:56 offset1:122
	s_waitcnt vmcnt(0)
	ds_write2_b32 v13, v16, v12 offset0:188 offset1:254
	s_waitcnt lgkmcnt(0)
	ds_read2_b32 v[16:17], v21 offset1:33
	s_waitcnt lgkmcnt(0)
	v_cvt_pk_bf16_f32 v28, v16, v17
	ds_read2_b32 v[16:17], v21 offset0:66 offset1:99
	s_waitcnt lgkmcnt(0)
	v_cvt_pk_bf16_f32 v29, v16, v17
	ds_read2_b32 v[16:17], v21 offset0:132 offset1:165
	v_lshl_add_u64 v[12:13], v[6:7], 0, v[128:129]
	s_waitcnt lgkmcnt(0)
	v_cvt_pk_bf16_f32 v30, v16, v17
	ds_read2_b32 v[16:17], v21 offset0:198 offset1:231
	v_lshlrev_b32_e32 v128, 11, v15
	s_waitcnt lgkmcnt(0)
	v_cvt_pk_bf16_f32 v31, v16, v17
	v_lshl_add_u64 v[16:17], v[12:13], 0, v[128:129]
	global_store_dwordx4 v[16:17], v[28:31], off sc1
	ds_read2_b32 v[16:17], v21 offset0:8 offset1:41
	v_or_b32_e32 v15, v22, v14
	s_waitcnt lgkmcnt(0)
	v_cvt_pk_bf16_f32 v28, v16, v17
	ds_read2_b32 v[16:17], v21 offset0:74 offset1:107
	s_waitcnt lgkmcnt(0)
	v_cvt_pk_bf16_f32 v29, v16, v17
	ds_read2_b32 v[16:17], v21 offset0:140 offset1:173
	s_waitcnt lgkmcnt(0)
	v_cvt_pk_bf16_f32 v30, v16, v17
	ds_read2_b32 v[16:17], v21 offset0:206 offset1:239
	v_lshlrev_b32_e32 v128, 11, v15
	s_waitcnt lgkmcnt(0)
	v_cvt_pk_bf16_f32 v31, v16, v17
	v_lshl_add_u64 v[16:17], v[12:13], 0, v[128:129]
	global_store_dwordx4 v[16:17], v[28:31], off sc1
	ds_read2_b32 v[16:17], v21 offset0:16 offset1:49
	v_or_b32_e32 v15, v23, v14
	s_waitcnt lgkmcnt(0)
	v_cvt_pk_bf16_f32 v28, v16, v17
	ds_read2_b32 v[16:17], v21 offset0:82 offset1:115
	s_waitcnt lgkmcnt(0)
	v_cvt_pk_bf16_f32 v29, v16, v17
	ds_read2_b32 v[16:17], v21 offset0:148 offset1:181
	s_waitcnt lgkmcnt(0)
	v_cvt_pk_bf16_f32 v30, v16, v17
	ds_read2_b32 v[16:17], v21 offset0:214 offset1:247
	v_lshlrev_b32_e32 v128, 11, v15
	s_waitcnt lgkmcnt(0)
	v_cvt_pk_bf16_f32 v31, v16, v17
	v_lshl_add_u64 v[16:17], v[12:13], 0, v[128:129]
	global_store_dwordx4 v[16:17], v[28:31], off sc1
	ds_read2_b32 v[16:17], v21 offset0:24 offset1:57
	v_or_b32_e32 v14, v24, v14
	s_waitcnt lgkmcnt(0)
	v_cvt_pk_bf16_f32 v28, v16, v17
	ds_read2_b32 v[16:17], v21 offset0:90 offset1:123
	v_lshlrev_b32_e32 v128, 11, v14
	s_waitcnt lgkmcnt(0)
	v_cvt_pk_bf16_f32 v29, v16, v17
	ds_read2_b32 v[16:17], v21 offset0:156 offset1:189
	v_lshl_add_u64 v[12:13], v[12:13], 0, v[128:129]
	s_waitcnt lgkmcnt(0)
	v_cvt_pk_bf16_f32 v30, v16, v17
	ds_read2_b32 v[16:17], v21 offset0:222 offset1:255
	s_waitcnt lgkmcnt(0)
	v_cvt_pk_bf16_f32 v31, v16, v17
	global_store_dwordx4 v[12:13], v[28:31], off sc1
	s_waitcnt lgkmcnt(0)

; __device__ __forceinline__ void transpose_item(const float* W, int ldw, int k0, int n0, bf16_t* WT, int ldt, int drow0, int dk0, LAS float* scr, int lane) {
;     ...
;     for (int i = 0; i < 32; ++i) { const int kk = 2 * i + (lane >> 5); tv[i] = W[(size_t)(k0 + kk) * ldw + n0 + (lane & 31)]; }
; __device__ __forceinline__ void prep_weights(const Params& P, LAS unsigned char* lds, int lay, int bid, int G, int sel) {
;     ...
;           if (r < 2 * I_DN) { if (!((sel >> (2 + r / I_DN)) & 1)) continue; const int mat = lay * 2 + r / I_DN, ii = r % I_DN, kb = ii / 32, nb = ii % 32;
;               transpose_item(P.w_down + (size_t)mat * DFF * 1024, 1024, kb * 64, nb * 32, (bf16_t*)(ws + OFF_WDN + mat * SZ_WDN1), DFF, nb * 32, kb * 64, scr, lane); continue; }
.LBB0_1105:
	s_andn2_saveexec_b64 s[8:9], s[8:9]
	s_cbranch_execz .LBB0_1107
	v_add_u32_e32 v12, 0xffffea00, v3
	s_movk_i32 s0, 0x57f
	v_cmp_lt_u32_e32 vcc, s0, v12
	s_movk_i32 s0, 0x580
	v_readlane_b32 s44, v250, 0
	v_cndmask_b32_e64 v13, 0, 1, vcc
	v_or_b32_e32 v17, 2, v13
	v_add_u32_e32 v13, 0xffffe480, v3
	v_cmp_gt_u32_e32 vcc, s0, v12
	v_readlane_b32 s45, v250, 1
	s_mov_b32 s0, 0xb00000
	v_cndmask_b32_e32 v16, v13, v12, vcc
	v_mov_b64_e32 v[12:13], s[44:45]
	v_mad_u64_u32 v[14:15], s[0:1], v17, s0, v[12:13]
	v_lshlrev_b32_e32 v12, 1, v16
	v_and_b32_e32 v27, 0xfc0, v12
	v_lshlrev_b32_e32 v12, 5, v16
	v_readlane_b32 s0, v252, 51
	v_and_b32_e32 v16, 0x3e0, v12
	v_readlane_b32 s1, v252, 52
	v_lshlrev_b32_e32 v128, 2, v16
	v_lshl_add_u64 v[14:15], v[14:15], 0, v[128:129]
	v_mov_b64_e32 v[12:13], s[0:1]
	s_mov_b32 s0, 0x580000
	v_mad_u64_u32 v[12:13], s[0:1], v17, s0, v[12:13]
	v_or_b32_e32 v17, v27, v18
	v_lshlrev_b32_e32 v128, 2, v0
	v_lshl_add_u64 v[14:15], v[14:15], 0, v[128:129]
	v_lshlrev_b32_e32 v128, 12, v17
	v_lshl_add_u64 v[14:15], v[14:15], 0, v[128:129]
	s_movk_i32 s0, 0x2000
	v_add_co_u32_e32 v28, vcc, s0, v14
	s_movk_i32 s0, 0x4000
	s_nop 0
	v_addc_co_u32_e32 v29, vcc, 0, v15, vcc
	global_load_dword v17, v[14:15], off
	global_load_dword v30, v[28:29], off
	v_add_co_u32_e32 v28, vcc, s0, v14
	s_movk_i32 s0, 0x6000
	s_nop 0
	v_addc_co_u32_e32 v29, vcc, 0, v15, vcc
	global_load_dword v31, v[28:29], off
	v_add_co_u32_e32 v28, vcc, s0, v14
	s_mov_b32 s0, 0xa000
	s_nop 0
	v_addc_co_u32_e32 v29, vcc, 0, v15, vcc
	global_load_dword v32, v[28:29], off
	v_add_co_u32_e32 v28, vcc, s25, v14
	v_lshlrev_b32_e32 v128, 1, v27
	s_nop 0
	v_addc_co_u32_e32 v29, vcc, 0, v15, vcc
	global_load_dword v33, v[28:29], off
	v_add_co_u32_e32 v28, vcc, s0, v14
	s_mov_b32 s0, 0xc000
	s_nop 0
	v_addc_co_u32_e32 v29, vcc, 0, v15, vcc
	global_load_dword v34, v[28:29], off
	v_add_co_u32_e32 v28, vcc, s0, v14
	s_mov_b32 s0, 0xe000
	s_nop 0
	v_addc_co_u32_e32 v29, vcc, 0, v15, vcc
	global_load_dword v35, v[28:29], off
	v_add_co_u32_e32 v28, vcc, s0, v14
	s_mov_b32 s0, 0x10000
	s_nop 0
	v_addc_co_u32_e32 v29, vcc, 0, v15, vcc
	global_load_dword v36, v[28:29], off
	v_add_co_u32_e32 v28, vcc, s0, v14
	s_mov_b32 s0, 0x12000
	s_nop 0
	v_addc_co_u32_e32 v29, vcc, 0, v15, vcc
	global_load_dword v37, v[28:29], off
	v_add_co_u32_e32 v28, vcc, s0, v14
	s_mov_b32 s0, 0x14000
	s_nop 0
	v_addc_co_u32_e32 v29, vcc, 0, v15, vcc
	global_load_dword v38, v[28:29], off
	v_add_co_u32_e32 v28, vcc, s0, v14
	s_mov_b32 s0, 0x16000
	s_nop 0
	v_addc_co_u32_e32 v29, vcc, 0, v15, vcc
	global_load_dword v39, v[28:29], off
	v_add_co_u32_e32 v28, vcc, s0, v14
	s_mov_b32 s0, 0x18000
	s_nop 0
	v_addc_co_u32_e32 v29, vcc, 0, v15, vcc
	global_load_dword v40, v[28:29], off
	v_add_co_u32_e32 v28, vcc, s0, v14
	s_mov_b32 s0, 0x1a000
	s_nop 0
	v_addc_co_u32_e32 v29, vcc, 0, v15, vcc
	global_load_dword v41, v[28:29], off
	v_add_co_u32_e32 v28, vcc, s0, v14
	s_mov_b32 s0, 0x1c000
	s_nop 0
	v_addc_co_u32_e32 v29, vcc, 0, v15, vcc
	global_load_dword v42, v[28:29], off
	v_add_co_u32_e32 v28, vcc, s0, v14
	s_mov_b32 s0, 0x1e000
	s_nop 0
	v_addc_co_u32_e32 v29, vcc, 0, v15, vcc
	global_load_dword v43, v[28:29], off
	v_add_co_u32_e32 v28, vcc, s0, v14
	s_mov_b32 s0, 0x20000
	s_nop 0
	v_addc_co_u32_e32 v29, vcc, 0, v15, vcc
	global_load_dword v44, v[28:29], off
	v_add_co_u32_e32 v28, vcc, s0, v14
	s_mov_b32 s0, 0x22000
	s_nop 0
	v_addc_co_u32_e32 v29, vcc, 0, v15, vcc
	global_load_dword v45, v[28:29], off
	v_add_co_u32_e32 v28, vcc, s0, v14
	s_mov_b32 s0, 0x24000
	s_nop 0
	v_addc_co_u32_e32 v29, vcc, 0, v15, vcc
	global_load_dword v46, v[28:29], off
	v_add_co_u32_e32 v28, vcc, s0, v14
	s_mov_b32 s0, 0x26000
	s_nop 0
	v_addc_co_u32_e32 v29, vcc, 0, v15, vcc
	global_load_dword v47, v[28:29], off
	v_add_co_u32_e32 v28, vcc, s0, v14
	s_mov_b32 s0, 0x28000
	s_nop 0
	v_addc_co_u32_e32 v29, vcc, 0, v15, vcc
	global_load_dword v48, v[28:29], off
	v_add_co_u32_e32 v28, vcc, s0, v14
	s_mov_b32 s0, 0x2a000
	s_nop 0
	v_addc_co_u32_e32 v29, vcc, 0, v15, vcc
	global_load_dword v49, v[28:29], off
	v_add_co_u32_e32 v28, vcc, s0, v14
	s_mov_b32 s0, 0x2c000
	s_nop 0
	v_addc_co_u32_e32 v29, vcc, 0, v15, vcc
	global_load_dword v50, v[28:29], off
	v_add_co_u32_e32 v28, vcc, s0, v14
	s_mov_b32 s0, 0x2e000
	s_nop 0
	v_addc_co_u32_e32 v29, vcc, 0, v15, vcc
	global_load_dword v51, v[28:29], off
	v_add_co_u32_e32 v28, vcc, s0, v14
	s_mov_b32 s0, 0x30000
	s_nop 0
	v_addc_co_u32_e32 v29, vcc, 0, v15, vcc
	global_load_dword v52, v[28:29], off
	v_add_co_u32_e32 v28, vcc, s0, v14
	s_mov_b32 s0, 0x32000
	s_nop 0
	v_addc_co_u32_e32 v29, vcc, 0, v15, vcc
	global_load_dword v53, v[28:29], off
	v_add_co_u32_e32 v28, vcc, s0, v14
	s_mov_b32 s0, 0x34000
	s_nop 0
	v_addc_co_u32_e32 v29, vcc, 0, v15, vcc
	global_load_dword v54, v[28:29], off
	v_add_co_u32_e32 v28, vcc, s0, v14
	s_mov_b32 s0, 0x36000
	s_nop 0
	v_addc_co_u32_e32 v29, vcc, 0, v15, vcc
	global_load_dword v55, v[28:29], off
	v_add_co_u32_e32 v28, vcc, s0, v14
	s_mov_b32 s0, 0x38000
	s_nop 0
	v_addc_co_u32_e32 v29, vcc, 0, v15, vcc
	global_load_dword v56, v[28:29], off
	v_add_co_u32_e32 v28, vcc, s0, v14
	s_mov_b32 s0, 0x3a000
	s_nop 0
	v_addc_co_u32_e32 v29, vcc, 0, v15, vcc
	global_load_dword v57, v[28:29], off
	v_add_co_u32_e32 v28, vcc, s0, v14
	s_mov_b32 s0, 0x3c000
	s_nop 0
	v_addc_co_u32_e32 v29, vcc, 0, v15, vcc
	global_load_dword v58, v[28:29], off
	v_add_co_u32_e32 v28, vcc, s0, v14
	s_mov_b32 s0, 0x3e000
	s_nop 0
	v_addc_co_u32_e32 v29, vcc, 0, v15, vcc
	v_add_co_u32_e32 v14, vcc, s0, v14
	global_load_dword v28, v[28:29], off
	s_nop 0
	v_addc_co_u32_e32 v15, vcc, 0, v15, vcc
	global_load_dword v14, v[14:15], off
	v_add_u32_e32 v15, 0x400, v19
	s_waitcnt vmcnt(30)
; #define LAS __attribute__((address_space(3)))
; #define GAS __attribute__((address_space(1)))
; __device__ __forceinline__ unsigned cvt_pk_bf16(float lo, float hi) { unsigned r; asm volatile("v_cvt_pk_bf16_f32 %0, %1, %2" : "=v"(r) : "v"(lo), "v"(hi)); return r; }
; __device__ __forceinline__ void transpose_item(const float* W, int ldw, int k0, int n0, bf16_t* WT, int ldt, int drow0, int dk0, LAS float* scr, int lane) {
;     ...
;     for (int i = 0; i < 32; ++i) { const int kk = 2 * i + (lane >> 5); scr[kk * 33 + (lane & 31)] = tv[i]; }
;     asm volatile("s_waitcnt lgkmcnt(0)" ::: "memory");
;     const int c = lane & 7;
; #pragma unroll
;     for (int j = 0; j < 4; ++j) { const int n = (lane >> 3) + 8 * j; const LAS float* s = scr + (8 * c) * 33 + n;
;         u32x4 o; o.x = cvt_pk_bf16(s[0 * 33], s[1 * 33]); o.y = cvt_pk_bf16(s[2 * 33], s[3 * 33]); o.z = cvt_pk_bf16(s[4 * 33], s[5 * 33]); o.w = cvt_pk_bf16(s[6 * 33], s[7 * 33]);
;         *(GAS u32x4*)((GAS bf16_t*)WT + (size_t)(drow0 + n) * ldt + dk0 + 8 * c) = o; }
; __device__ __forceinline__ void prep_weights(const Params& P, LAS unsigned char* lds, int lay, int bid, int G, int sel) {
;     ...
;               transpose_item(P.w_down + (size_t)mat * DFF * 1024, 1024, kb * 64, nb * 32, (bf16_t*)(ws + OFF_WDN + mat * SZ_WDN1), DFF, nb * 32, kb * 64, scr, lane); continue; }
	ds_write2_b32 v19, v17, v30 offset1:66
	s_waitcnt vmcnt(28)
	ds_write2_b32 v19, v31, v32 offset0:132 offset1:198
	s_waitcnt vmcnt(26)
	ds_write2_b32 v15, v33, v34 offset0:8 offset1:74
	s_waitcnt vmcnt(24)
	ds_write2_b32 v15, v35, v36 offset0:140 offset1:206
	v_add_u32_e32 v15, 0x800, v19
	s_waitcnt vmcnt(22)
	ds_write2_b32 v15, v37, v38 offset0:16 offset1:82
	s_waitcnt vmcnt(20)
	ds_write2_b32 v15, v39, v40 offset0:148 offset1:214
	v_add_u32_e32 v15, 0xc00, v19
	s_waitcnt vmcnt(18)
	ds_write2_b32 v15, v41, v42 offset0:24 offset1:90
	s_waitcnt vmcnt(16)
	ds_write2_b32 v15, v43, v44 offset0:156 offset1:222
	v_add_u32_e32 v15, 0x1000, v19
	s_waitcnt vmcnt(14)
	ds_write2_b32 v15, v45, v46 offset0:32 offset1:98
	s_waitcnt vmcnt(12)
	ds_write2_b32 v15, v47, v48 offset0:164 offset1:230
	v_add_u32_e32 v15, 0x1400, v19
	s_waitcnt vmcnt(10)
	ds_write2_b32 v15, v49, v50 offset0:40 offset1:106
	s_waitcnt vmcnt(8)
	ds_write2_b32 v15, v51, v52 offset0:172 offset1:238
	v_add_u32_e32 v15, 0x1800, v19
	s_waitcnt vmcnt(6)
	ds_write2_b32 v15, v53, v54 offset0:48 offset1:114
	s_waitcnt vmcnt(4)
	ds_write2_b32 v15, v55, v56 offset0:180 offset1:246
	v_add_u32_e32 v15, 0x1c00, v19
	s_waitcnt vmcnt(2)
	ds_write2_b32 v15, v57, v58 offset0:56 offset1:122
	s_waitcnt vmcnt(0)
	ds_write2_b32 v15, v28, v14 offset0:188 offset1:254
	s_waitcnt lgkmcnt(0)
	v_lshl_add_u64 v[12:13], v[12:13], 0, v[128:129]
	v_lshlrev_b32_e32 v128, 1, v2
	v_lshl_add_u64 v[28:29], v[12:13], 0, v[128:129]
	ds_read2_b32 v[12:13], v21 offset1:33
	s_waitcnt lgkmcnt(0)
	v_cvt_pk_bf16_f32 v12, v12, v13
	ds_read2_b32 v[14:15], v21 offset0:66 offset1:99
	v_or_b32_e32 v17, v16, v20
	s_waitcnt lgkmcnt(0)
	v_cvt_pk_bf16_f32 v13, v14, v15
	ds_read2_b32 v[14:15], v21 offset0:132 offset1:165
	v_mul_u32_u24_e32 v17, 0xb00, v17
	s_waitcnt lgkmcnt(0)
	v_cvt_pk_bf16_f32 v14, v14, v15
	ds_read2_b32 v[30:31], v21 offset0:198 offset1:231
	v_lshlrev_b32_e32 v128, 1, v17
	s_waitcnt lgkmcnt(0)
	v_cvt_pk_bf16_f32 v15, v30, v31
	v_lshl_add_u64 v[30:31], v[28:29], 0, v[128:129]
	global_store_dwordx4 v[30:31], v[12:15], off sc1
	ds_read2_b32 v[12:13], v21 offset0:8 offset1:41
	v_or_b32_e32 v17, v16, v22
	s_waitcnt lgkmcnt(0)
	v_cvt_pk_bf16_f32 v12, v12, v13
	ds_read2_b32 v[14:15], v21 offset0:74 offset1:107
	s_waitcnt lgkmcnt(0)
	v_cvt_pk_bf16_f32 v13, v14, v15
	ds_read2_b32 v[14:15], v21 offset0:140 offset1:173
	v_mul_u32_u24_e32 v17, 0xb00, v17
	s_waitcnt lgkmcnt(0)
	v_cvt_pk_bf16_f32 v14, v14, v15
	ds_read2_b32 v[30:31], v21 offset0:206 offset1:239
	v_lshlrev_b32_e32 v128, 1, v17
	s_waitcnt lgkmcnt(0)
	v_cvt_pk_bf16_f32 v15, v30, v31
	v_lshl_add_u64 v[30:31], v[28:29], 0, v[128:129]
	global_store_dwordx4 v[30:31], v[12:15], off sc1
	ds_read2_b32 v[12:13], v21 offset0:16 offset1:49
	v_or_b32_e32 v17, v16, v23
	s_waitcnt lgkmcnt(0)
	v_cvt_pk_bf16_f32 v12, v12, v13
	ds_read2_b32 v[14:15], v21 offset0:82 offset1:115
	s_waitcnt lgkmcnt(0)
	v_cvt_pk_bf16_f32 v13, v14, v15
	ds_read2_b32 v[14:15], v21 offset0:148 offset1:181
	v_mul_u32_u24_e32 v17, 0xb00, v17
	s_waitcnt lgkmcnt(0)
	v_cvt_pk_bf16_f32 v14, v14, v15
	ds_read2_b32 v[30:31], v21 offset0:214 offset1:247
	v_lshlrev_b32_e32 v128, 1, v17
	s_waitcnt lgkmcnt(0)
	v_cvt_pk_bf16_f32 v15, v30, v31
	v_lshl_add_u64 v[30:31], v[28:29], 0, v[128:129]
	v_or_b32_e32 v16, v16, v24
	global_store_dwordx4 v[30:31], v[12:15], off sc1
	ds_read2_b32 v[12:13], v21 offset0:24 offset1:57
	v_mul_u32_u24_e32 v16, 0xb00, v16
	s_waitcnt lgkmcnt(0)
	v_cvt_pk_bf16_f32 v12, v12, v13
	ds_read2_b32 v[14:15], v21 offset0:90 offset1:123
	v_lshlrev_b32_e32 v128, 1, v16
	s_waitcnt lgkmcnt(0)
	v_cvt_pk_bf16_f32 v13, v14, v15
	ds_read2_b32 v[14:15], v21 offset0:156 offset1:189
	v_lshl_add_u64 v[16:17], v[28:29], 0, v[128:129]
	s_waitcnt lgkmcnt(0)
	v_cvt_pk_bf16_f32 v14, v14, v15
	ds_read2_b32 v[30:31], v21 offset0:222 offset1:255
	s_waitcnt lgkmcnt(0)
	v_cvt_pk_bf16_f32 v15, v30, v31
	global_store_dwordx4 v[16:17], v[12:15], off sc1
	s_waitcnt lgkmcnt(0)
	v_readlane_b32 s46, v250, 2
	v_readlane_b32 s47, v250, 3
	v_readlane_b32 s48, v250, 4
	v_readlane_b32 s49, v250, 5
	v_readlane_b32 s50, v250, 6
	v_readlane_b32 s51, v250, 7
	v_readlane_b32 s52, v250, 8
	v_readlane_b32 s53, v250, 9
	v_readlane_b32 s54, v250, 10
	v_readlane_b32 s55, v250, 11
	v_readlane_b32 s56, v250, 12
	v_readlane_b32 s57, v250, 13
	v_readlane_b32 s58, v250, 14
	v_readlane_b32 s59, v250, 15

; __device__ __forceinline__ void prep_weights(const Params& P, LAS unsigned char* lds, int lay, int bid, int G, int sel) {
;     ...
;           for (int m0 = 0; m0 < 64; m0 += 32) { float wv[32];
; #pragma unroll
;               for (int m = 0; m < 32; ++m) wv[m] = wp[(size_t)(m0 + m) * 1024];
; #pragma unroll
;               for (int m = 0; m < 32; ++m) { const int t = ((m0 + m) * j) & 63; cs += tab64[t] * wv[m]; sn += tab64[(t + 48) & 63] * wv[m]; } }
.LBB0_1117:
	s_lshl_b32 s74, s3, 10
	v_lshl_add_u64 v[24:25], s[74:75], 2, v[2:3]
	v_add_co_u32_e32 v12, vcc, 0x1000, v24
	global_load_dword v50, v[24:25], off
	s_nop 0
	v_addc_co_u32_e32 v13, vcc, 0, v25, vcc
	global_load_dword v52, v[12:13], off
	v_add_co_u32_e32 v12, vcc, 0x2000, v24
	s_add_i32 s0, 0, 0x24000
	s_nop 0
	v_addc_co_u32_e32 v13, vcc, 0, v25, vcc
	global_load_dword v54, v[12:13], off
	v_add_co_u32_e32 v12, vcc, 0x3000, v24
	s_nop 1
	v_addc_co_u32_e32 v13, vcc, 0, v25, vcc
	global_load_dword v56, v[12:13], off
	v_add_co_u32_e32 v12, vcc, 0x4000, v24
	s_nop 1
	v_addc_co_u32_e32 v13, vcc, 0, v25, vcc
	global_load_dword v58, v[12:13], off
	v_add_co_u32_e32 v12, vcc, 0x5000, v24
	s_nop 1
	v_addc_co_u32_e32 v13, vcc, 0, v25, vcc
	global_load_dword v60, v[12:13], off
	v_add_co_u32_e32 v12, vcc, 0x6000, v24
	s_nop 1
	v_addc_co_u32_e32 v13, vcc, 0, v25, vcc
	global_load_dword v62, v[12:13], off
	v_add_co_u32_e32 v12, vcc, 0x7000, v24
	s_nop 1
	v_addc_co_u32_e32 v13, vcc, 0, v25, vcc
	global_load_dword v64, v[12:13], off
	v_add_co_u32_e32 v12, vcc, s21, v24
	s_nop 1
	v_addc_co_u32_e32 v13, vcc, 0, v25, vcc
	global_load_dword v66, v[12:13], off offset:-4096
	global_load_dword v68, v[12:13], off
	v_add_co_u32_e32 v12, vcc, s14, v24
	s_nop 1
	v_addc_co_u32_e32 v13, vcc, 0, v25, vcc
	global_load_dword v28, v[12:13], off offset:-4096
	global_load_dword v30, v[12:13], off
	v_add_co_u32_e32 v12, vcc, s15, v24
	s_nop 1
	v_addc_co_u32_e32 v13, vcc, 0, v25, vcc
	global_load_dword v32, v[12:13], off offset:-4096
	global_load_dword v34, v[12:13], off
	v_add_co_u32_e32 v12, vcc, s26, v24
	s_nop 1
	v_addc_co_u32_e32 v13, vcc, 0, v25, vcc
	global_load_dword v36, v[12:13], off offset:-4096
	global_load_dword v38, v[12:13], off
	v_add_co_u32_e32 v12, vcc, s27, v24
	s_nop 1
	v_addc_co_u32_e32 v13, vcc, 0, v25, vcc
	global_load_dword v40, v[12:13], off offset:-4096
	global_load_dword v42, v[12:13], off
	v_add_co_u32_e32 v12, vcc, s63, v24
	s_nop 1
	v_addc_co_u32_e32 v13, vcc, 0, v25, vcc
	global_load_dword v44, v[12:13], off offset:-4096
	global_load_dword v46, v[12:13], off
	v_add_co_u32_e32 v12, vcc, s64, v24
	s_nop 1
	v_addc_co_u32_e32 v13, vcc, 0, v25, vcc
	global_load_dword v48, v[12:13], off offset:-4096
	global_load_dword v6, v[12:13], off
	v_add_co_u32_e32 v12, vcc, s65, v24
	s_nop 1
	v_addc_co_u32_e32 v13, vcc, 0, v25, vcc
	v_add_co_u32_e32 v14, vcc, s66, v24
	global_load_dword v8, v[12:13], off offset:-4096
	global_load_dword v10, v[12:13], off
	v_addc_co_u32_e32 v15, vcc, 0, v25, vcc
	v_add_co_u32_e32 v18, vcc, s67, v24
	v_mul_u32_u24_e32 v13, s3, v11
	s_nop 0
	v_addc_co_u32_e32 v19, vcc, 0, v25, vcc
	v_add_co_u32_e32 v22, vcc, s68, v24
	v_and_b32_e32 v13, 32, v13
	s_nop 0
	v_addc_co_u32_e32 v23, vcc, 0, v25, vcc
	v_add_co_u32_e32 v26, vcc, s69, v24
	v_lshl_add_u32 v13, v13, 2, s0
	s_nop 0
	v_addc_co_u32_e32 v27, vcc, 0, v25, vcc
	global_load_dword v12, v[14:15], off offset:-4096
	s_nop 0
	global_load_dword v14, v[14:15], off
	s_nop 0
	global_load_dword v16, v[18:19], off offset:-4096
	s_nop 0
	global_load_dword v18, v[18:19], off
	s_nop 0
	global_load_dword v20, v[22:23], off offset:-4096
	s_nop 0
	global_load_dword v22, v[22:23], off
	s_nop 0
	global_load_dword v24, v[26:27], off offset:-4096
	s_nop 0
	global_load_dword v26, v[26:27], off
	ds_read_b32 v70, v13
	v_mad_u32_u24 v13, s3, v11, 48
	v_and_b32_e32 v13, 48, v13
	v_lshl_add_u32 v13, v13, 2, s0
	ds_read_b32 v71, v13
	v_mad_u32_u24 v13, s3, v11, v11
	v_and_b32_e32 v15, 63, v13
	v_lshl_add_u32 v15, v15, 2, s0
	ds_read_b32 v72, v15
	v_add_u32_e32 v15, 48, v13
	v_and_b32_e32 v15, 63, v15
	v_lshl_add_u32 v15, v15, 2, s0
	v_add_u32_e32 v13, v13, v11
	ds_read_b32 v73, v15
	v_and_b32_e32 v15, 62, v13
	v_lshl_add_u32 v15, v15, 2, s0
	ds_read_b32 v74, v15
	v_add_u32_e32 v15, 48, v13
	v_and_b32_e32 v15, 62, v15
	v_lshl_add_u32 v15, v15, 2, s0
	v_add_u32_e32 v13, v13, v11
	ds_read_b32 v75, v15
	v_and_b32_e32 v15, 63, v13
	v_lshl_add_u32 v15, v15, 2, s0
	ds_read_b32 v76, v15
	v_add_u32_e32 v15, 48, v13
	v_and_b32_e32 v15, 63, v15
	v_lshl_add_u32 v15, v15, 2, s0
	v_add_u32_e32 v13, v13, v11
	ds_read_b32 v77, v15
	v_and_b32_e32 v15, 60, v13
	v_lshl_add_u32 v15, v15, 2, s0
	ds_read_b32 v78, v15
	v_add_u32_e32 v15, 48, v13
	v_and_b32_e32 v15, 60, v15
	v_lshl_add_u32 v15, v15, 2, s0
	v_add_u32_e32 v13, v13, v11
	ds_read_b32 v79, v15
	v_and_b32_e32 v15, 63, v13
	v_lshl_add_u32 v15, v15, 2, s0
	ds_read_b32 v80, v15
	v_add_u32_e32 v15, 48, v13
	v_and_b32_e32 v15, 63, v15
	v_lshl_add_u32 v15, v15, 2, s0
	v_add_u32_e32 v13, v13, v11
	ds_read_b32 v81, v15
	v_and_b32_e32 v15, 62, v13
	v_lshl_add_u32 v15, v15, 2, s0
	ds_read_b32 v82, v15
	v_add_u32_e32 v15, 48, v13
	v_and_b32_e32 v15, 62, v15
	v_lshl_add_u32 v15, v15, 2, s0
	v_add_u32_e32 v13, v13, v11
	ds_read_b32 v83, v15
	v_and_b32_e32 v15, 63, v13
	v_lshl_add_u32 v15, v15, 2, s0
	ds_read_b32 v84, v15
	v_add_u32_e32 v15, 48, v13
	v_and_b32_e32 v15, 63, v15
	v_lshl_add_u32 v15, v15, 2, s0
	v_add_u32_e32 v13, v13, v11
	ds_read_b32 v85, v15
	v_and_b32_e32 v15, 56, v13
	v_lshl_add_u32 v15, v15, 2, s0
	ds_read_b32 v86, v15
	v_add_u32_e32 v15, 48, v13
	v_and_b32_e32 v15, 56, v15
	v_lshl_add_u32 v15, v15, 2, s0
	v_add_u32_e32 v13, v13, v11
	ds_read_b32 v87, v15
	v_and_b32_e32 v15, 63, v13
	v_lshl_add_u32 v15, v15, 2, s0
	ds_read_b32 v88, v15
	v_add_u32_e32 v15, 48, v13
	v_and_b32_e32 v15, 63, v15
	v_lshl_add_u32 v15, v15, 2, s0
	v_add_u32_e32 v13, v13, v11
	ds_read_b32 v89, v15
	v_and_b32_e32 v15, 62, v13
	v_lshl_add_u32 v15, v15, 2, s0
	s_waitcnt vmcnt(31) lgkmcnt(14)
; __device__ __forceinline__ void prep_weights(const Params& P, LAS unsigned char* lds, int lay, int bid, int G, int sel) {
;     ...
;               for (int m = 0; m < 32; ++m) wv[m] = wp[(size_t)(m0 + m) * 1024];
; #pragma unroll
;               for (int m = 0; m < 32; ++m) { const int t = ((m0 + m) * j) & 63; cs += tab64[t] * wv[m]; sn += tab64[(t + 48) & 63] * wv[m]; } }
	v_pk_fma_f32 v[4:5], v[50:51], v[70:71], v[4:5] op_sel_hi:[0,1,1]
	ds_read_b32 v50, v15
	v_add_u32_e32 v15, 48, v13
	v_and_b32_e32 v15, 62, v15
	v_lshl_add_u32 v15, v15, 2, s0
	v_add_u32_e32 v13, v13, v11
	ds_read_b32 v51, v15
	v_and_b32_e32 v15, 63, v13
	v_lshl_add_u32 v15, v15, 2, s0
	s_waitcnt vmcnt(30)
	v_pk_fma_f32 v[4:5], v[52:53], v[72:73], v[4:5] op_sel_hi:[0,1,1]
	ds_read_b32 v52, v15
	v_add_u32_e32 v15, 48, v13
	v_and_b32_e32 v15, 63, v15
	v_lshl_add_u32 v15, v15, 2, s0
	v_add_u32_e32 v13, v13, v11
	ds_read_b32 v53, v15
	v_and_b32_e32 v15, 60, v13
	v_lshl_add_u32 v15, v15, 2, s0
	s_waitcnt vmcnt(29)
	v_pk_fma_f32 v[4:5], v[54:55], v[74:75], v[4:5] op_sel_hi:[0,1,1]
	ds_read_b32 v54, v15
	v_add_u32_e32 v15, 48, v13
	v_and_b32_e32 v15, 60, v15
	v_lshl_add_u32 v15, v15, 2, s0
	v_add_u32_e32 v13, v13, v11
	ds_read_b32 v55, v15
	v_and_b32_e32 v15, 63, v13
	v_lshl_add_u32 v15, v15, 2, s0
	s_waitcnt vmcnt(28) lgkmcnt(14)
	v_pk_fma_f32 v[4:5], v[56:57], v[76:77], v[4:5] op_sel_hi:[0,1,1]
	ds_read_b32 v56, v15
	v_add_u32_e32 v15, 48, v13
	v_and_b32_e32 v15, 63, v15
	v_lshl_add_u32 v15, v15, 2, s0
	v_add_u32_e32 v13, v13, v11
	ds_read_b32 v57, v15
	v_and_b32_e32 v15, 62, v13
	v_lshl_add_u32 v15, v15, 2, s0
	s_waitcnt vmcnt(27)
	v_pk_fma_f32 v[4:5], v[58:59], v[78:79], v[4:5] op_sel_hi:[0,1,1]
	ds_read_b32 v58, v15
	v_add_u32_e32 v15, 48, v13
	v_and_b32_e32 v15, 62, v15
	v_lshl_add_u32 v15, v15, 2, s0
	v_add_u32_e32 v13, v13, v11
	ds_read_b32 v59, v15
	v_and_b32_e32 v15, 63, v13
	v_lshl_add_u32 v15, v15, 2, s0
	s_waitcnt vmcnt(26)
	v_pk_fma_f32 v[4:5], v[60:61], v[80:81], v[4:5] op_sel_hi:[0,1,1]
	ds_read_b32 v60, v15
	v_add_u32_e32 v15, 48, v13
	v_and_b32_e32 v15, 63, v15
	v_lshl_add_u32 v15, v15, 2, s0
	v_add_u32_e32 v13, v13, v11
	ds_read_b32 v61, v15
	v_and_b32_e32 v15, 48, v13
	v_lshl_add_u32 v15, v15, 2, s0
	s_waitcnt vmcnt(25) lgkmcnt(14)
	v_pk_fma_f32 v[4:5], v[62:63], v[82:83], v[4:5] op_sel_hi:[0,1,1]
	ds_read_b32 v62, v15
	v_add_u32_e32 v15, 48, v13
	v_and_b32_e32 v15, 48, v15
	v_lshl_add_u32 v15, v15, 2, s0
	v_add_u32_e32 v13, v13, v11
	ds_read_b32 v63, v15
	v_and_b32_e32 v15, 63, v13
	v_lshl_add_u32 v15, v15, 2, s0
	s_waitcnt vmcnt(24)
	v_pk_fma_f32 v[4:5], v[64:65], v[84:85], v[4:5] op_sel_hi:[0,1,1]
	ds_read_b32 v64, v15
	v_add_u32_e32 v15, 48, v13
	v_and_b32_e32 v15, 63, v15
	v_lshl_add_u32 v15, v15, 2, s0
	v_add_u32_e32 v13, v13, v11
	ds_read_b32 v65, v15
	v_and_b32_e32 v15, 62, v13
	v_lshl_add_u32 v15, v15, 2, s0
	s_waitcnt vmcnt(23)
	v_pk_fma_f32 v[4:5], v[66:67], v[86:87], v[4:5] op_sel_hi:[0,1,1]
	ds_read_b32 v66, v15
	v_add_u32_e32 v15, 48, v13
	v_and_b32_e32 v15, 62, v15
	v_lshl_add_u32 v15, v15, 2, s0
	v_add_u32_e32 v13, v13, v11
	ds_read_b32 v67, v15
	v_and_b32_e32 v15, 63, v13
	v_lshl_add_u32 v15, v15, 2, s0
	s_waitcnt vmcnt(22) lgkmcnt(14)
	v_pk_fma_f32 v[4:5], v[68:69], v[88:89], v[4:5] op_sel_hi:[0,1,1]
	ds_read_b32 v68, v15
	v_add_u32_e32 v15, 48, v13
	v_and_b32_e32 v15, 63, v15
	v_lshl_add_u32 v15, v15, 2, s0
	v_add_u32_e32 v13, v13, v11
	ds_read_b32 v69, v15
	v_and_b32_e32 v15, 60, v13
	v_lshl_add_u32 v15, v15, 2, s0
	ds_read_b32 v70, v15
	v_add_u32_e32 v15, 48, v13
	v_and_b32_e32 v15, 60, v15
	v_lshl_add_u32 v15, v15, 2, s0
	v_add_u32_e32 v13, v13, v11
	ds_read_b32 v71, v15
	v_and_b32_e32 v15, 63, v13
	v_lshl_add_u32 v15, v15, 2, s0
	s_waitcnt vmcnt(21)
	v_pk_fma_f32 v[4:5], v[28:29], v[50:51], v[4:5] op_sel_hi:[0,1,1]
	ds_read_b32 v28, v15
	v_add_u32_e32 v15, 48, v13
	v_and_b32_e32 v15, 63, v15
	v_lshl_add_u32 v15, v15, 2, s0
	v_add_u32_e32 v13, v13, v11
	ds_read_b32 v29, v15
	v_and_b32_e32 v15, 62, v13
	v_lshl_add_u32 v15, v15, 2, s0
	s_waitcnt vmcnt(20)
	v_pk_fma_f32 v[4:5], v[30:31], v[52:53], v[4:5] op_sel_hi:[0,1,1]
	ds_read_b32 v30, v15
	v_add_u32_e32 v15, 48, v13
	v_and_b32_e32 v15, 62, v15
	v_lshl_add_u32 v15, v15, 2, s0
	v_add_u32_e32 v13, v13, v11
	ds_read_b32 v31, v15
	v_and_b32_e32 v15, 63, v13
	v_lshl_add_u32 v15, v15, 2, s0
	s_waitcnt vmcnt(19) lgkmcnt(14)
	v_pk_fma_f32 v[4:5], v[32:33], v[54:55], v[4:5] op_sel_hi:[0,1,1]
	ds_read_b32 v32, v15
	v_add_u32_e32 v15, 48, v13
	v_and_b32_e32 v15, 63, v15
	v_lshl_add_u32 v15, v15, 2, s0
	v_add_u32_e32 v13, v13, v11
	ds_read_b32 v33, v15
	v_and_b32_e32 v15, 56, v13
	v_lshl_add_u32 v15, v15, 2, s0
	s_waitcnt vmcnt(18)
; __device__ __forceinline__ unsigned f2bf(float f) { unsigned u = __float_as_uint(f); return (u + 0x7fffu + ((u >> 16) & 1u)) >> 16; }
; __device__ __forceinline__ void prep_weights(const Params& P, LAS unsigned char* lds, int lay, int bid, int G, int sel) {
;     ...
;               for (int m = 0; m < 32; ++m) { const int t = ((m0 + m) * j) & 63; cs += tab64[t] * wv[m]; sn += tab64[(t + 48) & 63] * wv[m]; } }
;           bf16_t* o = (bf16_t*)(ws + OFF_WOUT + l * SZ_WOUT1) + (size_t)n * 1280; o[768 + gj] = (bf16_t)f2bf(cs); o[1024 + gj] = (bf16_t)f2bf(-sn); }
	v_pk_fma_f32 v[4:5], v[34:35], v[56:57], v[4:5] op_sel_hi:[0,1,1]
	ds_read_b32 v34, v15
	v_add_u32_e32 v15, 48, v13
	v_and_b32_e32 v15, 56, v15
	v_lshl_add_u32 v15, v15, 2, s0
	v_add_u32_e32 v13, v13, v11
	ds_read_b32 v35, v15
	v_and_b32_e32 v15, 63, v13
	v_lshl_add_u32 v15, v15, 2, s0
	s_waitcnt vmcnt(17)
	v_pk_fma_f32 v[4:5], v[36:37], v[58:59], v[4:5] op_sel_hi:[0,1,1]
	ds_read_b32 v36, v15
	v_add_u32_e32 v15, 48, v13
	v_and_b32_e32 v15, 63, v15
	v_lshl_add_u32 v15, v15, 2, s0
	v_add_u32_e32 v13, v13, v11
	ds_read_b32 v37, v15
	v_and_b32_e32 v15, 62, v13
	v_lshl_add_u32 v15, v15, 2, s0
	s_waitcnt vmcnt(16)
	v_pk_fma_f32 v[4:5], v[38:39], v[60:61], v[4:5] op_sel_hi:[0,1,1]
	ds_read_b32 v38, v15
	v_add_u32_e32 v15, 48, v13
	v_and_b32_e32 v15, 62, v15
	v_lshl_add_u32 v15, v15, 2, s0
	v_add_u32_e32 v13, v13, v11
	ds_read_b32 v39, v15
	v_and_b32_e32 v15, 63, v13
	v_lshl_add_u32 v15, v15, 2, s0
	s_waitcnt vmcnt(15) lgkmcnt(14)
	v_pk_fma_f32 v[4:5], v[40:41], v[62:63], v[4:5] op_sel_hi:[0,1,1]
	ds_read_b32 v40, v15
	v_add_u32_e32 v15, 48, v13
	v_and_b32_e32 v15, 63, v15
	v_lshl_add_u32 v15, v15, 2, s0
	v_add_u32_e32 v13, v13, v11
	ds_read_b32 v41, v15
	v_and_b32_e32 v15, 60, v13
	v_lshl_add_u32 v15, v15, 2, s0
	s_waitcnt vmcnt(14)
	v_pk_fma_f32 v[4:5], v[42:43], v[64:65], v[4:5] op_sel_hi:[0,1,1]
	ds_read_b32 v42, v15
	v_add_u32_e32 v15, 48, v13
	v_and_b32_e32 v15, 60, v15
	v_lshl_add_u32 v15, v15, 2, s0
	v_add_u32_e32 v13, v13, v11
	ds_read_b32 v43, v15
	v_and_b32_e32 v15, 63, v13
	v_lshl_add_u32 v15, v15, 2, s0
	s_waitcnt vmcnt(13)
	v_pk_fma_f32 v[4:5], v[44:45], v[66:67], v[4:5] op_sel_hi:[0,1,1]
	ds_read_b32 v44, v15
	v_add_u32_e32 v15, 48, v13
	v_and_b32_e32 v15, 63, v15
	v_lshl_add_u32 v15, v15, 2, s0
	v_add_u32_e32 v13, v13, v11
	ds_read_b32 v45, v15
	v_and_b32_e32 v15, 62, v13
	v_lshl_add_u32 v15, v15, 2, s0
	s_waitcnt vmcnt(12)
	v_pk_fma_f32 v[4:5], v[46:47], v[68:69], v[4:5] op_sel_hi:[0,1,1]
	ds_read_b32 v46, v15
	v_add_u32_e32 v15, 48, v13
	v_and_b32_e32 v15, 62, v15
	s_waitcnt vmcnt(11) lgkmcnt(14)
	v_pk_fma_f32 v[4:5], v[48:49], v[70:71], v[4:5] op_sel_hi:[0,1,1]
	v_lshl_add_u32 v15, v15, 2, s0
	v_add_u32_e32 v13, v13, v11
	ds_read_b32 v47, v15
	v_and_b32_e32 v15, 63, v13
	v_add_u32_e32 v13, 48, v13
	s_waitcnt vmcnt(10)
	v_pk_fma_f32 v[4:5], v[6:7], v[28:29], v[4:5] op_sel_hi:[0,1,1]
	v_and_b32_e32 v13, 63, v13
	s_waitcnt vmcnt(9)
	v_pk_fma_f32 v[4:5], v[8:9], v[30:31], v[4:5] op_sel_hi:[0,1,1]
	v_lshl_add_u32 v13, v13, 2, s0
	s_waitcnt vmcnt(8) lgkmcnt(14)
	v_pk_fma_f32 v[4:5], v[10:11], v[32:33], v[4:5] op_sel_hi:[0,1,1]
	v_lshl_add_u32 v15, v15, 2, s0
	s_waitcnt vmcnt(7) lgkmcnt(12)
	v_pk_fma_f32 v[4:5], v[12:13], v[34:35], v[4:5] op_sel_hi:[0,1,1]
	s_waitcnt vmcnt(6) lgkmcnt(10)
	v_pk_fma_f32 v[4:5], v[14:15], v[36:37], v[4:5] op_sel_hi:[0,1,1]
	ds_read_b32 v48, v15
	ds_read_b32 v49, v13
	s_waitcnt vmcnt(5) lgkmcnt(10)
	v_pk_fma_f32 v[4:5], v[16:17], v[38:39], v[4:5] op_sel_hi:[0,1,1]
	s_waitcnt vmcnt(4) lgkmcnt(8)
	v_pk_fma_f32 v[4:5], v[18:19], v[40:41], v[4:5] op_sel_hi:[0,1,1]
	s_waitcnt vmcnt(3) lgkmcnt(6)
	v_pk_fma_f32 v[4:5], v[20:21], v[42:43], v[4:5] op_sel_hi:[0,1,1]
	s_waitcnt vmcnt(2) lgkmcnt(4)
	v_pk_fma_f32 v[4:5], v[22:23], v[44:45], v[4:5] op_sel_hi:[0,1,1]
	s_waitcnt vmcnt(1) lgkmcnt(2)
	v_pk_fma_f32 v[4:5], v[24:25], v[46:47], v[4:5] op_sel_hi:[0,1,1]
	s_waitcnt vmcnt(0) lgkmcnt(0)
	v_pk_fma_f32 v[4:5], v[26:27], v[48:49], v[4:5] op_sel_hi:[0,1,1]
	s_and_b64 vcc, exec, s[42:43]
	s_mov_b64 s[42:43], 0
	s_mov_b32 s3, 32
	s_cbranch_vccnz .LBB0_1117
	v_readlane_b32 s0, v252, 60
	v_readlane_b32 s1, v252, 61
	v_bfe_u32 v6, v4, 16, 1
	v_add3_u32 v4, v4, v6, s19
	v_mov_b64_e32 v[2:3], s[0:1]
	v_lshrrev_b32_e32 v6, 9, v7
	v_mad_u64_u32 v[2:3], s[0:1], v9, s23, v[2:3]
	v_and_b32_e32 v128, 0x1fe, v6
	v_lshl_add_u64 v[2:3], v[2:3], 0, v[128:129]
	global_store_short_d16_hi v[2:3], v4, off offset:1536 sc1
	v_xor_b32_e32 v4, 0x80000000, v5
	v_bfe_u32 v5, v4, 16, 1
	v_add3_u32 v4, v4, v5, s19
	s_mov_b32 s0, 0x27fff
	global_store_short_d16_hi v[2:3], v4, off offset:2048 sc1
	v_add_u32_e32 v2, 0x18000, v7
	v_cmp_lt_i32_e32 vcc, s0, v7
	s_or_b64 s[40:41], vcc, s[40:41]
	v_mov_b32_e32 v7, v2
	s_andn2_b64 exec, exec, s[40:41]
	s_cbranch_execnz .LBB0_1116

; __device__ __forceinline__ unsigned f2bf(float f) { unsigned u = __float_as_uint(f); return (u + 0x7fffu + ((u >> 16) & 1u)) >> 16; }
; __device__ __forceinline__ void prep_weights(const Params& P, LAS unsigned char* lds, int lay, int bid, int G, int sel) {
;     ...
;       for (int i0 = gt; i0 < ((sel & 64) ? 131072 : 0); i0 += NGT) { const int idx = l * 131072 + i0; const int i = idx & 63, j = (idx >> 6) & 63, hi = idx >> 12;
;           ((bf16_t*)(ws + OFF_WGT))[idx] = (bf16_t)f2bf(P.lru_wg[(size_t)hi * 4096 + i * 64 + j]); }
.LBB0_1122:
	v_add_u32_e32 v8, 0x20000, v2
	v_add_u32_e32 v10, 0x20000, v3
	v_ashrrev_i32_e32 v14, 12, v8
	v_lshlrev_b32_e32 v13, 6, v2
	v_ashrrev_i32_e32 v12, 12, v10
	v_ashrrev_i32_e32 v15, 31, v14
	v_lshlrev_b32_e32 v11, 6, v3
	v_and_b32_e32 v16, 0xfc0, v13
	v_ashrrev_i32_e32 v13, 31, v12
	v_lshlrev_b64 v[14:15], 14, v[14:15]
	v_lshrrev_b32_e32 v9, 6, v2
	v_and_b32_e32 v11, 0xfc0, v11
	v_lshlrev_b32_e32 v128, 2, v16
	v_lshlrev_b64 v[12:13], 14, v[12:13]
	v_lshl_add_u64 v[14:15], s[58:59], 0, v[14:15]
	v_lshrrev_b32_e32 v1, 6, v3
	v_and_b32_e32 v9, 63, v9
	v_lshl_add_u64 v[12:13], s[58:59], 0, v[12:13]
	v_lshl_add_u64 v[14:15], v[14:15], 0, v[128:129]
	v_lshlrev_b32_e32 v128, 2, v11
	v_and_b32_e32 v1, 63, v1
	v_lshl_add_u64 v[12:13], v[12:13], 0, v[128:129]
	v_lshlrev_b32_e32 v128, 2, v9
	v_lshl_add_u64 v[14:15], v[14:15], 0, v[128:129]
	v_lshlrev_b32_e32 v128, 2, v1
	v_lshl_add_u64 v[12:13], v[12:13], 0, v[128:129]
	global_load_dword v1, v[14:15], off
	s_nop 0
	global_load_dword v12, v[12:13], off
	v_add_u32_e32 v7, -2, v7
	v_ashrrev_i32_e32 v9, 31, v8
	v_cmp_eq_u32_e32 vcc, 0, v7
	v_add_u32_e32 v3, 0x30000, v3
	v_add_u32_e32 v2, 0x30000, v2
	v_ashrrev_i32_e32 v11, 31, v10
	v_lshl_add_u64 v[8:9], v[8:9], 1, s[12:13]
	s_or_b64 s[40:41], vcc, s[40:41]
	v_lshl_add_u64 v[10:11], v[10:11], 1, s[12:13]
	s_waitcnt vmcnt(1)
	v_and_b32_sdwa v13, v1, v170 dst_sel:DWORD dst_unused:UNUSED_PAD src0_sel:WORD_1 src1_sel:DWORD
	s_waitcnt vmcnt(0)
	v_and_b32_sdwa v14, v12, v170 dst_sel:DWORD dst_unused:UNUSED_PAD src0_sel:WORD_1 src1_sel:DWORD
	v_add3_u32 v1, v1, v13, s19
	v_add3_u32 v12, v12, v14, s19
	global_store_short_d16_hi v[8:9], v1, off sc1
	global_store_short_d16_hi v[10:11], v12, off sc1
	s_andn2_b64 exec, exec, s[40:41]
	s_cbranch_execnz .LBB0_1122
	s_or_b64 exec, exec, s[40:41]
	s_mov_b32 s0, 0x18000
	v_cmp_ne_u32_e32 vcc, v4, v5
	v_mad_u32_u24 v2, v5, s0, v0
	s_orn2_b64 s[40:41], vcc, exec

; __device__ __forceinline__ unsigned f2bf(float f) { unsigned u = __float_as_uint(f); return (u + 0x7fffu + ((u >> 16) & 1u)) >> 16; }
; __device__ __forceinline__ void prep_weights(const Params& P, LAS unsigned char* lds, int lay, int bid, int G, int sel) {
;     ...
;       for (int i0 = gt; i0 < ((sel & 64) ? 131072 : 0); i0 += NGT) { const int idx = l * 131072 + i0; const int i = idx & 63, j = (idx >> 6) & 63, hi = idx >> 12;
;           ((bf16_t*)(ws + OFF_WGT))[idx] = (bf16_t)f2bf(P.lru_wg[(size_t)hi * 4096 + i * 64 + j]); }
.LBB0_1126:
	v_add_u32_e32 v3, 0x20000, v2
	v_ashrrev_i32_e32 v8, 12, v3
	v_ashrrev_i32_e32 v9, 31, v8
	v_and_b32_e32 v3, 0xfc0, v1
	v_lshlrev_b64 v[8:9], 14, v[8:9]
	v_lshl_add_u64 v[8:9], s[58:59], 0, v[8:9]
	v_lshlrev_b32_e32 v128, 2, v3
	v_lshrrev_b32_e32 v3, 4, v2
	v_lshl_add_u64 v[8:9], v[8:9], 0, v[128:129]
	v_and_b32_e32 v128, 0xfc, v3
	v_lshl_add_u64 v[8:9], v[8:9], 0, v[128:129]
	global_load_dword v3, v[8:9], off
	v_cmp_lt_i32_e32 vcc, s19, v2
	v_add_u32_e32 v1, 0x600000, v1
	s_or_b64 s[38:39], vcc, s[38:39]
	s_waitcnt vmcnt(0)
	v_bfe_u32 v7, v3, 16, 1
	v_add3_u32 v3, v3, v7, s19
	global_store_short_d16_hi v[4:5], v3, off sc1
	v_add_u32_e32 v3, 0x18000, v2
	v_lshl_add_u64 v[4:5], v[4:5], 0, s[2:3]
	v_mov_b32_e32 v2, v3
	s_andn2_b64 exec, exec, s[38:39]
	s_cbranch_execnz .LBB0_1126

; __device__ __forceinline__ unsigned f2bf(float f) { unsigned u = __float_as_uint(f); return (u + 0x7fffu + ((u >> 16) & 1u)) >> 16; }
; __device__ __forceinline__ void prep_weights(const Params& P, LAS unsigned char* lds, int lay, int bid, int G, int sel) {
;     ...
;       for (int i0 = gt; i0 < ((sel & 64) ? 65536 : 0); i0 += NGT) { const int idx = l * 65536 + i0; ((bf16_t*)(ws + OFF_GWS))[idx] = (bf16_t)f2bf(P.gmlp_ws[idx]); } }
.LBB0_1130:
	v_add_u32_e32 v10, 0x10000, v3
	v_add_u32_e32 v8, 0x10000, v2
	v_ashrrev_i32_e32 v11, 31, v10
	v_ashrrev_i32_e32 v9, 31, v8
	v_lshl_add_u64 v[14:15], v[10:11], 2, s[80:81]
	v_lshl_add_u64 v[12:13], v[8:9], 2, s[80:81]
	global_load_dword v1, v[14:15], off
	global_load_dword v7, v[12:13], off
	v_add_u32_e32 v6, -2, v6
	v_cmp_eq_u32_e32 vcc, 0, v6
	v_add_u32_e32 v3, 0x30000, v3
	v_add_u32_e32 v2, 0x30000, v2
	v_lshl_add_u64 v[8:9], v[8:9], 1, s[60:61]
	s_or_b64 s[40:41], vcc, s[40:41]
	v_lshl_add_u64 v[10:11], v[10:11], 1, s[60:61]
	s_waitcnt vmcnt(1)
	v_and_b32_sdwa v12, v1, v170 dst_sel:DWORD dst_unused:UNUSED_PAD src0_sel:WORD_1 src1_sel:DWORD
	s_waitcnt vmcnt(0)
	v_and_b32_sdwa v13, v7, v170 dst_sel:DWORD dst_unused:UNUSED_PAD src0_sel:WORD_1 src1_sel:DWORD
	v_add3_u32 v7, v7, v13, s19
	v_add3_u32 v1, v1, v12, s19
	global_store_short_d16_hi v[8:9], v7, off sc1
	global_store_short_d16_hi v[10:11], v1, off sc1
	s_andn2_b64 exec, exec, s[40:41]
	s_cbranch_execnz .LBB0_1130
	s_or_b64 exec, exec, s[40:41]
	s_mov_b32 s0, 0x18000
	v_cmp_ne_u32_e32 vcc, v4, v5
	v_mad_u32_u24 v0, v5, s0, v0
	s_orn2_b64 s[40:41], vcc, exec

; __device__ __forceinline__ unsigned f2bf(float f) { unsigned u = __float_as_uint(f); return (u + 0x7fffu + ((u >> 16) & 1u)) >> 16; }
; __device__ __forceinline__ void prep_weights(const Params& P, LAS unsigned char* lds, int lay, int bid, int G, int sel) {
;     ...
;       for (int i0 = gt; i0 < ((sel & 64) ? 65536 : 0); i0 += NGT) { const int idx = l * 65536 + i0; ((bf16_t*)(ws + OFF_GWS))[idx] = (bf16_t)f2bf(P.gmlp_ws[idx]); } }
.LBB0_1134:
	global_load_dword v5, v[2:3], off
	v_add_u32_e32 v4, 0x18000, v4
	v_cmp_lt_i32_e32 vcc, s71, v4
	v_lshl_add_u64 v[2:3], v[2:3], 0, s[4:5]
	s_or_b64 s[38:39], vcc, s[38:39]
	s_waitcnt vmcnt(0)
	v_bfe_u32 v6, v5, 16, 1
	v_add3_u32 v5, v5, v6, s19
	global_store_short_d16_hi v[0:1], v5, off sc1
	v_lshl_add_u64 v[0:1], v[0:1], 0, s[2:3]
	s_andn2_b64 exec, exec, s[38:39]
	s_cbranch_execnz .LBB0_1134

; #define LAS __attribute__((address_space(3)))
; #define GAS __attribute__((address_space(1)))
; __device__ __forceinline__ void prep_dft(const Params& P, LAS unsigned char* lds, int bid, int G) {
;     ...
;       for (int rr = bid; rr < 4096; rr += G) { const int r = ((rr >> 11) << 12) + (rr & 2047); const int k = r & 4095;   const LAS unsigned short* tb = (r >> 12) ? tabs : tabc; const int n0 = tid * 8; unsigned e[8];
; #pragma unroll
;           for (int j = 0; j < 8; ++j) e[j] = tb[(k * (n0 + j)) & 4095];
;           u32x4 o; o.x = e[0] | (e[1] << 16); o.y = e[2] | (e[3] << 16); o.z = e[4] | (e[5] << 16); o.w = e[6] | (e[7] << 16);
;           *(GAS u32x4*)((GAS bf16_t*)DFTM + (size_t)r * 4096 + n0) = o; }
;       bf16_t* DFTMC = (bf16_t*)(ws + OFF_DFTMC);
;       for (int it = bid; it < 32; it += G) { const int r = it * 16 + (tid >> 5), n0 = (tid & 31) * 8, k = r & 255; const LAS unsigned short* tb = (r >> 8) ? tabs : tabc; unsigned e[8];
; #pragma unroll
;           for (int j = 0; j < 8; ++j) e[j] = tb[((k * (n0 + j)) & 255) << 4];
;           u32x4 o; o.x = e[0] | (e[1] << 16); o.y = e[2] | (e[3] << 16); o.z = e[4] | (e[5] << 16); o.w = e[6] | (e[7] << 16);
;           *(GAS u32x4*)((GAS bf16_t*)DFTMC + (size_t)r * 256 + n0) = o; } }
.LBB0_1147:
	s_addk_i32 s1, 0xc0
	s_and_b32 s2, s1, 0x7ff
	v_mul_lo_u32 v1, s2, v2
	v_and_b32_e32 v3, 0xff8, v1
	v_add_u32_e32 v1, s2, v1
	v_and_b32_e32 v6, 0xfff, v1
	v_add_u32_e32 v1, s2, v1
	v_and_b32_e32 v7, 0xffe, v1
	v_add_u32_e32 v1, s2, v1
	v_and_b32_e32 v8, 0xfff, v1
	v_add_u32_e32 v1, s2, v1
	v_and_b32_e32 v9, 0xffc, v1
	v_add_u32_e32 v1, s2, v1
	s_cmpk_lt_u32 s1, 0x800
	v_and_b32_e32 v10, 0xfff, v1
	v_add_u32_e32 v1, s2, v1
	s_cselect_b32 s3, 0x20000, s4
	v_and_b32_e32 v11, 0xffe, v1
	v_add_u32_e32 v1, s2, v1
	s_add_i32 s3, s3, 0
	v_and_b32_e32 v1, 0xfff, v1
	v_lshl_add_u32 v3, v3, 1, s3
	v_lshl_add_u32 v6, v6, 1, s3
	v_lshl_add_u32 v7, v7, 1, s3
	v_lshl_add_u32 v8, v8, 1, s3
	v_lshl_add_u32 v9, v9, 1, s3
	v_lshl_add_u32 v10, v10, 1, s3
	v_lshl_add_u32 v11, v11, 1, s3
	v_lshl_add_u32 v1, v1, 1, s3
	ds_read_u16 v3, v3
	ds_read_u16 v6, v6
	ds_read_u16 v7, v7
	ds_read_u16 v8, v8
	ds_read_u16 v9, v9
	ds_read_u16 v10, v10
	ds_read_u16 v11, v11
	ds_read_u16 v1, v1
	s_and_b32 s3, s0, 0x1000
	s_or_b32 s2, s3, s2
	s_lshl_b32 s74, s2, 13
	s_addk_i32 s0, 0x180
	s_waitcnt lgkmcnt(6)
	v_lshl_or_b32 v6, v6, 16, v3
	s_waitcnt lgkmcnt(4)
	v_lshl_or_b32 v7, v8, 16, v7
	s_waitcnt lgkmcnt(2)
	v_lshl_or_b32 v8, v10, 16, v9
	s_waitcnt lgkmcnt(0)
	v_lshl_or_b32 v9, v1, 16, v11
	v_lshl_add_u64 v[10:11], v[4:5], 0, s[74:75]
	s_cmpk_gt_u32 s1, 0xf3f
	global_store_dwordx4 v[10:11], v[6:9], off sc1
	s_cbranch_scc0 .LBB0_1147
.LBB0_1148:
	v_readlane_b32 s0, v253, 7
	v_readlane_b32 s1, v253, 8
	s_andn2_b64 vcc, exec, s[0:1]
	s_mov_b64 s[4:5], 0x30000
	s_mov_b64 s[10:11], 0x60000
	s_cbranch_vccnz .LBB0_1150
	v_lshlrev_b32_e32 v2, 4, v0
	v_readlane_b32 s0, v252, 12
	v_and_b32_e32 v128, 0x1f0, v2
	v_readlane_b32 s1, v252, 13
	v_ashrrev_i32_e32 v1, 5, v0
	v_mov_b32_e32 v2, 0x20000
	v_lshl_add_u64 v[4:5], s[0:1], 0, v[128:129]
	v_readlane_b32 s0, v253, 9
	s_nop 1
	v_add_u32_e32 v6, s0, v1
	s_movk_i32 s0, 0x100
	v_cmp_gt_u32_e32 vcc, s0, v6
	v_mov_b32_e32 v1, 0x22000
	s_nop 0
	v_cndmask_b32_e32 v1, v1, v2, vcc
	v_lshlrev_b32_e32 v2, 4, v6
	v_mul_lo_u32 v0, v0, v2
	v_lshlrev_b32_e32 v0, 3, v0
	v_and_b32_e32 v3, 0xf80, v0
	v_add_u32_e32 v0, v0, v2
	v_and_b32_e32 v7, 0xff0, v0
	v_add_u32_e32 v0, v0, v2
	v_and_b32_e32 v8, 0xfe0, v0
	v_add_u32_e32 v0, v0, v2
	v_and_b32_e32 v9, 0xff0, v0
	v_add_u32_e32 v0, v0, v2
	v_and_b32_e32 v10, 0xfc0, v0
	v_add_u32_e32 v0, v0, v2
	v_add_u32_e32 v1, 0, v1
	v_and_b32_e32 v11, 0xff0, v0
	v_add_u32_e32 v0, v0, v2
	v_lshl_add_u32 v3, v3, 1, v1
	v_lshl_add_u32 v7, v7, 1, v1
	v_and_b32_e32 v12, 0xfe0, v0
	v_add_u32_e32 v0, v0, v2
	ds_read_u16 v3, v3
	ds_read_u16 v7, v7
	v_and_b32_e32 v0, 0xff0, v0
	v_lshl_add_u32 v8, v8, 1, v1
	v_lshl_add_u32 v9, v9, 1, v1
	v_lshl_add_u32 v10, v10, 1, v1
	v_lshl_add_u32 v11, v11, 1, v1
	v_lshl_add_u32 v12, v12, 1, v1
	v_lshl_add_u32 v0, v0, 1, v1
	ds_read_u16 v8, v8
	ds_read_u16 v9, v9
	ds_read_u16 v10, v10
	ds_read_u16 v11, v11
	ds_read_u16 v12, v12
	ds_read_u16 v13, v0
	s_waitcnt lgkmcnt(6)
	v_lshl_or_b32 v0, v7, 16, v3
	v_ashrrev_i32_e32 v7, 31, v6
	v_lshlrev_b64 v[6:7], 9, v[6:7]
	s_waitcnt lgkmcnt(4)
	v_lshl_or_b32 v1, v9, 16, v8
	s_waitcnt lgkmcnt(2)
	v_lshl_or_b32 v2, v11, 16, v10
	s_waitcnt lgkmcnt(0)
	v_lshl_or_b32 v3, v13, 16, v12
	v_lshl_add_u64 v[4:5], v[4:5], 0, v[6:7]
	global_store_dwordx4 v[4:5], v[0:3], off sc1

; __device__ __forceinline__ void transpose_item(const float* W, int ldw, int k0, int n0, bf16_t* WT, int ldt, int drow0, int dk0, LAS float* scr, int lane) {
;     ...
;     for (int i = 0; i < 32; ++i) { const int kk = 2 * i + (lane >> 5); tv[i] = W[(size_t)(k0 + kk) * ldw + n0 + (lane & 31)]; }
; __device__ __forceinline__ void prep_weights(const Params& P, LAS unsigned char* lds, int lay, int bid, int G, int sel) {
;     ...
;           if (r < 2 * I_GU) { if (!((sel >> (r / I_GU)) & 1)) continue; const int mat = lay * 2 + r / I_GU, ii = r % I_GU, kb = ii / 176, nb = ii % 176, n0 = nb * 32;
;               const int drow = n0 < DFF ? (n0 >> 7) * 256 + (n0 & 127) : ((n0 - DFF) >> 7) * 256 + 128 + ((n0 - DFF) & 127);
;               transpose_item(P.w_gu + (size_t)mat * 1024 * 5632, 5632, kb * 64, n0, (bf16_t*)(ws + OFF_WGU + mat * SZ_WGU1), 1024, drow, kb * 64, scr, lane); continue; }
.LBB0_1154:
	s_or_b64 exec, exec, s[46:47]
	v_mov_b64_e32 v[16:17], s[78:79]
	s_mov_b32 s0, 0x1600000
	v_mad_i64_i32 v[32:33], s[0:1], v13, s0, v[16:17]
	v_lshlrev_b32_sdwa v14, v249, sext(v14) dst_sel:DWORD dst_unused:UNUSED_PAD src0_sel:DWORD src1_sel:WORD_0
	v_mov_b64_e32 v[16:17], s[92:93]
	s_mov_b32 s0, 0xb00000
	v_mad_i64_i32 v[16:17], s[0:1], v13, s0, v[16:17]
	v_or_b32_e32 v13, v14, v22
	v_ashrrev_i32_e32 v19, 31, v18
	v_lshl_add_u64 v[18:19], v[18:19], 2, v[32:33]
	v_mul_i32_i24_e32 v32, 0x1600, v13
	v_lshl_add_u64 v[18:19], v[18:19], 0, v[128:129]
	v_ashrrev_i32_e32 v33, 31, v32
	v_lshl_add_u64 v[18:19], v[32:33], 2, v[18:19]
	v_add_co_u32_e32 v32, vcc, s14, v18
	s_mov_b32 s0, 0x16000
	s_nop 0
	v_addc_co_u32_e32 v33, vcc, 0, v19, vcc
	global_load_dword v13, v[18:19], off
	global_load_dword v15, v[32:33], off
	v_add_co_u32_e32 v32, vcc, s0, v18
	s_mov_b32 s0, 0x21000
	s_nop 0
	v_addc_co_u32_e32 v33, vcc, 0, v19, vcc
	global_load_dword v34, v[32:33], off
	v_add_co_u32_e32 v32, vcc, s0, v18
	s_mov_b32 s0, 0x2c000
	s_nop 0
	v_addc_co_u32_e32 v33, vcc, 0, v19, vcc
	global_load_dword v35, v[32:33], off
	v_add_co_u32_e32 v32, vcc, s0, v18
	s_mov_b32 s0, 0x37000
	s_nop 0
	v_addc_co_u32_e32 v33, vcc, 0, v19, vcc
	global_load_dword v36, v[32:33], off
	v_add_co_u32_e32 v32, vcc, s0, v18
	s_mov_b32 s0, 0x42000
	s_nop 0
	v_addc_co_u32_e32 v33, vcc, 0, v19, vcc
	global_load_dword v37, v[32:33], off
	v_add_co_u32_e32 v32, vcc, s0, v18
	s_mov_b32 s0, 0x4d000
	s_nop 0
	v_addc_co_u32_e32 v33, vcc, 0, v19, vcc
	global_load_dword v38, v[32:33], off
	v_add_co_u32_e32 v32, vcc, s0, v18
	s_mov_b32 s0, 0x58000
	s_nop 0
	v_addc_co_u32_e32 v33, vcc, 0, v19, vcc
	global_load_dword v39, v[32:33], off
	v_add_co_u32_e32 v32, vcc, s0, v18
	s_mov_b32 s0, 0x63000
	s_nop 0
	v_addc_co_u32_e32 v33, vcc, 0, v19, vcc
	global_load_dword v40, v[32:33], off
	v_add_co_u32_e32 v32, vcc, s0, v18
	s_mov_b32 s0, 0x6e000
	s_nop 0
	v_addc_co_u32_e32 v33, vcc, 0, v19, vcc
	global_load_dword v41, v[32:33], off
	v_add_co_u32_e32 v32, vcc, s0, v18
	s_mov_b32 s0, 0x79000
	s_nop 0
	v_addc_co_u32_e32 v33, vcc, 0, v19, vcc
	global_load_dword v42, v[32:33], off
	v_add_co_u32_e32 v32, vcc, s0, v18
	s_mov_b32 s0, 0x84000
	s_nop 0
	v_addc_co_u32_e32 v33, vcc, 0, v19, vcc
	global_load_dword v43, v[32:33], off
	v_add_co_u32_e32 v32, vcc, s0, v18
	s_mov_b32 s0, 0x8f000
	s_nop 0
	v_addc_co_u32_e32 v33, vcc, 0, v19, vcc
	global_load_dword v44, v[32:33], off
	v_add_co_u32_e32 v32, vcc, s0, v18
	s_mov_b32 s0, 0x9a000
	s_nop 0
	v_addc_co_u32_e32 v33, vcc, 0, v19, vcc
	global_load_dword v45, v[32:33], off
	v_add_co_u32_e32 v32, vcc, s0, v18
	s_mov_b32 s0, 0xa5000
	s_nop 0
	v_addc_co_u32_e32 v33, vcc, 0, v19, vcc
	global_load_dword v46, v[32:33], off
	v_add_co_u32_e32 v32, vcc, s0, v18
	s_mov_b32 s0, 0xb0000
	s_nop 0
	v_addc_co_u32_e32 v33, vcc, 0, v19, vcc
	global_load_dword v47, v[32:33], off
	v_add_co_u32_e32 v32, vcc, s0, v18
	s_mov_b32 s0, 0xbb000
	s_nop 0
	v_addc_co_u32_e32 v33, vcc, 0, v19, vcc
	global_load_dword v48, v[32:33], off
	v_add_co_u32_e32 v32, vcc, s0, v18
	s_mov_b32 s0, 0xc6000
	s_nop 0
	v_addc_co_u32_e32 v33, vcc, 0, v19, vcc
	global_load_dword v49, v[32:33], off
	v_add_co_u32_e32 v32, vcc, s0, v18
	s_mov_b32 s0, 0xd1000
	s_nop 0
	v_addc_co_u32_e32 v33, vcc, 0, v19, vcc
	global_load_dword v50, v[32:33], off
	v_add_co_u32_e32 v32, vcc, s0, v18
	s_mov_b32 s0, 0xdc000
	s_nop 0
	v_addc_co_u32_e32 v33, vcc, 0, v19, vcc
	global_load_dword v51, v[32:33], off
	v_add_co_u32_e32 v32, vcc, s0, v18
	s_mov_b32 s0, 0xe7000
	s_nop 0
	v_addc_co_u32_e32 v33, vcc, 0, v19, vcc
	global_load_dword v52, v[32:33], off
	v_add_co_u32_e32 v32, vcc, s0, v18
	s_mov_b32 s0, 0xf2000
	s_nop 0
	v_addc_co_u32_e32 v33, vcc, 0, v19, vcc
	global_load_dword v53, v[32:33], off
	v_add_co_u32_e32 v32, vcc, s0, v18
	s_mov_b32 s0, 0xfd000
	s_nop 0
	v_addc_co_u32_e32 v33, vcc, 0, v19, vcc
	global_load_dword v54, v[32:33], off
	v_add_co_u32_e32 v32, vcc, s0, v18
	s_mov_b32 s0, 0x108000
	s_nop 0
	v_addc_co_u32_e32 v33, vcc, 0, v19, vcc
	global_load_dword v55, v[32:33], off
	v_add_co_u32_e32 v32, vcc, s0, v18
	s_mov_b32 s0, 0x113000
	s_nop 0
	v_addc_co_u32_e32 v33, vcc, 0, v19, vcc
	global_load_dword v56, v[32:33], off
	v_add_co_u32_e32 v32, vcc, s0, v18
	s_mov_b32 s0, 0x11e000
	s_nop 0
	v_addc_co_u32_e32 v33, vcc, 0, v19, vcc
	global_load_dword v57, v[32:33], off
	v_add_co_u32_e32 v32, vcc, s0, v18
	s_mov_b32 s0, 0x129000
	s_nop 0
	v_addc_co_u32_e32 v33, vcc, 0, v19, vcc
	global_load_dword v58, v[32:33], off
	v_add_co_u32_e32 v32, vcc, s0, v18
	s_mov_b32 s0, 0x134000
	s_nop 0
	v_addc_co_u32_e32 v33, vcc, 0, v19, vcc
	global_load_dword v59, v[32:33], off
	v_add_co_u32_e32 v32, vcc, s0, v18
	s_mov_b32 s0, 0x13f000
	s_nop 0
	v_addc_co_u32_e32 v33, vcc, 0, v19, vcc
	global_load_dword v60, v[32:33], off
	v_add_co_u32_e32 v32, vcc, s0, v18
	s_mov_b32 s0, 0x14a000
	s_nop 0
	v_addc_co_u32_e32 v33, vcc, 0, v19, vcc
	global_load_dword v61, v[32:33], off
	v_add_co_u32_e32 v32, vcc, s0, v18
	s_mov_b32 s0, 0x155000
	s_nop 0
	v_addc_co_u32_e32 v33, vcc, 0, v19, vcc
	v_add_co_u32_e32 v18, vcc, s0, v18
	global_load_dword v32, v[32:33], off
	s_nop 0
	v_addc_co_u32_e32 v19, vcc, 0, v19, vcc
	global_load_dword v18, v[18:19], off
	s_waitcnt vmcnt(30)
; #define LAS __attribute__((address_space(3)))
; #define GAS __attribute__((address_space(1)))
; __device__ __forceinline__ unsigned cvt_pk_bf16(float lo, float hi) { unsigned r; asm volatile("v_cvt_pk_bf16_f32 %0, %1, %2" : "=v"(r) : "v"(lo), "v"(hi)); return r; }
; __device__ __forceinline__ void transpose_item(const float* W, int ldw, int k0, int n0, bf16_t* WT, int ldt, int drow0, int dk0, LAS float* scr, int lane) {
;     ...
;     for (int i = 0; i < 32; ++i) { const int kk = 2 * i + (lane >> 5); scr[kk * 33 + (lane & 31)] = tv[i]; }
;     asm volatile("s_waitcnt lgkmcnt(0)" ::: "memory");
;     const int c = lane & 7;
; #pragma unroll
;     for (int j = 0; j < 4; ++j) { const int n = (lane >> 3) + 8 * j; const LAS float* s = scr + (8 * c) * 33 + n;
;         u32x4 o; o.x = cvt_pk_bf16(s[0 * 33], s[1 * 33]); o.y = cvt_pk_bf16(s[2 * 33], s[3 * 33]); o.z = cvt_pk_bf16(s[4 * 33], s[5 * 33]); o.w = cvt_pk_bf16(s[6 * 33], s[7 * 33]);
;         *(GAS u32x4*)((GAS bf16_t*)WT + (size_t)(drow0 + n) * ldt + dk0 + 8 * c) = o; }
; __device__ __forceinline__ void prep_weights(const Params& P, LAS unsigned char* lds, int lay, int bid, int G, int sel) {
;     ...
;               const int drow = n0 < DFF ? (n0 >> 7) * 256 + (n0 & 127) : ((n0 - DFF) >> 7) * 256 + 128 + ((n0 - DFF) & 127);
;               transpose_item(P.w_gu + (size_t)mat * 1024 * 5632, 5632, kb * 64, n0, (bf16_t*)(ws + OFF_WGU + mat * SZ_WGU1), 1024, drow, kb * 64, scr, lane); continue; }
	ds_write2_b32 v23, v13, v15 offset1:66
	s_waitcnt vmcnt(28)
	ds_write2_b32 v23, v34, v35 offset0:132 offset1:198
	v_add_u32_e32 v13, 0x400, v23
	s_waitcnt vmcnt(26)
	ds_write2_b32 v13, v36, v37 offset0:8 offset1:74
	s_waitcnt vmcnt(24)
	ds_write2_b32 v13, v38, v39 offset0:140 offset1:206
	v_add_u32_e32 v13, 0x800, v23
	s_waitcnt vmcnt(22)
	ds_write2_b32 v13, v40, v41 offset0:16 offset1:82
	s_waitcnt vmcnt(20)
	ds_write2_b32 v13, v42, v43 offset0:148 offset1:214
	v_add_u32_e32 v13, 0xc00, v23
	s_waitcnt vmcnt(18)
	ds_write2_b32 v13, v44, v45 offset0:24 offset1:90
	s_waitcnt vmcnt(16)
	ds_write2_b32 v13, v46, v47 offset0:156 offset1:222
	v_add_u32_e32 v13, 0x1000, v23
	s_waitcnt vmcnt(14)
	ds_write2_b32 v13, v48, v49 offset0:32 offset1:98
	s_waitcnt vmcnt(12)
	ds_write2_b32 v13, v50, v51 offset0:164 offset1:230
	v_add_u32_e32 v13, 0x1400, v23
	s_waitcnt vmcnt(10)
	ds_write2_b32 v13, v52, v53 offset0:40 offset1:106
	s_waitcnt vmcnt(8)
	ds_write2_b32 v13, v54, v55 offset0:172 offset1:238
	v_add_u32_e32 v13, 0x1800, v23
	s_waitcnt vmcnt(6)
	ds_write2_b32 v13, v56, v57 offset0:48 offset1:114
	s_waitcnt vmcnt(4)
	ds_write2_b32 v13, v58, v59 offset0:180 offset1:246
	v_add_u32_e32 v13, 0x1c00, v23
	s_waitcnt vmcnt(2)
	ds_write2_b32 v13, v60, v61 offset0:56 offset1:122
	s_waitcnt vmcnt(0)
	ds_write2_b32 v13, v32, v18 offset0:188 offset1:254
	v_ashrrev_i32_e32 v15, 31, v14
	s_waitcnt lgkmcnt(0)
	v_lshl_add_u64 v[14:15], v[14:15], 1, v[16:17]
	v_mov_b32_e32 v13, v129
	v_lshl_add_u64 v[18:19], v[14:15], 0, v[12:13]
	ds_read2_b32 v[14:15], v25 offset1:33
	s_waitcnt lgkmcnt(0)
	v_cvt_pk_bf16_f32 v14, v14, v15
	ds_read2_b32 v[16:17], v25 offset0:66 offset1:99
	s_waitcnt lgkmcnt(0)
	v_cvt_pk_bf16_f32 v15, v16, v17
	ds_read2_b32 v[16:17], v25 offset0:132 offset1:165
	s_waitcnt lgkmcnt(0)
	v_cvt_pk_bf16_f32 v16, v16, v17
	ds_read2_b32 v[32:33], v25 offset0:198 offset1:231
	s_waitcnt lgkmcnt(0)
	v_cvt_pk_bf16_f32 v17, v32, v33
	v_add_u32_e32 v32, v31, v24
	v_ashrrev_i32_e32 v33, 31, v32
	v_lshlrev_b64 v[32:33], 11, v[32:33]
	v_lshl_add_u64 v[32:33], v[18:19], 0, v[32:33]
	global_store_dwordx4 v[32:33], v[14:17], off sc1
	ds_read2_b32 v[14:15], v25 offset0:8 offset1:41
	s_waitcnt lgkmcnt(0)
	v_cvt_pk_bf16_f32 v14, v14, v15
	ds_read2_b32 v[16:17], v25 offset0:74 offset1:107
	s_waitcnt lgkmcnt(0)
	v_cvt_pk_bf16_f32 v15, v16, v17
	ds_read2_b32 v[16:17], v25 offset0:140 offset1:173
	s_waitcnt lgkmcnt(0)
	v_cvt_pk_bf16_f32 v16, v16, v17
	ds_read2_b32 v[32:33], v25 offset0:206 offset1:239
	s_waitcnt lgkmcnt(0)
	v_cvt_pk_bf16_f32 v17, v32, v33
	v_add_u32_e32 v32, v31, v26
	v_ashrrev_i32_e32 v33, 31, v32
	v_lshlrev_b64 v[32:33], 11, v[32:33]
	v_lshl_add_u64 v[32:33], v[18:19], 0, v[32:33]
	global_store_dwordx4 v[32:33], v[14:17], off sc1
	ds_read2_b32 v[14:15], v25 offset0:16 offset1:49
	s_waitcnt lgkmcnt(0)
	v_cvt_pk_bf16_f32 v14, v14, v15
	ds_read2_b32 v[16:17], v25 offset0:82 offset1:115
	s_waitcnt lgkmcnt(0)
	v_cvt_pk_bf16_f32 v15, v16, v17
	ds_read2_b32 v[16:17], v25 offset0:148 offset1:181
	s_waitcnt lgkmcnt(0)
	v_cvt_pk_bf16_f32 v16, v16, v17
	ds_read2_b32 v[32:33], v25 offset0:214 offset1:247
	s_waitcnt lgkmcnt(0)
	v_cvt_pk_bf16_f32 v17, v32, v33
	v_add_u32_e32 v32, v31, v27
	v_ashrrev_i32_e32 v33, 31, v32
	v_lshlrev_b64 v[32:33], 11, v[32:33]
	v_lshl_add_u64 v[32:33], v[18:19], 0, v[32:33]
	global_store_dwordx4 v[32:33], v[14:17], off sc1
	ds_read2_b32 v[14:15], v25 offset0:24 offset1:57
	s_waitcnt lgkmcnt(0)
	v_cvt_pk_bf16_f32 v14, v14, v15
	ds_read2_b32 v[16:17], v25 offset0:90 offset1:123
	s_waitcnt lgkmcnt(0)
	v_cvt_pk_bf16_f32 v15, v16, v17
	ds_read2_b32 v[16:17], v25 offset0:156 offset1:189
	s_waitcnt lgkmcnt(0)
	v_cvt_pk_bf16_f32 v16, v16, v17
	ds_read2_b32 v[32:33], v25 offset0:222 offset1:255
	s_waitcnt lgkmcnt(0)
	v_cvt_pk_bf16_f32 v17, v32, v33
	v_add_u32_e32 v32, v31, v28
	v_ashrrev_i32_e32 v33, 31, v32
	v_lshlrev_b64 v[32:33], 11, v[32:33]
	v_lshl_add_u64 v[18:19], v[18:19], 0, v[32:33]
	global_store_dwordx4 v[18:19], v[14:17], off sc1
	s_waitcnt lgkmcnt(0)

; __device__ __forceinline__ void prep_weights(const Params& P, LAS unsigned char* lds, int lay, int bid, int G, int sel) {
;     ...
;       for (int it = gw; it < NIT; it += NGW) { int r = it;
;           if (r < 2 * I_GU) { if (!((sel >> (r / I_GU)) & 1)) continue; const int mat = lay * 2 + r / I_GU, ii = r % I_GU, kb = ii / 176, nb = ii % 176, n0 = nb * 32;
;               const int drow = n0 < DFF ? (n0 >> 7) * 256 + (n0 & 127) : ((n0 - DFF) >> 7) * 256 + 128 + ((n0 - DFF) & 127);
;               transpose_item(P.w_gu + (size_t)mat * 1024 * 5632, 5632, kb * 64, n0, (bf16_t*)(ws + OFF_WGU + mat * SZ_WGU1), 1024, drow, kb * 64, scr, lane); continue; }
;           r -= 2 * I_GU;
;           if (r < 2 * I_DN) { if (!((sel >> (2 + r / I_DN)) & 1)) continue; const int mat = lay * 2 + r / I_DN, ii = r % I_DN, kb = ii / 32, nb = ii % 32;
;               transpose_item(P.w_down + (size_t)mat * DFF * 1024, 1024, kb * 64, nb * 32, (bf16_t*)(ws + OFF_WDN + mat * SZ_WDN1), DFF, nb * 32, kb * 64, scr, lane); continue; }
;           r -= 2 * I_DN;
;           if (r < I_IN) { if (!(sel & 16)) continue; const int mat = lay, kb = r / 56, nb = r % 56;
;               transpose_item(P.w_in + (size_t)mat * 1024 * 1792, 1792, kb * 64, nb * 32, (bf16_t*)(ws + OFF_WIN + mat * SZ_WIN1), 1024, nb * 32, kb * 64, scr, lane); continue; }
;           r -= I_IN;
;           if (sel & 32) { const int mat = lay, kb = r / 32, nb = r % 32;
;               transpose_item(P.w_out + (size_t)mat * 1024 * 1024, 1024, kb * 64, nb * 32, (bf16_t*)(ws + OFF_WOUT + mat * SZ_WOUT1), 1280, nb * 32, kb * 64, scr, lane); } } }
.LBB0_1157:
	s_movk_i32 s0, 0x15ff
	v_cmp_lt_i32_e32 vcc, s0, v20
	s_and_saveexec_b64 s[0:1], vcc
	s_xor_b64 s[42:43], exec, s[0:1]
	s_cbranch_execz .LBB0_1169
	s_movk_i32 s0, 0x20ff
	v_cmp_lt_u32_e32 vcc, s0, v20
	s_and_saveexec_b64 s[0:1], vcc
	s_xor_b64 s[8:9], exec, s[0:1]
	s_cbranch_execz .LBB0_1164
	s_movk_i32 s0, 0x247f
	v_cmp_lt_u32_e32 vcc, s0, v20
	s_and_saveexec_b64 s[0:1], vcc
	s_xor_b64 s[46:47], exec, s[0:1]
	s_cbranch_execz .LBB0_1161
	v_and_b32_e32 v13, 0x7fffffc0, v29
	v_add_u32_e32 v14, 0xffffb700, v13
	v_and_b32_e32 v13, 0x3e0, v30
	v_or_b32_e32 v18, v14, v22
	v_lshlrev_b32_e32 v16, 2, v13
	v_mov_b32_e32 v17, v129
	v_mov_b32_e32 v19, v129
	v_lshl_add_u64 v[16:17], v[4:5], 0, v[16:17]
	v_lshlrev_b64 v[32:33], 12, v[18:19]
	v_lshl_add_u64 v[32:33], v[16:17], 0, v[32:33]
	global_load_dword v15, v[32:33], off
	v_or_b32_e32 v32, 2, v18
	v_mov_b32_e32 v33, v129
	v_lshlrev_b64 v[32:33], 12, v[32:33]
	v_lshl_add_u64 v[32:33], v[16:17], 0, v[32:33]
	global_load_dword v31, v[32:33], off
	v_or_b32_e32 v32, 4, v18
	v_mov_b32_e32 v33, v129
	v_lshlrev_b64 v[32:33], 12, v[32:33]
	v_lshl_add_u64 v[32:33], v[16:17], 0, v[32:33]
	global_load_dword v34, v[32:33], off
	v_or_b32_e32 v32, 6, v18
	v_mov_b32_e32 v33, v129
	v_lshlrev_b64 v[32:33], 12, v[32:33]
	v_lshl_add_u64 v[32:33], v[16:17], 0, v[32:33]
	global_load_dword v35, v[32:33], off
	v_or_b32_e32 v32, 8, v18
	v_mov_b32_e32 v33, v129
	v_lshlrev_b64 v[32:33], 12, v[32:33]
	v_lshl_add_u64 v[32:33], v[16:17], 0, v[32:33]
	global_load_dword v36, v[32:33], off
	v_or_b32_e32 v32, 10, v18
	v_mov_b32_e32 v33, v129
	v_lshlrev_b64 v[32:33], 12, v[32:33]
	v_lshl_add_u64 v[32:33], v[16:17], 0, v[32:33]
	global_load_dword v37, v[32:33], off
	v_or_b32_e32 v32, 12, v18
	v_mov_b32_e32 v33, v129
	v_lshlrev_b64 v[32:33], 12, v[32:33]
	v_lshl_add_u64 v[32:33], v[16:17], 0, v[32:33]
	global_load_dword v38, v[32:33], off
	v_or_b32_e32 v32, 14, v18
	v_mov_b32_e32 v33, v129
	v_lshlrev_b64 v[32:33], 12, v[32:33]
	v_lshl_add_u64 v[32:33], v[16:17], 0, v[32:33]
	global_load_dword v39, v[32:33], off
	v_or_b32_e32 v32, 16, v18
	v_mov_b32_e32 v33, v129
	v_lshlrev_b64 v[32:33], 12, v[32:33]
	v_lshl_add_u64 v[32:33], v[16:17], 0, v[32:33]
	global_load_dword v40, v[32:33], off
	v_or_b32_e32 v32, 18, v18
	v_mov_b32_e32 v33, v129
	v_lshlrev_b64 v[32:33], 12, v[32:33]
	v_lshl_add_u64 v[32:33], v[16:17], 0, v[32:33]
	global_load_dword v41, v[32:33], off
	v_or_b32_e32 v32, 20, v18
	v_mov_b32_e32 v33, v129
	v_lshlrev_b64 v[32:33], 12, v[32:33]
	v_lshl_add_u64 v[32:33], v[16:17], 0, v[32:33]
	global_load_dword v42, v[32:33], off
	v_or_b32_e32 v32, 22, v18
	v_mov_b32_e32 v33, v129
	v_lshlrev_b64 v[32:33], 12, v[32:33]
	v_lshl_add_u64 v[32:33], v[16:17], 0, v[32:33]
	global_load_dword v43, v[32:33], off
	v_or_b32_e32 v32, 24, v18
	v_mov_b32_e32 v33, v129
	v_lshlrev_b64 v[32:33], 12, v[32:33]
	v_lshl_add_u64 v[32:33], v[16:17], 0, v[32:33]
	global_load_dword v44, v[32:33], off
	v_or_b32_e32 v32, 26, v18
	v_mov_b32_e32 v33, v129
	v_lshlrev_b64 v[32:33], 12, v[32:33]
	v_lshl_add_u64 v[32:33], v[16:17], 0, v[32:33]
	global_load_dword v45, v[32:33], off
	v_or_b32_e32 v32, 28, v18
	v_mov_b32_e32 v33, v129
	v_lshlrev_b64 v[32:33], 12, v[32:33]
	v_lshl_add_u64 v[32:33], v[16:17], 0, v[32:33]
	global_load_dword v46, v[32:33], off
	v_or_b32_e32 v32, 30, v18
	v_mov_b32_e32 v33, v129
	v_lshlrev_b64 v[32:33], 12, v[32:33]
	v_lshl_add_u64 v[32:33], v[16:17], 0, v[32:33]
	global_load_dword v47, v[32:33], off
	v_or_b32_e32 v32, 32, v18
	v_mov_b32_e32 v33, v129
	v_lshlrev_b64 v[32:33], 12, v[32:33]
	v_lshl_add_u64 v[32:33], v[16:17], 0, v[32:33]
	global_load_dword v48, v[32:33], off
	v_or_b32_e32 v32, 34, v18
	v_mov_b32_e32 v33, v129
	v_lshlrev_b64 v[32:33], 12, v[32:33]
	v_lshl_add_u64 v[32:33], v[16:17], 0, v[32:33]
	global_load_dword v49, v[32:33], off
	v_or_b32_e32 v32, 36, v18
	v_mov_b32_e32 v33, v129
	v_lshlrev_b64 v[32:33], 12, v[32:33]
	v_lshl_add_u64 v[32:33], v[16:17], 0, v[32:33]
	global_load_dword v50, v[32:33], off
	v_or_b32_e32 v32, 38, v18
	v_mov_b32_e32 v33, v129
	v_lshlrev_b64 v[32:33], 12, v[32:33]
	v_lshl_add_u64 v[32:33], v[16:17], 0, v[32:33]
	global_load_dword v51, v[32:33], off
	v_or_b32_e32 v32, 40, v18
	v_mov_b32_e32 v33, v129
	v_lshlrev_b64 v[32:33], 12, v[32:33]
	v_lshl_add_u64 v[32:33], v[16:17], 0, v[32:33]
	global_load_dword v52, v[32:33], off
	v_or_b32_e32 v32, 42, v18
	v_mov_b32_e32 v33, v129
	v_lshlrev_b64 v[32:33], 12, v[32:33]
	v_lshl_add_u64 v[32:33], v[16:17], 0, v[32:33]
	global_load_dword v53, v[32:33], off
	v_or_b32_e32 v32, 44, v18
	v_mov_b32_e32 v33, v129
	v_lshlrev_b64 v[32:33], 12, v[32:33]
	v_lshl_add_u64 v[32:33], v[16:17], 0, v[32:33]
	global_load_dword v54, v[32:33], off
	v_or_b32_e32 v32, 46, v18
	v_mov_b32_e32 v33, v129
	v_lshlrev_b64 v[32:33], 12, v[32:33]
	v_lshl_add_u64 v[32:33], v[16:17], 0, v[32:33]
	global_load_dword v55, v[32:33], off
	v_or_b32_e32 v32, 48, v18
	v_mov_b32_e32 v33, v129
	v_lshlrev_b64 v[32:33], 12, v[32:33]
	v_lshl_add_u64 v[32:33], v[16:17], 0, v[32:33]
	global_load_dword v56, v[32:33], off
	v_or_b32_e32 v32, 50, v18
	v_mov_b32_e32 v33, v129
	v_lshlrev_b64 v[32:33], 12, v[32:33]
	v_lshl_add_u64 v[32:33], v[16:17], 0, v[32:33]
	global_load_dword v57, v[32:33], off
	v_or_b32_e32 v32, 52, v18
	v_mov_b32_e32 v33, v129
	v_lshlrev_b64 v[32:33], 12, v[32:33]
	v_lshl_add_u64 v[32:33], v[16:17], 0, v[32:33]
	global_load_dword v58, v[32:33], off
	v_or_b32_e32 v32, 54, v18
	v_mov_b32_e32 v33, v129
	v_lshlrev_b64 v[32:33], 12, v[32:33]
	v_lshl_add_u64 v[32:33], v[16:17], 0, v[32:33]
	global_load_dword v59, v[32:33], off
	v_or_b32_e32 v32, 56, v18
	v_mov_b32_e32 v33, v129
	v_lshlrev_b64 v[32:33], 12, v[32:33]
	v_lshl_add_u64 v[32:33], v[16:17], 0, v[32:33]
	global_load_dword v60, v[32:33], off
	v_or_b32_e32 v32, 58, v18
	v_mov_b32_e32 v33, v129
	v_lshlrev_b64 v[32:33], 12, v[32:33]
	v_lshl_add_u64 v[32:33], v[16:17], 0, v[32:33]
	global_load_dword v61, v[32:33], off
	v_or_b32_e32 v32, 60, v18
	v_mov_b32_e32 v33, v129
	v_or_b32_e32 v18, 62, v18
	v_lshlrev_b64 v[32:33], 12, v[32:33]
	v_lshlrev_b64 v[18:19], 12, v[18:19]
	v_lshl_add_u64 v[32:33], v[16:17], 0, v[32:33]
	v_lshl_add_u64 v[16:17], v[16:17], 0, v[18:19]
	global_load_dword v32, v[32:33], off
	s_nop 0
	global_load_dword v16, v[16:17], off
	s_waitcnt vmcnt(30)
; #define LAS __attribute__((address_space(3)))
; #define GAS __attribute__((address_space(1)))
; __device__ __forceinline__ unsigned cvt_pk_bf16(float lo, float hi) { unsigned r; asm volatile("v_cvt_pk_bf16_f32 %0, %1, %2" : "=v"(r) : "v"(lo), "v"(hi)); return r; }
; __device__ __forceinline__ void transpose_item(const float* W, int ldw, int k0, int n0, bf16_t* WT, int ldt, int drow0, int dk0, LAS float* scr, int lane) {
;     ...
;     for (int i = 0; i < 32; ++i) { const int kk = 2 * i + (lane >> 5); scr[kk * 33 + (lane & 31)] = tv[i]; }
;     asm volatile("s_waitcnt lgkmcnt(0)" ::: "memory");
;     const int c = lane & 7;
; #pragma unroll
;     for (int j = 0; j < 4; ++j) { const int n = (lane >> 3) + 8 * j; const LAS float* s = scr + (8 * c) * 33 + n;
;         u32x4 o; o.x = cvt_pk_bf16(s[0 * 33], s[1 * 33]); o.y = cvt_pk_bf16(s[2 * 33], s[3 * 33]); o.z = cvt_pk_bf16(s[4 * 33], s[5 * 33]); o.w = cvt_pk_bf16(s[6 * 33], s[7 * 33]);
;         *(GAS u32x4*)((GAS bf16_t*)WT + (size_t)(drow0 + n) * ldt + dk0 + 8 * c) = o; }
; __device__ __forceinline__ void prep_weights(const Params& P, LAS unsigned char* lds, int lay, int bid, int G, int sel) {
;     ...
;           if (r < I_IN) { if (!(sel & 16)) continue; const int mat = lay, kb = r / 56, nb = r % 56;
;               transpose_item(P.w_in + (size_t)mat * 1024 * 1792, 1792, kb * 64, nb * 32, (bf16_t*)(ws + OFF_WIN + mat * SZ_WIN1), 1024, nb * 32, kb * 64, scr, lane); continue; }
	ds_write2_b32 v23, v15, v31 offset1:66
	s_waitcnt vmcnt(28)
	ds_write2_b32 v23, v34, v35 offset0:132 offset1:198
	v_add_u32_e32 v15, 0x400, v23
	s_waitcnt vmcnt(26)
	ds_write2_b32 v15, v36, v37 offset0:8 offset1:74
	s_waitcnt vmcnt(24)
	ds_write2_b32 v15, v38, v39 offset0:140 offset1:206
	v_add_u32_e32 v15, 0x800, v23
	s_waitcnt vmcnt(22)
	ds_write2_b32 v15, v40, v41 offset0:16 offset1:82
	s_waitcnt vmcnt(20)
	ds_write2_b32 v15, v42, v43 offset0:148 offset1:214
	v_add_u32_e32 v15, 0xc00, v23
	s_waitcnt vmcnt(18)
	ds_write2_b32 v15, v44, v45 offset0:24 offset1:90
	s_waitcnt vmcnt(16)
	ds_write2_b32 v15, v46, v47 offset0:156 offset1:222
	v_add_u32_e32 v15, 0x1000, v23
	s_waitcnt vmcnt(14)
	ds_write2_b32 v15, v48, v49 offset0:32 offset1:98
	s_waitcnt vmcnt(12)
	ds_write2_b32 v15, v50, v51 offset0:164 offset1:230
	v_add_u32_e32 v15, 0x1400, v23
	s_waitcnt vmcnt(10)
	ds_write2_b32 v15, v52, v53 offset0:40 offset1:106
	s_waitcnt vmcnt(8)
	ds_write2_b32 v15, v54, v55 offset0:172 offset1:238
	v_add_u32_e32 v15, 0x1800, v23
	s_waitcnt vmcnt(6)
	ds_write2_b32 v15, v56, v57 offset0:48 offset1:114
	s_waitcnt vmcnt(4)
	ds_write2_b32 v15, v58, v59 offset0:180 offset1:246
	v_add_u32_e32 v15, 0x1c00, v23
	s_waitcnt vmcnt(2)
	ds_write2_b32 v15, v60, v61 offset0:56 offset1:122
	s_waitcnt vmcnt(0)
	ds_write2_b32 v15, v32, v16 offset0:188 offset1:254
	s_waitcnt lgkmcnt(0)
	v_mov_b32_e32 v15, v129
	v_lshl_add_u64 v[18:19], v[14:15], 1, v[0:1]
	ds_read2_b32 v[14:15], v25 offset1:33
	s_waitcnt lgkmcnt(0)
	v_cvt_pk_bf16_f32 v14, v14, v15
	ds_read2_b32 v[16:17], v25 offset0:66 offset1:99
	s_waitcnt lgkmcnt(0)
	v_cvt_pk_bf16_f32 v15, v16, v17
	ds_read2_b32 v[16:17], v25 offset0:132 offset1:165
	v_or_b32_e32 v31, v13, v24
	s_waitcnt lgkmcnt(0)
	v_cvt_pk_bf16_f32 v16, v16, v17
	ds_read2_b32 v[32:33], v25 offset0:198 offset1:231
	v_mul_u32_u24_e32 v31, 0x500, v31
	s_waitcnt lgkmcnt(0)
	v_cvt_pk_bf16_f32 v17, v32, v33
	v_lshlrev_b32_e32 v32, 1, v31
	v_mov_b32_e32 v33, v129
	v_lshl_add_u64 v[32:33], v[18:19], 0, v[32:33]
	global_store_dwordx4 v[32:33], v[14:17], off sc1
	ds_read2_b32 v[14:15], v25 offset0:8 offset1:41
	v_or_b32_e32 v31, v13, v26
	s_waitcnt lgkmcnt(0)
	v_cvt_pk_bf16_f32 v14, v14, v15
	ds_read2_b32 v[16:17], v25 offset0:74 offset1:107
	s_waitcnt lgkmcnt(0)
	v_cvt_pk_bf16_f32 v15, v16, v17
	ds_read2_b32 v[16:17], v25 offset0:140 offset1:173
	s_waitcnt lgkmcnt(0)
	v_cvt_pk_bf16_f32 v16, v16, v17
	ds_read2_b32 v[32:33], v25 offset0:206 offset1:239
	v_mul_u32_u24_e32 v31, 0x500, v31
	s_waitcnt lgkmcnt(0)
	v_cvt_pk_bf16_f32 v17, v32, v33
	v_lshlrev_b32_e32 v32, 1, v31
	v_mov_b32_e32 v33, v129
	v_lshl_add_u64 v[32:33], v[18:19], 0, v[32:33]
	global_store_dwordx4 v[32:33], v[14:17], off sc1
	ds_read2_b32 v[14:15], v25 offset0:16 offset1:49
	v_or_b32_e32 v31, v13, v27
	s_waitcnt lgkmcnt(0)
	v_cvt_pk_bf16_f32 v14, v14, v15
	ds_read2_b32 v[16:17], v25 offset0:82 offset1:115
	s_waitcnt lgkmcnt(0)
	v_cvt_pk_bf16_f32 v15, v16, v17
	ds_read2_b32 v[16:17], v25 offset0:148 offset1:181
	s_waitcnt lgkmcnt(0)
	v_cvt_pk_bf16_f32 v16, v16, v17
	ds_read2_b32 v[32:33], v25 offset0:214 offset1:247
	v_mul_u32_u24_e32 v31, 0x500, v31
	s_waitcnt lgkmcnt(0)
	v_cvt_pk_bf16_f32 v17, v32, v33
	v_lshlrev_b32_e32 v32, 1, v31
	v_mov_b32_e32 v33, v129
	v_lshl_add_u64 v[32:33], v[18:19], 0, v[32:33]
	global_store_dwordx4 v[32:33], v[14:17], off sc1
	ds_read2_b32 v[14:15], v25 offset0:24 offset1:57
	v_or_b32_e32 v13, v13, v28
	s_waitcnt lgkmcnt(0)
	v_cvt_pk_bf16_f32 v14, v14, v15
	ds_read2_b32 v[16:17], v25 offset0:90 offset1:123
	s_waitcnt lgkmcnt(0)
	v_cvt_pk_bf16_f32 v15, v16, v17
	ds_read2_b32 v[16:17], v25 offset0:156 offset1:189
	s_waitcnt lgkmcnt(0)
	v_cvt_pk_bf16_f32 v16, v16, v17
	ds_read2_b32 v[32:33], v25 offset0:222 offset1:255
	v_mul_u32_u24_e32 v13, 0x500, v13
	s_waitcnt lgkmcnt(0)
	v_cvt_pk_bf16_f32 v17, v32, v33
	v_lshlrev_b32_e32 v32, 1, v13
	v_mov_b32_e32 v33, v129
	v_lshl_add_u64 v[18:19], v[18:19], 0, v[32:33]
	global_store_dwordx4 v[18:19], v[14:17], off sc1
	s_waitcnt lgkmcnt(0)
.LBB0_1161:
	s_andn2_saveexec_b64 s[46:47], s[46:47]
	s_cbranch_execz .LBB0_1163
	v_add_u16_e32 v13, 0xdf00, v20
	v_lshrrev_b16_e32 v14, 3, v13
	v_mul_u32_u24_e32 v14, 0x2493, v14
	v_lshrrev_b32_e32 v18, 16, v14
	v_mul_lo_u16_e32 v14, 56, v18
	v_sub_u16_e32 v13, v13, v14
	v_lshlrev_b16_e32 v13, 5, v13
	v_lshl_or_b32 v16, v18, 6, v22
	v_lshlrev_b32_e32 v14, 2, v13
	v_mov_b32_e32 v15, v129
	v_lshl_add_u64 v[14:15], v[6:7], 0, v[14:15]
	v_mul_u32_u24_e32 v16, 0x700, v16
	v_mov_b32_e32 v17, v129
	v_lshl_add_u64 v[14:15], v[16:17], 2, v[14:15]
	v_add_co_u32_e32 v16, vcc, 0x3000, v14
	s_mov_b32 s0, 0xa000
	s_nop 0
	v_addc_co_u32_e32 v17, vcc, 0, v15, vcc
	global_load_dword v31, v[16:17], off offset:2048
	v_add_co_u32_e32 v16, vcc, 0x7000, v14
	global_load_dword v19, v[14:15], off
	s_nop 0
	v_addc_co_u32_e32 v17, vcc, 0, v15, vcc
	global_load_dword v32, v[16:17], off
	v_add_co_u32_e32 v16, vcc, s0, v14
	s_mov_b32 s0, 0xe000
	s_nop 0
	v_addc_co_u32_e32 v17, vcc, 0, v15, vcc
	global_load_dword v33, v[16:17], off offset:2048
	v_add_co_u32_e32 v16, vcc, s0, v14
	s_mov_b32 s0, 0x18000
	s_nop 0
	v_addc_co_u32_e32 v17, vcc, 0, v15, vcc
	global_load_dword v34, v[16:17], off
	v_add_co_u32_e32 v16, vcc, 0x11000, v14
	s_nop 1
	v_addc_co_u32_e32 v17, vcc, 0, v15, vcc
	global_load_dword v35, v[16:17], off offset:2048
	v_add_co_u32_e32 v16, vcc, 0x15000, v14
	s_nop 1
	v_addc_co_u32_e32 v17, vcc, 0, v15, vcc
	global_load_dword v36, v[16:17], off
	v_add_co_u32_e32 v16, vcc, s0, v14
	s_mov_b32 s0, 0x1c000
	s_nop 0
	v_addc_co_u32_e32 v17, vcc, 0, v15, vcc
	global_load_dword v37, v[16:17], off offset:2048
; __device__ __forceinline__ void transpose_item(const float* W, int ldw, int k0, int n0, bf16_t* WT, int ldt, int drow0, int dk0, LAS float* scr, int lane) {
;     ...
;     for (int i = 0; i < 32; ++i) { const int kk = 2 * i + (lane >> 5); tv[i] = W[(size_t)(k0 + kk) * ldw + n0 + (lane & 31)]; }
; __device__ __forceinline__ void prep_weights(const Params& P, LAS unsigned char* lds, int lay, int bid, int G, int sel) {
;     ...
;               transpose_item(P.w_in + (size_t)mat * 1024 * 1792, 1792, kb * 64, nb * 32, (bf16_t*)(ws + OFF_WIN + mat * SZ_WIN1), 1024, nb * 32, kb * 64, scr, lane); continue; }
	v_add_co_u32_e32 v16, vcc, s0, v14
	s_mov_b32 s0, 0x50000
	s_nop 0
	v_addc_co_u32_e32 v17, vcc, 0, v15, vcc
	global_load_dword v38, v[16:17], off
	v_add_co_u32_e32 v16, vcc, 0x1f000, v14
	s_nop 1
	v_addc_co_u32_e32 v17, vcc, 0, v15, vcc
	global_load_dword v39, v[16:17], off offset:2048
	v_add_co_u32_e32 v16, vcc, 0x23000, v14
	s_nop 1
	v_addc_co_u32_e32 v17, vcc, 0, v15, vcc
	global_load_dword v40, v[16:17], off
	v_add_co_u32_e32 v16, vcc, 0x26000, v14
	s_nop 1
	v_addc_co_u32_e32 v17, vcc, 0, v15, vcc
	global_load_dword v41, v[16:17], off offset:2048
	v_add_co_u32_e32 v16, vcc, 0x2a000, v14
	s_nop 1
	v_addc_co_u32_e32 v17, vcc, 0, v15, vcc
	global_load_dword v42, v[16:17], off
	v_add_co_u32_e32 v16, vcc, 0x2d000, v14
	s_nop 1
	v_addc_co_u32_e32 v17, vcc, 0, v15, vcc
	global_load_dword v43, v[16:17], off offset:2048
	v_add_co_u32_e32 v16, vcc, 0x31000, v14
	s_nop 1
	v_addc_co_u32_e32 v17, vcc, 0, v15, vcc
	global_load_dword v44, v[16:17], off
	v_add_co_u32_e32 v16, vcc, 0x34000, v14
	s_nop 1
	v_addc_co_u32_e32 v17, vcc, 0, v15, vcc
	global_load_dword v45, v[16:17], off offset:2048
	v_add_co_u32_e32 v16, vcc, 0x38000, v14
	s_nop 1
	v_addc_co_u32_e32 v17, vcc, 0, v15, vcc
	global_load_dword v46, v[16:17], off
	v_add_co_u32_e32 v16, vcc, 0x3b000, v14
	s_nop 1
	v_addc_co_u32_e32 v17, vcc, 0, v15, vcc
	global_load_dword v47, v[16:17], off offset:2048
	v_add_co_u32_e32 v16, vcc, 0x3f000, v14
	s_nop 1
	v_addc_co_u32_e32 v17, vcc, 0, v15, vcc
	global_load_dword v48, v[16:17], off
	v_add_co_u32_e32 v16, vcc, 0x42000, v14
	s_nop 1
	v_addc_co_u32_e32 v17, vcc, 0, v15, vcc
	global_load_dword v49, v[16:17], off offset:2048
	v_add_co_u32_e32 v16, vcc, 0x46000, v14
	s_nop 1
	v_addc_co_u32_e32 v17, vcc, 0, v15, vcc
	global_load_dword v50, v[16:17], off
	v_add_co_u32_e32 v16, vcc, 0x49000, v14
	s_nop 1
	v_addc_co_u32_e32 v17, vcc, 0, v15, vcc
	global_load_dword v51, v[16:17], off offset:2048
	v_add_co_u32_e32 v16, vcc, 0x4d000, v14
	s_nop 1
	v_addc_co_u32_e32 v17, vcc, 0, v15, vcc
	global_load_dword v52, v[16:17], off
	v_add_co_u32_e32 v16, vcc, s0, v14
	s_nop 1
	v_addc_co_u32_e32 v17, vcc, 0, v15, vcc
	global_load_dword v53, v[16:17], off offset:2048
	v_add_co_u32_e32 v16, vcc, 0x54000, v14
	s_nop 1
	v_addc_co_u32_e32 v17, vcc, 0, v15, vcc
	global_load_dword v54, v[16:17], off
	v_add_co_u32_e32 v16, vcc, 0x57000, v14
	s_nop 1
	v_addc_co_u32_e32 v17, vcc, 0, v15, vcc
	global_load_dword v55, v[16:17], off offset:2048
	v_add_co_u32_e32 v16, vcc, 0x5b000, v14
	s_nop 1
	v_addc_co_u32_e32 v17, vcc, 0, v15, vcc
	global_load_dword v56, v[16:17], off
	v_add_co_u32_e32 v16, vcc, 0x5e000, v14
	s_nop 1
	v_addc_co_u32_e32 v17, vcc, 0, v15, vcc
	global_load_dword v57, v[16:17], off offset:2048
	v_add_co_u32_e32 v16, vcc, 0x62000, v14
	s_nop 1
	v_addc_co_u32_e32 v17, vcc, 0, v15, vcc
	global_load_dword v58, v[16:17], off
	v_add_co_u32_e32 v16, vcc, 0x65000, v14
	s_nop 1
	v_addc_co_u32_e32 v17, vcc, 0, v15, vcc
	global_load_dword v59, v[16:17], off offset:2048
	v_add_co_u32_e32 v16, vcc, 0x69000, v14
	s_nop 1
	v_addc_co_u32_e32 v17, vcc, 0, v15, vcc
	v_add_co_u32_e32 v14, vcc, 0x6c000, v14
	global_load_dword v16, v[16:17], off
	s_nop 0
	v_addc_co_u32_e32 v15, vcc, 0, v15, vcc
	global_load_dword v14, v[14:15], off offset:2048
	v_add_u32_e32 v15, 0x400, v23
	s_waitcnt vmcnt(30)
	ds_write2_b32 v23, v19, v31 offset1:66
	s_waitcnt vmcnt(28)
	ds_write2_b32 v23, v32, v33 offset0:132 offset1:198
	s_waitcnt vmcnt(26)
	ds_write2_b32 v15, v34, v35 offset0:8 offset1:74
	s_waitcnt vmcnt(24)
	ds_write2_b32 v15, v36, v37 offset0:140 offset1:206
	v_add_u32_e32 v15, 0x800, v23
	s_waitcnt vmcnt(22)
; #define LAS __attribute__((address_space(3)))
; #define GAS __attribute__((address_space(1)))
; __device__ __forceinline__ unsigned cvt_pk_bf16(float lo, float hi) { unsigned r; asm volatile("v_cvt_pk_bf16_f32 %0, %1, %2" : "=v"(r) : "v"(lo), "v"(hi)); return r; }
; __device__ __forceinline__ void transpose_item(const float* W, int ldw, int k0, int n0, bf16_t* WT, int ldt, int drow0, int dk0, LAS float* scr, int lane) {
;     ...
;     for (int i = 0; i < 32; ++i) { const int kk = 2 * i + (lane >> 5); scr[kk * 33 + (lane & 31)] = tv[i]; }
;     asm volatile("s_waitcnt lgkmcnt(0)" ::: "memory");
;     const int c = lane & 7;
; #pragma unroll
;     for (int j = 0; j < 4; ++j) { const int n = (lane >> 3) + 8 * j; const LAS float* s = scr + (8 * c) * 33 + n;
;         u32x4 o; o.x = cvt_pk_bf16(s[0 * 33], s[1 * 33]); o.y = cvt_pk_bf16(s[2 * 33], s[3 * 33]); o.z = cvt_pk_bf16(s[4 * 33], s[5 * 33]); o.w = cvt_pk_bf16(s[6 * 33], s[7 * 33]);
;         *(GAS u32x4*)((GAS bf16_t*)WT + (size_t)(drow0 + n) * ldt + dk0 + 8 * c) = o; }
; __device__ __forceinline__ void prep_weights(const Params& P, LAS unsigned char* lds, int lay, int bid, int G, int sel) {
;     ...
;               transpose_item(P.w_in + (size_t)mat * 1024 * 1792, 1792, kb * 64, nb * 32, (bf16_t*)(ws + OFF_WIN + mat * SZ_WIN1), 1024, nb * 32, kb * 64, scr, lane); continue; }
	ds_write2_b32 v15, v38, v39 offset0:16 offset1:82
	s_waitcnt vmcnt(20)
	ds_write2_b32 v15, v40, v41 offset0:148 offset1:214
	v_add_u32_e32 v15, 0xc00, v23
	s_waitcnt vmcnt(18)
	ds_write2_b32 v15, v42, v43 offset0:24 offset1:90
	s_waitcnt vmcnt(16)
	ds_write2_b32 v15, v44, v45 offset0:156 offset1:222
	v_add_u32_e32 v15, 0x1000, v23
	s_waitcnt vmcnt(14)
	ds_write2_b32 v15, v46, v47 offset0:32 offset1:98
	s_waitcnt vmcnt(12)
	ds_write2_b32 v15, v48, v49 offset0:164 offset1:230
	v_add_u32_e32 v15, 0x1400, v23
	s_waitcnt vmcnt(10)
	ds_write2_b32 v15, v50, v51 offset0:40 offset1:106
	s_waitcnt vmcnt(8)
	ds_write2_b32 v15, v52, v53 offset0:172 offset1:238
	v_add_u32_e32 v15, 0x1800, v23
	s_waitcnt vmcnt(6)
	ds_write2_b32 v15, v54, v55 offset0:48 offset1:114
	s_waitcnt vmcnt(4)
	ds_write2_b32 v15, v56, v57 offset0:180 offset1:246
	v_add_u32_e32 v15, 0x1c00, v23
	s_waitcnt vmcnt(2)
	ds_write2_b32 v15, v58, v59 offset0:56 offset1:122
	s_waitcnt vmcnt(0)
	ds_write2_b32 v15, v16, v14 offset0:188 offset1:254
	s_waitcnt lgkmcnt(0)
	v_lshlrev_b32_e32 v14, 7, v18
	v_mov_b32_e32 v15, v129
	v_lshl_add_u64 v[18:19], v[2:3], 0, v[14:15]
	ds_read2_b32 v[14:15], v25 offset1:33
	s_waitcnt lgkmcnt(0)
	v_cvt_pk_bf16_f32 v14, v14, v15
	ds_read2_b32 v[16:17], v25 offset0:66 offset1:99
	s_waitcnt lgkmcnt(0)
	v_cvt_pk_bf16_f32 v15, v16, v17
	ds_read2_b32 v[16:17], v25 offset0:132 offset1:165
	s_waitcnt lgkmcnt(0)
	v_cvt_pk_bf16_f32 v16, v16, v17
	ds_read2_b32 v[32:33], v25 offset0:198 offset1:231
	v_or_b32_e32 v31, v24, v13
	s_waitcnt lgkmcnt(0)
	v_cvt_pk_bf16_f32 v17, v32, v33
	v_lshlrev_b32_e32 v32, 11, v31
	v_mov_b32_e32 v33, v129
	v_lshl_add_u64 v[32:33], v[18:19], 0, v[32:33]
	global_store_dwordx4 v[32:33], v[14:17], off sc1
	ds_read2_b32 v[14:15], v25 offset0:8 offset1:41
	v_or_b32_e32 v31, v26, v13
	s_waitcnt lgkmcnt(0)
	v_cvt_pk_bf16_f32 v14, v14, v15
	ds_read2_b32 v[16:17], v25 offset0:74 offset1:107
	s_waitcnt lgkmcnt(0)
	v_cvt_pk_bf16_f32 v15, v16, v17
	ds_read2_b32 v[16:17], v25 offset0:140 offset1:173
	s_waitcnt lgkmcnt(0)
	v_cvt_pk_bf16_f32 v16, v16, v17
	ds_read2_b32 v[32:33], v25 offset0:206 offset1:239
	s_waitcnt lgkmcnt(0)
	v_cvt_pk_bf16_f32 v17, v32, v33
	v_lshlrev_b32_e32 v32, 11, v31
	v_mov_b32_e32 v33, v129
	v_lshl_add_u64 v[32:33], v[18:19], 0, v[32:33]
	global_store_dwordx4 v[32:33], v[14:17], off sc1
	ds_read2_b32 v[14:15], v25 offset0:16 offset1:49
	v_or_b32_e32 v31, v27, v13
	s_waitcnt lgkmcnt(0)
	v_cvt_pk_bf16_f32 v14, v14, v15
	ds_read2_b32 v[16:17], v25 offset0:82 offset1:115
	s_waitcnt lgkmcnt(0)
	v_cvt_pk_bf16_f32 v15, v16, v17
	ds_read2_b32 v[16:17], v25 offset0:148 offset1:181
	s_waitcnt lgkmcnt(0)
	v_cvt_pk_bf16_f32 v16, v16, v17
	ds_read2_b32 v[32:33], v25 offset0:214 offset1:247
	s_waitcnt lgkmcnt(0)
	v_cvt_pk_bf16_f32 v17, v32, v33
	v_lshlrev_b32_e32 v32, 11, v31
	v_mov_b32_e32 v33, v129
	v_lshl_add_u64 v[32:33], v[18:19], 0, v[32:33]
	global_store_dwordx4 v[32:33], v[14:17], off sc1
	ds_read2_b32 v[14:15], v25 offset0:24 offset1:57
	v_or_b32_e32 v13, v28, v13
	s_waitcnt lgkmcnt(0)
	v_cvt_pk_bf16_f32 v14, v14, v15
	ds_read2_b32 v[16:17], v25 offset0:90 offset1:123
	s_waitcnt lgkmcnt(0)
	v_cvt_pk_bf16_f32 v15, v16, v17
	ds_read2_b32 v[16:17], v25 offset0:156 offset1:189
	s_waitcnt lgkmcnt(0)
	v_cvt_pk_bf16_f32 v16, v16, v17
	ds_read2_b32 v[32:33], v25 offset0:222 offset1:255
	s_waitcnt lgkmcnt(0)
	v_cvt_pk_bf16_f32 v17, v32, v33
	v_lshlrev_b32_e32 v32, 11, v13
	v_mov_b32_e32 v33, v129
	v_lshl_add_u64 v[18:19], v[18:19], 0, v[32:33]
	global_store_dwordx4 v[18:19], v[14:17], off sc1
	s_waitcnt lgkmcnt(0)

; __device__ __forceinline__ void transpose_item(const float* W, int ldw, int k0, int n0, bf16_t* WT, int ldt, int drow0, int dk0, LAS float* scr, int lane) {
;     ...
;     for (int i = 0; i < 32; ++i) { const int kk = 2 * i + (lane >> 5); tv[i] = W[(size_t)(k0 + kk) * ldw + n0 + (lane & 31)]; }
; __device__ __forceinline__ void prep_weights(const Params& P, LAS unsigned char* lds, int lay, int bid, int G, int sel) {
;     ...
;           if (r < 2 * I_DN) { if (!((sel >> (2 + r / I_DN)) & 1)) continue; const int mat = lay * 2 + r / I_DN, ii = r % I_DN, kb = ii / 32, nb = ii % 32;
;               transpose_item(P.w_down + (size_t)mat * DFF * 1024, 1024, kb * 64, nb * 32, (bf16_t*)(ws + OFF_WDN + mat * SZ_WDN1), DFF, nb * 32, kb * 64, scr, lane); continue; }
.LBB0_1164:
	s_andn2_saveexec_b64 s[8:9], s[8:9]
	s_cbranch_execz .LBB0_1168
	v_add_u32_e32 v13, 0xffffe480, v20
	s_movk_i32 s0, 0xfa80
	v_cmp_gt_u32_e32 vcc, s0, v13
	s_and_saveexec_b64 s[46:47], vcc
	s_cbranch_execz .LBB0_1167
	v_add_u32_e32 v13, 0xffffc900, v29
	v_and_b32_e32 v18, 0xfc0, v13
	v_add_u32_e32 v13, 0xfffc9000, v30
	v_and_b32_e32 v13, 0x3e0, v13
	v_or_b32_e32 v16, v18, v22
	v_lshlrev_b32_e32 v14, 2, v13
	v_mov_b32_e32 v15, v129
	v_lshl_add_u64 v[14:15], v[8:9], 0, v[14:15]
	v_lshlrev_b32_e32 v16, 12, v16
	v_mov_b32_e32 v17, v129
	v_lshl_add_u64 v[14:15], v[14:15], 0, v[16:17]
	v_add_co_u32_e32 v16, vcc, 0x2000, v14
	global_load_dword v19, v[14:15], off
	s_nop 0
	v_addc_co_u32_e32 v17, vcc, 0, v15, vcc
	global_load_dword v31, v[16:17], off
	v_add_co_u32_e32 v16, vcc, 0x4000, v14
	s_mov_b32 s0, 0x10000
	s_nop 0
	v_addc_co_u32_e32 v17, vcc, 0, v15, vcc
	global_load_dword v32, v[16:17], off
	v_add_co_u32_e32 v16, vcc, 0x6000, v14
	s_nop 1
	v_addc_co_u32_e32 v17, vcc, 0, v15, vcc
	global_load_dword v33, v[16:17], off
	v_add_co_u32_e32 v16, vcc, s25, v14
	s_nop 1
	v_addc_co_u32_e32 v17, vcc, 0, v15, vcc
	global_load_dword v34, v[16:17], off
	v_add_co_u32_e32 v16, vcc, 0xa000, v14
	s_nop 1
	v_addc_co_u32_e32 v17, vcc, 0, v15, vcc
	global_load_dword v35, v[16:17], off
	v_add_co_u32_e32 v16, vcc, 0xc000, v14
	s_nop 1
	v_addc_co_u32_e32 v17, vcc, 0, v15, vcc
	global_load_dword v36, v[16:17], off
	v_add_co_u32_e32 v16, vcc, 0xe000, v14
	s_nop 1
	v_addc_co_u32_e32 v17, vcc, 0, v15, vcc
	global_load_dword v37, v[16:17], off
	v_add_co_u32_e32 v16, vcc, s0, v14
	s_mov_b32 s0, 0x12000
	s_nop 0
	v_addc_co_u32_e32 v17, vcc, 0, v15, vcc
	global_load_dword v38, v[16:17], off
	v_add_co_u32_e32 v16, vcc, s0, v14
	s_mov_b32 s0, 0x14000
	s_nop 0
	v_addc_co_u32_e32 v17, vcc, 0, v15, vcc
	global_load_dword v39, v[16:17], off
	v_add_co_u32_e32 v16, vcc, s0, v14
	s_mov_b32 s0, 0x16000
	s_nop 0
	v_addc_co_u32_e32 v17, vcc, 0, v15, vcc
	global_load_dword v40, v[16:17], off
	v_add_co_u32_e32 v16, vcc, s0, v14
	s_mov_b32 s0, 0x18000
	s_nop 0
	v_addc_co_u32_e32 v17, vcc, 0, v15, vcc
	global_load_dword v41, v[16:17], off
	v_add_co_u32_e32 v16, vcc, s0, v14
	s_mov_b32 s0, 0x1a000
	s_nop 0
	v_addc_co_u32_e32 v17, vcc, 0, v15, vcc
	global_load_dword v42, v[16:17], off
	v_add_co_u32_e32 v16, vcc, s0, v14
	s_mov_b32 s0, 0x1c000
	s_nop 0
	v_addc_co_u32_e32 v17, vcc, 0, v15, vcc
	global_load_dword v43, v[16:17], off
	v_add_co_u32_e32 v16, vcc, s0, v14
	s_mov_b32 s0, 0x1e000
	s_nop 0
	v_addc_co_u32_e32 v17, vcc, 0, v15, vcc
	global_load_dword v44, v[16:17], off
	v_add_co_u32_e32 v16, vcc, s0, v14
	s_mov_b32 s0, 0x20000
	s_nop 0
	v_addc_co_u32_e32 v17, vcc, 0, v15, vcc
	global_load_dword v45, v[16:17], off
	v_add_co_u32_e32 v16, vcc, s0, v14
	s_mov_b32 s0, 0x22000
	s_nop 0
	v_addc_co_u32_e32 v17, vcc, 0, v15, vcc
	global_load_dword v46, v[16:17], off
	v_add_co_u32_e32 v16, vcc, s0, v14
	s_mov_b32 s0, 0x24000
	s_nop 0
	v_addc_co_u32_e32 v17, vcc, 0, v15, vcc
	global_load_dword v47, v[16:17], off
	v_add_co_u32_e32 v16, vcc, s0, v14
	s_mov_b32 s0, 0x26000
	s_nop 0
	v_addc_co_u32_e32 v17, vcc, 0, v15, vcc
	global_load_dword v48, v[16:17], off
	v_add_co_u32_e32 v16, vcc, s0, v14
	s_mov_b32 s0, 0x28000
	s_nop 0
	v_addc_co_u32_e32 v17, vcc, 0, v15, vcc
	global_load_dword v49, v[16:17], off
	v_add_co_u32_e32 v16, vcc, s0, v14
	s_mov_b32 s0, 0x2a000
	s_nop 0
	v_addc_co_u32_e32 v17, vcc, 0, v15, vcc
	global_load_dword v50, v[16:17], off
	v_add_co_u32_e32 v16, vcc, s0, v14
	s_mov_b32 s0, 0x2c000
	s_nop 0
	v_addc_co_u32_e32 v17, vcc, 0, v15, vcc
	global_load_dword v51, v[16:17], off
	v_add_co_u32_e32 v16, vcc, s0, v14
	s_mov_b32 s0, 0x2e000
	s_nop 0
	v_addc_co_u32_e32 v17, vcc, 0, v15, vcc
	global_load_dword v52, v[16:17], off
	v_add_co_u32_e32 v16, vcc, s0, v14
	s_mov_b32 s0, 0x30000
	s_nop 0
	v_addc_co_u32_e32 v17, vcc, 0, v15, vcc
	global_load_dword v53, v[16:17], off
	v_add_co_u32_e32 v16, vcc, s0, v14
	s_mov_b32 s0, 0x32000
	s_nop 0
	v_addc_co_u32_e32 v17, vcc, 0, v15, vcc
	global_load_dword v54, v[16:17], off
	v_add_co_u32_e32 v16, vcc, s0, v14
	s_mov_b32 s0, 0x34000
	s_nop 0
	v_addc_co_u32_e32 v17, vcc, 0, v15, vcc
	global_load_dword v55, v[16:17], off
	v_add_co_u32_e32 v16, vcc, s0, v14
	s_mov_b32 s0, 0x36000
	s_nop 0
	v_addc_co_u32_e32 v17, vcc, 0, v15, vcc
	global_load_dword v56, v[16:17], off
	v_add_co_u32_e32 v16, vcc, s0, v14
	s_mov_b32 s0, 0x38000
	s_nop 0
	v_addc_co_u32_e32 v17, vcc, 0, v15, vcc
	global_load_dword v57, v[16:17], off
	v_add_co_u32_e32 v16, vcc, s0, v14
	s_mov_b32 s0, 0x3a000
	s_nop 0
	v_addc_co_u32_e32 v17, vcc, 0, v15, vcc
	global_load_dword v58, v[16:17], off
	v_add_co_u32_e32 v16, vcc, s0, v14
	s_mov_b32 s0, 0x3c000
	s_nop 0
	v_addc_co_u32_e32 v17, vcc, 0, v15, vcc
	global_load_dword v59, v[16:17], off
	v_add_co_u32_e32 v16, vcc, s0, v14
	s_mov_b32 s0, 0x3e000
	s_nop 0
	v_addc_co_u32_e32 v17, vcc, 0, v15, vcc
	v_add_co_u32_e32 v14, vcc, s0, v14
	global_load_dword v16, v[16:17], off
	s_nop 0
	v_addc_co_u32_e32 v15, vcc, 0, v15, vcc
	global_load_dword v14, v[14:15], off
	v_add_u32_e32 v15, 0x400, v23
	s_waitcnt vmcnt(30)
; #define LAS __attribute__((address_space(3)))
; #define GAS __attribute__((address_space(1)))
; __device__ __forceinline__ unsigned cvt_pk_bf16(float lo, float hi) { unsigned r; asm volatile("v_cvt_pk_bf16_f32 %0, %1, %2" : "=v"(r) : "v"(lo), "v"(hi)); return r; }
; __device__ __forceinline__ void transpose_item(const float* W, int ldw, int k0, int n0, bf16_t* WT, int ldt, int drow0, int dk0, LAS float* scr, int lane) {
;     ...
;     for (int i = 0; i < 32; ++i) { const int kk = 2 * i + (lane >> 5); scr[kk * 33 + (lane & 31)] = tv[i]; }
;     asm volatile("s_waitcnt lgkmcnt(0)" ::: "memory");
;     const int c = lane & 7;
; #pragma unroll
;     for (int j = 0; j < 4; ++j) { const int n = (lane >> 3) + 8 * j; const LAS float* s = scr + (8 * c) * 33 + n;
;         u32x4 o; o.x = cvt_pk_bf16(s[0 * 33], s[1 * 33]); o.y = cvt_pk_bf16(s[2 * 33], s[3 * 33]); o.z = cvt_pk_bf16(s[4 * 33], s[5 * 33]); o.w = cvt_pk_bf16(s[6 * 33], s[7 * 33]);
;         *(GAS u32x4*)((GAS bf16_t*)WT + (size_t)(drow0 + n) * ldt + dk0 + 8 * c) = o; }
; __device__ __forceinline__ void prep_weights(const Params& P, LAS unsigned char* lds, int lay, int bid, int G, int sel) {
;     ...
;               transpose_item(P.w_down + (size_t)mat * DFF * 1024, 1024, kb * 64, nb * 32, (bf16_t*)(ws + OFF_WDN + mat * SZ_WDN1), DFF, nb * 32, kb * 64, scr, lane); continue; }
	ds_write2_b32 v23, v19, v31 offset1:66
	s_waitcnt vmcnt(28)
	ds_write2_b32 v23, v32, v33 offset0:132 offset1:198
	s_waitcnt vmcnt(26)
	ds_write2_b32 v15, v34, v35 offset0:8 offset1:74
	s_waitcnt vmcnt(24)
	ds_write2_b32 v15, v36, v37 offset0:140 offset1:206
	v_add_u32_e32 v15, 0x800, v23
	s_waitcnt vmcnt(22)
	ds_write2_b32 v15, v38, v39 offset0:16 offset1:82
	s_waitcnt vmcnt(20)
	ds_write2_b32 v15, v40, v41 offset0:148 offset1:214
	v_add_u32_e32 v15, 0xc00, v23
	s_waitcnt vmcnt(18)
	ds_write2_b32 v15, v42, v43 offset0:24 offset1:90
	s_waitcnt vmcnt(16)
	ds_write2_b32 v15, v44, v45 offset0:156 offset1:222
	v_add_u32_e32 v15, 0x1000, v23
	s_waitcnt vmcnt(14)
	ds_write2_b32 v15, v46, v47 offset0:32 offset1:98
	s_waitcnt vmcnt(12)
	ds_write2_b32 v15, v48, v49 offset0:164 offset1:230
	v_add_u32_e32 v15, 0x1400, v23
	s_waitcnt vmcnt(10)
	ds_write2_b32 v15, v50, v51 offset0:40 offset1:106
	s_waitcnt vmcnt(8)
	ds_write2_b32 v15, v52, v53 offset0:172 offset1:238
	v_add_u32_e32 v15, 0x1800, v23
	s_waitcnt vmcnt(6)
	ds_write2_b32 v15, v54, v55 offset0:48 offset1:114
	s_waitcnt vmcnt(4)
	ds_write2_b32 v15, v56, v57 offset0:180 offset1:246
	v_add_u32_e32 v15, 0x1c00, v23
	s_waitcnt vmcnt(2)
	ds_write2_b32 v15, v58, v59 offset0:56 offset1:122
	s_waitcnt vmcnt(0)
	ds_write2_b32 v15, v16, v14 offset0:188 offset1:254
	s_waitcnt lgkmcnt(0)
	v_lshlrev_b32_e32 v14, 1, v18
	v_mov_b32_e32 v15, v129
	v_lshl_add_u64 v[18:19], v[10:11], 0, v[14:15]
	ds_read2_b32 v[14:15], v25 offset1:33
	s_waitcnt lgkmcnt(0)
	v_cvt_pk_bf16_f32 v14, v14, v15
	ds_read2_b32 v[16:17], v25 offset0:66 offset1:99
	s_waitcnt lgkmcnt(0)
	v_cvt_pk_bf16_f32 v15, v16, v17
	ds_read2_b32 v[16:17], v25 offset0:132 offset1:165
	v_or_b32_e32 v31, v13, v24
	s_waitcnt lgkmcnt(0)
	v_cvt_pk_bf16_f32 v16, v16, v17
	ds_read2_b32 v[32:33], v25 offset0:198 offset1:231
	v_mul_u32_u24_e32 v31, 0xb00, v31
	s_waitcnt lgkmcnt(0)
	v_cvt_pk_bf16_f32 v17, v32, v33
	v_lshlrev_b32_e32 v32, 1, v31
	v_mov_b32_e32 v33, v129
	v_lshl_add_u64 v[32:33], v[18:19], 0, v[32:33]
	global_store_dwordx4 v[32:33], v[14:17], off sc1
	ds_read2_b32 v[14:15], v25 offset0:8 offset1:41
	v_or_b32_e32 v31, v13, v26
	s_waitcnt lgkmcnt(0)
	v_cvt_pk_bf16_f32 v14, v14, v15
	ds_read2_b32 v[16:17], v25 offset0:74 offset1:107
	s_waitcnt lgkmcnt(0)
	v_cvt_pk_bf16_f32 v15, v16, v17
	ds_read2_b32 v[16:17], v25 offset0:140 offset1:173
	s_waitcnt lgkmcnt(0)
	v_cvt_pk_bf16_f32 v16, v16, v17
	ds_read2_b32 v[32:33], v25 offset0:206 offset1:239
	v_mul_u32_u24_e32 v31, 0xb00, v31
	s_waitcnt lgkmcnt(0)
	v_cvt_pk_bf16_f32 v17, v32, v33
	v_lshlrev_b32_e32 v32, 1, v31
	v_mov_b32_e32 v33, v129
	v_lshl_add_u64 v[32:33], v[18:19], 0, v[32:33]
	global_store_dwordx4 v[32:33], v[14:17], off sc1
	ds_read2_b32 v[14:15], v25 offset0:16 offset1:49
	v_or_b32_e32 v31, v13, v27
	s_waitcnt lgkmcnt(0)
	v_cvt_pk_bf16_f32 v14, v14, v15
	ds_read2_b32 v[16:17], v25 offset0:82 offset1:115
	s_waitcnt lgkmcnt(0)
	v_cvt_pk_bf16_f32 v15, v16, v17
	ds_read2_b32 v[16:17], v25 offset0:148 offset1:181
	s_waitcnt lgkmcnt(0)
	v_cvt_pk_bf16_f32 v16, v16, v17
	ds_read2_b32 v[32:33], v25 offset0:214 offset1:247
	v_mul_u32_u24_e32 v31, 0xb00, v31
	s_waitcnt lgkmcnt(0)
	v_cvt_pk_bf16_f32 v17, v32, v33
	v_lshlrev_b32_e32 v32, 1, v31
	v_mov_b32_e32 v33, v129
	v_lshl_add_u64 v[32:33], v[18:19], 0, v[32:33]
	global_store_dwordx4 v[32:33], v[14:17], off sc1
	ds_read2_b32 v[14:15], v25 offset0:24 offset1:57
	v_or_b32_e32 v13, v13, v28
	s_waitcnt lgkmcnt(0)
	v_cvt_pk_bf16_f32 v14, v14, v15
	ds_read2_b32 v[16:17], v25 offset0:90 offset1:123
	s_waitcnt lgkmcnt(0)
	v_cvt_pk_bf16_f32 v15, v16, v17
	ds_read2_b32 v[16:17], v25 offset0:156 offset1:189
	s_waitcnt lgkmcnt(0)
	v_cvt_pk_bf16_f32 v16, v16, v17
	ds_read2_b32 v[32:33], v25 offset0:222 offset1:255
	v_mul_u32_u24_e32 v13, 0xb00, v13
	s_waitcnt lgkmcnt(0)
	v_cvt_pk_bf16_f32 v17, v32, v33
	v_lshlrev_b32_e32 v32, 1, v13
	v_mov_b32_e32 v33, v129
	v_lshl_add_u64 v[18:19], v[18:19], 0, v[32:33]
	global_store_dwordx4 v[18:19], v[14:17], off sc1
	s_waitcnt lgkmcnt(0)

; __device__ __forceinline__ void prep_weights(const Params& P, LAS unsigned char* lds, int lay, int bid, int G, int sel) {
;     ...
;           for (int m0 = 0; m0 < 64; m0 += 32) { float wv[32];
; #pragma unroll
;               for (int m = 0; m < 32; ++m) wv[m] = wp[(size_t)(m0 + m) * 1024];
; #pragma unroll
;               for (int m = 0; m < 32; ++m) { const int t = ((m0 + m) * j) & 63; cs += tab64[t] * wv[m]; sn += tab64[(t + 48) & 63] * wv[m]; } }
.LBB0_1178:
	s_lshl_b32 s74, s3, 10
	v_lshl_add_u64 v[24:25], s[74:75], 2, v[2:3]
	v_add_co_u32_e32 v10, vcc, 0x1000, v24
	global_load_dword v50, v[24:25], off
	s_nop 0
	v_addc_co_u32_e32 v11, vcc, 0, v25, vcc
	global_load_dword v52, v[10:11], off
	v_add_co_u32_e32 v10, vcc, 0x2000, v24
	s_add_i32 s0, 0, 0x24000
	s_nop 0
	v_addc_co_u32_e32 v11, vcc, 0, v25, vcc
	global_load_dword v54, v[10:11], off
	v_add_co_u32_e32 v10, vcc, 0x3000, v24
	s_nop 1
	v_addc_co_u32_e32 v11, vcc, 0, v25, vcc
	global_load_dword v56, v[10:11], off
	v_add_co_u32_e32 v10, vcc, 0x4000, v24
	s_nop 1
	v_addc_co_u32_e32 v11, vcc, 0, v25, vcc
	global_load_dword v58, v[10:11], off
	v_add_co_u32_e32 v10, vcc, 0x5000, v24
	s_nop 1
	v_addc_co_u32_e32 v11, vcc, 0, v25, vcc
	global_load_dword v60, v[10:11], off
	v_add_co_u32_e32 v10, vcc, 0x6000, v24
	s_nop 1
	v_addc_co_u32_e32 v11, vcc, 0, v25, vcc
	global_load_dword v62, v[10:11], off
	v_add_co_u32_e32 v10, vcc, 0x7000, v24
	s_nop 1
	v_addc_co_u32_e32 v11, vcc, 0, v25, vcc
	global_load_dword v64, v[10:11], off
	v_add_co_u32_e32 v10, vcc, s21, v24
	s_nop 1
	v_addc_co_u32_e32 v11, vcc, 0, v25, vcc
	global_load_dword v66, v[10:11], off offset:-4096
	global_load_dword v68, v[10:11], off
	v_add_co_u32_e32 v10, vcc, s14, v24
	s_nop 1
	v_addc_co_u32_e32 v11, vcc, 0, v25, vcc
	global_load_dword v28, v[10:11], off offset:-4096
	global_load_dword v30, v[10:11], off
	v_add_co_u32_e32 v10, vcc, s15, v24
	s_nop 1
	v_addc_co_u32_e32 v11, vcc, 0, v25, vcc
	global_load_dword v32, v[10:11], off offset:-4096
	global_load_dword v34, v[10:11], off
	v_add_co_u32_e32 v10, vcc, s26, v24
	s_nop 1
	v_addc_co_u32_e32 v11, vcc, 0, v25, vcc
	global_load_dword v36, v[10:11], off offset:-4096
	global_load_dword v38, v[10:11], off
	v_add_co_u32_e32 v10, vcc, s27, v24
	s_nop 1
	v_addc_co_u32_e32 v11, vcc, 0, v25, vcc
	global_load_dword v40, v[10:11], off offset:-4096
	global_load_dword v42, v[10:11], off
	v_add_co_u32_e32 v10, vcc, s63, v24
	s_nop 1
	v_addc_co_u32_e32 v11, vcc, 0, v25, vcc
	global_load_dword v44, v[10:11], off offset:-4096
	global_load_dword v46, v[10:11], off
	v_add_co_u32_e32 v10, vcc, s64, v24
	s_nop 1
	v_addc_co_u32_e32 v11, vcc, 0, v25, vcc
	global_load_dword v48, v[10:11], off offset:-4096
	global_load_dword v6, v[10:11], off
	v_add_co_u32_e32 v10, vcc, s65, v24
	s_nop 1
	v_addc_co_u32_e32 v11, vcc, 0, v25, vcc
	v_add_co_u32_e32 v14, vcc, s66, v24
	global_load_dword v8, v[10:11], off offset:-4096
	s_nop 0
	global_load_dword v10, v[10:11], off
	v_addc_co_u32_e32 v15, vcc, 0, v25, vcc
	v_add_co_u32_e32 v18, vcc, s67, v24
	v_mul_u32_u24_e32 v11, s3, v9
	s_nop 0
	v_addc_co_u32_e32 v19, vcc, 0, v25, vcc
	v_add_co_u32_e32 v22, vcc, s68, v24
	v_and_b32_e32 v11, 32, v11
	s_nop 0
	v_addc_co_u32_e32 v23, vcc, 0, v25, vcc
	v_add_co_u32_e32 v26, vcc, s69, v24
	v_lshl_add_u32 v11, v11, 2, s0
	s_nop 0
	v_addc_co_u32_e32 v27, vcc, 0, v25, vcc
	global_load_dword v12, v[14:15], off offset:-4096
	s_nop 0
	global_load_dword v14, v[14:15], off
	s_nop 0
	global_load_dword v16, v[18:19], off offset:-4096
	s_nop 0
	global_load_dword v18, v[18:19], off
	s_nop 0
	global_load_dword v20, v[22:23], off offset:-4096
	s_nop 0
	global_load_dword v22, v[22:23], off
	s_nop 0
	global_load_dword v24, v[26:27], off offset:-4096
	s_nop 0
	global_load_dword v26, v[26:27], off
	ds_read_b32 v70, v11
	v_mad_u32_u24 v11, s3, v9, 48
	v_and_b32_e32 v11, 48, v11
	v_lshl_add_u32 v11, v11, 2, s0
	ds_read_b32 v71, v11
	v_mad_u32_u24 v11, s3, v9, v9
	v_and_b32_e32 v13, 63, v11
	v_lshl_add_u32 v13, v13, 2, s0
	ds_read_b32 v72, v13
	v_add_u32_e32 v13, 48, v11
	v_and_b32_e32 v13, 63, v13
	v_lshl_add_u32 v13, v13, 2, s0
	v_add_u32_e32 v11, v11, v9
	ds_read_b32 v73, v13
	v_and_b32_e32 v13, 62, v11
	v_lshl_add_u32 v13, v13, 2, s0
	ds_read_b32 v74, v13
	v_add_u32_e32 v13, 48, v11
	v_and_b32_e32 v13, 62, v13
	v_lshl_add_u32 v13, v13, 2, s0
	v_add_u32_e32 v11, v11, v9
	ds_read_b32 v75, v13
	v_and_b32_e32 v13, 63, v11
	v_lshl_add_u32 v13, v13, 2, s0
	ds_read_b32 v76, v13
	v_add_u32_e32 v13, 48, v11
	v_and_b32_e32 v13, 63, v13
	v_lshl_add_u32 v13, v13, 2, s0
	v_add_u32_e32 v11, v11, v9
	ds_read_b32 v77, v13
	v_and_b32_e32 v13, 60, v11
	v_lshl_add_u32 v13, v13, 2, s0
	ds_read_b32 v78, v13
	v_add_u32_e32 v13, 48, v11
	v_and_b32_e32 v13, 60, v13
	v_lshl_add_u32 v13, v13, 2, s0
	v_add_u32_e32 v11, v11, v9
	ds_read_b32 v79, v13
	v_and_b32_e32 v13, 63, v11
	v_lshl_add_u32 v13, v13, 2, s0
	ds_read_b32 v80, v13
	v_add_u32_e32 v13, 48, v11
	v_and_b32_e32 v13, 63, v13
	v_lshl_add_u32 v13, v13, 2, s0
	v_add_u32_e32 v11, v11, v9
	ds_read_b32 v81, v13
	v_and_b32_e32 v13, 62, v11
	v_lshl_add_u32 v13, v13, 2, s0
	ds_read_b32 v82, v13
	v_add_u32_e32 v13, 48, v11
	v_and_b32_e32 v13, 62, v13
	v_lshl_add_u32 v13, v13, 2, s0
	v_add_u32_e32 v11, v11, v9
	ds_read_b32 v83, v13
	v_and_b32_e32 v13, 63, v11
	v_lshl_add_u32 v13, v13, 2, s0
	ds_read_b32 v84, v13
	v_add_u32_e32 v13, 48, v11
	v_and_b32_e32 v13, 63, v13
	v_lshl_add_u32 v13, v13, 2, s0
	v_add_u32_e32 v11, v11, v9
	ds_read_b32 v85, v13
	v_and_b32_e32 v13, 56, v11
	v_lshl_add_u32 v13, v13, 2, s0
	ds_read_b32 v86, v13
	v_add_u32_e32 v13, 48, v11
	v_and_b32_e32 v13, 56, v13
	v_lshl_add_u32 v13, v13, 2, s0
	v_add_u32_e32 v11, v11, v9
	ds_read_b32 v87, v13
	v_and_b32_e32 v13, 63, v11
	v_lshl_add_u32 v13, v13, 2, s0
	ds_read_b32 v88, v13
	v_add_u32_e32 v13, 48, v11
	v_and_b32_e32 v13, 63, v13
	v_lshl_add_u32 v13, v13, 2, s0
	v_add_u32_e32 v11, v11, v9
	ds_read_b32 v89, v13
	v_and_b32_e32 v13, 62, v11
	v_lshl_add_u32 v13, v13, 2, s0
	s_waitcnt vmcnt(31) lgkmcnt(14)
; __device__ __forceinline__ void prep_weights(const Params& P, LAS unsigned char* lds, int lay, int bid, int G, int sel) {
;     ...
;               for (int m = 0; m < 32; ++m) wv[m] = wp[(size_t)(m0 + m) * 1024];
; #pragma unroll
;               for (int m = 0; m < 32; ++m) { const int t = ((m0 + m) * j) & 63; cs += tab64[t] * wv[m]; sn += tab64[(t + 48) & 63] * wv[m]; } }
	v_pk_fma_f32 v[4:5], v[50:51], v[70:71], v[4:5] op_sel_hi:[0,1,1]
	ds_read_b32 v50, v13
	v_add_u32_e32 v13, 48, v11
	v_and_b32_e32 v13, 62, v13
	v_lshl_add_u32 v13, v13, 2, s0
	v_add_u32_e32 v11, v11, v9
	ds_read_b32 v51, v13
	v_and_b32_e32 v13, 63, v11
	v_lshl_add_u32 v13, v13, 2, s0
	s_waitcnt vmcnt(30)
	v_pk_fma_f32 v[4:5], v[52:53], v[72:73], v[4:5] op_sel_hi:[0,1,1]
	ds_read_b32 v52, v13
	v_add_u32_e32 v13, 48, v11
	v_and_b32_e32 v13, 63, v13
	v_lshl_add_u32 v13, v13, 2, s0
	v_add_u32_e32 v11, v11, v9
	ds_read_b32 v53, v13
	v_and_b32_e32 v13, 60, v11
	v_lshl_add_u32 v13, v13, 2, s0
	s_waitcnt vmcnt(29)
	v_pk_fma_f32 v[4:5], v[54:55], v[74:75], v[4:5] op_sel_hi:[0,1,1]
	ds_read_b32 v54, v13
	v_add_u32_e32 v13, 48, v11
	v_and_b32_e32 v13, 60, v13
	v_lshl_add_u32 v13, v13, 2, s0
	v_add_u32_e32 v11, v11, v9
	ds_read_b32 v55, v13
	v_and_b32_e32 v13, 63, v11
	v_lshl_add_u32 v13, v13, 2, s0
	s_waitcnt vmcnt(28) lgkmcnt(14)
	v_pk_fma_f32 v[4:5], v[56:57], v[76:77], v[4:5] op_sel_hi:[0,1,1]
	ds_read_b32 v56, v13
	v_add_u32_e32 v13, 48, v11
	v_and_b32_e32 v13, 63, v13
	v_lshl_add_u32 v13, v13, 2, s0
	v_add_u32_e32 v11, v11, v9
	ds_read_b32 v57, v13
	v_and_b32_e32 v13, 62, v11
	v_lshl_add_u32 v13, v13, 2, s0
	s_waitcnt vmcnt(27)
	v_pk_fma_f32 v[4:5], v[58:59], v[78:79], v[4:5] op_sel_hi:[0,1,1]
	ds_read_b32 v58, v13
	v_add_u32_e32 v13, 48, v11
	v_and_b32_e32 v13, 62, v13
	v_lshl_add_u32 v13, v13, 2, s0
	v_add_u32_e32 v11, v11, v9
	ds_read_b32 v59, v13
	v_and_b32_e32 v13, 63, v11
	v_lshl_add_u32 v13, v13, 2, s0
	s_waitcnt vmcnt(26)
	v_pk_fma_f32 v[4:5], v[60:61], v[80:81], v[4:5] op_sel_hi:[0,1,1]
	ds_read_b32 v60, v13
	v_add_u32_e32 v13, 48, v11
	v_and_b32_e32 v13, 63, v13
	v_lshl_add_u32 v13, v13, 2, s0
	v_add_u32_e32 v11, v11, v9
	ds_read_b32 v61, v13
	v_and_b32_e32 v13, 48, v11
	v_lshl_add_u32 v13, v13, 2, s0
	s_waitcnt vmcnt(25) lgkmcnt(14)
	v_pk_fma_f32 v[4:5], v[62:63], v[82:83], v[4:5] op_sel_hi:[0,1,1]
	ds_read_b32 v62, v13
	v_add_u32_e32 v13, 48, v11
	v_and_b32_e32 v13, 48, v13
	v_lshl_add_u32 v13, v13, 2, s0
	v_add_u32_e32 v11, v11, v9
	ds_read_b32 v63, v13
	v_and_b32_e32 v13, 63, v11
	v_lshl_add_u32 v13, v13, 2, s0
	s_waitcnt vmcnt(24)
	v_pk_fma_f32 v[4:5], v[64:65], v[84:85], v[4:5] op_sel_hi:[0,1,1]
	ds_read_b32 v64, v13
	v_add_u32_e32 v13, 48, v11
	v_and_b32_e32 v13, 63, v13
	v_lshl_add_u32 v13, v13, 2, s0
	v_add_u32_e32 v11, v11, v9
	ds_read_b32 v65, v13
	v_and_b32_e32 v13, 62, v11
	v_lshl_add_u32 v13, v13, 2, s0
	s_waitcnt vmcnt(23)
	v_pk_fma_f32 v[4:5], v[66:67], v[86:87], v[4:5] op_sel_hi:[0,1,1]
	ds_read_b32 v66, v13
	v_add_u32_e32 v13, 48, v11
	v_and_b32_e32 v13, 62, v13
	v_lshl_add_u32 v13, v13, 2, s0
	v_add_u32_e32 v11, v11, v9
	ds_read_b32 v67, v13
	v_and_b32_e32 v13, 63, v11
	v_lshl_add_u32 v13, v13, 2, s0
	s_waitcnt vmcnt(22) lgkmcnt(14)
	v_pk_fma_f32 v[4:5], v[68:69], v[88:89], v[4:5] op_sel_hi:[0,1,1]
	ds_read_b32 v68, v13
	v_add_u32_e32 v13, 48, v11
	v_and_b32_e32 v13, 63, v13
	v_lshl_add_u32 v13, v13, 2, s0
	v_add_u32_e32 v11, v11, v9
	ds_read_b32 v69, v13
	v_and_b32_e32 v13, 60, v11
	v_lshl_add_u32 v13, v13, 2, s0
	ds_read_b32 v70, v13
	v_add_u32_e32 v13, 48, v11
	v_and_b32_e32 v13, 60, v13
	v_lshl_add_u32 v13, v13, 2, s0
	v_add_u32_e32 v11, v11, v9
	ds_read_b32 v71, v13
	v_and_b32_e32 v13, 63, v11
	v_lshl_add_u32 v13, v13, 2, s0
	s_waitcnt vmcnt(21)
	v_pk_fma_f32 v[4:5], v[28:29], v[50:51], v[4:5] op_sel_hi:[0,1,1]
	ds_read_b32 v28, v13
	v_add_u32_e32 v13, 48, v11
	v_and_b32_e32 v13, 63, v13
	v_lshl_add_u32 v13, v13, 2, s0
	v_add_u32_e32 v11, v11, v9
	ds_read_b32 v29, v13
	v_and_b32_e32 v13, 62, v11
	v_lshl_add_u32 v13, v13, 2, s0
	s_waitcnt vmcnt(20)
	v_pk_fma_f32 v[4:5], v[30:31], v[52:53], v[4:5] op_sel_hi:[0,1,1]
	ds_read_b32 v30, v13
	v_add_u32_e32 v13, 48, v11
	v_and_b32_e32 v13, 62, v13
	v_lshl_add_u32 v13, v13, 2, s0
	v_add_u32_e32 v11, v11, v9
	ds_read_b32 v31, v13
	v_and_b32_e32 v13, 63, v11
	v_lshl_add_u32 v13, v13, 2, s0
	s_waitcnt vmcnt(19) lgkmcnt(14)
	v_pk_fma_f32 v[4:5], v[32:33], v[54:55], v[4:5] op_sel_hi:[0,1,1]
	ds_read_b32 v32, v13
	v_add_u32_e32 v13, 48, v11
	v_and_b32_e32 v13, 63, v13
	v_lshl_add_u32 v13, v13, 2, s0
	v_add_u32_e32 v11, v11, v9
	ds_read_b32 v33, v13
	v_and_b32_e32 v13, 56, v11
	v_lshl_add_u32 v13, v13, 2, s0
	s_waitcnt vmcnt(18)
; __device__ __forceinline__ unsigned f2bf(float f) { unsigned u = __float_as_uint(f); return (u + 0x7fffu + ((u >> 16) & 1u)) >> 16; }
; __device__ __forceinline__ void prep_weights(const Params& P, LAS unsigned char* lds, int lay, int bid, int G, int sel) {
;     ...
;               for (int m = 0; m < 32; ++m) { const int t = ((m0 + m) * j) & 63; cs += tab64[t] * wv[m]; sn += tab64[(t + 48) & 63] * wv[m]; } }
;           bf16_t* o = (bf16_t*)(ws + OFF_WOUT + l * SZ_WOUT1) + (size_t)n * 1280; o[768 + gj] = (bf16_t)f2bf(cs); o[1024 + gj] = (bf16_t)f2bf(-sn); }
	v_pk_fma_f32 v[4:5], v[34:35], v[56:57], v[4:5] op_sel_hi:[0,1,1]
	ds_read_b32 v34, v13
	v_add_u32_e32 v13, 48, v11
	v_and_b32_e32 v13, 56, v13
	v_lshl_add_u32 v13, v13, 2, s0
	v_add_u32_e32 v11, v11, v9
	ds_read_b32 v35, v13
	v_and_b32_e32 v13, 63, v11
	v_lshl_add_u32 v13, v13, 2, s0
	s_waitcnt vmcnt(17)
	v_pk_fma_f32 v[4:5], v[36:37], v[58:59], v[4:5] op_sel_hi:[0,1,1]
	ds_read_b32 v36, v13
	v_add_u32_e32 v13, 48, v11
	v_and_b32_e32 v13, 63, v13
	v_lshl_add_u32 v13, v13, 2, s0
	v_add_u32_e32 v11, v11, v9
	ds_read_b32 v37, v13
	v_and_b32_e32 v13, 62, v11
	v_lshl_add_u32 v13, v13, 2, s0
	s_waitcnt vmcnt(16)
	v_pk_fma_f32 v[4:5], v[38:39], v[60:61], v[4:5] op_sel_hi:[0,1,1]
	ds_read_b32 v38, v13
	v_add_u32_e32 v13, 48, v11
	v_and_b32_e32 v13, 62, v13
	v_lshl_add_u32 v13, v13, 2, s0
	v_add_u32_e32 v11, v11, v9
	ds_read_b32 v39, v13
	v_and_b32_e32 v13, 63, v11
	v_lshl_add_u32 v13, v13, 2, s0
	s_waitcnt vmcnt(15) lgkmcnt(14)
	v_pk_fma_f32 v[4:5], v[40:41], v[62:63], v[4:5] op_sel_hi:[0,1,1]
	ds_read_b32 v40, v13
	v_add_u32_e32 v13, 48, v11
	v_and_b32_e32 v13, 63, v13
	v_lshl_add_u32 v13, v13, 2, s0
	v_add_u32_e32 v11, v11, v9
	ds_read_b32 v41, v13
	v_and_b32_e32 v13, 60, v11
	v_lshl_add_u32 v13, v13, 2, s0
	s_waitcnt vmcnt(14)
	v_pk_fma_f32 v[4:5], v[42:43], v[64:65], v[4:5] op_sel_hi:[0,1,1]
	ds_read_b32 v42, v13
	v_add_u32_e32 v13, 48, v11
	v_and_b32_e32 v13, 60, v13
	v_lshl_add_u32 v13, v13, 2, s0
	v_add_u32_e32 v11, v11, v9
	ds_read_b32 v43, v13
	v_and_b32_e32 v13, 63, v11
	v_lshl_add_u32 v13, v13, 2, s0
	s_waitcnt vmcnt(13)
	v_pk_fma_f32 v[4:5], v[44:45], v[66:67], v[4:5] op_sel_hi:[0,1,1]
	ds_read_b32 v44, v13
	v_add_u32_e32 v13, 48, v11
	v_and_b32_e32 v13, 63, v13
	v_lshl_add_u32 v13, v13, 2, s0
	v_add_u32_e32 v11, v11, v9
	ds_read_b32 v45, v13
	v_and_b32_e32 v13, 62, v11
	v_lshl_add_u32 v13, v13, 2, s0
	s_waitcnt vmcnt(12)
	v_pk_fma_f32 v[4:5], v[46:47], v[68:69], v[4:5] op_sel_hi:[0,1,1]
	ds_read_b32 v46, v13
	v_add_u32_e32 v13, 48, v11
	v_and_b32_e32 v13, 62, v13
	v_lshl_add_u32 v13, v13, 2, s0
	v_add_u32_e32 v11, v11, v9
	s_waitcnt vmcnt(11) lgkmcnt(14)
	v_pk_fma_f32 v[4:5], v[48:49], v[70:71], v[4:5] op_sel_hi:[0,1,1]
	ds_read_b32 v47, v13
	v_and_b32_e32 v13, 63, v11
	v_add_u32_e32 v11, 48, v11
	v_and_b32_e32 v11, 63, v11
	s_waitcnt vmcnt(10)
	v_pk_fma_f32 v[4:5], v[6:7], v[28:29], v[4:5] op_sel_hi:[0,1,1]
	v_lshl_add_u32 v11, v11, 2, s0
	s_waitcnt vmcnt(9)
	v_pk_fma_f32 v[4:5], v[8:9], v[30:31], v[4:5] op_sel_hi:[0,1,1]
	v_lshl_add_u32 v13, v13, 2, s0
	s_waitcnt vmcnt(8) lgkmcnt(14)
	v_pk_fma_f32 v[4:5], v[10:11], v[32:33], v[4:5] op_sel_hi:[0,1,1]
	s_waitcnt vmcnt(7) lgkmcnt(12)
	v_pk_fma_f32 v[4:5], v[12:13], v[34:35], v[4:5] op_sel_hi:[0,1,1]
	s_waitcnt vmcnt(6) lgkmcnt(10)
	v_pk_fma_f32 v[4:5], v[14:15], v[36:37], v[4:5] op_sel_hi:[0,1,1]
	ds_read_b32 v48, v13
	ds_read_b32 v49, v11
	s_waitcnt vmcnt(5) lgkmcnt(10)
	v_pk_fma_f32 v[4:5], v[16:17], v[38:39], v[4:5] op_sel_hi:[0,1,1]
	s_waitcnt vmcnt(4) lgkmcnt(8)
	v_pk_fma_f32 v[4:5], v[18:19], v[40:41], v[4:5] op_sel_hi:[0,1,1]
	s_waitcnt vmcnt(3) lgkmcnt(6)
	v_pk_fma_f32 v[4:5], v[20:21], v[42:43], v[4:5] op_sel_hi:[0,1,1]
	s_waitcnt vmcnt(2) lgkmcnt(4)
	v_pk_fma_f32 v[4:5], v[22:23], v[44:45], v[4:5] op_sel_hi:[0,1,1]
	s_waitcnt vmcnt(1) lgkmcnt(2)
	v_pk_fma_f32 v[4:5], v[24:25], v[46:47], v[4:5] op_sel_hi:[0,1,1]
	s_waitcnt vmcnt(0) lgkmcnt(0)
	v_pk_fma_f32 v[4:5], v[26:27], v[48:49], v[4:5] op_sel_hi:[0,1,1]
	s_and_b64 vcc, exec, s[42:43]
	s_mov_b64 s[42:43], 0
	s_mov_b32 s3, 32
	s_cbranch_vccnz .LBB0_1178
	v_readlane_b32 s0, v252, 40
	v_readlane_b32 s1, v252, 41
	v_bfe_u32 v6, v4, 16, 1
	v_add3_u32 v4, v4, v6, s19
	v_mov_b64_e32 v[2:3], s[0:1]
	v_lshrrev_b32_e32 v6, 9, v1
	v_mad_u64_u32 v[2:3], s[0:1], v7, s23, v[2:3]
	v_and_b32_e32 v128, 0x1fe, v6
	v_lshl_add_u64 v[2:3], v[2:3], 0, v[128:129]
	global_store_short_d16_hi v[2:3], v4, off offset:1536 sc1
	v_xor_b32_e32 v4, 0x80000000, v5
	v_bfe_u32 v5, v4, 16, 1
	v_add3_u32 v4, v4, v5, s19
	s_mov_b32 s0, 0x27fff
	global_store_short_d16_hi v[2:3], v4, off offset:2048 sc1
	v_add_u32_e32 v2, 0x18000, v1
	v_cmp_lt_i32_e32 vcc, s0, v1
	s_or_b64 s[40:41], vcc, s[40:41]
	v_mov_b32_e32 v1, v2
	s_andn2_b64 exec, exec, s[40:41]
	s_cbranch_execnz .LBB0_1177

; __device__ __forceinline__ unsigned f2bf(float f) { unsigned u = __float_as_uint(f); return (u + 0x7fffu + ((u >> 16) & 1u)) >> 16; }
; __device__ __forceinline__ void prep_weights(const Params& P, LAS unsigned char* lds, int lay, int bid, int G, int sel) {
;     ...
;       for (int i0 = gt; i0 < ((sel & 64) ? 131072 : 0); i0 += NGT) { const int idx = l * 131072 + i0; const int i = idx & 63, j = (idx >> 6) & 63, hi = idx >> 12;
;           ((bf16_t*)(ws + OFF_WGT))[idx] = (bf16_t)f2bf(P.lru_wg[(size_t)hi * 4096 + i * 64 + j]); }
.LBB0_1183:
	v_ashrrev_i32_e32 v10, 12, v2
	v_lshrrev_b32_e32 v9, 6, v2
	v_ashrrev_i32_e32 v8, 12, v3
	v_lshlrev_b32_e32 v13, 6, v2
	v_ashrrev_i32_e32 v11, 31, v10
	v_lshlrev_b32_e32 v12, 6, v3
	v_and_b32_e32 v14, 63, v9
	v_ashrrev_i32_e32 v9, 31, v8
	v_and_b32_e32 v13, 0xfc0, v13
	v_lshlrev_b64 v[10:11], 14, v[10:11]
	v_and_b32_e32 v12, 0xfc0, v12
	v_lshlrev_b64 v[8:9], 14, v[8:9]
	v_lshlrev_b32_e32 v128, 2, v13
	v_lshl_add_u64 v[10:11], s[58:59], 0, v[10:11]
	v_lshrrev_b32_e32 v1, 6, v3
	v_lshl_add_u64 v[8:9], s[58:59], 0, v[8:9]
	v_lshl_add_u64 v[10:11], v[10:11], 0, v[128:129]
	v_lshlrev_b32_e32 v128, 2, v12
	v_and_b32_e32 v1, 63, v1
	v_lshl_add_u64 v[8:9], v[8:9], 0, v[128:129]
	v_lshlrev_b32_e32 v128, 2, v14
	v_lshl_add_u64 v[10:11], v[10:11], 0, v[128:129]
	v_lshlrev_b32_e32 v128, 2, v1
	v_lshl_add_u64 v[8:9], v[8:9], 0, v[128:129]
	global_load_dword v1, v[10:11], off
	global_load_dword v12, v[8:9], off
	v_add_u32_e32 v7, -2, v7
	v_ashrrev_i32_e32 v11, 31, v2
	v_mov_b32_e32 v10, v2
	v_cmp_eq_u32_e32 vcc, 0, v7
	v_ashrrev_i32_e32 v9, 31, v3
	v_mov_b32_e32 v8, v3
	v_add_u32_e32 v3, 0x30000, v3
	v_add_u32_e32 v2, 0x30000, v2
	v_lshl_add_u64 v[10:11], v[10:11], 1, s[12:13]
	s_or_b64 s[40:41], vcc, s[40:41]
	v_lshl_add_u64 v[8:9], v[8:9], 1, s[12:13]
	s_waitcnt vmcnt(1)
	v_and_b32_sdwa v13, v1, v170 dst_sel:DWORD dst_unused:UNUSED_PAD src0_sel:WORD_1 src1_sel:DWORD
	s_waitcnt vmcnt(0)
	v_and_b32_sdwa v14, v12, v170 dst_sel:DWORD dst_unused:UNUSED_PAD src0_sel:WORD_1 src1_sel:DWORD
	v_add3_u32 v1, v1, v13, s19
	v_add3_u32 v12, v12, v14, s19
	global_store_short_d16_hi v[10:11], v1, off sc1
	global_store_short_d16_hi v[8:9], v12, off sc1
	s_andn2_b64 exec, exec, s[40:41]
	s_cbranch_execnz .LBB0_1183
	s_or_b64 exec, exec, s[40:41]
	s_mov_b32 s0, 0x18000
	v_cmp_ne_u32_e32 vcc, v4, v5
	v_mad_u32_u24 v2, v5, s0, v0
	s_orn2_b64 s[40:41], vcc, exec

; __device__ __forceinline__ unsigned f2bf(float f) { unsigned u = __float_as_uint(f); return (u + 0x7fffu + ((u >> 16) & 1u)) >> 16; }
; __device__ __forceinline__ void prep_weights(const Params& P, LAS unsigned char* lds, int lay, int bid, int G, int sel) {
;     ...
;       for (int i0 = gt; i0 < ((sel & 64) ? 131072 : 0); i0 += NGT) { const int idx = l * 131072 + i0; const int i = idx & 63, j = (idx >> 6) & 63, hi = idx >> 12;
;           ((bf16_t*)(ws + OFF_WGT))[idx] = (bf16_t)f2bf(P.lru_wg[(size_t)hi * 4096 + i * 64 + j]); }
.LBB0_1187:
	v_ashrrev_i32_e32 v8, 12, v2
	v_ashrrev_i32_e32 v9, 31, v8
	v_and_b32_e32 v3, 0xfc0, v1
	v_lshlrev_b64 v[8:9], 14, v[8:9]
	v_lshl_add_u64 v[8:9], s[58:59], 0, v[8:9]
	v_lshlrev_b32_e32 v128, 2, v3
	v_lshrrev_b32_e32 v3, 4, v2
	v_lshl_add_u64 v[8:9], v[8:9], 0, v[128:129]
	v_and_b32_e32 v128, 0xfc, v3
	v_lshl_add_u64 v[8:9], v[8:9], 0, v[128:129]
	global_load_dword v3, v[8:9], off
	v_cmp_lt_i32_e32 vcc, s19, v2
	v_add_u32_e32 v1, 0x600000, v1
	s_or_b64 s[38:39], vcc, s[38:39]
	s_waitcnt vmcnt(0)
	v_bfe_u32 v7, v3, 16, 1
	v_add3_u32 v3, v3, v7, s19
	global_store_short_d16_hi v[4:5], v3, off sc1
	v_add_u32_e32 v3, 0x18000, v2
	v_lshl_add_u64 v[4:5], v[4:5], 0, s[4:5]
	v_mov_b32_e32 v2, v3
	s_andn2_b64 exec, exec, s[38:39]
	s_cbranch_execnz .LBB0_1187

; __device__ __forceinline__ unsigned f2bf(float f) { unsigned u = __float_as_uint(f); return (u + 0x7fffu + ((u >> 16) & 1u)) >> 16; }
; __device__ __forceinline__ void prep_weights(const Params& P, LAS unsigned char* lds, int lay, int bid, int G, int sel) {
;     ...
;       for (int i0 = gt; i0 < ((sel & 64) ? 65536 : 0); i0 += NGT) { const int idx = l * 65536 + i0; ((bf16_t*)(ws + OFF_GWS))[idx] = (bf16_t)f2bf(P.gmlp_ws[idx]); } }
.LBB0_1191:
	v_ashrrev_i32_e32 v9, 31, v3
	v_mov_b32_e32 v8, v3
	v_ashrrev_i32_e32 v11, 31, v2
	v_mov_b32_e32 v10, v2
	v_lshl_add_u64 v[14:15], v[8:9], 2, s[80:81]
	v_lshl_add_u64 v[12:13], v[10:11], 2, s[80:81]
	global_load_dword v1, v[14:15], off
	global_load_dword v7, v[12:13], off
	v_add_u32_e32 v6, -2, v6
	v_cmp_eq_u32_e32 vcc, 0, v6
	v_add_u32_e32 v3, 0x30000, v3
	v_add_u32_e32 v2, 0x30000, v2
	v_lshl_add_u64 v[10:11], v[10:11], 1, s[60:61]
	s_or_b64 s[40:41], vcc, s[40:41]
	v_lshl_add_u64 v[8:9], v[8:9], 1, s[60:61]
	s_waitcnt vmcnt(1)
	v_and_b32_sdwa v12, v1, v170 dst_sel:DWORD dst_unused:UNUSED_PAD src0_sel:WORD_1 src1_sel:DWORD
	s_waitcnt vmcnt(0)
	v_and_b32_sdwa v13, v7, v170 dst_sel:DWORD dst_unused:UNUSED_PAD src0_sel:WORD_1 src1_sel:DWORD
	v_add3_u32 v7, v7, v13, s19
	v_add3_u32 v1, v1, v12, s19
	global_store_short_d16_hi v[10:11], v7, off sc1
	global_store_short_d16_hi v[8:9], v1, off sc1
	s_andn2_b64 exec, exec, s[40:41]
	s_cbranch_execnz .LBB0_1191
	s_or_b64 exec, exec, s[40:41]
	s_mov_b32 s0, 0x18000
	v_cmp_ne_u32_e32 vcc, v4, v5
	v_mad_u32_u24 v0, v5, s0, v0
	s_orn2_b64 s[40:41], vcc, exec

; __device__ __forceinline__ unsigned f2bf(float f) { unsigned u = __float_as_uint(f); return (u + 0x7fffu + ((u >> 16) & 1u)) >> 16; }
; __device__ __forceinline__ void prep_weights(const Params& P, LAS unsigned char* lds, int lay, int bid, int G, int sel) {
;     ...
;       for (int i0 = gt; i0 < ((sel & 64) ? 65536 : 0); i0 += NGT) { const int idx = l * 65536 + i0; ((bf16_t*)(ws + OFF_GWS))[idx] = (bf16_t)f2bf(P.gmlp_ws[idx]); } }
.LBB0_1195:
	global_load_dword v5, v[2:3], off
	v_add_u32_e32 v4, 0x18000, v4
	v_cmp_lt_i32_e32 vcc, s71, v4
	v_lshl_add_u64 v[2:3], v[2:3], 0, s[10:11]
	s_or_b64 s[38:39], vcc, s[38:39]
	s_waitcnt vmcnt(0)
	v_bfe_u32 v6, v5, 16, 1
	v_add3_u32 v5, v5, v6, s19
	global_store_short_d16_hi v[0:1], v5, off sc1
	v_lshl_add_u64 v[0:1], v[0:1], 0, s[4:5]
	s_andn2_b64 exec, exec, s[38:39]
	s_cbranch_execnz .LBB0_1195

; __device__ __forceinline__ void phase_final(const Params& P) {
;     ...
;     for (int r = gw; r < TL; r += NGW) { float* hr = P.out + (size_t)r * 1024; const int rn = r + NGW; f32x4 vn[4];
;         if (rn < TL) {
; #pragma unroll
;             for (int j = 0; j < 4; ++j) vn[j] = *(const f32x4*)(P.out + (size_t)rn * 1024 + 4 * lane + 256 * j); }
;         __builtin_amdgcn_sched_barrier(0);
;         float ss = 0.f;
; #pragma unroll
;         for (int j = 0; j < 4; ++j) ss += (v[j].x * v[j].x + v[j].y * v[j].y) + (v[j].z * v[j].z + v[j].w * v[j].w);
;         const float rstd = 1.0f / sqrtf(wave_sum(ss) * (1.0f / 1024.0f) + 1e-6f);
; #pragma unroll
;         for (int j = 0; j < 4; ++j) *(f32x4*)(hr + 4 * lane + 256 * j) = v[j] * rstd * gg[j];
;         if (rn < TL) {
; #pragma unroll
;             for (int j = 0; j < 4; ++j) v[j] = vn[j]; } }
.LBB0_1259:
	s_or_b64 exec, exec, s[44:45]
	s_and_b64 s[0:1], exec, vcc
	s_or_b64 s[42:43], s[0:1], s[42:43]
	v_pk_mul_f32 v[64:65], v[30:31], v[30:31]
	v_pk_mul_f32 v[66:67], v[28:29], v[28:29]
	v_pk_mul_f32 v[60:61], v[26:27], v[26:27]
	v_pk_mul_f32 v[62:63], v[24:25], v[24:25]
	v_pk_mov_b32 v[68:69], v[66:67], v[64:65] op_sel:[1,0]
	v_mov_b32_e32 v67, v65
	v_pk_add_f32 v[64:65], v[68:69], v[66:67]
	v_pk_mov_b32 v[66:67], v[62:63], v[60:61] op_sel:[1,0]
	v_mov_b32_e32 v63, v61
	v_pk_add_f32 v[60:61], v[66:67], v[62:63]
	v_pk_add_f32 v[64:65], v[64:65], v[64:65] op_sel_hi:[0,1]
	v_pk_add_f32 v[60:61], v[60:61], v[60:61] op_sel_hi:[0,1]
	v_mul_f32_e32 v60, v20, v20
	v_pk_fma_f32 v[62:63], v[20:21], v[20:21], v[60:61] op_sel_hi:[1,1,0]
	v_mul_f32_e32 v60, v22, v22
	v_pk_fma_f32 v[66:67], v[22:23], v[22:23], v[60:61] op_sel_hi:[1,1,0]
	v_mul_f32_e32 v62, v16, v16
	v_mul_f32_e32 v66, v17, v17
	v_mul_f32_e32 v64, v18, v18
	v_mul_f32_e32 v60, v19, v19
	v_pk_add_f32 v[62:63], v[62:63], v[66:67]
	v_pk_add_f32 v[60:61], v[64:65], v[60:61]
	s_mov_b32 s0, 0xf800000
	v_pk_add_f32 v[60:61], v[62:63], v[60:61]
	s_nop 0
	v_add_f32_e32 v59, v60, v61
	ds_bpermute_b32 v60, v49, v59
	s_waitcnt lgkmcnt(0)
	v_add_f32_e32 v59, v59, v60
	ds_bpermute_b32 v60, v54, v59
	s_waitcnt lgkmcnt(0)
	v_add_f32_e32 v59, v59, v60
	ds_bpermute_b32 v60, v55, v59
	s_waitcnt lgkmcnt(0)
	v_add_f32_e32 v59, v59, v60
	ds_bpermute_b32 v60, v56, v59
	s_waitcnt lgkmcnt(0)
	v_add_f32_e32 v59, v59, v60
	ds_bpermute_b32 v60, v57, v59
	s_waitcnt lgkmcnt(0)
	v_add_f32_e32 v59, v59, v60
	ds_bpermute_b32 v60, v58, v59
	s_waitcnt lgkmcnt(0)
	v_add_f32_e32 v59, v59, v60
	v_fmamk_f32 v59, v59, 0x3a800000, v137
	v_mul_f32_e32 v60, 0x4f800000, v59
	v_cmp_gt_f32_e32 vcc, s0, v59
	s_nop 1
	v_cndmask_b32_e32 v59, v59, v60, vcc
	v_sqrt_f32_e32 v60, v59
	s_nop 0
	v_add_u32_e32 v61, -1, v60
	v_add_u32_e32 v62, 1, v60
	v_fma_f32 v63, -v61, v60, v59
	v_fma_f32 v64, -v62, v60, v59
	v_cmp_ge_f32_e64 s[38:39], 0, v63
	s_nop 1
	v_cndmask_b32_e64 v60, v60, v61, s[38:39]
	v_cmp_lt_f32_e64 s[38:39], 0, v64
	s_nop 1
	v_cndmask_b32_e64 v60, v60, v62, s[38:39]
	v_mul_f32_e32 v61, 0x37800000, v60
	v_cndmask_b32_e32 v60, v60, v61, vcc
	v_cmp_class_f32_e32 vcc, v59, v169
	s_nop 1
	v_cndmask_b32_e32 v59, v60, v59, vcc
	v_div_scale_f32 v62, s[0:1], v59, v59, 1.0
	v_rcp_f32_e32 v63, v62
	v_div_scale_f32 v64, vcc, 1.0, v59, 1.0
	v_readlane_b32 s0, v253, 56
	v_fma_f32 v65, -v62, v63, 1.0
	v_fmac_f32_e32 v63, v65, v63
	v_mul_f32_e32 v65, v64, v63
	v_fma_f32 v66, -v62, v65, v64
	v_fmac_f32_e32 v65, v66, v63
	v_fma_f32 v62, -v62, v65, v64
	v_div_fmas_f32 v62, v62, v63, v65
	v_div_fixup_f32 v62, v62, v59, 1.0
	v_pk_mul_f32 v[28:29], v[28:29], v[62:63] op_sel_hi:[1,0]
	v_pk_mul_f32 v[30:31], v[30:31], v[62:63] op_sel_hi:[1,0]
	v_pk_mul_f32 v[24:25], v[24:25], v[62:63] op_sel_hi:[1,0]
	v_pk_mul_f32 v[26:27], v[26:27], v[62:63] op_sel_hi:[1,0]
	v_pk_mul_f32 v[20:21], v[20:21], v[62:63] op_sel_hi:[1,0]
	v_pk_mul_f32 v[22:23], v[22:23], v[62:63] op_sel_hi:[1,0]
	v_pk_mul_f32 v[16:17], v[16:17], v[62:63] op_sel_hi:[1,0]
	v_pk_mul_f32 v[18:19], v[18:19], v[62:63] op_sel_hi:[1,0]
	v_lshl_add_u64 v[60:61], v[50:51], 0, v[128:129]
	v_pk_mul_f32 v[30:31], v[2:3], v[30:31]
	v_pk_mul_f32 v[28:29], v[0:1], v[28:29]
	v_pk_mul_f32 v[26:27], v[6:7], v[26:27]
	v_pk_mul_f32 v[24:25], v[4:5], v[24:25]
	v_pk_mul_f32 v[22:23], v[10:11], v[22:23]
	v_pk_mul_f32 v[20:21], v[8:9], v[20:21]
	v_pk_mul_f32 v[18:19], v[14:15], v[18:19]
	v_pk_mul_f32 v[16:17], v[12:13], v[16:17]
	v_readlane_b32 s1, v253, 57
	global_store_dwordx4 v[60:61], v[28:31], off sc1
	global_store_dwordx4 v[60:61], v[24:27], off offset:1024 sc1
	global_store_dwordx4 v[60:61], v[20:23], off offset:2048 sc1
	global_store_dwordx4 v[60:61], v[16:19], off offset:3072 sc1
	v_lshl_add_u64 v[52:53], v[52:53], 0, s[0:1]
	v_lshl_add_u64 v[50:51], v[50:51], 0, s[0:1]
	s_waitcnt vmcnt(7)
	v_mov_b32_e32 v28, v32
	v_mov_b32_e32 v29, v33
	v_mov_b32_e32 v30, v34
	v_mov_b32_e32 v31, v35
	s_waitcnt vmcnt(6)
	v_mov_b32_e32 v24, v36
	v_mov_b32_e32 v25, v37
	v_mov_b32_e32 v26, v38
	v_mov_b32_e32 v27, v39
	s_waitcnt vmcnt(5)
	v_mov_b32_e32 v20, v40
	v_mov_b32_e32 v21, v41
	v_mov_b32_e32 v22, v42
	v_mov_b32_e32 v23, v43
	s_waitcnt vmcnt(4)
	v_mov_b32_e32 v16, v44
	v_mov_b32_e32 v17, v45
	v_mov_b32_e32 v18, v46
	v_mov_b32_e32 v19, v47
	s_andn2_b64 exec, exec, s[42:43]
	s_cbranch_execz .LBB0_1278

; #define GAS __attribute__((address_space(1)))
; __device__ __forceinline__ unsigned cvt_pk_bf16(float lo, float hi) { unsigned r; asm volatile("v_cvt_pk_bf16_f32 %0, %1, %2" : "=v"(r) : "v"(lo), "v"(hi)); return r; }
; __device__ __forceinline__ void phase_norm(const Params& P, int l, int sub, int addpart) {
;     ...
;         float ss = 0.f;
; #pragma unroll
;         for (int j = 0; j < 4; ++j) ss += (v[j].x * v[j].x + v[j].y * v[j].y) + (v[j].z * v[j].z + v[j].w * v[j].w);
;         const float rstd = 1.0f / sqrtf(wave_sum(ss) * (1.0f / 1024.0f) + 1e-6f);
; #pragma unroll
;         for (int j = 0; j < 4; ++j) { const f32x4 y = v[j] * rstd * gg[j] * (sc[j] + 1.0f) + sh[j];
;             u32x2 w; w.x = cvt_pk_bf16(y.x, y.y); w.y = cvt_pk_bf16(y.z, y.w); *(GAS u32x2*)((GAS bf16_t*)XN + (size_t)r * 1024 + 4 * lane + 256 * j) = w; }
;         if (rn < rend) {
; #pragma unroll
;             for (int j = 0; j < 4; ++j) { v[j] = vn[j]; sc[j] = scn[j]; sh[j] = shn[j]; } }
.LBB0_1269:
	s_or_b64 exec, exec, s[38:39]
	v_mov_b32_e32 v138, v58
	v_mov_b32_e32 v139, v56
	v_mov_b32_e32 v146, v59
	v_mov_b32_e32 v147, v57
	v_pk_mul_f32 v[138:139], v[138:139], v[138:139]
	v_pk_mul_f32 v[148:149], v[126:127], v[126:127]
	v_pk_fma_f32 v[138:139], v[146:147], v[146:147], v[138:139]
	v_pk_fma_f32 v[148:149], v[60:61], v[60:61], v[148:149]
	v_pk_add_f32 v[138:139], v[138:139], v[138:139] op_sel_hi:[0,1]
	v_pk_add_f32 v[148:149], v[148:149], v[148:149] op_sel_hi:[0,1]
	v_mul_f32_e32 v138, v52, v52
	v_mul_f32_e32 v151, v54, v54
	v_mul_f32_e32 v63, v55, v55
	v_mov_b32_e32 v150, v62
	v_pk_fma_f32 v[146:147], v[52:53], v[52:53], v[138:139] op_sel_hi:[1,1,0]
	v_mul_f32_e32 v148, v36, v36
	v_mul_f32_e32 v138, v37, v37
	v_pk_add_f32 v[150:151], v[62:63], v[150:151]
	v_mul_f32_e32 v146, v38, v38
	v_pk_add_f32 v[138:139], v[138:139], v[148:149]
	v_mul_f32_e32 v148, v62, v62
	v_mov_b32_e32 v149, v151
	v_pk_add_f32 v[146:147], v[148:149], v[146:147]
	s_and_b64 s[0:1], exec, vcc
	v_pk_add_f32 v[138:139], v[146:147], v[138:139]
	s_or_b64 s[26:27], s[0:1], s[26:27]
	v_add_f32_e32 v39, v138, v139
	ds_bpermute_b32 v63, v140, v39
	s_mov_b32 s0, 0xf800000
	v_mov_b32_e32 v146, v126
	v_mov_b32_e32 v147, v60
	v_mov_b32_e32 v60, v127
	s_waitcnt lgkmcnt(0)
	v_add_f32_e32 v39, v39, v63
	ds_bpermute_b32 v63, v141, v39
	v_pk_add_f32 v[42:43], v[42:43], 1.0 op_sel_hi:[1,0]
	v_pk_add_f32 v[40:41], v[40:41], 1.0 op_sel_hi:[1,0]
	s_waitcnt vmcnt(3)
	v_pk_add_f32 v[30:31], v[30:31], 1.0 op_sel_hi:[1,0]
	v_pk_add_f32 v[28:29], v[28:29], 1.0 op_sel_hi:[1,0]
	s_waitcnt lgkmcnt(0)
	v_add_f32_e32 v39, v39, v63
	ds_bpermute_b32 v63, v142, v39
	s_waitcnt vmcnt(2)
	v_pk_add_f32 v[16:17], v[16:17], 1.0 op_sel_hi:[1,0]
	v_pk_add_f32 v[18:19], v[18:19], 1.0 op_sel_hi:[1,0]
	s_waitcnt lgkmcnt(0)
	v_add_f32_e32 v39, v39, v63
	ds_bpermute_b32 v63, v143, v39
	s_waitcnt lgkmcnt(0)
	v_add_f32_e32 v39, v39, v63
	ds_bpermute_b32 v63, v144, v39
	s_waitcnt lgkmcnt(0)
	v_add_f32_e32 v39, v39, v63
	ds_bpermute_b32 v63, v145, v39
	s_waitcnt lgkmcnt(0)
	v_add_f32_e32 v39, v39, v63
	v_fmamk_f32 v39, v39, 0x3a800000, v137
	v_cmp_gt_f32_e32 vcc, s0, v39
	v_mul_f32_e32 v63, 0x4f800000, v39
	s_nop 0
	v_cndmask_b32_e32 v39, v39, v63, vcc
	v_sqrt_f32_e32 v63, v39
	s_nop 0
	v_add_u32_e32 v113, -1, v63
	v_fma_f32 v115, -v113, v63, v39
	v_cmp_ge_f32_e64 s[38:39], 0, v115
	v_add_u32_e32 v115, 1, v63
	s_nop 0
	v_cndmask_b32_e64 v113, v63, v113, s[38:39]
	v_fma_f32 v63, -v115, v63, v39
	v_cmp_lt_f32_e64 s[38:39], 0, v63
	s_nop 1
	v_cndmask_b32_e64 v63, v113, v115, s[38:39]
	v_mul_f32_e32 v113, 0x37800000, v63
	v_cndmask_b32_e32 v63, v63, v113, vcc
	v_cmp_class_f32_e32 vcc, v39, v169
	s_nop 1
	v_cndmask_b32_e32 v39, v63, v39, vcc
	v_div_scale_f32 v63, s[0:1], v39, v39, 1.0
	v_rcp_f32_e32 v113, v63
	v_readlane_b32 s0, v253, 34
	v_readlane_b32 s1, v253, 35
	v_fma_f32 v115, -v63, v113, 1.0
	v_fmac_f32_e32 v113, v115, v113
	v_div_scale_f32 v115, vcc, 1.0, v39, 1.0
	v_mul_f32_e32 v117, v115, v113
	v_fma_f32 v119, -v63, v117, v115
	v_fmac_f32_e32 v117, v119, v113
	v_fma_f32 v63, -v63, v117, v115
	v_div_fmas_f32 v63, v63, v113, v117
	v_div_fixup_f32 v138, v63, v39, 1.0
	v_pk_mul_f32 v[146:147], v[146:147], v[138:139] op_sel_hi:[1,0]
	v_pk_mul_f32 v[60:61], v[60:61], v[138:139] op_sel_hi:[1,0]
	v_pk_mul_f32 v[126:127], v[2:3], v[146:147]
	v_pk_mul_f32 v[60:61], v[0:1], v[60:61]
	v_pk_fma_f32 v[42:43], v[42:43], v[126:127], v[46:47]
	v_pk_fma_f32 v[40:41], v[40:41], v[60:61], v[44:45]
	s_waitcnt vmcnt(1)
	v_pk_add_f32 v[46:47], v[48:49], 1.0 op_sel_hi:[1,0]
	v_cvt_pk_bf16_f32 v40, v40, v41
	v_cvt_pk_bf16_f32 v41, v42, v43
	v_pk_mul_f32 v[42:43], v[56:57], v[138:139] op_sel_hi:[1,0]
	global_store_dwordx2 v[124:125], v[40:41], off offset:-1536 sc1
	v_pk_mul_f32 v[40:41], v[58:59], v[138:139] op_sel_hi:[1,0]
	v_pk_mul_f32 v[42:43], v[4:5], v[42:43]
	v_pk_mul_f32 v[40:41], v[6:7], v[40:41]
	v_pk_add_f32 v[44:45], v[50:51], 1.0 op_sel_hi:[1,0]
	v_pk_fma_f32 v[32:33], v[46:47], v[42:43], v[32:33]
	v_pk_fma_f32 v[34:35], v[44:45], v[40:41], v[34:35]
	v_cvt_pk_bf16_f32 v32, v32, v33
	v_mov_b32_e32 v39, v62
	v_cvt_pk_bf16_f32 v33, v34, v35
	global_store_dwordx2 v[124:125], v[32:33], off offset:-1024 sc1
	v_pk_mul_f32 v[32:33], v[54:55], v[138:139] op_sel_hi:[1,0]
	v_pk_mul_f32 v[34:35], v[52:53], v[138:139] op_sel_hi:[1,0]
	v_pk_mul_f32 v[32:33], v[10:11], v[32:33]
	v_pk_mul_f32 v[34:35], v[8:9], v[34:35]
	v_pk_fma_f32 v[26:27], v[30:31], v[32:33], v[26:27]
	v_pk_fma_f32 v[24:25], v[28:29], v[34:35], v[24:25]
	v_mov_b64_e32 v[28:29], v[92:93]
	v_cvt_pk_bf16_f32 v24, v24, v25
	v_cvt_pk_bf16_f32 v25, v26, v27
	v_pk_mul_f32 v[26:27], v[36:37], v[138:139] op_sel_hi:[1,0]
	global_store_dwordx2 v[124:125], v[24:25], off offset:-512 sc1
	v_pk_mul_f32 v[24:25], v[38:39], v[138:139] op_sel_hi:[1,0]
	v_pk_mul_f32 v[26:27], v[12:13], v[26:27]
	v_pk_mul_f32 v[24:25], v[14:15], v[24:25]
	s_waitcnt vmcnt(3)
	v_pk_fma_f32 v[16:17], v[16:17], v[26:27], v[20:21]
	v_pk_fma_f32 v[18:19], v[18:19], v[24:25], v[22:23]
	v_cvt_pk_bf16_f32 v16, v16, v17
	v_mov_b64_e32 v[48:49], v[96:97]
	v_cvt_pk_bf16_f32 v17, v18, v19
	global_store_dwordx2 v[124:125], v[16:17], off sc1
	v_mov_b64_e32 v[16:17], v[88:89]
	v_mov_b64_e32 v[40:41], v[68:69]
	v_mov_b64_e32 v[20:21], v[100:101]
	v_mov_b64_e32 v[24:25], v[84:85]
	v_mov_b64_e32 v[32:33], v[80:81]
	v_mov_b64_e32 v[44:45], v[72:73]
	v_lshl_add_u64 v[124:125], v[124:125], 0, s[0:1]
	v_mov_b32_e32 v138, v128
	v_mov_b64_e32 v[18:19], v[90:91]
	v_mov_b64_e32 v[30:31], v[94:95]
	v_mov_b64_e32 v[50:51], v[98:99]
	v_mov_b64_e32 v[42:43], v[70:71]
	v_mov_b64_e32 v[22:23], v[102:103]
	v_mov_b64_e32 v[26:27], v[86:87]
	v_mov_b64_e32 v[34:35], v[82:83]
	v_mov_b64_e32 v[46:47], v[74:75]
	v_mov_b32_e32 v127, v64
	v_mov_b32_e32 v61, v65
	v_mov_b32_e32 v126, v66
	v_mov_b32_e32 v60, v67
	v_mov_b32_e32 v56, v76
	v_mov_b32_e32 v57, v77
	v_mov_b32_e32 v58, v78
	v_mov_b32_e32 v59, v79
	v_mov_b32_e32 v52, v104
	v_mov_b32_e32 v53, v105
	v_mov_b32_e32 v54, v106
	v_mov_b32_e32 v55, v107
	v_mov_b32_e32 v36, v108
	v_mov_b32_e32 v37, v109
	v_mov_b32_e32 v38, v110
	v_mov_b32_e32 v62, v111
	s_andn2_b64 exec, exec, s[26:27]
	s_cbranch_execz .LBB0_1290

; __device__ __forceinline__ void phase_norm(const Params& P, int l, int sub, int addpart) {
;     ...
;         if (addpart && r >= TL) { float* hw = (float*)(P.ws + OFF_HC) + (size_t)(r - TL) * 1024;
; #pragma unroll
;             for (int j = 0; j < 4; ++j) *(f32x4*)(hw + 4 * lane + 256 * j) = v[j]; }
.LBB0_1274:
	s_or_b64 exec, exec, s[42:43]
	v_add_u32_e32 v39, 0x8000, v138
	v_cmp_gt_i32_e64 s[38:39], s25, v39
	s_and_saveexec_b64 s[0:1], s[38:39]
	s_xor_b64 s[38:39], exec, s[0:1]
	s_andn2_saveexec_b64 s[38:39], s[38:39]
	s_cbranch_execz .LBB0_1269
	v_mov_b32_e32 v139, v129
	v_lshlrev_b64 v[138:139], 12, v[138:139]
	v_lshl_add_u64 v[138:139], v[120:121], 0, v[138:139]
	v_mov_b32_e32 v146, v127
	v_mov_b32_e32 v147, v61
	v_mov_b32_e32 v148, v126
	v_mov_b32_e32 v149, v60
	v_mov_b32_e32 v39, v62
	global_store_dwordx4 v[138:139], v[146:149], off sc1
	global_store_dwordx4 v[138:139], v[56:59], off offset:1024 sc1
	global_store_dwordx4 v[138:139], v[52:55], off offset:2048 sc1
	global_store_dwordx4 v[138:139], v[36:39], off offset:3072 sc1
	s_branch .LBB0_1269
